# on top of the s_setprio deletion: 120 duplicate lgkmcnt(0) waits after barriers and 142 unneeded s_nop 0 before LDS-DMA removed (m0 written >=2 instructions earlier)
# speedup vs baseline: 1.0013x; 1.0013x over previous
.LBB0_387:
	s_add_u32 s20, s50, 0x100
	s_addc_u32 s21, s51, 0
	s_waitcnt lgkmcnt(0)
	s_add_u32 s46, s48, 0x100
	s_addc_u32 s47, s49, 0
	s_barrier
	v_mfma_f32_16x16x32_bf16 v[32:35], v[16:19], v[76:79], 0
	v_mfma_f32_16x16x32_bf16 v[36:39], v[24:27], v[76:79], 0
	s_waitcnt lgkmcnt(0)
	v_mfma_f32_16x16x32_bf16 v[40:43], v[16:19], v[84:87], 0
	v_mfma_f32_16x16x32_bf16 v[44:47], v[24:27], v[84:87], 0
	v_mfma_f32_16x16x32_bf16 v[48:51], v[16:19], v[92:95], 0
	v_mfma_f32_16x16x32_bf16 v[52:55], v[24:27], v[92:95], 0
	v_mfma_f32_16x16x32_bf16 v[56:59], v[16:19], v[64:67], 0
	v_mfma_f32_16x16x32_bf16 v[60:63], v[24:27], v[64:67], 0
	v_mfma_f32_16x16x32_bf16 v[32:35], v[20:23], v[80:83], v[32:35]
	v_mfma_f32_16x16x32_bf16 v[36:39], v[28:31], v[80:83], v[36:39]
	v_mfma_f32_16x16x32_bf16 v[40:43], v[20:23], v[88:91], v[40:43]
	v_mfma_f32_16x16x32_bf16 v[44:47], v[28:31], v[88:91], v[44:47]
	v_mfma_f32_16x16x32_bf16 v[48:51], v[20:23], v[96:99], v[48:51]
	v_mfma_f32_16x16x32_bf16 v[52:55], v[28:31], v[96:99], v[52:55]
	v_mfma_f32_16x16x32_bf16 v[56:59], v[20:23], v[72:75], v[56:59]
	v_mfma_f32_16x16x32_bf16 v[60:63], v[28:31], v[72:75], v[60:63]
	v_mfma_f32_16x16x32_bf16 v[68:71], v[0:3], v[76:79], 0
	v_mfma_f32_16x16x32_bf16 v[76:79], v[8:11], v[76:79], 0
	v_mfma_f32_16x16x32_bf16 v[68:71], v[4:7], v[80:83], v[68:71]
	v_mfma_f32_16x16x32_bf16 v[76:79], v[12:15], v[80:83], v[76:79]
	v_mfma_f32_16x16x32_bf16 v[80:83], v[0:3], v[84:87], 0
	v_mfma_f32_16x16x32_bf16 v[84:87], v[8:11], v[84:87], 0
	v_mfma_f32_16x16x32_bf16 v[80:83], v[4:7], v[88:91], v[80:83]
	v_mfma_f32_16x16x32_bf16 v[84:87], v[12:15], v[88:91], v[84:87]
	v_mfma_f32_16x16x32_bf16 v[88:91], v[0:3], v[92:95], 0
	v_mfma_f32_16x16x32_bf16 v[92:95], v[8:11], v[92:95], 0
	v_mfma_f32_16x16x32_bf16 v[88:91], v[4:7], v[96:99], v[88:91]
	v_mfma_f32_16x16x32_bf16 v[92:95], v[12:15], v[96:99], v[92:95]
	v_mfma_f32_16x16x32_bf16 v[96:99], v[0:3], v[64:67], 0
	v_mfma_f32_16x16x32_bf16 v[64:67], v[8:11], v[64:67], 0
	v_mfma_f32_16x16x32_bf16 v[128:131], v[4:7], v[72:75], v[96:99]
	v_mfma_f32_16x16x32_bf16 v[132:135], v[12:15], v[72:75], v[64:67]
	s_barrier
	s_mov_b32 m0, s58
	ds_read_b128 v[112:115], v145 offset:16384
	ds_read_b128 v[116:119], v145 offset:17408
	ds_read_b128 v[104:107], v145 offset:18432
	ds_read_b128 v[108:111], v145 offset:19456
	ds_read_b128 v[96:99], v145 offset:20480
	ds_read_b128 v[100:103], v145 offset:21504
	ds_read_b128 v[64:67], v145 offset:22528
	ds_read_b128 v[72:75], v145 offset:23552
	global_load_lds_dwordx4 v139, s[46:47]
	s_mov_b32 m0, s59
	s_nop 0
	global_load_lds_dwordx4 v141, s[46:47]
	s_add_u32 s46, s48, 0x80100
	s_addc_u32 s47, s49, 0
	s_mov_b32 m0, s60
	s_and_b64 vcc, exec, s[44:45]
	global_load_lds_dwordx4 v139, s[46:47]
	s_mov_b32 m0, s61
	s_nop 0
	global_load_lds_dwordx4 v141, s[46:47]
	s_mov_b32 m0, s41
	s_mov_b64 s[46:47], -1
	global_load_lds_dwordx4 v138, s[20:21]
	s_mov_b32 m0, s62
	s_nop 0
	global_load_lds_dwordx4 v140, s[20:21]
	s_cbranch_vccz .LBB0_389
	s_waitcnt vmcnt(8)
	s_mov_b64 s[46:47], 0

.LBB0_391:
	s_ashr_i32 s9, s8, 31
	s_lshl_b64 s[20:21], s[8:9], 20
	s_add_u32 s44, s26, s20
	s_addc_u32 s45, s27, s21
	s_ashr_i32 s37, s36, 31
	s_lshl_b64 s[20:21], s[36:37], 20
	s_add_u32 s46, s17, s20
	s_addc_u32 s47, s24, s21
	s_add_u32 s52, s50, 0x180
	s_addc_u32 s53, s51, 0
	s_waitcnt lgkmcnt(0)
	s_and_b64 s[20:21], s[42:43], exec
	s_cselect_b32 s9, s47, s49
	s_cselect_b32 s12, s46, s48
	s_cselect_b32 s20, s45, s51
	s_cselect_b32 s21, s44, s50
	s_add_u32 s54, s48, 0x180
	s_addc_u32 s55, s49, 0
	s_barrier
	s_waitcnt lgkmcnt(0)
	v_mfma_f32_16x16x32_bf16 v[120:123], v[16:19], v[112:115], 0
	v_mfma_f32_16x16x32_bf16 v[148:151], v[20:23], v[116:119], v[120:123]
	v_mfma_f32_16x16x32_bf16 v[120:123], v[24:27], v[112:115], 0
	v_mfma_f32_16x16x32_bf16 v[152:155], v[28:31], v[116:119], v[120:123]
	v_mfma_f32_16x16x32_bf16 v[120:123], v[16:19], v[104:107], 0
	v_mfma_f32_16x16x32_bf16 v[156:159], v[20:23], v[108:111], v[120:123]
	v_mfma_f32_16x16x32_bf16 v[120:123], v[24:27], v[104:107], 0
	v_mfma_f32_16x16x32_bf16 v[160:163], v[28:31], v[108:111], v[120:123]
	v_mfma_f32_16x16x32_bf16 v[120:123], v[16:19], v[96:99], 0
	v_mfma_f32_16x16x32_bf16 v[16:19], v[16:19], v[64:67], 0
	v_mfma_f32_16x16x32_bf16 v[164:167], v[20:23], v[100:103], v[120:123]
	v_mfma_f32_16x16x32_bf16 v[120:123], v[24:27], v[96:99], 0
	v_mfma_f32_16x16x32_bf16 v[20:23], v[20:23], v[72:75], v[16:19]
	v_mfma_f32_16x16x32_bf16 v[16:19], v[24:27], v[64:67], 0
	v_mfma_f32_16x16x32_bf16 v[168:171], v[28:31], v[100:103], v[120:123]
	v_mfma_f32_16x16x32_bf16 v[28:31], v[28:31], v[72:75], v[16:19]
	v_mfma_f32_16x16x32_bf16 v[16:19], v[0:3], v[112:115], 0
	v_mfma_f32_16x16x32_bf16 v[172:175], v[4:7], v[116:119], v[16:19]
	v_mfma_f32_16x16x32_bf16 v[16:19], v[8:11], v[112:115], 0
	v_mfma_f32_16x16x32_bf16 v[176:179], v[12:15], v[116:119], v[16:19]
	v_mfma_f32_16x16x32_bf16 v[16:19], v[0:3], v[104:107], 0
	v_mfma_f32_16x16x32_bf16 v[180:183], v[4:7], v[108:111], v[16:19]
	v_mfma_f32_16x16x32_bf16 v[16:19], v[8:11], v[104:107], 0
	v_mfma_f32_16x16x32_bf16 v[184:187], v[12:15], v[108:111], v[16:19]
	v_mfma_f32_16x16x32_bf16 v[16:19], v[0:3], v[96:99], 0
	v_mfma_f32_16x16x32_bf16 v[0:3], v[0:3], v[64:67], 0
	v_mfma_f32_16x16x32_bf16 v[188:191], v[4:7], v[100:103], v[16:19]
	v_mfma_f32_16x16x32_bf16 v[16:19], v[8:11], v[96:99], 0
	v_mfma_f32_16x16x32_bf16 v[4:7], v[4:7], v[72:75], v[0:3]
	v_mfma_f32_16x16x32_bf16 v[0:3], v[8:11], v[64:67], 0
	v_mfma_f32_16x16x32_bf16 v[192:195], v[12:15], v[100:103], v[16:19]
	v_mfma_f32_16x16x32_bf16 v[196:199], v[12:15], v[72:75], v[0:3]
	s_barrier
	v_add_u32_e32 v146, s71, v142
	v_add_u32_e32 v147, s72, v142
	s_nop 1
	ds_read_b128 v[0:3], v146
	ds_read_b128 v[8:11], v146 offset:1024
	ds_read_b128 v[12:15], v146 offset:2048
	ds_read_b128 v[200:203], v146 offset:3072
	ds_read_b128 v[204:207], v147
	ds_read_b128 v[208:211], v147 offset:1024
	ds_read_b128 v[212:215], v147 offset:2048
	ds_read_b128 v[216:219], v147 offset:3072
	s_add_u32 s56, s50, 0x80100
	s_addc_u32 s57, s51, 0
	s_mov_b32 m0, s63
	ds_read_b128 v[16:19], v145 offset:32768
	ds_read_b128 v[24:27], v145 offset:33792
	ds_read_b128 v[100:103], v145 offset:34816
	ds_read_b128 v[220:223], v145 offset:35840
	ds_read_b128 v[224:227], v145 offset:36864
	ds_read_b128 v[228:231], v145 offset:37888
	ds_read_b128 v[232:235], v145 offset:38912
	ds_read_b128 v[236:239], v145 offset:39936
	global_load_lds_dwordx4 v138, s[56:57]
	s_mov_b32 m0, s64
	s_nop 0
	global_load_lds_dwordx4 v140, s[56:57]
	s_waitcnt vmcnt(8)
	s_waitcnt lgkmcnt(0)
	s_barrier
	v_mfma_f32_16x16x32_bf16 v[32:35], v[0:3], v[16:19], v[32:35]
	v_mfma_f32_16x16x32_bf16 v[120:123], v[8:11], v[24:27], v[32:35]
	v_mfma_f32_16x16x32_bf16 v[32:35], v[12:15], v[16:19], v[36:39]
	v_mfma_f32_16x16x32_bf16 v[112:115], v[200:203], v[24:27], v[32:35]
	v_mfma_f32_16x16x32_bf16 v[32:35], v[0:3], v[100:103], v[40:43]
	v_mfma_f32_16x16x32_bf16 v[104:107], v[8:11], v[220:223], v[32:35]
	v_mfma_f32_16x16x32_bf16 v[32:35], v[12:15], v[100:103], v[44:47]
	v_mfma_f32_16x16x32_bf16 v[96:99], v[200:203], v[220:223], v[32:35]
	v_mfma_f32_16x16x32_bf16 v[32:35], v[0:3], v[224:227], v[48:51]
	v_mfma_f32_16x16x32_bf16 v[72:75], v[8:11], v[228:231], v[32:35]
	v_mfma_f32_16x16x32_bf16 v[32:35], v[12:15], v[224:227], v[52:55]
	v_mfma_f32_16x16x32_bf16 v[64:67], v[200:203], v[228:231], v[32:35]
	v_mfma_f32_16x16x32_bf16 v[32:35], v[0:3], v[232:235], v[56:59]
	v_mfma_f32_16x16x32_bf16 v[40:43], v[8:11], v[236:239], v[32:35]
	v_mfma_f32_16x16x32_bf16 v[32:35], v[12:15], v[232:235], v[60:63]
	v_mfma_f32_16x16x32_bf16 v[32:35], v[200:203], v[236:239], v[32:35]
	v_mfma_f32_16x16x32_bf16 v[36:39], v[204:207], v[16:19], v[68:71]
	v_mfma_f32_16x16x32_bf16 v[16:19], v[212:215], v[16:19], v[76:79]
	v_mfma_f32_16x16x32_bf16 v[116:119], v[216:219], v[24:27], v[16:19]
	v_mfma_f32_16x16x32_bf16 v[16:19], v[204:207], v[100:103], v[80:83]
	v_mfma_f32_16x16x32_bf16 v[108:111], v[208:211], v[220:223], v[16:19]
	v_mfma_f32_16x16x32_bf16 v[16:19], v[212:215], v[100:103], v[84:87]
	v_mfma_f32_16x16x32_bf16 v[100:103], v[216:219], v[220:223], v[16:19]
	v_mfma_f32_16x16x32_bf16 v[16:19], v[204:207], v[224:227], v[88:91]
	v_mfma_f32_16x16x32_bf16 v[76:79], v[208:211], v[228:231], v[16:19]
	v_mfma_f32_16x16x32_bf16 v[16:19], v[212:215], v[224:227], v[92:95]
	v_mfma_f32_16x16x32_bf16 v[68:71], v[216:219], v[228:231], v[16:19]
	v_mfma_f32_16x16x32_bf16 v[16:19], v[204:207], v[232:235], v[128:131]
	v_mfma_f32_16x16x32_bf16 v[44:47], v[208:211], v[236:239], v[16:19]
	v_mfma_f32_16x16x32_bf16 v[16:19], v[212:215], v[232:235], v[132:135]
	v_mfma_f32_16x16x32_bf16 v[124:127], v[208:211], v[24:27], v[36:39]
	v_mfma_f32_16x16x32_bf16 v[36:39], v[216:219], v[236:239], v[16:19]
	s_barrier
	s_add_i32 s37, s71, s25
	s_mov_b32 m0, s37
	s_add_i32 s39, s37, 0x2000
	ds_read_b128 v[52:55], v145 offset:49152
	ds_read_b128 v[60:63], v145 offset:50176
	ds_read_b128 v[128:131], v145 offset:51200
	ds_read_b128 v[132:135], v145 offset:52224
	ds_read_b128 v[220:223], v145 offset:53248
	ds_read_b128 v[224:227], v145 offset:54272
	ds_read_b128 v[228:231], v145 offset:55296
	ds_read_b128 v[232:235], v145 offset:56320
	global_load_lds_dwordx4 v139, s[54:55]
	s_mov_b32 m0, s39
	s_nop 0
	global_load_lds_dwordx4 v141, s[54:55]
	s_add_u32 s54, s48, 0x80180
	s_addc_u32 s55, s49, 0
	s_add_i32 s75, s72, s25
	s_mov_b32 m0, s75
	s_add_i32 s76, s75, 0x2000
	s_nop 0
	global_load_lds_dwordx4 v139, s[54:55]
	s_mov_b32 m0, s76
	s_nop 0
	global_load_lds_dwordx4 v141, s[54:55]
	s_mov_b32 m0, s65
	s_nop 0
	global_load_lds_dwordx4 v138, s[52:53]
	s_mov_b32 m0, s66
	s_nop 0
	global_load_lds_dwordx4 v140, s[52:53]
	s_waitcnt vmcnt(8)
	s_waitcnt lgkmcnt(0)
	s_barrier
	v_mfma_f32_16x16x32_bf16 v[16:19], v[0:3], v[52:55], v[148:151]
	v_mfma_f32_16x16x32_bf16 v[92:95], v[8:11], v[60:63], v[16:19]
	v_mfma_f32_16x16x32_bf16 v[16:19], v[12:15], v[52:55], v[152:155]
	v_mfma_f32_16x16x32_bf16 v[84:87], v[200:203], v[60:63], v[16:19]
	v_mfma_f32_16x16x32_bf16 v[16:19], v[0:3], v[128:131], v[156:159]
	v_mfma_f32_16x16x32_bf16 v[56:59], v[8:11], v[132:135], v[16:19]
	v_mfma_f32_16x16x32_bf16 v[16:19], v[12:15], v[128:131], v[160:163]
	v_mfma_f32_16x16x32_bf16 v[48:51], v[200:203], v[132:135], v[16:19]
	v_mfma_f32_16x16x32_bf16 v[16:19], v[0:3], v[220:223], v[164:167]
	v_mfma_f32_16x16x32_bf16 v[0:3], v[0:3], v[228:231], v[20:23]
	v_mfma_f32_16x16x32_bf16 v[24:27], v[8:11], v[224:227], v[16:19]
	v_mfma_f32_16x16x32_bf16 v[16:19], v[12:15], v[220:223], v[168:171]
	v_mfma_f32_16x16x32_bf16 v[8:11], v[8:11], v[232:235], v[0:3]
	v_mfma_f32_16x16x32_bf16 v[0:3], v[12:15], v[228:231], v[28:31]
	v_mfma_f32_16x16x32_bf16 v[16:19], v[200:203], v[224:227], v[16:19]
	v_mfma_f32_16x16x32_bf16 v[0:3], v[200:203], v[232:235], v[0:3]
	v_mfma_f32_16x16x32_bf16 v[12:15], v[204:207], v[52:55], v[172:175]
	v_mfma_f32_16x16x32_bf16 v[88:91], v[208:211], v[60:63], v[12:15]
	v_mfma_f32_16x16x32_bf16 v[12:15], v[212:215], v[52:55], v[176:179]
	v_mfma_f32_16x16x32_bf16 v[80:83], v[216:219], v[60:63], v[12:15]
	v_mfma_f32_16x16x32_bf16 v[12:15], v[204:207], v[128:131], v[180:183]
	v_mfma_f32_16x16x32_bf16 v[60:63], v[208:211], v[132:135], v[12:15]
	v_mfma_f32_16x16x32_bf16 v[12:15], v[212:215], v[128:131], v[184:187]
	v_mfma_f32_16x16x32_bf16 v[52:55], v[216:219], v[132:135], v[12:15]
	v_mfma_f32_16x16x32_bf16 v[12:15], v[204:207], v[220:223], v[188:191]
	v_mfma_f32_16x16x32_bf16 v[28:31], v[208:211], v[224:227], v[12:15]
	v_mfma_f32_16x16x32_bf16 v[12:15], v[212:215], v[220:223], v[192:195]
	v_mfma_f32_16x16x32_bf16 v[4:7], v[204:207], v[228:231], v[4:7]
	v_mfma_f32_16x16x32_bf16 v[20:23], v[216:219], v[224:227], v[12:15]
	v_mfma_f32_16x16x32_bf16 v[12:15], v[208:211], v[232:235], v[4:7]
	v_mfma_f32_16x16x32_bf16 v[4:7], v[212:215], v[228:231], v[196:199]
	v_mfma_f32_16x16x32_bf16 v[4:7], v[216:219], v[232:235], v[4:7]
	s_barrier
	s_add_u32 s56, s50, 0x100
	s_addc_u32 s57, s51, 0
	s_add_u32 s77, s48, 0x200
	s_addc_u32 s78, s49, 0
	s_mov_b32 s79, 0
.LBB0_392:
	s_add_u32 s48, s56, 0x100
	s_addc_u32 s49, s57, 0
	s_cmp_eq_u32 s79, 28
	s_cselect_b32 s54, s21, s48
	s_cselect_b32 s55, s20, s49
	s_cselect_b32 s52, s12, s77
	s_cselect_b32 s53, s9, s78
	s_add_u32 s50, s54, 0x80
	s_addc_u32 s51, s55, 0
	s_add_i32 s80, 0, 0x10000
	s_add_i32 s82, 0, 0x14000
	v_add_u32_e32 v152, s80, v142
	v_add_u32_e32 v168, s82, v142
	ds_read_b128 v[128:131], v152
	ds_read_b128 v[132:135], v152 offset:1024
	ds_read_b128 v[148:151], v152 offset:2048
	ds_read_b128 v[152:155], v152 offset:3072
	ds_read_b128 v[156:159], v168
	ds_read_b128 v[160:163], v168 offset:1024
	ds_read_b128 v[164:167], v168 offset:2048
	ds_read_b128 v[168:171], v168 offset:3072
	s_add_u32 s56, s56, 0x80080
	s_addc_u32 s57, s57, 0
	s_mov_b32 m0, s0
	ds_read_b128 v[172:175], v145
	ds_read_b128 v[176:179], v145 offset:1024
	ds_read_b128 v[180:183], v145 offset:2048
	ds_read_b128 v[184:187], v145 offset:3072
	ds_read_b128 v[188:191], v145 offset:4096
	ds_read_b128 v[192:195], v145 offset:5120
	ds_read_b128 v[196:199], v145 offset:6144
	ds_read_b128 v[200:203], v145 offset:7168
	global_load_lds_dwordx4 v138, s[56:57]
	s_mov_b32 m0, s1
	s_nop 0
	global_load_lds_dwordx4 v140, s[56:57]
	s_waitcnt vmcnt(8)
	s_waitcnt lgkmcnt(0)
	s_barrier
	v_mfma_f32_16x16x32_bf16 v[120:123], v[128:131], v[172:175], v[120:123]
	v_mfma_f32_16x16x32_bf16 v[112:115], v[148:151], v[172:175], v[112:115]
	v_mfma_f32_16x16x32_bf16 v[104:107], v[128:131], v[180:183], v[104:107]
	v_mfma_f32_16x16x32_bf16 v[96:99], v[148:151], v[180:183], v[96:99]
	v_mfma_f32_16x16x32_bf16 v[72:75], v[128:131], v[188:191], v[72:75]
	v_mfma_f32_16x16x32_bf16 v[64:67], v[148:151], v[188:191], v[64:67]
	v_mfma_f32_16x16x32_bf16 v[40:43], v[128:131], v[196:199], v[40:43]
	v_mfma_f32_16x16x32_bf16 v[32:35], v[148:151], v[196:199], v[32:35]
	v_mfma_f32_16x16x32_bf16 v[120:123], v[132:135], v[176:179], v[120:123]
	v_mfma_f32_16x16x32_bf16 v[112:115], v[152:155], v[176:179], v[112:115]
	v_mfma_f32_16x16x32_bf16 v[104:107], v[132:135], v[184:187], v[104:107]
	v_mfma_f32_16x16x32_bf16 v[96:99], v[152:155], v[184:187], v[96:99]
	v_mfma_f32_16x16x32_bf16 v[72:75], v[132:135], v[192:195], v[72:75]
	v_mfma_f32_16x16x32_bf16 v[64:67], v[152:155], v[192:195], v[64:67]
	v_mfma_f32_16x16x32_bf16 v[40:43], v[132:135], v[200:203], v[40:43]
	v_mfma_f32_16x16x32_bf16 v[32:35], v[152:155], v[200:203], v[32:35]
	v_mfma_f32_16x16x32_bf16 v[124:127], v[156:159], v[172:175], v[124:127]
	v_mfma_f32_16x16x32_bf16 v[116:119], v[164:167], v[172:175], v[116:119]
	v_mfma_f32_16x16x32_bf16 v[108:111], v[156:159], v[180:183], v[108:111]
	v_mfma_f32_16x16x32_bf16 v[100:103], v[164:167], v[180:183], v[100:103]
	v_mfma_f32_16x16x32_bf16 v[76:79], v[156:159], v[188:191], v[76:79]
	v_mfma_f32_16x16x32_bf16 v[68:71], v[164:167], v[188:191], v[68:71]
	v_mfma_f32_16x16x32_bf16 v[44:47], v[156:159], v[196:199], v[44:47]
	v_mfma_f32_16x16x32_bf16 v[36:39], v[164:167], v[196:199], v[36:39]
	v_mfma_f32_16x16x32_bf16 v[124:127], v[160:163], v[176:179], v[124:127]
	v_mfma_f32_16x16x32_bf16 v[116:119], v[168:171], v[176:179], v[116:119]
	v_mfma_f32_16x16x32_bf16 v[108:111], v[160:163], v[184:187], v[108:111]
	v_mfma_f32_16x16x32_bf16 v[100:103], v[168:171], v[184:187], v[100:103]
	v_mfma_f32_16x16x32_bf16 v[76:79], v[160:163], v[192:195], v[76:79]
	v_mfma_f32_16x16x32_bf16 v[68:71], v[168:171], v[192:195], v[68:71]
	v_mfma_f32_16x16x32_bf16 v[44:47], v[160:163], v[200:203], v[44:47]
	v_mfma_f32_16x16x32_bf16 v[36:39], v[168:171], v[200:203], v[36:39]
	s_barrier
	s_add_i32 s56, s80, s25
	s_mov_b32 m0, s56
	ds_read_b128 v[172:175], v145 offset:16384
	ds_read_b128 v[176:179], v145 offset:17408
	ds_read_b128 v[180:183], v145 offset:18432
	ds_read_b128 v[184:187], v145 offset:19456
	ds_read_b128 v[188:191], v145 offset:20480
	ds_read_b128 v[192:195], v145 offset:21504
	ds_read_b128 v[196:199], v145 offset:22528
	ds_read_b128 v[200:203], v145 offset:23552
	global_load_lds_dwordx4 v139, s[52:53]
	s_add_i32 m0, s56, 0x2000
	s_add_u32 s56, s52, 0x80000
	s_addc_u32 s57, s53, 0
	s_add_i32 s80, s82, s25
	s_nop 0
	global_load_lds_dwordx4 v141, s[52:53]
	s_mov_b32 m0, s80
	s_nop 0
	global_load_lds_dwordx4 v139, s[56:57]
	s_add_i32 m0, s80, 0x2000
	s_nop 0
	global_load_lds_dwordx4 v141, s[56:57]
	s_mov_b32 m0, s41
	s_nop 0
	global_load_lds_dwordx4 v138, s[54:55]
	s_mov_b32 m0, s62
	s_nop 0
	global_load_lds_dwordx4 v140, s[54:55]
	s_waitcnt vmcnt(8)
	s_waitcnt lgkmcnt(0)
	s_barrier
	v_mfma_f32_16x16x32_bf16 v[92:95], v[128:131], v[172:175], v[92:95]
	v_mfma_f32_16x16x32_bf16 v[84:87], v[148:151], v[172:175], v[84:87]
	v_mfma_f32_16x16x32_bf16 v[56:59], v[128:131], v[180:183], v[56:59]
	v_mfma_f32_16x16x32_bf16 v[48:51], v[148:151], v[180:183], v[48:51]
	v_mfma_f32_16x16x32_bf16 v[24:27], v[128:131], v[188:191], v[24:27]
	v_mfma_f32_16x16x32_bf16 v[16:19], v[148:151], v[188:191], v[16:19]
	v_mfma_f32_16x16x32_bf16 v[8:11], v[128:131], v[196:199], v[8:11]
	v_mfma_f32_16x16x32_bf16 v[0:3], v[148:151], v[196:199], v[0:3]
	v_mfma_f32_16x16x32_bf16 v[92:95], v[132:135], v[176:179], v[92:95]
	v_mfma_f32_16x16x32_bf16 v[84:87], v[152:155], v[176:179], v[84:87]
	v_mfma_f32_16x16x32_bf16 v[56:59], v[132:135], v[184:187], v[56:59]
	v_mfma_f32_16x16x32_bf16 v[48:51], v[152:155], v[184:187], v[48:51]
	v_mfma_f32_16x16x32_bf16 v[24:27], v[132:135], v[192:195], v[24:27]
	v_mfma_f32_16x16x32_bf16 v[16:19], v[152:155], v[192:195], v[16:19]
	v_mfma_f32_16x16x32_bf16 v[8:11], v[132:135], v[200:203], v[8:11]
	v_mfma_f32_16x16x32_bf16 v[0:3], v[152:155], v[200:203], v[0:3]
	v_mfma_f32_16x16x32_bf16 v[88:91], v[156:159], v[172:175], v[88:91]
	v_mfma_f32_16x16x32_bf16 v[80:83], v[164:167], v[172:175], v[80:83]
	v_mfma_f32_16x16x32_bf16 v[60:63], v[156:159], v[180:183], v[60:63]
	v_mfma_f32_16x16x32_bf16 v[52:55], v[164:167], v[180:183], v[52:55]
	v_mfma_f32_16x16x32_bf16 v[28:31], v[156:159], v[188:191], v[28:31]
	v_mfma_f32_16x16x32_bf16 v[20:23], v[164:167], v[188:191], v[20:23]
	v_mfma_f32_16x16x32_bf16 v[12:15], v[156:159], v[196:199], v[12:15]
	v_mfma_f32_16x16x32_bf16 v[4:7], v[164:167], v[196:199], v[4:7]
	v_mfma_f32_16x16x32_bf16 v[88:91], v[160:163], v[176:179], v[88:91]
	v_mfma_f32_16x16x32_bf16 v[80:83], v[168:171], v[176:179], v[80:83]
	v_mfma_f32_16x16x32_bf16 v[60:63], v[160:163], v[184:187], v[60:63]
	v_mfma_f32_16x16x32_bf16 v[52:55], v[168:171], v[184:187], v[52:55]
	v_mfma_f32_16x16x32_bf16 v[28:31], v[160:163], v[192:195], v[28:31]
	v_mfma_f32_16x16x32_bf16 v[20:23], v[168:171], v[192:195], v[20:23]
	v_mfma_f32_16x16x32_bf16 v[12:15], v[160:163], v[200:203], v[12:15]
	v_mfma_f32_16x16x32_bf16 v[4:7], v[168:171], v[200:203], v[4:7]
	s_barrier
	ds_read_b128 v[128:131], v146
	ds_read_b128 v[132:135], v146 offset:1024
	ds_read_b128 v[148:151], v146 offset:2048
	ds_read_b128 v[152:155], v146 offset:3072
	ds_read_b128 v[156:159], v147
	ds_read_b128 v[160:163], v147 offset:1024
	ds_read_b128 v[164:167], v147 offset:2048
	ds_read_b128 v[168:171], v147 offset:3072
	s_add_u32 s54, s54, 0x80000
	s_addc_u32 s55, s55, 0
	s_mov_b32 m0, s63
	ds_read_b128 v[172:175], v145 offset:32768
	ds_read_b128 v[176:179], v145 offset:33792
	ds_read_b128 v[180:183], v145 offset:34816
	ds_read_b128 v[184:187], v145 offset:35840
	ds_read_b128 v[188:191], v145 offset:36864
	ds_read_b128 v[192:195], v145 offset:37888
	ds_read_b128 v[196:199], v145 offset:38912
	ds_read_b128 v[200:203], v145 offset:39936
	global_load_lds_dwordx4 v138, s[54:55]
	s_mov_b32 m0, s64
	s_nop 0
	global_load_lds_dwordx4 v140, s[54:55]
	s_waitcnt vmcnt(8)
	s_waitcnt lgkmcnt(0)
	s_barrier
	v_mfma_f32_16x16x32_bf16 v[120:123], v[128:131], v[172:175], v[120:123]
	v_mfma_f32_16x16x32_bf16 v[112:115], v[148:151], v[172:175], v[112:115]
	v_mfma_f32_16x16x32_bf16 v[104:107], v[128:131], v[180:183], v[104:107]
	v_mfma_f32_16x16x32_bf16 v[96:99], v[148:151], v[180:183], v[96:99]
	v_mfma_f32_16x16x32_bf16 v[72:75], v[128:131], v[188:191], v[72:75]
	v_mfma_f32_16x16x32_bf16 v[64:67], v[148:151], v[188:191], v[64:67]
	v_mfma_f32_16x16x32_bf16 v[40:43], v[128:131], v[196:199], v[40:43]
	v_mfma_f32_16x16x32_bf16 v[32:35], v[148:151], v[196:199], v[32:35]
	v_mfma_f32_16x16x32_bf16 v[120:123], v[132:135], v[176:179], v[120:123]
	v_mfma_f32_16x16x32_bf16 v[112:115], v[152:155], v[176:179], v[112:115]
	v_mfma_f32_16x16x32_bf16 v[104:107], v[132:135], v[184:187], v[104:107]
	v_mfma_f32_16x16x32_bf16 v[96:99], v[152:155], v[184:187], v[96:99]
	v_mfma_f32_16x16x32_bf16 v[72:75], v[132:135], v[192:195], v[72:75]
	v_mfma_f32_16x16x32_bf16 v[64:67], v[152:155], v[192:195], v[64:67]
	v_mfma_f32_16x16x32_bf16 v[40:43], v[132:135], v[200:203], v[40:43]
	v_mfma_f32_16x16x32_bf16 v[32:35], v[152:155], v[200:203], v[32:35]
	v_mfma_f32_16x16x32_bf16 v[124:127], v[156:159], v[172:175], v[124:127]
	v_mfma_f32_16x16x32_bf16 v[116:119], v[164:167], v[172:175], v[116:119]
	v_mfma_f32_16x16x32_bf16 v[108:111], v[156:159], v[180:183], v[108:111]
	v_mfma_f32_16x16x32_bf16 v[100:103], v[164:167], v[180:183], v[100:103]
	v_mfma_f32_16x16x32_bf16 v[76:79], v[156:159], v[188:191], v[76:79]
	v_mfma_f32_16x16x32_bf16 v[68:71], v[164:167], v[188:191], v[68:71]
	v_mfma_f32_16x16x32_bf16 v[44:47], v[156:159], v[196:199], v[44:47]
	v_mfma_f32_16x16x32_bf16 v[36:39], v[164:167], v[196:199], v[36:39]
	v_mfma_f32_16x16x32_bf16 v[124:127], v[160:163], v[176:179], v[124:127]
	v_mfma_f32_16x16x32_bf16 v[116:119], v[168:171], v[176:179], v[116:119]
	v_mfma_f32_16x16x32_bf16 v[108:111], v[160:163], v[184:187], v[108:111]
	v_mfma_f32_16x16x32_bf16 v[100:103], v[168:171], v[184:187], v[100:103]
	v_mfma_f32_16x16x32_bf16 v[76:79], v[160:163], v[192:195], v[76:79]
	v_mfma_f32_16x16x32_bf16 v[68:71], v[168:171], v[192:195], v[68:71]
	v_mfma_f32_16x16x32_bf16 v[44:47], v[160:163], v[200:203], v[44:47]
	v_mfma_f32_16x16x32_bf16 v[36:39], v[168:171], v[200:203], v[36:39]
	s_barrier
	s_add_u32 s54, s52, 0x80
	s_mov_b32 m0, s37
	s_addc_u32 s55, s53, 0
	ds_read_b128 v[172:175], v145 offset:49152
	ds_read_b128 v[176:179], v145 offset:50176
	ds_read_b128 v[180:183], v145 offset:51200
	ds_read_b128 v[184:187], v145 offset:52224
	ds_read_b128 v[188:191], v145 offset:53248
	ds_read_b128 v[192:195], v145 offset:54272
	ds_read_b128 v[196:199], v145 offset:55296
	ds_read_b128 v[200:203], v145 offset:56320
	s_add_u32 s52, s52, 0x80080
	global_load_lds_dwordx4 v139, s[54:55]
	s_mov_b32 m0, s39
	s_addc_u32 s53, s53, 0
	global_load_lds_dwordx4 v141, s[54:55]
	s_mov_b32 m0, s75
	s_nop 0
	global_load_lds_dwordx4 v139, s[52:53]
	s_mov_b32 m0, s76
	s_nop 0
	global_load_lds_dwordx4 v141, s[52:53]
	s_mov_b32 m0, s65
	s_nop 0
	global_load_lds_dwordx4 v138, s[50:51]
	s_mov_b32 m0, s66
	s_nop 0
	global_load_lds_dwordx4 v140, s[50:51]
	s_waitcnt vmcnt(8)
	s_waitcnt lgkmcnt(0)
	s_barrier
	v_mfma_f32_16x16x32_bf16 v[92:95], v[128:131], v[172:175], v[92:95]
	v_mfma_f32_16x16x32_bf16 v[84:87], v[148:151], v[172:175], v[84:87]
	v_mfma_f32_16x16x32_bf16 v[56:59], v[128:131], v[180:183], v[56:59]
	v_mfma_f32_16x16x32_bf16 v[48:51], v[148:151], v[180:183], v[48:51]
	v_mfma_f32_16x16x32_bf16 v[24:27], v[128:131], v[188:191], v[24:27]
	v_mfma_f32_16x16x32_bf16 v[16:19], v[148:151], v[188:191], v[16:19]
	v_mfma_f32_16x16x32_bf16 v[8:11], v[128:131], v[196:199], v[8:11]
	v_mfma_f32_16x16x32_bf16 v[0:3], v[148:151], v[196:199], v[0:3]
	v_mfma_f32_16x16x32_bf16 v[92:95], v[132:135], v[176:179], v[92:95]
	v_mfma_f32_16x16x32_bf16 v[84:87], v[152:155], v[176:179], v[84:87]
	v_mfma_f32_16x16x32_bf16 v[56:59], v[132:135], v[184:187], v[56:59]
	v_mfma_f32_16x16x32_bf16 v[48:51], v[152:155], v[184:187], v[48:51]
	v_mfma_f32_16x16x32_bf16 v[24:27], v[132:135], v[192:195], v[24:27]
	v_mfma_f32_16x16x32_bf16 v[16:19], v[152:155], v[192:195], v[16:19]
	v_mfma_f32_16x16x32_bf16 v[8:11], v[132:135], v[200:203], v[8:11]
	v_mfma_f32_16x16x32_bf16 v[0:3], v[152:155], v[200:203], v[0:3]
	v_mfma_f32_16x16x32_bf16 v[88:91], v[156:159], v[172:175], v[88:91]
	v_mfma_f32_16x16x32_bf16 v[80:83], v[164:167], v[172:175], v[80:83]
	v_mfma_f32_16x16x32_bf16 v[60:63], v[156:159], v[180:183], v[60:63]
	v_mfma_f32_16x16x32_bf16 v[52:55], v[164:167], v[180:183], v[52:55]
	v_mfma_f32_16x16x32_bf16 v[28:31], v[156:159], v[188:191], v[28:31]
	v_mfma_f32_16x16x32_bf16 v[20:23], v[164:167], v[188:191], v[20:23]
	v_mfma_f32_16x16x32_bf16 v[12:15], v[156:159], v[196:199], v[12:15]
	v_mfma_f32_16x16x32_bf16 v[4:7], v[164:167], v[196:199], v[4:7]
	v_mfma_f32_16x16x32_bf16 v[88:91], v[160:163], v[176:179], v[88:91]
	v_mfma_f32_16x16x32_bf16 v[80:83], v[168:171], v[176:179], v[80:83]
	v_mfma_f32_16x16x32_bf16 v[60:63], v[160:163], v[184:187], v[60:63]
	v_mfma_f32_16x16x32_bf16 v[52:55], v[168:171], v[184:187], v[52:55]
	v_mfma_f32_16x16x32_bf16 v[28:31], v[160:163], v[192:195], v[28:31]
	v_mfma_f32_16x16x32_bf16 v[20:23], v[168:171], v[192:195], v[20:23]
	v_mfma_f32_16x16x32_bf16 v[12:15], v[160:163], v[200:203], v[12:15]
	v_mfma_f32_16x16x32_bf16 v[4:7], v[168:171], v[200:203], v[4:7]
	s_barrier
	s_add_i32 s79, s79, 2
	s_add_u32 s77, s77, 0x100
	s_addc_u32 s78, s78, 0
	s_cmp_gt_u32 s79, 29
	s_mov_b64 s[56:57], s[48:49]
	s_cbranch_scc0 .LBB0_392
	s_and_b64 vcc, exec, s[4:5]
	s_cbranch_vccz .LBB0_395
	s_barrier

.LBB0_424:
	s_add_u32 s20, s48, 0x100
	s_addc_u32 s21, s49, 0
	s_waitcnt lgkmcnt(0)
	s_add_u32 s44, s46, 0x100
	s_addc_u32 s45, s47, 0
	s_barrier
	s_waitcnt lgkmcnt(0)
	v_mfma_f32_16x16x32_bf16 v[32:35], v[16:19], v[72:75], 0
	v_mfma_f32_16x16x32_bf16 v[36:39], v[24:27], v[72:75], 0
	v_mfma_f32_16x16x32_bf16 v[40:43], v[16:19], v[80:83], 0
	v_mfma_f32_16x16x32_bf16 v[44:47], v[24:27], v[80:83], 0
	v_mfma_f32_16x16x32_bf16 v[48:51], v[16:19], v[92:95], 0
	v_mfma_f32_16x16x32_bf16 v[52:55], v[24:27], v[92:95], 0
	v_mfma_f32_16x16x32_bf16 v[56:59], v[16:19], v[60:63], 0
	v_mfma_f32_16x16x32_bf16 v[64:67], v[24:27], v[60:63], 0
	v_mfma_f32_16x16x32_bf16 v[32:35], v[20:23], v[76:79], v[32:35]
	v_mfma_f32_16x16x32_bf16 v[36:39], v[28:31], v[76:79], v[36:39]
	v_mfma_f32_16x16x32_bf16 v[40:43], v[20:23], v[84:87], v[40:43]
	v_mfma_f32_16x16x32_bf16 v[44:47], v[28:31], v[84:87], v[44:47]
	v_mfma_f32_16x16x32_bf16 v[48:51], v[20:23], v[96:99], v[48:51]
	v_mfma_f32_16x16x32_bf16 v[52:55], v[28:31], v[96:99], v[52:55]
	v_mfma_f32_16x16x32_bf16 v[56:59], v[20:23], v[88:91], v[56:59]
	v_mfma_f32_16x16x32_bf16 v[64:67], v[28:31], v[88:91], v[64:67]
	v_mfma_f32_16x16x32_bf16 v[68:71], v[0:3], v[72:75], 0
	v_mfma_f32_16x16x32_bf16 v[72:75], v[8:11], v[72:75], 0
	v_mfma_f32_16x16x32_bf16 v[68:71], v[4:7], v[76:79], v[68:71]
	v_mfma_f32_16x16x32_bf16 v[72:75], v[12:15], v[76:79], v[72:75]
	v_mfma_f32_16x16x32_bf16 v[76:79], v[0:3], v[80:83], 0
	v_mfma_f32_16x16x32_bf16 v[80:83], v[8:11], v[80:83], 0
	v_mfma_f32_16x16x32_bf16 v[76:79], v[4:7], v[84:87], v[76:79]
	v_mfma_f32_16x16x32_bf16 v[80:83], v[12:15], v[84:87], v[80:83]
	v_mfma_f32_16x16x32_bf16 v[84:87], v[0:3], v[92:95], 0
	v_mfma_f32_16x16x32_bf16 v[92:95], v[8:11], v[92:95], 0
	v_mfma_f32_16x16x32_bf16 v[128:131], v[12:15], v[96:99], v[92:95]
	v_mfma_f32_16x16x32_bf16 v[92:95], v[0:3], v[60:63], 0
	v_mfma_f32_16x16x32_bf16 v[60:63], v[8:11], v[60:63], 0
	v_mfma_f32_16x16x32_bf16 v[84:87], v[4:7], v[96:99], v[84:87]
	v_mfma_f32_16x16x32_bf16 v[132:135], v[4:7], v[88:91], v[92:95]
	v_mfma_f32_16x16x32_bf16 v[136:139], v[12:15], v[88:91], v[60:63]
	s_barrier
	s_mov_b32 m0, s39
	ds_read_b128 v[108:111], v150 offset:16384
	ds_read_b128 v[112:115], v150 offset:17408
	ds_read_b128 v[100:103], v150 offset:18432
	ds_read_b128 v[104:107], v150 offset:19456
	ds_read_b128 v[92:95], v150 offset:20480
	ds_read_b128 v[96:99], v150 offset:21504
	ds_read_b128 v[60:63], v150 offset:22528
	ds_read_b128 v[88:91], v150 offset:23552
	global_load_lds_dwordx4 v144, s[44:45]
	s_mov_b32 m0, s56
	s_nop 0
	global_load_lds_dwordx4 v146, s[44:45]
	s_add_u32 s44, s46, 0x80100
	s_addc_u32 s45, s47, 0
	s_mov_b32 m0, s57
	s_and_b64 vcc, exec, s[42:43]
	global_load_lds_dwordx4 v144, s[44:45]
	s_mov_b32 m0, s58
	s_nop 0
	global_load_lds_dwordx4 v146, s[44:45]
	s_mov_b32 m0, s26
	s_mov_b64 s[44:45], -1
	global_load_lds_dwordx4 v143, s[20:21]
	s_mov_b32 m0, s59
	s_nop 0
	global_load_lds_dwordx4 v145, s[20:21]
	s_cbranch_vccz .LBB0_426
	s_waitcnt vmcnt(8)
	s_mov_b64 s[44:45], 0

.LBB0_428:
	s_ashr_i32 s7, s6, 31
	s_lshl_b64 s[20:21], s[6:7], 20
	s_add_u32 s42, s14, s20
	s_addc_u32 s43, s15, s21
	s_ashr_i32 s9, s8, 31
	s_lshl_b64 s[20:21], s[8:9], 20
	s_add_u32 s44, s17, s20
	s_addc_u32 s45, s24, s21
	s_add_u32 s50, s48, 0x180
	s_addc_u32 s51, s49, 0
	s_waitcnt lgkmcnt(0)
	s_and_b64 s[20:21], s[40:41], exec
	s_cselect_b32 s9, s45, s47
	s_cselect_b32 s12, s44, s46
	s_cselect_b32 s20, s43, s49
	s_cselect_b32 s21, s42, s48
	s_add_u32 s52, s46, 0x180
	s_addc_u32 s53, s47, 0
	s_barrier
	s_waitcnt lgkmcnt(0)
	v_mfma_f32_16x16x32_bf16 v[116:119], v[16:19], v[108:111], 0
	v_mfma_f32_16x16x32_bf16 v[156:159], v[20:23], v[112:115], v[116:119]
	v_mfma_f32_16x16x32_bf16 v[116:119], v[24:27], v[108:111], 0
	v_mfma_f32_16x16x32_bf16 v[160:163], v[28:31], v[112:115], v[116:119]
	v_mfma_f32_16x16x32_bf16 v[116:119], v[16:19], v[100:103], 0
	v_mfma_f32_16x16x32_bf16 v[164:167], v[20:23], v[104:107], v[116:119]
	v_mfma_f32_16x16x32_bf16 v[116:119], v[24:27], v[100:103], 0
	v_mfma_f32_16x16x32_bf16 v[168:171], v[28:31], v[104:107], v[116:119]
	v_mfma_f32_16x16x32_bf16 v[116:119], v[16:19], v[92:95], 0
	v_mfma_f32_16x16x32_bf16 v[16:19], v[16:19], v[60:63], 0
	v_mfma_f32_16x16x32_bf16 v[172:175], v[20:23], v[96:99], v[116:119]
	v_mfma_f32_16x16x32_bf16 v[16:19], v[20:23], v[88:91], v[16:19]
	v_mfma_f32_16x16x32_bf16 v[20:23], v[24:27], v[60:63], 0
	v_mfma_f32_16x16x32_bf16 v[116:119], v[24:27], v[92:95], 0
	v_mfma_f32_16x16x32_bf16 v[20:23], v[28:31], v[88:91], v[20:23]
	v_mfma_f32_16x16x32_bf16 v[176:179], v[28:31], v[96:99], v[116:119]
	v_mfma_f32_16x16x32_bf16 v[24:27], v[0:3], v[108:111], 0
	v_mfma_f32_16x16x32_bf16 v[180:183], v[4:7], v[112:115], v[24:27]
	v_mfma_f32_16x16x32_bf16 v[24:27], v[8:11], v[108:111], 0
	v_mfma_f32_16x16x32_bf16 v[184:187], v[12:15], v[112:115], v[24:27]
	v_mfma_f32_16x16x32_bf16 v[24:27], v[0:3], v[100:103], 0
	v_mfma_f32_16x16x32_bf16 v[188:191], v[4:7], v[104:107], v[24:27]
	v_mfma_f32_16x16x32_bf16 v[24:27], v[8:11], v[100:103], 0
	v_mfma_f32_16x16x32_bf16 v[192:195], v[12:15], v[104:107], v[24:27]
	v_mfma_f32_16x16x32_bf16 v[24:27], v[0:3], v[92:95], 0
	v_mfma_f32_16x16x32_bf16 v[0:3], v[0:3], v[60:63], 0
	v_mfma_f32_16x16x32_bf16 v[196:199], v[4:7], v[96:99], v[24:27]
	v_mfma_f32_16x16x32_bf16 v[24:27], v[8:11], v[92:95], 0
	v_mfma_f32_16x16x32_bf16 v[0:3], v[4:7], v[88:91], v[0:3]
	v_mfma_f32_16x16x32_bf16 v[4:7], v[8:11], v[60:63], 0
	v_mfma_f32_16x16x32_bf16 v[200:203], v[12:15], v[96:99], v[24:27]
	v_mfma_f32_16x16x32_bf16 v[204:207], v[12:15], v[88:91], v[4:7]
	s_barrier
	v_add_u32_e32 v153, s69, v147
	v_add_u32_e32 v154, s70, v147
	s_nop 1
	ds_read_b128 v[4:7], v153
	ds_read_b128 v[8:11], v153 offset:1024
	ds_read_b128 v[208:211], v153 offset:2048
	ds_read_b128 v[212:215], v153 offset:3072
	ds_read_b128 v[216:219], v154
	ds_read_b128 v[220:223], v154 offset:1024
	ds_read_b128 v[224:227], v154 offset:2048
	ds_read_b128 v[228:231], v154 offset:3072
	s_add_u32 s54, s48, 0x80100
	s_addc_u32 s55, s49, 0
	s_mov_b32 m0, s60
	ds_read_b128 v[12:15], v150 offset:32768
	ds_read_b128 v[24:27], v150 offset:33792
	ds_read_b128 v[28:31], v150 offset:34816
	ds_read_b128 v[96:99], v150 offset:35840
	ds_read_b128 v[232:235], v150 offset:36864
	ds_read_b128 v[236:239], v150 offset:37888
	ds_read_b128 v[240:243], v150 offset:38912
	ds_read_b128 v[244:247], v150 offset:39936
	global_load_lds_dwordx4 v143, s[54:55]
	s_mov_b32 m0, s61
	s_nop 0
	global_load_lds_dwordx4 v145, s[54:55]
	s_waitcnt vmcnt(8)
	s_waitcnt lgkmcnt(0)
	s_barrier
	v_mfma_f32_16x16x32_bf16 v[32:35], v[4:7], v[12:15], v[32:35]
	v_mfma_f32_16x16x32_bf16 v[124:127], v[8:11], v[24:27], v[32:35]
	v_mfma_f32_16x16x32_bf16 v[32:35], v[208:211], v[12:15], v[36:39]
	v_mfma_f32_16x16x32_bf16 v[120:123], v[212:215], v[24:27], v[32:35]
	v_mfma_f32_16x16x32_bf16 v[32:35], v[4:7], v[28:31], v[40:43]
	v_mfma_f32_16x16x32_bf16 v[108:111], v[8:11], v[96:99], v[32:35]
	v_mfma_f32_16x16x32_bf16 v[32:35], v[208:211], v[28:31], v[44:47]
	v_mfma_f32_16x16x32_bf16 v[104:107], v[212:215], v[96:99], v[32:35]
	v_mfma_f32_16x16x32_bf16 v[32:35], v[4:7], v[232:235], v[48:51]
	v_mfma_f32_16x16x32_bf16 v[92:95], v[8:11], v[236:239], v[32:35]
	v_mfma_f32_16x16x32_bf16 v[32:35], v[208:211], v[232:235], v[52:55]
	v_mfma_f32_16x16x32_bf16 v[88:91], v[212:215], v[236:239], v[32:35]
	v_mfma_f32_16x16x32_bf16 v[32:35], v[4:7], v[240:243], v[56:59]
	v_mfma_f32_16x16x32_bf16 v[60:63], v[8:11], v[244:247], v[32:35]
	v_mfma_f32_16x16x32_bf16 v[32:35], v[208:211], v[240:243], v[64:67]
	v_mfma_f32_16x16x32_bf16 v[56:59], v[212:215], v[244:247], v[32:35]
	v_mfma_f32_16x16x32_bf16 v[32:35], v[216:219], v[12:15], v[68:71]
	v_mfma_f32_16x16x32_bf16 v[12:15], v[224:227], v[12:15], v[72:75]
	v_mfma_f32_16x16x32_bf16 v[112:115], v[228:231], v[24:27], v[12:15]
	v_mfma_f32_16x16x32_bf16 v[12:15], v[216:219], v[28:31], v[76:79]
	v_mfma_f32_16x16x32_bf16 v[100:103], v[220:223], v[96:99], v[12:15]
	v_mfma_f32_16x16x32_bf16 v[12:15], v[224:227], v[28:31], v[80:83]
	v_mfma_f32_16x16x32_bf16 v[96:99], v[228:231], v[96:99], v[12:15]
	v_mfma_f32_16x16x32_bf16 v[12:15], v[216:219], v[232:235], v[84:87]
	v_mfma_f32_16x16x32_bf16 v[84:87], v[220:223], v[236:239], v[12:15]
	v_mfma_f32_16x16x32_bf16 v[12:15], v[224:227], v[232:235], v[128:131]
	v_mfma_f32_16x16x32_bf16 v[80:83], v[228:231], v[236:239], v[12:15]
	v_mfma_f32_16x16x32_bf16 v[12:15], v[216:219], v[240:243], v[132:135]
	v_mfma_f32_16x16x32_bf16 v[52:55], v[220:223], v[244:247], v[12:15]
	v_mfma_f32_16x16x32_bf16 v[12:15], v[224:227], v[240:243], v[136:139]
	v_mfma_f32_16x16x32_bf16 v[116:119], v[220:223], v[24:27], v[32:35]
	v_mfma_f32_16x16x32_bf16 v[48:51], v[228:231], v[244:247], v[12:15]
	s_barrier
	s_add_i32 s37, s69, s25
	s_mov_b32 m0, s37
	s_add_i32 s74, s37, 0x2000
	ds_read_b128 v[32:35], v150 offset:49152
	ds_read_b128 v[36:39], v150 offset:50176
	ds_read_b128 v[128:131], v150 offset:51200
	ds_read_b128 v[132:135], v150 offset:52224
	ds_read_b128 v[136:139], v150 offset:53248
	ds_read_b128 v[232:235], v150 offset:54272
	ds_read_b128 v[236:239], v150 offset:55296
	ds_read_b128 v[240:243], v150 offset:56320
	global_load_lds_dwordx4 v144, s[52:53]
	s_mov_b32 m0, s74
	s_nop 0
	global_load_lds_dwordx4 v146, s[52:53]
	s_add_u32 s52, s46, 0x80180
	s_addc_u32 s53, s47, 0
	s_add_i32 s75, s70, s25
	s_mov_b32 m0, s75
	s_add_i32 s76, s75, 0x2000
	s_nop 0
	global_load_lds_dwordx4 v144, s[52:53]
	s_mov_b32 m0, s76
	s_nop 0
	global_load_lds_dwordx4 v146, s[52:53]
	s_mov_b32 m0, s62
	s_nop 0
	global_load_lds_dwordx4 v143, s[50:51]
	s_mov_b32 m0, s63
	s_nop 0
	global_load_lds_dwordx4 v145, s[50:51]
	s_waitcnt vmcnt(8)
	s_waitcnt lgkmcnt(0)
	s_barrier
	v_mfma_f32_16x16x32_bf16 v[12:15], v[4:7], v[32:35], v[156:159]
	v_mfma_f32_16x16x32_bf16 v[76:79], v[8:11], v[36:39], v[12:15]
	v_mfma_f32_16x16x32_bf16 v[12:15], v[208:211], v[32:35], v[160:163]
	v_mfma_f32_16x16x32_bf16 v[72:75], v[212:215], v[36:39], v[12:15]
	v_mfma_f32_16x16x32_bf16 v[12:15], v[4:7], v[128:131], v[164:167]
	v_mfma_f32_16x16x32_bf16 v[44:47], v[8:11], v[132:135], v[12:15]
	v_mfma_f32_16x16x32_bf16 v[12:15], v[208:211], v[128:131], v[168:171]
	v_mfma_f32_16x16x32_bf16 v[40:43], v[212:215], v[132:135], v[12:15]
	v_mfma_f32_16x16x32_bf16 v[12:15], v[4:7], v[136:139], v[172:175]
	v_mfma_f32_16x16x32_bf16 v[28:31], v[8:11], v[232:235], v[12:15]
	v_mfma_f32_16x16x32_bf16 v[12:15], v[208:211], v[136:139], v[176:179]
	v_mfma_f32_16x16x32_bf16 v[4:7], v[4:7], v[236:239], v[16:19]
	v_mfma_f32_16x16x32_bf16 v[24:27], v[212:215], v[232:235], v[12:15]
	v_mfma_f32_16x16x32_bf16 v[12:15], v[8:11], v[240:243], v[4:7]
	v_mfma_f32_16x16x32_bf16 v[4:7], v[208:211], v[236:239], v[20:23]
	v_mfma_f32_16x16x32_bf16 v[8:11], v[212:215], v[240:243], v[4:7]
	v_mfma_f32_16x16x32_bf16 v[4:7], v[216:219], v[32:35], v[180:183]
	v_mfma_f32_16x16x32_bf16 v[68:71], v[220:223], v[36:39], v[4:7]
	v_mfma_f32_16x16x32_bf16 v[4:7], v[224:227], v[32:35], v[184:187]
	v_mfma_f32_16x16x32_bf16 v[64:67], v[228:231], v[36:39], v[4:7]
	v_mfma_f32_16x16x32_bf16 v[4:7], v[216:219], v[128:131], v[188:191]
	v_mfma_f32_16x16x32_bf16 v[36:39], v[220:223], v[132:135], v[4:7]
	v_mfma_f32_16x16x32_bf16 v[4:7], v[224:227], v[128:131], v[192:195]
	v_mfma_f32_16x16x32_bf16 v[32:35], v[228:231], v[132:135], v[4:7]
	v_mfma_f32_16x16x32_bf16 v[4:7], v[216:219], v[136:139], v[196:199]
	v_mfma_f32_16x16x32_bf16 v[20:23], v[220:223], v[232:235], v[4:7]
	v_mfma_f32_16x16x32_bf16 v[4:7], v[224:227], v[136:139], v[200:203]
	v_mfma_f32_16x16x32_bf16 v[0:3], v[216:219], v[236:239], v[0:3]
	v_mfma_f32_16x16x32_bf16 v[16:19], v[228:231], v[232:235], v[4:7]
	v_mfma_f32_16x16x32_bf16 v[4:7], v[220:223], v[240:243], v[0:3]
	v_mfma_f32_16x16x32_bf16 v[0:3], v[224:227], v[236:239], v[204:207]
	v_mfma_f32_16x16x32_bf16 v[0:3], v[228:231], v[240:243], v[0:3]
	s_barrier
	s_add_u32 s54, s48, 0x100
	s_addc_u32 s55, s49, 0
	s_add_u32 s77, s46, 0x200
	s_addc_u32 s78, s47, 0
	s_mov_b32 s79, 0
.LBB0_429:
	s_add_u32 s46, s54, 0x100
	s_addc_u32 s47, s55, 0
	s_cmp_eq_u32 s79, 28
	s_cselect_b32 s52, s21, s46
	s_cselect_b32 s53, s20, s47
	s_cselect_b32 s50, s12, s77
	s_cselect_b32 s51, s9, s78
	s_add_u32 s48, s52, 0x80
	s_addc_u32 s49, s53, 0
	s_add_i32 s80, 0, 0x10000
	v_add_u32_e32 v155, s80, v147
	s_add_i32 s82, 0, 0x14000
	ds_read_b128 v[128:131], v155
	ds_read_b128 v[132:135], v155 offset:1024
	ds_read_b128 v[136:139], v155 offset:2048
	ds_read_b128 v[156:159], v155 offset:3072
	v_add_u32_e32 v155, s82, v147
	ds_read_b128 v[160:163], v155
	ds_read_b128 v[164:167], v155 offset:1024
	ds_read_b128 v[168:171], v155 offset:2048
	ds_read_b128 v[172:175], v155 offset:3072
	s_add_u32 s54, s54, 0x80080
	s_addc_u32 s55, s55, 0
	s_mov_b32 m0, s0
	ds_read_b128 v[176:179], v150
	ds_read_b128 v[180:183], v150 offset:1024
	ds_read_b128 v[184:187], v150 offset:2048
	ds_read_b128 v[188:191], v150 offset:3072
	ds_read_b128 v[192:195], v150 offset:4096
	ds_read_b128 v[196:199], v150 offset:5120
	ds_read_b128 v[200:203], v150 offset:6144
	ds_read_b128 v[204:207], v150 offset:7168
	global_load_lds_dwordx4 v143, s[54:55]
	s_mov_b32 m0, s1
	s_nop 0
	global_load_lds_dwordx4 v145, s[54:55]
	s_waitcnt vmcnt(8)
	s_waitcnt lgkmcnt(0)
	s_barrier
	v_mfma_f32_16x16x32_bf16 v[124:127], v[128:131], v[176:179], v[124:127]
	v_mfma_f32_16x16x32_bf16 v[120:123], v[136:139], v[176:179], v[120:123]
	v_mfma_f32_16x16x32_bf16 v[108:111], v[128:131], v[184:187], v[108:111]
	v_mfma_f32_16x16x32_bf16 v[104:107], v[136:139], v[184:187], v[104:107]
	v_mfma_f32_16x16x32_bf16 v[92:95], v[128:131], v[192:195], v[92:95]
	v_mfma_f32_16x16x32_bf16 v[88:91], v[136:139], v[192:195], v[88:91]
	v_mfma_f32_16x16x32_bf16 v[60:63], v[128:131], v[200:203], v[60:63]
	v_mfma_f32_16x16x32_bf16 v[56:59], v[136:139], v[200:203], v[56:59]
	v_mfma_f32_16x16x32_bf16 v[124:127], v[132:135], v[180:183], v[124:127]
	v_mfma_f32_16x16x32_bf16 v[120:123], v[156:159], v[180:183], v[120:123]
	v_mfma_f32_16x16x32_bf16 v[108:111], v[132:135], v[188:191], v[108:111]
	v_mfma_f32_16x16x32_bf16 v[104:107], v[156:159], v[188:191], v[104:107]
	v_mfma_f32_16x16x32_bf16 v[92:95], v[132:135], v[196:199], v[92:95]
	v_mfma_f32_16x16x32_bf16 v[88:91], v[156:159], v[196:199], v[88:91]
	v_mfma_f32_16x16x32_bf16 v[60:63], v[132:135], v[204:207], v[60:63]
	v_mfma_f32_16x16x32_bf16 v[56:59], v[156:159], v[204:207], v[56:59]
	v_mfma_f32_16x16x32_bf16 v[116:119], v[160:163], v[176:179], v[116:119]
	v_mfma_f32_16x16x32_bf16 v[112:115], v[168:171], v[176:179], v[112:115]
	v_mfma_f32_16x16x32_bf16 v[100:103], v[160:163], v[184:187], v[100:103]
	v_mfma_f32_16x16x32_bf16 v[96:99], v[168:171], v[184:187], v[96:99]
	v_mfma_f32_16x16x32_bf16 v[84:87], v[160:163], v[192:195], v[84:87]
	v_mfma_f32_16x16x32_bf16 v[80:83], v[168:171], v[192:195], v[80:83]
	v_mfma_f32_16x16x32_bf16 v[52:55], v[160:163], v[200:203], v[52:55]
	v_mfma_f32_16x16x32_bf16 v[48:51], v[168:171], v[200:203], v[48:51]
	v_mfma_f32_16x16x32_bf16 v[116:119], v[164:167], v[180:183], v[116:119]
	v_mfma_f32_16x16x32_bf16 v[112:115], v[172:175], v[180:183], v[112:115]
	v_mfma_f32_16x16x32_bf16 v[100:103], v[164:167], v[188:191], v[100:103]
	v_mfma_f32_16x16x32_bf16 v[96:99], v[172:175], v[188:191], v[96:99]
	v_mfma_f32_16x16x32_bf16 v[84:87], v[164:167], v[196:199], v[84:87]
	v_mfma_f32_16x16x32_bf16 v[80:83], v[172:175], v[196:199], v[80:83]
	v_mfma_f32_16x16x32_bf16 v[52:55], v[164:167], v[204:207], v[52:55]
	v_mfma_f32_16x16x32_bf16 v[48:51], v[172:175], v[204:207], v[48:51]
	s_barrier
	s_add_i32 s54, s80, s25
	s_mov_b32 m0, s54
	ds_read_b128 v[176:179], v150 offset:16384
	ds_read_b128 v[180:183], v150 offset:17408
	ds_read_b128 v[184:187], v150 offset:18432
	ds_read_b128 v[188:191], v150 offset:19456
	ds_read_b128 v[192:195], v150 offset:20480
	ds_read_b128 v[196:199], v150 offset:21504
	ds_read_b128 v[200:203], v150 offset:22528
	ds_read_b128 v[204:207], v150 offset:23552
	global_load_lds_dwordx4 v144, s[50:51]
	s_add_i32 m0, s54, 0x2000
	s_add_u32 s54, s50, 0x80000
	s_addc_u32 s55, s51, 0
	s_add_i32 s80, s82, s25
	s_nop 0
	global_load_lds_dwordx4 v146, s[50:51]
	s_mov_b32 m0, s80
	s_nop 0
	global_load_lds_dwordx4 v144, s[54:55]
	s_add_i32 m0, s80, 0x2000
	s_nop 0
	global_load_lds_dwordx4 v146, s[54:55]
	s_mov_b32 m0, s26
	s_nop 0
	global_load_lds_dwordx4 v143, s[52:53]
	s_mov_b32 m0, s59
	s_nop 0
	global_load_lds_dwordx4 v145, s[52:53]
	s_waitcnt vmcnt(8)
	s_waitcnt lgkmcnt(0)
	s_barrier
	v_mfma_f32_16x16x32_bf16 v[76:79], v[128:131], v[176:179], v[76:79]
	v_mfma_f32_16x16x32_bf16 v[72:75], v[136:139], v[176:179], v[72:75]
	v_mfma_f32_16x16x32_bf16 v[44:47], v[128:131], v[184:187], v[44:47]
	v_mfma_f32_16x16x32_bf16 v[40:43], v[136:139], v[184:187], v[40:43]
	v_mfma_f32_16x16x32_bf16 v[28:31], v[128:131], v[192:195], v[28:31]
	v_mfma_f32_16x16x32_bf16 v[24:27], v[136:139], v[192:195], v[24:27]
	v_mfma_f32_16x16x32_bf16 v[12:15], v[128:131], v[200:203], v[12:15]
	v_mfma_f32_16x16x32_bf16 v[8:11], v[136:139], v[200:203], v[8:11]
	v_mfma_f32_16x16x32_bf16 v[76:79], v[132:135], v[180:183], v[76:79]
	v_mfma_f32_16x16x32_bf16 v[72:75], v[156:159], v[180:183], v[72:75]
	v_mfma_f32_16x16x32_bf16 v[44:47], v[132:135], v[188:191], v[44:47]
	v_mfma_f32_16x16x32_bf16 v[40:43], v[156:159], v[188:191], v[40:43]
	v_mfma_f32_16x16x32_bf16 v[28:31], v[132:135], v[196:199], v[28:31]
	v_mfma_f32_16x16x32_bf16 v[24:27], v[156:159], v[196:199], v[24:27]
	v_mfma_f32_16x16x32_bf16 v[12:15], v[132:135], v[204:207], v[12:15]
	v_mfma_f32_16x16x32_bf16 v[8:11], v[156:159], v[204:207], v[8:11]
	v_mfma_f32_16x16x32_bf16 v[68:71], v[160:163], v[176:179], v[68:71]
	v_mfma_f32_16x16x32_bf16 v[64:67], v[168:171], v[176:179], v[64:67]
	v_mfma_f32_16x16x32_bf16 v[36:39], v[160:163], v[184:187], v[36:39]
	v_mfma_f32_16x16x32_bf16 v[32:35], v[168:171], v[184:187], v[32:35]
	v_mfma_f32_16x16x32_bf16 v[20:23], v[160:163], v[192:195], v[20:23]
	v_mfma_f32_16x16x32_bf16 v[16:19], v[168:171], v[192:195], v[16:19]
	v_mfma_f32_16x16x32_bf16 v[4:7], v[160:163], v[200:203], v[4:7]
	v_mfma_f32_16x16x32_bf16 v[0:3], v[168:171], v[200:203], v[0:3]
	v_mfma_f32_16x16x32_bf16 v[68:71], v[164:167], v[180:183], v[68:71]
	v_mfma_f32_16x16x32_bf16 v[64:67], v[172:175], v[180:183], v[64:67]
	v_mfma_f32_16x16x32_bf16 v[36:39], v[164:167], v[188:191], v[36:39]
	v_mfma_f32_16x16x32_bf16 v[32:35], v[172:175], v[188:191], v[32:35]
	v_mfma_f32_16x16x32_bf16 v[20:23], v[164:167], v[196:199], v[20:23]
	v_mfma_f32_16x16x32_bf16 v[16:19], v[172:175], v[196:199], v[16:19]
	v_mfma_f32_16x16x32_bf16 v[4:7], v[164:167], v[204:207], v[4:7]
	v_mfma_f32_16x16x32_bf16 v[0:3], v[172:175], v[204:207], v[0:3]
	s_barrier
	ds_read_b128 v[128:131], v153
	ds_read_b128 v[132:135], v153 offset:1024
	ds_read_b128 v[136:139], v153 offset:2048
	ds_read_b128 v[156:159], v153 offset:3072
	ds_read_b128 v[160:163], v154
	ds_read_b128 v[164:167], v154 offset:1024
	ds_read_b128 v[168:171], v154 offset:2048
	ds_read_b128 v[172:175], v154 offset:3072
	s_add_u32 s52, s52, 0x80000
	s_addc_u32 s53, s53, 0
	s_mov_b32 m0, s60
	ds_read_b128 v[176:179], v150 offset:32768
	ds_read_b128 v[180:183], v150 offset:33792
	ds_read_b128 v[184:187], v150 offset:34816
	ds_read_b128 v[188:191], v150 offset:35840
	ds_read_b128 v[192:195], v150 offset:36864
	ds_read_b128 v[196:199], v150 offset:37888
	ds_read_b128 v[200:203], v150 offset:38912
	ds_read_b128 v[204:207], v150 offset:39936
	global_load_lds_dwordx4 v143, s[52:53]
	s_mov_b32 m0, s61
	s_nop 0
	global_load_lds_dwordx4 v145, s[52:53]
	s_waitcnt vmcnt(8)
	s_waitcnt lgkmcnt(0)
	s_barrier
	v_mfma_f32_16x16x32_bf16 v[124:127], v[128:131], v[176:179], v[124:127]
	v_mfma_f32_16x16x32_bf16 v[120:123], v[136:139], v[176:179], v[120:123]
	v_mfma_f32_16x16x32_bf16 v[108:111], v[128:131], v[184:187], v[108:111]
	v_mfma_f32_16x16x32_bf16 v[104:107], v[136:139], v[184:187], v[104:107]
	v_mfma_f32_16x16x32_bf16 v[92:95], v[128:131], v[192:195], v[92:95]
	v_mfma_f32_16x16x32_bf16 v[88:91], v[136:139], v[192:195], v[88:91]
	v_mfma_f32_16x16x32_bf16 v[60:63], v[128:131], v[200:203], v[60:63]
	v_mfma_f32_16x16x32_bf16 v[56:59], v[136:139], v[200:203], v[56:59]
	v_mfma_f32_16x16x32_bf16 v[124:127], v[132:135], v[180:183], v[124:127]
	v_mfma_f32_16x16x32_bf16 v[120:123], v[156:159], v[180:183], v[120:123]
	v_mfma_f32_16x16x32_bf16 v[108:111], v[132:135], v[188:191], v[108:111]
	v_mfma_f32_16x16x32_bf16 v[104:107], v[156:159], v[188:191], v[104:107]
	v_mfma_f32_16x16x32_bf16 v[92:95], v[132:135], v[196:199], v[92:95]
	v_mfma_f32_16x16x32_bf16 v[88:91], v[156:159], v[196:199], v[88:91]
	v_mfma_f32_16x16x32_bf16 v[60:63], v[132:135], v[204:207], v[60:63]
	v_mfma_f32_16x16x32_bf16 v[56:59], v[156:159], v[204:207], v[56:59]
	v_mfma_f32_16x16x32_bf16 v[116:119], v[160:163], v[176:179], v[116:119]
	v_mfma_f32_16x16x32_bf16 v[112:115], v[168:171], v[176:179], v[112:115]
	v_mfma_f32_16x16x32_bf16 v[100:103], v[160:163], v[184:187], v[100:103]
	v_mfma_f32_16x16x32_bf16 v[96:99], v[168:171], v[184:187], v[96:99]
	v_mfma_f32_16x16x32_bf16 v[84:87], v[160:163], v[192:195], v[84:87]
	v_mfma_f32_16x16x32_bf16 v[80:83], v[168:171], v[192:195], v[80:83]
	v_mfma_f32_16x16x32_bf16 v[52:55], v[160:163], v[200:203], v[52:55]
	v_mfma_f32_16x16x32_bf16 v[48:51], v[168:171], v[200:203], v[48:51]
	v_mfma_f32_16x16x32_bf16 v[116:119], v[164:167], v[180:183], v[116:119]
	v_mfma_f32_16x16x32_bf16 v[112:115], v[172:175], v[180:183], v[112:115]
	v_mfma_f32_16x16x32_bf16 v[100:103], v[164:167], v[188:191], v[100:103]
	v_mfma_f32_16x16x32_bf16 v[96:99], v[172:175], v[188:191], v[96:99]
	v_mfma_f32_16x16x32_bf16 v[84:87], v[164:167], v[196:199], v[84:87]
	v_mfma_f32_16x16x32_bf16 v[80:83], v[172:175], v[196:199], v[80:83]
	v_mfma_f32_16x16x32_bf16 v[52:55], v[164:167], v[204:207], v[52:55]
	v_mfma_f32_16x16x32_bf16 v[48:51], v[172:175], v[204:207], v[48:51]
	s_barrier
	s_add_u32 s52, s50, 0x80
	s_mov_b32 m0, s37
	s_addc_u32 s53, s51, 0
	ds_read_b128 v[176:179], v150 offset:49152
	ds_read_b128 v[180:183], v150 offset:50176
	ds_read_b128 v[184:187], v150 offset:51200
	ds_read_b128 v[188:191], v150 offset:52224
	ds_read_b128 v[192:195], v150 offset:53248
	ds_read_b128 v[196:199], v150 offset:54272
	ds_read_b128 v[200:203], v150 offset:55296
	ds_read_b128 v[204:207], v150 offset:56320
	s_add_u32 s50, s50, 0x80080
	global_load_lds_dwordx4 v144, s[52:53]
	s_mov_b32 m0, s74
	s_addc_u32 s51, s51, 0
	global_load_lds_dwordx4 v146, s[52:53]
	s_mov_b32 m0, s75
	s_nop 0
	global_load_lds_dwordx4 v144, s[50:51]
	s_mov_b32 m0, s76
	s_nop 0
	global_load_lds_dwordx4 v146, s[50:51]
	s_mov_b32 m0, s62
	s_nop 0
	global_load_lds_dwordx4 v143, s[48:49]
	s_mov_b32 m0, s63
	s_nop 0
	global_load_lds_dwordx4 v145, s[48:49]
	s_waitcnt vmcnt(8)
	s_waitcnt lgkmcnt(0)
	s_barrier
	v_mfma_f32_16x16x32_bf16 v[76:79], v[128:131], v[176:179], v[76:79]
	v_mfma_f32_16x16x32_bf16 v[72:75], v[136:139], v[176:179], v[72:75]
	v_mfma_f32_16x16x32_bf16 v[44:47], v[128:131], v[184:187], v[44:47]
	v_mfma_f32_16x16x32_bf16 v[40:43], v[136:139], v[184:187], v[40:43]
	v_mfma_f32_16x16x32_bf16 v[28:31], v[128:131], v[192:195], v[28:31]
	v_mfma_f32_16x16x32_bf16 v[24:27], v[136:139], v[192:195], v[24:27]
	v_mfma_f32_16x16x32_bf16 v[12:15], v[128:131], v[200:203], v[12:15]
	v_mfma_f32_16x16x32_bf16 v[8:11], v[136:139], v[200:203], v[8:11]
	v_mfma_f32_16x16x32_bf16 v[76:79], v[132:135], v[180:183], v[76:79]
	v_mfma_f32_16x16x32_bf16 v[72:75], v[156:159], v[180:183], v[72:75]
	v_mfma_f32_16x16x32_bf16 v[44:47], v[132:135], v[188:191], v[44:47]
	v_mfma_f32_16x16x32_bf16 v[40:43], v[156:159], v[188:191], v[40:43]
	v_mfma_f32_16x16x32_bf16 v[28:31], v[132:135], v[196:199], v[28:31]
	v_mfma_f32_16x16x32_bf16 v[24:27], v[156:159], v[196:199], v[24:27]
	v_mfma_f32_16x16x32_bf16 v[12:15], v[132:135], v[204:207], v[12:15]
	v_mfma_f32_16x16x32_bf16 v[8:11], v[156:159], v[204:207], v[8:11]
	v_mfma_f32_16x16x32_bf16 v[68:71], v[160:163], v[176:179], v[68:71]
	v_mfma_f32_16x16x32_bf16 v[64:67], v[168:171], v[176:179], v[64:67]
	v_mfma_f32_16x16x32_bf16 v[36:39], v[160:163], v[184:187], v[36:39]
	v_mfma_f32_16x16x32_bf16 v[32:35], v[168:171], v[184:187], v[32:35]
	v_mfma_f32_16x16x32_bf16 v[20:23], v[160:163], v[192:195], v[20:23]
	v_mfma_f32_16x16x32_bf16 v[16:19], v[168:171], v[192:195], v[16:19]
	v_mfma_f32_16x16x32_bf16 v[4:7], v[160:163], v[200:203], v[4:7]
	v_mfma_f32_16x16x32_bf16 v[0:3], v[168:171], v[200:203], v[0:3]
	v_mfma_f32_16x16x32_bf16 v[68:71], v[164:167], v[180:183], v[68:71]
	v_mfma_f32_16x16x32_bf16 v[64:67], v[172:175], v[180:183], v[64:67]
	v_mfma_f32_16x16x32_bf16 v[36:39], v[164:167], v[188:191], v[36:39]
	v_mfma_f32_16x16x32_bf16 v[32:35], v[172:175], v[188:191], v[32:35]
	v_mfma_f32_16x16x32_bf16 v[20:23], v[164:167], v[196:199], v[20:23]
	v_mfma_f32_16x16x32_bf16 v[16:19], v[172:175], v[196:199], v[16:19]
	v_mfma_f32_16x16x32_bf16 v[4:7], v[164:167], v[204:207], v[4:7]
	v_mfma_f32_16x16x32_bf16 v[0:3], v[172:175], v[204:207], v[0:3]
	s_barrier
	s_add_i32 s79, s79, 2
	s_add_u32 s77, s77, 0x100
	s_addc_u32 s78, s78, 0
	s_cmp_gt_u32 s79, 29
	s_mov_b64 s[54:55], s[46:47]
	s_cbranch_scc0 .LBB0_429
	s_and_b64 vcc, exec, s[4:5]
	s_cbranch_vccz .LBB0_432
	s_barrier

.LBB0_497:
	s_or_b64 exec, exec, s[2:3]
	v_lshlrev_b32_e32 v0, 11, v149
	v_lshlrev_b32_e32 v20, 4, v18
	v_or_b32_e32 v4, v20, v0
	v_ashrrev_i32_e32 v4, 8, v4
	v_xor_b32_e32 v5, v4, v2
	v_and_b32_e32 v6, 3, v4
	v_lshrrev_b32_e32 v4, 1, v4
	v_and_b32_e32 v3, 0x7ffffff0, v19
	v_and_b32_e32 v4, 12, v4
	v_or3_b32 v4, v6, v4, v3
	v_mul_lo_u32 v4, v4, s25
	v_lshlrev_b32_e32 v5, 3, v5
	v_and_or_b32 v4, v5, s26, v4
	v_lshlrev_b32_e32 v158, 1, v4
	v_or_b32_e32 v4, 0x400, v20
	v_or_b32_e32 v0, v4, v0
	s_lshl_b32 s2, s4, 2
	v_ashrrev_i32_e32 v0, 8, v0
	s_add_i32 s76, s2, 4
	v_xor_b32_e32 v5, v0, v2
	v_and_b32_e32 v6, 3, v0
	v_lshrrev_b32_e32 v0, 1, v0
	s_or_b32 s2, s2, 3
	v_and_b32_e32 v0, 12, v0
	s_mul_i32 s3, s2, 0x50000
	v_or3_b32 v0, v6, v0, v3
	s_lshl_b32 s3, s3, 1
	v_mul_lo_u32 v0, v0, s25
	v_lshlrev_b32_e32 v5, 3, v5
	s_add_u32 s4, s69, s3
	s_mov_b32 m0, s56
	v_and_or_b32 v0, v5, s26, v0
	s_addc_u32 s5, s70, 0
	v_lshl_add_u32 v159, v0, 1, v148
	s_waitcnt lgkmcnt(0)
	s_barrier
	v_lshlrev_b32_e32 v6, 1, v2
	global_load_lds_dwordx4 v158, s[4:5]
	s_mov_b32 m0, s63
	v_and_b32_e32 v6, 32, v6
	global_load_lds_dwordx4 v159, s[4:5]
	v_bfe_u32 v0, v2, 2, 2
	v_and_b32_e32 v5, 12, v19
	v_add_u32_e32 v3, v6, v3
	v_lshlrev_b32_e32 v22, 3, v18
	v_or3_b32 v0, v0, v5, v3
	v_and_b32_e32 v21, 24, v22
	v_mul_lo_u32 v0, v0, s25
	v_or_b32_e32 v0, v0, v21
	v_and_b32_e32 v23, 32, v2
	s_and_b32 s8, s1, 0xffffff00
	v_or_b32_e32 v2, v0, v23
	s_waitcnt vmcnt(0)
	s_cmpk_eq_i32 s8, 0x100
	v_lshlrev_b32_e32 v160, 1, v2
	v_lshrrev_b32_e32 v2, 4, v4
	s_waitcnt lgkmcnt(0)
	s_barrier
	s_cselect_b64 s[4:5], -1, 0
	s_cmpk_lg_i32 s8, 0x100
	v_and_or_b32 v0, v2, s27, v0
	s_cselect_b64 s[40:41], -1, 0
	v_lshlrev_b32_e32 v161, 1, v0
	s_and_b64 vcc, exec, s[40:41]
	s_waitcnt vmcnt(0)
	s_cbranch_vccnz .LBB0_499
	s_lshl_b32 s8, s76, 6
	s_addk_i32 s8, 0xff80
	s_mul_hi_u32 s9, s8, 0x2800
	s_mulk_i32 s8, 0x2800
	s_add_u32 s8, s69, s8
	s_mov_b32 m0, s57
	s_addc_u32 s9, s70, s9
	global_load_lds_dwordx4 v158, s[8:9]
	s_mov_b32 m0, s58
	s_nop 0
	global_load_lds_dwordx4 v159, s[8:9]
	s_add_u32 s8, s71, s3
	s_addc_u32 s9, s72, 0
	s_mov_b32 m0, s59
	s_nop 0
	global_load_lds_dwordx4 v160, s[8:9]
	s_mov_b32 m0, s60
	s_nop 0
	global_load_lds_dwordx4 v161, s[8:9]
	s_waitcnt lgkmcnt(0)
	s_barrier
.LBB0_499:
	s_cmpk_lt_u32 s1, 0x100
	s_cselect_b64 s[42:43], -1, 0
	s_cmpk_gt_u32 s1, 0xff
	s_cselect_b64 s[44:45], -1, 0
	s_and_b64 vcc, exec, s[44:45]
	s_cbranch_vccnz .LBB0_501
	s_lshl_b32 s1, s76, 6
	s_addk_i32 s1, 0xff80
	s_mul_hi_u32 s9, s1, 0x2800
	s_mulk_i32 s1, 0x2800
	s_add_u32 s8, s69, s1
	s_mov_b32 m0, s57
	s_addc_u32 s9, s70, s9
	global_load_lds_dwordx4 v158, s[8:9]
	s_mov_b32 m0, s58
	s_nop 0
	global_load_lds_dwordx4 v159, s[8:9]
	s_add_u32 s8, s71, s3
	s_addc_u32 s9, s72, 0
	s_mov_b32 m0, s59
	s_nop 0
	global_load_lds_dwordx4 v160, s[8:9]
	s_mov_b32 m0, s60
	s_nop 0
	global_load_lds_dwordx4 v161, s[8:9]

.LBB0_508:
	s_waitcnt lgkmcnt(0)
	s_barrier
	s_and_b64 vcc, exec, s[2:3]
	s_cbranch_vccnz .LBB0_510
	s_lshl_b32 s8, s76, 6
	s_mul_i32 s5, s76, 0xa0000
	s_add_i32 s4, s8, 0xffffff40
	s_add_i32 s5, s5, 0xffe20000
	s_mul_hi_u32 s9, s4, 0x2800
	s_add_u32 s4, s69, s5
	s_mov_b32 m0, s56
	s_addc_u32 s5, s70, s9
	global_load_lds_dwordx4 v158, s[4:5]
	s_mov_b32 m0, s63
	s_nop 0
	global_load_lds_dwordx4 v159, s[4:5]
	s_add_i32 s4, s8, 0xffffff80
	s_mul_hi_u32 s5, s4, 0x2800
	s_mulk_i32 s4, 0x2800
	s_add_u32 s4, s71, s4
	s_addc_u32 s5, s72, s5
	s_add_i32 m0, s56, 0x10000
	s_nop 0
	global_load_lds_dwordx4 v160, s[4:5]
	s_add_i32 m0, s56, 0x10400
	s_nop 0
	global_load_lds_dwordx4 v161, s[4:5]

.LBB0_569:
	s_waitcnt lgkmcnt(0)
	s_barrier
	s_and_b64 vcc, exec, s[2:3]
	s_cbranch_vccnz .LBB0_571
	s_add_u32 s0, s8, 0x100000
	s_mov_b32 m0, s56
	s_addc_u32 s1, s9, 0
	global_load_lds_dwordx4 v165, s[0:1]
	s_mov_b32 m0, s38
	s_nop 0
	global_load_lds_dwordx4 v166, s[0:1]
	s_add_u32 s0, s8, 0x80400
	s_addc_u32 s1, s9, 0
	s_mov_b32 m0, s45
	s_nop 0
	global_load_lds_dwordx4 v146, s[0:1]
	s_mov_b32 m0, s46
	s_nop 0
	global_load_lds_dwordx4 v144, s[0:1]

.LBB0_573:
	v_lshlrev_b32_e32 v4, 1, v32
	v_and_b32_e32 v4, 32, v4
	v_and_b32_e32 v5, 0xc0, v33
	v_and_b32_e32 v6, 0x100, v35
	s_waitcnt lgkmcnt(0)
	s_barrier
	v_add3_u32 v4, v4, s47, v5
	v_add3_u32 v147, v4, v6, v34
	ds_read_b64_tr_b16 v[16:17], v147 offset:0
	ds_read_b64_tr_b16 v[18:19], v147 offset:0x800
	ds_read_b64_tr_b16 v[12:13], v147 offset:0x1000
	ds_read_b64_tr_b16 v[14:15], v147 offset:0x1800
	ds_read_b64_tr_b16 v[8:9], v147 offset:0x2000
	ds_read_b64_tr_b16 v[10:11], v147 offset:0x2800
	ds_read_b64_tr_b16 v[4:5], v147 offset:0x3000
	ds_read_b64_tr_b16 v[6:7], v147 offset:0x3800
	s_and_b64 vcc, exec, s[4:5]
	s_cbranch_vccnz .LBB0_575
	s_add_u32 s0, s8, 0x100000
	s_mov_b32 m0, s56
	s_addc_u32 s1, s9, 0
	global_load_lds_dwordx4 v165, s[0:1]
	s_mov_b32 m0, s38
	s_nop 0
	global_load_lds_dwordx4 v166, s[0:1]
	s_add_u32 s0, s8, 0x80400
	s_addc_u32 s1, s9, 0
	s_mov_b32 m0, s45
	s_nop 0
	global_load_lds_dwordx4 v146, s[0:1]
	s_mov_b32 m0, s46
	s_nop 0
	global_load_lds_dwordx4 v144, s[0:1]

.LBB0_577:
	s_waitcnt lgkmcnt(0)
	s_barrier
	s_and_b64 vcc, exec, s[2:3]
	s_cbranch_vccnz .LBB0_579
	s_add_u32 s0, s8, 0x180000
	s_mov_b32 m0, s39
	s_addc_u32 s1, s9, 0
	global_load_lds_dwordx4 v165, s[0:1]
	s_mov_b32 m0, s40
	s_nop 0
	global_load_lds_dwordx4 v166, s[0:1]
	s_add_u32 s0, s8, 0x100400
	s_addc_u32 s1, s9, 0
	s_mov_b32 m0, s41
	s_nop 0
	global_load_lds_dwordx4 v146, s[0:1]
	s_mov_b32 m0, s42
	s_nop 0
	global_load_lds_dwordx4 v144, s[0:1]

.LBB0_583:
	s_waitcnt lgkmcnt(0)
	s_barrier
	v_add_u32_e32 v148, 0x4000, v147
	ds_read_b64_tr_b16 v[108:109], v148 offset:0
	ds_read_b64_tr_b16 v[110:111], v148 offset:0x800
	ds_read_b64_tr_b16 v[104:105], v148 offset:0x1000
	ds_read_b64_tr_b16 v[106:107], v148 offset:0x1800
	ds_read_b64_tr_b16 v[100:101], v148 offset:0x2000
	ds_read_b64_tr_b16 v[102:103], v148 offset:0x2800
	ds_read_b64_tr_b16 v[96:97], v148 offset:0x3000
	ds_read_b64_tr_b16 v[98:99], v148 offset:0x3800
	s_and_b64 vcc, exec, s[4:5]
	s_cbranch_vccnz .LBB0_585
	s_add_u32 s0, s8, 0x180000
	s_mov_b32 m0, s39
	s_addc_u32 s1, s9, 0
	global_load_lds_dwordx4 v165, s[0:1]
	s_mov_b32 m0, s40
	s_nop 0
	global_load_lds_dwordx4 v166, s[0:1]
	s_add_u32 s0, s8, 0x100400
	s_addc_u32 s1, s9, 0
	s_mov_b32 m0, s41
	s_nop 0
	global_load_lds_dwordx4 v146, s[0:1]
	s_mov_b32 m0, s42
	s_nop 0
	global_load_lds_dwordx4 v144, s[0:1]

.LBB0_687:
	s_add_u32 s20, s52, 0x100
	s_addc_u32 s21, s53, 0
	s_waitcnt lgkmcnt(0)
	s_add_u32 s48, s50, 0x100
	s_addc_u32 s49, s51, 0
	s_barrier
	v_mfma_f32_16x16x32_bf16 v[32:35], v[16:19], v[68:71], 0
	v_mfma_f32_16x16x32_bf16 v[36:39], v[24:27], v[68:71], 0
	s_waitcnt lgkmcnt(0)
	v_mfma_f32_16x16x32_bf16 v[40:43], v[16:19], v[84:87], 0
	v_mfma_f32_16x16x32_bf16 v[44:47], v[24:27], v[84:87], 0
	v_mfma_f32_16x16x32_bf16 v[48:51], v[16:19], v[92:95], 0
	v_mfma_f32_16x16x32_bf16 v[52:55], v[24:27], v[92:95], 0
	v_mfma_f32_16x16x32_bf16 v[56:59], v[16:19], v[76:79], 0
	v_mfma_f32_16x16x32_bf16 v[60:63], v[24:27], v[76:79], 0
	v_mfma_f32_16x16x32_bf16 v[138:141], v[20:23], v[72:75], v[32:35]
	v_mfma_f32_16x16x32_bf16 v[36:39], v[28:31], v[72:75], v[36:39]
	v_mfma_f32_16x16x32_bf16 v[40:43], v[20:23], v[88:91], v[40:43]
	v_mfma_f32_16x16x32_bf16 v[44:47], v[28:31], v[88:91], v[44:47]
	v_mfma_f32_16x16x32_bf16 v[48:51], v[20:23], v[96:99], v[48:51]
	v_mfma_f32_16x16x32_bf16 v[52:55], v[28:31], v[96:99], v[52:55]
	v_mfma_f32_16x16x32_bf16 v[56:59], v[20:23], v[80:83], v[56:59]
	v_mfma_f32_16x16x32_bf16 v[60:63], v[28:31], v[80:83], v[60:63]
	v_mfma_f32_16x16x32_bf16 v[64:67], v[0:3], v[68:71], 0
	v_mfma_f32_16x16x32_bf16 v[68:71], v[8:11], v[68:71], 0
	v_mfma_f32_16x16x32_bf16 v[64:67], v[4:7], v[72:75], v[64:67]
	v_mfma_f32_16x16x32_bf16 v[68:71], v[12:15], v[72:75], v[68:71]
	v_mfma_f32_16x16x32_bf16 v[72:75], v[0:3], v[84:87], 0
	v_mfma_f32_16x16x32_bf16 v[84:87], v[8:11], v[84:87], 0
	v_mfma_f32_16x16x32_bf16 v[72:75], v[4:7], v[88:91], v[72:75]
	v_mfma_f32_16x16x32_bf16 v[84:87], v[12:15], v[88:91], v[84:87]
	v_mfma_f32_16x16x32_bf16 v[88:91], v[0:3], v[92:95], 0
	v_mfma_f32_16x16x32_bf16 v[92:95], v[8:11], v[92:95], 0
	v_mfma_f32_16x16x32_bf16 v[88:91], v[4:7], v[96:99], v[88:91]
	v_mfma_f32_16x16x32_bf16 v[92:95], v[12:15], v[96:99], v[92:95]
	v_mfma_f32_16x16x32_bf16 v[96:99], v[0:3], v[76:79], 0
	v_mfma_f32_16x16x32_bf16 v[76:79], v[8:11], v[76:79], 0
	v_mfma_f32_16x16x32_bf16 v[108:111], v[4:7], v[80:83], v[96:99]
	v_mfma_f32_16x16x32_bf16 v[120:123], v[12:15], v[80:83], v[76:79]
	s_barrier
	s_mov_b32 m0, s58
	ds_read_b128 v[116:119], v209 offset:16384
	ds_read_b128 v[124:127], v209 offset:17408
	ds_read_b128 v[104:107], v209 offset:18432
	ds_read_b128 v[112:115], v209 offset:19456
	ds_read_b128 v[96:99], v209 offset:20480
	ds_read_b128 v[100:103], v209 offset:21504
	ds_read_b128 v[76:79], v209 offset:22528
	ds_read_b128 v[80:83], v209 offset:23552
	global_load_lds_dwordx4 v203, s[48:49]
	s_mov_b32 m0, s59
	s_nop 0
	global_load_lds_dwordx4 v205, s[48:49]
	s_add_u32 s48, s50, 0x80100
	s_addc_u32 s49, s51, 0
	s_mov_b32 m0, s60
	s_and_b64 vcc, exec, s[46:47]
	global_load_lds_dwordx4 v203, s[48:49]
	s_mov_b32 m0, s61
	s_nop 0
	global_load_lds_dwordx4 v205, s[48:49]
	s_mov_b32 m0, s27
	s_mov_b64 s[48:49], -1
	global_load_lds_dwordx4 v202, s[20:21]
	s_mov_b32 m0, s62
	s_nop 0
	global_load_lds_dwordx4 v204, s[20:21]
	s_cbranch_vccz .LBB0_689
	s_waitcnt vmcnt(8)
	s_mov_b64 s[48:49], 0

.LBB0_691:
	s_ashr_i32 s41, s40, 31
	s_lshl_b64 s[20:21], s[40:41], 20
	s_add_u32 s46, s13, s20
	s_addc_u32 s47, s82, s21
	s_and_b64 s[20:21], s[44:45], exec
	s_cselect_b32 s3, s47, s53
	s_cselect_b32 s5, s46, s52
	s_ashr_i32 s43, s42, 31
	s_lshl_b64 s[20:21], s[42:43], 20
	s_add_u32 s48, s24, s20
	s_addc_u32 s49, s25, s21
	s_and_b64 s[20:21], s[44:45], exec
	s_cselect_b32 s12, s49, s51
	s_cselect_b32 s20, s48, s50
	s_add_u32 s54, s52, 0x180
	s_waitcnt lgkmcnt(0)
	s_addc_u32 s55, s53, 0
	s_add_u32 s56, s50, 0x180
	s_addc_u32 s57, s51, 0
	s_barrier
	s_waitcnt lgkmcnt(0)
	v_mfma_f32_16x16x32_bf16 v[128:131], v[16:19], v[116:119], 0
	v_mfma_f32_16x16x32_bf16 v[134:137], v[20:23], v[124:127], v[128:131]
	v_mfma_f32_16x16x32_bf16 v[128:131], v[24:27], v[116:119], 0
	v_mfma_f32_16x16x32_bf16 v[156:159], v[28:31], v[124:127], v[128:131]
	v_mfma_f32_16x16x32_bf16 v[128:131], v[16:19], v[104:107], 0
	v_mfma_f32_16x16x32_bf16 v[160:163], v[20:23], v[112:115], v[128:131]
	v_mfma_f32_16x16x32_bf16 v[128:131], v[24:27], v[104:107], 0
	v_mfma_f32_16x16x32_bf16 v[164:167], v[28:31], v[112:115], v[128:131]
	v_mfma_f32_16x16x32_bf16 v[128:131], v[16:19], v[96:99], 0
	v_mfma_f32_16x16x32_bf16 v[16:19], v[16:19], v[76:79], 0
	v_mfma_f32_16x16x32_bf16 v[168:171], v[20:23], v[100:103], v[128:131]
	v_mfma_f32_16x16x32_bf16 v[16:19], v[20:23], v[80:83], v[16:19]
	v_mfma_f32_16x16x32_bf16 v[20:23], v[24:27], v[76:79], 0
	v_mfma_f32_16x16x32_bf16 v[128:131], v[24:27], v[96:99], 0
	v_mfma_f32_16x16x32_bf16 v[20:23], v[28:31], v[80:83], v[20:23]
	v_mfma_f32_16x16x32_bf16 v[172:175], v[28:31], v[100:103], v[128:131]
	v_mfma_f32_16x16x32_bf16 v[24:27], v[0:3], v[116:119], 0
	v_mfma_f32_16x16x32_bf16 v[176:179], v[4:7], v[124:127], v[24:27]
	v_mfma_f32_16x16x32_bf16 v[24:27], v[8:11], v[116:119], 0
	v_mfma_f32_16x16x32_bf16 v[180:183], v[12:15], v[124:127], v[24:27]
	v_mfma_f32_16x16x32_bf16 v[24:27], v[0:3], v[104:107], 0
	v_mfma_f32_16x16x32_bf16 v[186:189], v[4:7], v[112:115], v[24:27]
	v_mfma_f32_16x16x32_bf16 v[24:27], v[8:11], v[104:107], 0
	v_mfma_f32_16x16x32_bf16 v[190:193], v[12:15], v[112:115], v[24:27]
	v_mfma_f32_16x16x32_bf16 v[24:27], v[0:3], v[96:99], 0
	v_mfma_f32_16x16x32_bf16 v[0:3], v[0:3], v[76:79], 0
	v_mfma_f32_16x16x32_bf16 v[194:197], v[4:7], v[100:103], v[24:27]
	v_mfma_f32_16x16x32_bf16 v[24:27], v[8:11], v[96:99], 0
	v_mfma_f32_16x16x32_bf16 v[0:3], v[4:7], v[80:83], v[0:3]
	v_mfma_f32_16x16x32_bf16 v[4:7], v[8:11], v[76:79], 0
	v_mfma_f32_16x16x32_bf16 v[198:201], v[12:15], v[100:103], v[24:27]
	v_mfma_f32_16x16x32_bf16 v[212:215], v[12:15], v[80:83], v[4:7]
	s_barrier
	v_add_u32_e32 v132, s72, v206
	v_add_u32_e32 v133, s73, v206
	s_nop 1
	ds_read_b128 v[4:7], v132
	ds_read_b128 v[8:11], v132 offset:1024
	ds_read_b128 v[216:219], v132 offset:2048
	ds_read_b128 v[220:223], v132 offset:3072
	ds_read_b128 v[224:227], v133
	ds_read_b128 v[228:231], v133 offset:1024
	ds_read_b128 v[232:235], v133 offset:2048
	ds_read_b128 v[236:239], v133 offset:3072
	s_add_u32 s76, s52, 0x80100
	s_addc_u32 s77, s53, 0
	s_mov_b32 m0, s63
	ds_read_b128 v[12:15], v209 offset:32768
	ds_read_b128 v[24:27], v209 offset:33792
	ds_read_b128 v[28:31], v209 offset:34816
	ds_read_b128 v[96:99], v209 offset:35840
	ds_read_b128 v[240:243], v209 offset:36864
	ds_read_b128 v[244:247], v209 offset:37888
	ds_read_b128 v[248:251], v209 offset:38912
	ds_read_b128 v[32:35], v209 offset:39936
	global_load_lds_dwordx4 v202, s[76:77]
	s_mov_b32 m0, s64
	s_nop 0
	global_load_lds_dwordx4 v204, s[76:77]
	s_waitcnt vmcnt(8)
	s_waitcnt lgkmcnt(0)
	s_barrier
	v_mfma_f32_16x16x32_bf16 v[36:39], v[216:219], v[12:15], v[36:39]
	v_mfma_f32_16x16x32_bf16 v[148:151], v[220:223], v[24:27], v[36:39]
	v_mfma_f32_16x16x32_bf16 v[36:39], v[4:7], v[28:31], v[40:43]
	v_mfma_f32_16x16x32_bf16 v[128:131], v[8:11], v[96:99], v[36:39]
	v_mfma_f32_16x16x32_bf16 v[36:39], v[216:219], v[28:31], v[44:47]
	v_mfma_f32_16x16x32_bf16 v[124:127], v[220:223], v[96:99], v[36:39]
	v_mfma_f32_16x16x32_bf16 v[36:39], v[4:7], v[240:243], v[48:51]
	v_mfma_f32_16x16x32_bf16 v[104:107], v[8:11], v[244:247], v[36:39]
	v_mfma_f32_16x16x32_bf16 v[36:39], v[216:219], v[240:243], v[52:55]
	v_mfma_f32_16x16x32_bf16 v[100:103], v[220:223], v[244:247], v[36:39]
	v_mfma_f32_16x16x32_bf16 v[36:39], v[4:7], v[248:251], v[56:59]
	v_mfma_f32_16x16x32_bf16 v[76:79], v[4:7], v[12:15], v[138:141]
	v_mfma_f32_16x16x32_bf16 v[80:83], v[8:11], v[32:35], v[36:39]
	v_mfma_f32_16x16x32_bf16 v[36:39], v[216:219], v[248:251], v[60:63]
	v_mfma_f32_16x16x32_bf16 v[152:155], v[8:11], v[24:27], v[76:79]
	v_mfma_f32_16x16x32_bf16 v[76:79], v[220:223], v[32:35], v[36:39]
	v_mfma_f32_16x16x32_bf16 v[36:39], v[224:227], v[12:15], v[64:67]
	v_mfma_f32_16x16x32_bf16 v[12:15], v[232:235], v[12:15], v[68:71]
	v_mfma_f32_16x16x32_bf16 v[140:143], v[236:239], v[24:27], v[12:15]
	v_mfma_f32_16x16x32_bf16 v[12:15], v[224:227], v[28:31], v[72:75]
	v_mfma_f32_16x16x32_bf16 v[116:119], v[228:231], v[96:99], v[12:15]
	v_mfma_f32_16x16x32_bf16 v[12:15], v[232:235], v[28:31], v[84:87]
	v_mfma_f32_16x16x32_bf16 v[112:115], v[236:239], v[96:99], v[12:15]
	v_mfma_f32_16x16x32_bf16 v[12:15], v[224:227], v[240:243], v[88:91]
	v_mfma_f32_16x16x32_bf16 v[96:99], v[228:231], v[244:247], v[12:15]
	v_mfma_f32_16x16x32_bf16 v[12:15], v[232:235], v[240:243], v[92:95]
	v_mfma_f32_16x16x32_bf16 v[88:91], v[236:239], v[244:247], v[12:15]
	v_mfma_f32_16x16x32_bf16 v[12:15], v[224:227], v[248:251], v[108:111]
	v_mfma_f32_16x16x32_bf16 v[72:75], v[228:231], v[32:35], v[12:15]
	v_mfma_f32_16x16x32_bf16 v[12:15], v[232:235], v[248:251], v[120:123]
	v_mfma_f32_16x16x32_bf16 v[144:147], v[228:231], v[24:27], v[36:39]
	v_mfma_f32_16x16x32_bf16 v[64:67], v[236:239], v[32:35], v[12:15]
	s_barrier
	s_add_i32 s21, s72, s26
	s_mov_b32 m0, s21
	s_add_i32 s41, s21, 0x2000
	ds_read_b128 v[32:35], v209 offset:49152
	ds_read_b128 v[36:39], v209 offset:50176
	ds_read_b128 v[68:71], v209 offset:51200
	ds_read_b128 v[84:87], v209 offset:52224
	ds_read_b128 v[92:95], v209 offset:53248
	ds_read_b128 v[108:111], v209 offset:54272
	ds_read_b128 v[120:123], v209 offset:55296
	ds_read_b128 v[240:243], v209 offset:56320
	global_load_lds_dwordx4 v203, s[56:57]
	s_mov_b32 m0, s41
	s_nop 0
	global_load_lds_dwordx4 v205, s[56:57]
	s_add_u32 s56, s50, 0x80180
	s_addc_u32 s57, s51, 0
	s_add_i32 s43, s73, s26
	s_mov_b32 m0, s43
	s_add_i32 s76, s43, 0x2000
	s_nop 0
	global_load_lds_dwordx4 v203, s[56:57]
	s_mov_b32 m0, s76
	s_nop 0
	global_load_lds_dwordx4 v205, s[56:57]
	s_mov_b32 m0, s65
	s_nop 0
	global_load_lds_dwordx4 v202, s[54:55]
	s_mov_b32 m0, s66
	s_nop 0
	global_load_lds_dwordx4 v204, s[54:55]
	s_waitcnt vmcnt(8)
	s_waitcnt lgkmcnt(0)
	s_barrier
	v_mfma_f32_16x16x32_bf16 v[12:15], v[4:7], v[32:35], v[134:137]
	v_mfma_f32_16x16x32_bf16 v[60:63], v[8:11], v[36:39], v[12:15]
	v_mfma_f32_16x16x32_bf16 v[12:15], v[216:219], v[32:35], v[156:159]
	v_mfma_f32_16x16x32_bf16 v[56:59], v[220:223], v[36:39], v[12:15]
	v_mfma_f32_16x16x32_bf16 v[12:15], v[4:7], v[68:71], v[160:163]
	v_mfma_f32_16x16x32_bf16 v[44:47], v[8:11], v[84:87], v[12:15]
	v_mfma_f32_16x16x32_bf16 v[12:15], v[216:219], v[68:71], v[164:167]
	v_mfma_f32_16x16x32_bf16 v[40:43], v[220:223], v[84:87], v[12:15]
	v_mfma_f32_16x16x32_bf16 v[12:15], v[4:7], v[92:95], v[168:171]
	v_mfma_f32_16x16x32_bf16 v[28:31], v[8:11], v[108:111], v[12:15]
	v_mfma_f32_16x16x32_bf16 v[12:15], v[216:219], v[92:95], v[172:175]
	v_mfma_f32_16x16x32_bf16 v[4:7], v[4:7], v[120:123], v[16:19]
	v_mfma_f32_16x16x32_bf16 v[24:27], v[220:223], v[108:111], v[12:15]
	v_mfma_f32_16x16x32_bf16 v[12:15], v[8:11], v[240:243], v[4:7]
	v_mfma_f32_16x16x32_bf16 v[4:7], v[216:219], v[120:123], v[20:23]
	v_mfma_f32_16x16x32_bf16 v[8:11], v[220:223], v[240:243], v[4:7]
	v_mfma_f32_16x16x32_bf16 v[4:7], v[224:227], v[32:35], v[176:179]
	v_mfma_f32_16x16x32_bf16 v[52:55], v[228:231], v[36:39], v[4:7]
	v_mfma_f32_16x16x32_bf16 v[4:7], v[232:235], v[32:35], v[180:183]
	v_mfma_f32_16x16x32_bf16 v[48:51], v[236:239], v[36:39], v[4:7]
	v_mfma_f32_16x16x32_bf16 v[4:7], v[224:227], v[68:71], v[186:189]
	v_mfma_f32_16x16x32_bf16 v[36:39], v[228:231], v[84:87], v[4:7]
	v_mfma_f32_16x16x32_bf16 v[4:7], v[232:235], v[68:71], v[190:193]
	v_mfma_f32_16x16x32_bf16 v[32:35], v[236:239], v[84:87], v[4:7]
	v_mfma_f32_16x16x32_bf16 v[4:7], v[224:227], v[92:95], v[194:197]
	v_mfma_f32_16x16x32_bf16 v[20:23], v[228:231], v[108:111], v[4:7]
	v_mfma_f32_16x16x32_bf16 v[4:7], v[232:235], v[92:95], v[198:201]
	v_mfma_f32_16x16x32_bf16 v[0:3], v[224:227], v[120:123], v[0:3]
	v_mfma_f32_16x16x32_bf16 v[16:19], v[236:239], v[108:111], v[4:7]
	v_mfma_f32_16x16x32_bf16 v[4:7], v[228:231], v[240:243], v[0:3]
	v_mfma_f32_16x16x32_bf16 v[0:3], v[232:235], v[120:123], v[212:215]
	v_mfma_f32_16x16x32_bf16 v[0:3], v[236:239], v[240:243], v[0:3]
	s_barrier
	s_add_u32 s77, s52, 0x200
	s_addc_u32 s78, s53, 0
	s_add_u32 s79, s50, 0x200
	s_addc_u32 s80, s51, 0
	s_add_u32 s50, s52, 0x80180
	s_addc_u32 s51, s53, 0
	s_mov_b32 s83, 0
.LBB0_692:
	s_cmp_eq_u32 s83, 28
	s_cselect_b32 s56, s5, s77
	s_cselect_b32 s57, s3, s78
	s_cselect_b32 s54, s20, s79
	s_cselect_b32 s55, s12, s80
	s_add_u32 s52, s56, 0x80
	s_addc_u32 s53, s57, 0
	s_add_i32 s84, 0, 0x10000
	s_add_i32 s86, 0, 0x14000
	v_add_u32_e32 v108, s84, v206
	v_add_u32_e32 v138, s86, v206
	ds_read_b128 v[68:71], v108
	ds_read_b128 v[84:87], v108 offset:1024
	ds_read_b128 v[92:95], v108 offset:2048
	ds_read_b128 v[108:111], v108 offset:3072
	ds_read_b128 v[120:123], v138
	ds_read_b128 v[134:137], v138 offset:1024
	ds_read_b128 v[156:159], v138 offset:2048
	ds_read_b128 v[160:163], v138 offset:3072
	s_mov_b32 m0, s0
	ds_read_b128 v[164:167], v209
	ds_read_b128 v[168:171], v209 offset:1024
	ds_read_b128 v[172:175], v209 offset:2048
	ds_read_b128 v[176:179], v209 offset:3072
	ds_read_b128 v[180:183], v209 offset:4096
	ds_read_b128 v[186:189], v209 offset:5120
	ds_read_b128 v[190:193], v209 offset:6144
	ds_read_b128 v[194:197], v209 offset:7168
	global_load_lds_dwordx4 v202, s[50:51]
	s_mov_b32 m0, s1
	s_nop 0
	global_load_lds_dwordx4 v204, s[50:51]
	s_waitcnt vmcnt(8)
	s_waitcnt lgkmcnt(0)
	s_barrier
	v_mfma_f32_16x16x32_bf16 v[152:155], v[68:71], v[164:167], v[152:155]
	v_mfma_f32_16x16x32_bf16 v[148:151], v[92:95], v[164:167], v[148:151]
	v_mfma_f32_16x16x32_bf16 v[128:131], v[68:71], v[172:175], v[128:131]
	v_mfma_f32_16x16x32_bf16 v[124:127], v[92:95], v[172:175], v[124:127]
	v_mfma_f32_16x16x32_bf16 v[104:107], v[68:71], v[180:183], v[104:107]
	v_mfma_f32_16x16x32_bf16 v[100:103], v[92:95], v[180:183], v[100:103]
	v_mfma_f32_16x16x32_bf16 v[80:83], v[68:71], v[190:193], v[80:83]
	v_mfma_f32_16x16x32_bf16 v[76:79], v[92:95], v[190:193], v[76:79]
	v_mfma_f32_16x16x32_bf16 v[152:155], v[84:87], v[168:171], v[152:155]
	v_mfma_f32_16x16x32_bf16 v[148:151], v[108:111], v[168:171], v[148:151]
	v_mfma_f32_16x16x32_bf16 v[128:131], v[84:87], v[176:179], v[128:131]
	v_mfma_f32_16x16x32_bf16 v[124:127], v[108:111], v[176:179], v[124:127]
	v_mfma_f32_16x16x32_bf16 v[104:107], v[84:87], v[186:189], v[104:107]
	v_mfma_f32_16x16x32_bf16 v[100:103], v[108:111], v[186:189], v[100:103]
	v_mfma_f32_16x16x32_bf16 v[80:83], v[84:87], v[194:197], v[80:83]
	v_mfma_f32_16x16x32_bf16 v[76:79], v[108:111], v[194:197], v[76:79]
	v_mfma_f32_16x16x32_bf16 v[144:147], v[120:123], v[164:167], v[144:147]
	v_mfma_f32_16x16x32_bf16 v[138:141], v[156:159], v[164:167], v[140:143]
	v_mfma_f32_16x16x32_bf16 v[116:119], v[120:123], v[172:175], v[116:119]
	v_mfma_f32_16x16x32_bf16 v[112:115], v[156:159], v[172:175], v[112:115]
	v_mfma_f32_16x16x32_bf16 v[96:99], v[120:123], v[180:183], v[96:99]
	v_mfma_f32_16x16x32_bf16 v[88:91], v[156:159], v[180:183], v[88:91]
	v_mfma_f32_16x16x32_bf16 v[72:75], v[120:123], v[190:193], v[72:75]
	v_mfma_f32_16x16x32_bf16 v[64:67], v[156:159], v[190:193], v[64:67]
	v_mfma_f32_16x16x32_bf16 v[144:147], v[134:137], v[168:171], v[144:147]
	v_mfma_f32_16x16x32_bf16 v[138:141], v[160:163], v[168:171], v[138:141]
	v_mfma_f32_16x16x32_bf16 v[116:119], v[134:137], v[176:179], v[116:119]
	v_mfma_f32_16x16x32_bf16 v[112:115], v[160:163], v[176:179], v[112:115]
	v_mfma_f32_16x16x32_bf16 v[96:99], v[134:137], v[186:189], v[96:99]
	v_mfma_f32_16x16x32_bf16 v[88:91], v[160:163], v[186:189], v[88:91]
	v_mfma_f32_16x16x32_bf16 v[72:75], v[134:137], v[194:197], v[72:75]
	v_mfma_f32_16x16x32_bf16 v[64:67], v[160:163], v[194:197], v[64:67]
	s_barrier
	s_add_i32 s84, s84, s26
	s_mov_b32 m0, s84
	ds_read_b128 v[164:167], v209 offset:16384
	ds_read_b128 v[168:171], v209 offset:17408
	ds_read_b128 v[172:175], v209 offset:18432
	ds_read_b128 v[176:179], v209 offset:19456
	ds_read_b128 v[180:183], v209 offset:20480
	ds_read_b128 v[186:189], v209 offset:21504
	ds_read_b128 v[190:193], v209 offset:22528
	ds_read_b128 v[194:197], v209 offset:23552
	global_load_lds_dwordx4 v203, s[54:55]
	s_add_i32 m0, s84, 0x2000
	s_add_u32 s84, s54, 0x80000
	s_addc_u32 s85, s55, 0
	s_add_i32 s86, s86, s26
	s_nop 0
	global_load_lds_dwordx4 v205, s[54:55]
	s_mov_b32 m0, s86
	s_nop 0
	global_load_lds_dwordx4 v203, s[84:85]
	s_add_i32 m0, s86, 0x2000
	s_nop 0
	global_load_lds_dwordx4 v205, s[84:85]
	s_mov_b32 m0, s27
	s_nop 0
	global_load_lds_dwordx4 v202, s[56:57]
	s_mov_b32 m0, s62
	s_nop 0
	global_load_lds_dwordx4 v204, s[56:57]
	s_waitcnt vmcnt(8)
	s_waitcnt lgkmcnt(0)
	s_barrier
	v_mfma_f32_16x16x32_bf16 v[60:63], v[68:71], v[164:167], v[60:63]
	v_mfma_f32_16x16x32_bf16 v[56:59], v[92:95], v[164:167], v[56:59]
	v_mfma_f32_16x16x32_bf16 v[44:47], v[68:71], v[172:175], v[44:47]
	v_mfma_f32_16x16x32_bf16 v[40:43], v[92:95], v[172:175], v[40:43]
	v_mfma_f32_16x16x32_bf16 v[28:31], v[68:71], v[180:183], v[28:31]
	v_mfma_f32_16x16x32_bf16 v[24:27], v[92:95], v[180:183], v[24:27]
	v_mfma_f32_16x16x32_bf16 v[12:15], v[68:71], v[190:193], v[12:15]
	v_mfma_f32_16x16x32_bf16 v[8:11], v[92:95], v[190:193], v[8:11]
	v_mfma_f32_16x16x32_bf16 v[60:63], v[84:87], v[168:171], v[60:63]
	v_mfma_f32_16x16x32_bf16 v[56:59], v[108:111], v[168:171], v[56:59]
	v_mfma_f32_16x16x32_bf16 v[44:47], v[84:87], v[176:179], v[44:47]
	v_mfma_f32_16x16x32_bf16 v[40:43], v[108:111], v[176:179], v[40:43]
	v_mfma_f32_16x16x32_bf16 v[28:31], v[84:87], v[186:189], v[28:31]
	v_mfma_f32_16x16x32_bf16 v[24:27], v[108:111], v[186:189], v[24:27]
	v_mfma_f32_16x16x32_bf16 v[12:15], v[84:87], v[194:197], v[12:15]
	v_mfma_f32_16x16x32_bf16 v[8:11], v[108:111], v[194:197], v[8:11]
	v_mfma_f32_16x16x32_bf16 v[52:55], v[120:123], v[164:167], v[52:55]
	v_mfma_f32_16x16x32_bf16 v[48:51], v[156:159], v[164:167], v[48:51]
	v_mfma_f32_16x16x32_bf16 v[36:39], v[120:123], v[172:175], v[36:39]
	v_mfma_f32_16x16x32_bf16 v[32:35], v[156:159], v[172:175], v[32:35]
	v_mfma_f32_16x16x32_bf16 v[20:23], v[120:123], v[180:183], v[20:23]
	v_mfma_f32_16x16x32_bf16 v[16:19], v[156:159], v[180:183], v[16:19]
	v_mfma_f32_16x16x32_bf16 v[4:7], v[120:123], v[190:193], v[4:7]
	v_mfma_f32_16x16x32_bf16 v[0:3], v[156:159], v[190:193], v[0:3]
	v_mfma_f32_16x16x32_bf16 v[52:55], v[134:137], v[168:171], v[52:55]
	v_mfma_f32_16x16x32_bf16 v[48:51], v[160:163], v[168:171], v[48:51]
	v_mfma_f32_16x16x32_bf16 v[36:39], v[134:137], v[176:179], v[36:39]
	v_mfma_f32_16x16x32_bf16 v[32:35], v[160:163], v[176:179], v[32:35]
	v_mfma_f32_16x16x32_bf16 v[20:23], v[134:137], v[186:189], v[20:23]
	v_mfma_f32_16x16x32_bf16 v[16:19], v[160:163], v[186:189], v[16:19]
	v_mfma_f32_16x16x32_bf16 v[4:7], v[134:137], v[194:197], v[4:7]
	v_mfma_f32_16x16x32_bf16 v[0:3], v[160:163], v[194:197], v[0:3]
	s_barrier
	ds_read_b128 v[68:71], v132
	ds_read_b128 v[84:87], v132 offset:1024
	ds_read_b128 v[92:95], v132 offset:2048
	ds_read_b128 v[108:111], v132 offset:3072
	ds_read_b128 v[120:123], v133
	ds_read_b128 v[134:137], v133 offset:1024
	ds_read_b128 v[156:159], v133 offset:2048
	ds_read_b128 v[160:163], v133 offset:3072
	s_add_u32 s56, s56, 0x80000
	s_addc_u32 s57, s57, 0
	s_mov_b32 m0, s63
	ds_read_b128 v[164:167], v209 offset:32768
	ds_read_b128 v[168:171], v209 offset:33792
	ds_read_b128 v[172:175], v209 offset:34816
	ds_read_b128 v[176:179], v209 offset:35840
	ds_read_b128 v[180:183], v209 offset:36864
	ds_read_b128 v[186:189], v209 offset:37888
	ds_read_b128 v[190:193], v209 offset:38912
	ds_read_b128 v[194:197], v209 offset:39936
	global_load_lds_dwordx4 v202, s[56:57]
	s_mov_b32 m0, s64
	s_nop 0
	global_load_lds_dwordx4 v204, s[56:57]
	s_waitcnt vmcnt(8)
	s_waitcnt lgkmcnt(0)
	s_barrier
	v_mfma_f32_16x16x32_bf16 v[152:155], v[68:71], v[164:167], v[152:155]
	v_mfma_f32_16x16x32_bf16 v[148:151], v[92:95], v[164:167], v[148:151]
	v_mfma_f32_16x16x32_bf16 v[128:131], v[68:71], v[172:175], v[128:131]
	v_mfma_f32_16x16x32_bf16 v[124:127], v[92:95], v[172:175], v[124:127]
	v_mfma_f32_16x16x32_bf16 v[104:107], v[68:71], v[180:183], v[104:107]
	v_mfma_f32_16x16x32_bf16 v[100:103], v[92:95], v[180:183], v[100:103]
	v_mfma_f32_16x16x32_bf16 v[80:83], v[68:71], v[190:193], v[80:83]
	v_mfma_f32_16x16x32_bf16 v[76:79], v[92:95], v[190:193], v[76:79]
	v_mfma_f32_16x16x32_bf16 v[152:155], v[84:87], v[168:171], v[152:155]
	v_mfma_f32_16x16x32_bf16 v[148:151], v[108:111], v[168:171], v[148:151]
	v_mfma_f32_16x16x32_bf16 v[128:131], v[84:87], v[176:179], v[128:131]
	v_mfma_f32_16x16x32_bf16 v[124:127], v[108:111], v[176:179], v[124:127]
	v_mfma_f32_16x16x32_bf16 v[104:107], v[84:87], v[186:189], v[104:107]
	v_mfma_f32_16x16x32_bf16 v[100:103], v[108:111], v[186:189], v[100:103]
	v_mfma_f32_16x16x32_bf16 v[80:83], v[84:87], v[194:197], v[80:83]
	v_mfma_f32_16x16x32_bf16 v[76:79], v[108:111], v[194:197], v[76:79]
	v_mfma_f32_16x16x32_bf16 v[142:145], v[120:123], v[164:167], v[144:147]
	v_mfma_f32_16x16x32_bf16 v[138:141], v[156:159], v[164:167], v[138:141]
	v_mfma_f32_16x16x32_bf16 v[116:119], v[120:123], v[172:175], v[116:119]
	v_mfma_f32_16x16x32_bf16 v[112:115], v[156:159], v[172:175], v[112:115]
	v_mfma_f32_16x16x32_bf16 v[96:99], v[120:123], v[180:183], v[96:99]
	v_mfma_f32_16x16x32_bf16 v[88:91], v[156:159], v[180:183], v[88:91]
	v_mfma_f32_16x16x32_bf16 v[72:75], v[120:123], v[190:193], v[72:75]
	v_mfma_f32_16x16x32_bf16 v[64:67], v[156:159], v[190:193], v[64:67]
	v_mfma_f32_16x16x32_bf16 v[144:147], v[134:137], v[168:171], v[142:145]
	v_mfma_f32_16x16x32_bf16 v[140:143], v[160:163], v[168:171], v[138:141]
	v_mfma_f32_16x16x32_bf16 v[116:119], v[134:137], v[176:179], v[116:119]
	v_mfma_f32_16x16x32_bf16 v[112:115], v[160:163], v[176:179], v[112:115]
	v_mfma_f32_16x16x32_bf16 v[96:99], v[134:137], v[186:189], v[96:99]
	v_mfma_f32_16x16x32_bf16 v[88:91], v[160:163], v[186:189], v[88:91]
	v_mfma_f32_16x16x32_bf16 v[72:75], v[134:137], v[194:197], v[72:75]
	v_mfma_f32_16x16x32_bf16 v[64:67], v[160:163], v[194:197], v[64:67]
	s_barrier
	s_add_u32 s56, s54, 0x80
	s_mov_b32 m0, s21
	s_addc_u32 s57, s55, 0
	ds_read_b128 v[164:167], v209 offset:49152
	ds_read_b128 v[168:171], v209 offset:50176
	ds_read_b128 v[172:175], v209 offset:51200
	ds_read_b128 v[176:179], v209 offset:52224
	ds_read_b128 v[180:183], v209 offset:53248
	ds_read_b128 v[186:189], v209 offset:54272
	ds_read_b128 v[190:193], v209 offset:55296
	ds_read_b128 v[194:197], v209 offset:56320
	s_add_u32 s54, s54, 0x80080
	global_load_lds_dwordx4 v203, s[56:57]
	s_mov_b32 m0, s41
	s_addc_u32 s55, s55, 0
	global_load_lds_dwordx4 v205, s[56:57]
	s_mov_b32 m0, s43
	s_nop 0
	global_load_lds_dwordx4 v203, s[54:55]
	s_mov_b32 m0, s76
	s_nop 0
	global_load_lds_dwordx4 v205, s[54:55]
	s_mov_b32 m0, s65
	s_nop 0
	global_load_lds_dwordx4 v202, s[52:53]
	s_mov_b32 m0, s66
	s_nop 0
	global_load_lds_dwordx4 v204, s[52:53]
	s_waitcnt vmcnt(8)
	s_waitcnt lgkmcnt(0)
	s_barrier
	v_mfma_f32_16x16x32_bf16 v[60:63], v[68:71], v[164:167], v[60:63]
	v_mfma_f32_16x16x32_bf16 v[56:59], v[92:95], v[164:167], v[56:59]
	v_mfma_f32_16x16x32_bf16 v[44:47], v[68:71], v[172:175], v[44:47]
	v_mfma_f32_16x16x32_bf16 v[40:43], v[92:95], v[172:175], v[40:43]
	v_mfma_f32_16x16x32_bf16 v[28:31], v[68:71], v[180:183], v[28:31]
	v_mfma_f32_16x16x32_bf16 v[24:27], v[92:95], v[180:183], v[24:27]
	v_mfma_f32_16x16x32_bf16 v[12:15], v[68:71], v[190:193], v[12:15]
	v_mfma_f32_16x16x32_bf16 v[8:11], v[92:95], v[190:193], v[8:11]
	v_mfma_f32_16x16x32_bf16 v[60:63], v[84:87], v[168:171], v[60:63]
	v_mfma_f32_16x16x32_bf16 v[56:59], v[108:111], v[168:171], v[56:59]
	v_mfma_f32_16x16x32_bf16 v[44:47], v[84:87], v[176:179], v[44:47]
	v_mfma_f32_16x16x32_bf16 v[40:43], v[108:111], v[176:179], v[40:43]
	v_mfma_f32_16x16x32_bf16 v[28:31], v[84:87], v[186:189], v[28:31]
	v_mfma_f32_16x16x32_bf16 v[24:27], v[108:111], v[186:189], v[24:27]
	v_mfma_f32_16x16x32_bf16 v[12:15], v[84:87], v[194:197], v[12:15]
	v_mfma_f32_16x16x32_bf16 v[8:11], v[108:111], v[194:197], v[8:11]
	v_mfma_f32_16x16x32_bf16 v[52:55], v[120:123], v[164:167], v[52:55]
	v_mfma_f32_16x16x32_bf16 v[48:51], v[156:159], v[164:167], v[48:51]
	v_mfma_f32_16x16x32_bf16 v[36:39], v[120:123], v[172:175], v[36:39]
	v_mfma_f32_16x16x32_bf16 v[32:35], v[156:159], v[172:175], v[32:35]
	v_mfma_f32_16x16x32_bf16 v[20:23], v[120:123], v[180:183], v[20:23]
	v_mfma_f32_16x16x32_bf16 v[16:19], v[156:159], v[180:183], v[16:19]
	v_mfma_f32_16x16x32_bf16 v[4:7], v[120:123], v[190:193], v[4:7]
	v_mfma_f32_16x16x32_bf16 v[0:3], v[156:159], v[190:193], v[0:3]
	v_mfma_f32_16x16x32_bf16 v[52:55], v[134:137], v[168:171], v[52:55]
	v_mfma_f32_16x16x32_bf16 v[48:51], v[160:163], v[168:171], v[48:51]
	v_mfma_f32_16x16x32_bf16 v[36:39], v[134:137], v[176:179], v[36:39]
	v_mfma_f32_16x16x32_bf16 v[32:35], v[160:163], v[176:179], v[32:35]
	v_mfma_f32_16x16x32_bf16 v[20:23], v[134:137], v[186:189], v[20:23]
	v_mfma_f32_16x16x32_bf16 v[16:19], v[160:163], v[186:189], v[16:19]
	v_mfma_f32_16x16x32_bf16 v[4:7], v[134:137], v[194:197], v[4:7]
	v_mfma_f32_16x16x32_bf16 v[0:3], v[160:163], v[194:197], v[0:3]
	s_barrier
	s_add_i32 s83, s83, 2
	s_add_u32 s77, s77, 0x100
	s_addc_u32 s78, s78, 0
	s_add_u32 s79, s79, 0x100
	s_addc_u32 s80, s80, 0
	s_add_u32 s50, s50, 0x100
	s_addc_u32 s51, s51, 0
	s_cmp_gt_u32 s83, 29
	s_cbranch_scc0 .LBB0_692
	s_and_b64 vcc, exec, s[8:9]
	s_cbranch_vccz .LBB0_695
	s_barrier

.LBB0_797:
	s_add_u32 s20, s46, 0x100
	s_addc_u32 s21, s47, 0
	s_waitcnt lgkmcnt(0)
	s_add_u32 s38, s44, 0x100
	s_addc_u32 s39, s45, 0
	s_barrier
	s_waitcnt lgkmcnt(0)
	v_mfma_f32_16x16x32_bf16 v[32:35], v[16:19], v[72:75], 0
	v_mfma_f32_16x16x32_bf16 v[36:39], v[24:27], v[72:75], 0
	v_mfma_f32_16x16x32_bf16 v[40:43], v[16:19], v[84:87], 0
	v_mfma_f32_16x16x32_bf16 v[44:47], v[24:27], v[84:87], 0
	v_mfma_f32_16x16x32_bf16 v[48:51], v[16:19], v[88:91], 0
	v_mfma_f32_16x16x32_bf16 v[52:55], v[24:27], v[88:91], 0
	v_mfma_f32_16x16x32_bf16 v[56:59], v[16:19], v[68:71], 0
	v_mfma_f32_16x16x32_bf16 v[60:63], v[24:27], v[68:71], 0
	v_mfma_f32_16x16x32_bf16 v[32:35], v[20:23], v[76:79], v[32:35]
	v_mfma_f32_16x16x32_bf16 v[36:39], v[28:31], v[76:79], v[36:39]
	v_mfma_f32_16x16x32_bf16 v[40:43], v[20:23], v[92:95], v[40:43]
	v_mfma_f32_16x16x32_bf16 v[44:47], v[28:31], v[92:95], v[44:47]
	v_mfma_f32_16x16x32_bf16 v[48:51], v[20:23], v[96:99], v[48:51]
	v_mfma_f32_16x16x32_bf16 v[52:55], v[28:31], v[96:99], v[52:55]
	v_mfma_f32_16x16x32_bf16 v[56:59], v[20:23], v[80:83], v[56:59]
	v_mfma_f32_16x16x32_bf16 v[60:63], v[28:31], v[80:83], v[60:63]
	v_mfma_f32_16x16x32_bf16 v[64:67], v[0:3], v[72:75], 0
	v_mfma_f32_16x16x32_bf16 v[72:75], v[8:11], v[72:75], 0
	v_mfma_f32_16x16x32_bf16 v[64:67], v[4:7], v[76:79], v[64:67]
	v_mfma_f32_16x16x32_bf16 v[72:75], v[12:15], v[76:79], v[72:75]
	v_mfma_f32_16x16x32_bf16 v[76:79], v[0:3], v[84:87], 0
	v_mfma_f32_16x16x32_bf16 v[84:87], v[8:11], v[84:87], 0
	v_mfma_f32_16x16x32_bf16 v[76:79], v[4:7], v[92:95], v[76:79]
	v_mfma_f32_16x16x32_bf16 v[84:87], v[12:15], v[92:95], v[84:87]
	v_mfma_f32_16x16x32_bf16 v[92:95], v[0:3], v[88:91], 0
	v_mfma_f32_16x16x32_bf16 v[88:91], v[8:11], v[88:91], 0
	v_mfma_f32_16x16x32_bf16 v[128:131], v[12:15], v[96:99], v[88:91]
	v_mfma_f32_16x16x32_bf16 v[88:91], v[0:3], v[68:71], 0
	v_mfma_f32_16x16x32_bf16 v[68:71], v[8:11], v[68:71], 0
	v_mfma_f32_16x16x32_bf16 v[92:95], v[4:7], v[96:99], v[92:95]
	v_mfma_f32_16x16x32_bf16 v[132:135], v[4:7], v[80:83], v[88:91]
	v_mfma_f32_16x16x32_bf16 v[136:139], v[12:15], v[80:83], v[68:71]
	s_barrier
	s_mov_b32 m0, s41
	ds_read_b128 v[108:111], v150 offset:16384
	ds_read_b128 v[112:115], v150 offset:17408
	ds_read_b128 v[100:103], v150 offset:18432
	ds_read_b128 v[104:107], v150 offset:19456
	ds_read_b128 v[88:91], v150 offset:20480
	ds_read_b128 v[96:99], v150 offset:21504
	ds_read_b128 v[68:71], v150 offset:22528
	ds_read_b128 v[80:83], v150 offset:23552
	global_load_lds_dwordx4 v144, s[38:39]
	s_mov_b32 m0, s43
	s_nop 0
	global_load_lds_dwordx4 v146, s[38:39]
	s_add_u32 s38, s44, 0x80100
	s_addc_u32 s39, s45, 0
	s_mov_b32 m0, s55
	s_and_b64 vcc, exec, s[36:37]
	global_load_lds_dwordx4 v144, s[38:39]
	s_mov_b32 m0, s56
	s_nop 0
	global_load_lds_dwordx4 v146, s[38:39]
	s_mov_b32 m0, s27
	s_mov_b64 s[38:39], -1
	global_load_lds_dwordx4 v143, s[20:21]
	s_mov_b32 m0, s57
	s_nop 0
	global_load_lds_dwordx4 v145, s[20:21]
	s_cbranch_vccz .LBB0_799
	s_waitcnt vmcnt(8)
	s_mov_b64 s[38:39], 0

.LBB0_801:
	s_ashr_i32 s7, s6, 31
	s_lshl_b64 s[20:21], s[6:7], 20
	s_add_u32 s36, s14, s20
	s_addc_u32 s37, s15, s21
	s_ashr_i32 s9, s8, 31
	s_lshl_b64 s[20:21], s[8:9], 20
	s_add_u32 s38, s24, s20
	s_addc_u32 s39, s25, s21
	s_add_u32 s48, s46, 0x180
	s_addc_u32 s49, s47, 0
	s_waitcnt lgkmcnt(0)
	s_and_b64 s[20:21], s[34:35], exec
	s_cselect_b32 s9, s39, s45
	s_cselect_b32 s12, s38, s44
	s_cselect_b32 s20, s37, s47
	s_cselect_b32 s21, s36, s46
	s_add_u32 s50, s44, 0x180
	s_addc_u32 s51, s45, 0
	s_barrier
	s_waitcnt lgkmcnt(0)
	v_mfma_f32_16x16x32_bf16 v[116:119], v[16:19], v[108:111], 0
	v_mfma_f32_16x16x32_bf16 v[154:157], v[20:23], v[112:115], v[116:119]
	v_mfma_f32_16x16x32_bf16 v[116:119], v[24:27], v[108:111], 0
	v_mfma_f32_16x16x32_bf16 v[158:161], v[28:31], v[112:115], v[116:119]
	v_mfma_f32_16x16x32_bf16 v[116:119], v[16:19], v[100:103], 0
	v_mfma_f32_16x16x32_bf16 v[162:165], v[20:23], v[104:107], v[116:119]
	v_mfma_f32_16x16x32_bf16 v[116:119], v[24:27], v[100:103], 0
	v_mfma_f32_16x16x32_bf16 v[166:169], v[28:31], v[104:107], v[116:119]
	v_mfma_f32_16x16x32_bf16 v[116:119], v[16:19], v[88:91], 0
	v_mfma_f32_16x16x32_bf16 v[16:19], v[16:19], v[68:71], 0
	v_mfma_f32_16x16x32_bf16 v[170:173], v[20:23], v[96:99], v[116:119]
	v_mfma_f32_16x16x32_bf16 v[116:119], v[24:27], v[88:91], 0
	v_mfma_f32_16x16x32_bf16 v[20:23], v[20:23], v[80:83], v[16:19]
	v_mfma_f32_16x16x32_bf16 v[16:19], v[24:27], v[68:71], 0
	v_mfma_f32_16x16x32_bf16 v[174:177], v[28:31], v[96:99], v[116:119]
	v_mfma_f32_16x16x32_bf16 v[28:31], v[28:31], v[80:83], v[16:19]
	v_mfma_f32_16x16x32_bf16 v[16:19], v[0:3], v[108:111], 0
	v_mfma_f32_16x16x32_bf16 v[178:181], v[4:7], v[112:115], v[16:19]
	v_mfma_f32_16x16x32_bf16 v[16:19], v[8:11], v[108:111], 0
	v_mfma_f32_16x16x32_bf16 v[182:185], v[12:15], v[112:115], v[16:19]
	v_mfma_f32_16x16x32_bf16 v[16:19], v[0:3], v[100:103], 0
	v_mfma_f32_16x16x32_bf16 v[186:189], v[4:7], v[104:107], v[16:19]
	v_mfma_f32_16x16x32_bf16 v[16:19], v[8:11], v[100:103], 0
	v_mfma_f32_16x16x32_bf16 v[190:193], v[12:15], v[104:107], v[16:19]
	v_mfma_f32_16x16x32_bf16 v[16:19], v[0:3], v[88:91], 0
	v_mfma_f32_16x16x32_bf16 v[0:3], v[0:3], v[68:71], 0
	v_mfma_f32_16x16x32_bf16 v[194:197], v[4:7], v[96:99], v[16:19]
	v_mfma_f32_16x16x32_bf16 v[16:19], v[8:11], v[88:91], 0
	v_mfma_f32_16x16x32_bf16 v[4:7], v[4:7], v[80:83], v[0:3]
	v_mfma_f32_16x16x32_bf16 v[0:3], v[8:11], v[68:71], 0
	v_mfma_f32_16x16x32_bf16 v[198:201], v[12:15], v[96:99], v[16:19]
	v_mfma_f32_16x16x32_bf16 v[202:205], v[12:15], v[80:83], v[0:3]
	s_barrier
	v_add_u32_e32 v152, s67, v147
	v_add_u32_e32 v153, s68, v147
	s_nop 1
	ds_read_b128 v[0:3], v152
	ds_read_b128 v[8:11], v152 offset:1024
	ds_read_b128 v[12:15], v152 offset:2048
	ds_read_b128 v[206:209], v152 offset:3072
	ds_read_b128 v[210:213], v153
	ds_read_b128 v[214:217], v153 offset:1024
	ds_read_b128 v[218:221], v153 offset:2048
	ds_read_b128 v[222:225], v153 offset:3072
	s_add_u32 s52, s46, 0x80100
	s_addc_u32 s53, s47, 0
	s_mov_b32 m0, s58
	ds_read_b128 v[16:19], v150 offset:32768
	ds_read_b128 v[24:27], v150 offset:33792
	ds_read_b128 v[100:103], v150 offset:34816
	ds_read_b128 v[226:229], v150 offset:35840
	ds_read_b128 v[230:233], v150 offset:36864
	ds_read_b128 v[234:237], v150 offset:37888
	ds_read_b128 v[238:241], v150 offset:38912
	ds_read_b128 v[242:245], v150 offset:39936
	global_load_lds_dwordx4 v143, s[52:53]
	s_mov_b32 m0, s59
	s_nop 0
	global_load_lds_dwordx4 v145, s[52:53]
	s_waitcnt vmcnt(8)
	s_waitcnt lgkmcnt(0)
	s_barrier
	v_mfma_f32_16x16x32_bf16 v[32:35], v[0:3], v[16:19], v[32:35]
	v_mfma_f32_16x16x32_bf16 v[120:123], v[8:11], v[24:27], v[32:35]
	v_mfma_f32_16x16x32_bf16 v[32:35], v[12:15], v[16:19], v[36:39]
	v_mfma_f32_16x16x32_bf16 v[112:115], v[206:209], v[24:27], v[32:35]
	v_mfma_f32_16x16x32_bf16 v[32:35], v[0:3], v[100:103], v[40:43]
	v_mfma_f32_16x16x32_bf16 v[104:107], v[8:11], v[226:229], v[32:35]
	v_mfma_f32_16x16x32_bf16 v[32:35], v[12:15], v[100:103], v[44:47]
	v_mfma_f32_16x16x32_bf16 v[96:99], v[206:209], v[226:229], v[32:35]
	v_mfma_f32_16x16x32_bf16 v[32:35], v[0:3], v[230:233], v[48:51]
	v_mfma_f32_16x16x32_bf16 v[88:91], v[8:11], v[234:237], v[32:35]
	v_mfma_f32_16x16x32_bf16 v[32:35], v[12:15], v[230:233], v[52:55]
	v_mfma_f32_16x16x32_bf16 v[80:83], v[206:209], v[234:237], v[32:35]
	v_mfma_f32_16x16x32_bf16 v[32:35], v[0:3], v[238:241], v[56:59]
	v_mfma_f32_16x16x32_bf16 v[68:71], v[8:11], v[242:245], v[32:35]
	v_mfma_f32_16x16x32_bf16 v[32:35], v[12:15], v[238:241], v[60:63]
	v_mfma_f32_16x16x32_bf16 v[52:55], v[206:209], v[242:245], v[32:35]
	v_mfma_f32_16x16x32_bf16 v[32:35], v[210:213], v[16:19], v[64:67]
	v_mfma_f32_16x16x32_bf16 v[16:19], v[218:221], v[16:19], v[72:75]
	v_mfma_f32_16x16x32_bf16 v[116:119], v[222:225], v[24:27], v[16:19]
	v_mfma_f32_16x16x32_bf16 v[16:19], v[210:213], v[100:103], v[76:79]
	v_mfma_f32_16x16x32_bf16 v[108:111], v[214:217], v[226:229], v[16:19]
	v_mfma_f32_16x16x32_bf16 v[16:19], v[218:221], v[100:103], v[84:87]
	v_mfma_f32_16x16x32_bf16 v[100:103], v[222:225], v[226:229], v[16:19]
	v_mfma_f32_16x16x32_bf16 v[16:19], v[210:213], v[230:233], v[92:95]
	v_mfma_f32_16x16x32_bf16 v[92:95], v[214:217], v[234:237], v[16:19]
	v_mfma_f32_16x16x32_bf16 v[16:19], v[218:221], v[230:233], v[128:131]
	v_mfma_f32_16x16x32_bf16 v[84:87], v[222:225], v[234:237], v[16:19]
	v_mfma_f32_16x16x32_bf16 v[16:19], v[210:213], v[238:241], v[132:135]
	v_mfma_f32_16x16x32_bf16 v[76:79], v[214:217], v[242:245], v[16:19]
	v_mfma_f32_16x16x32_bf16 v[16:19], v[218:221], v[238:241], v[136:139]
	v_mfma_f32_16x16x32_bf16 v[124:127], v[214:217], v[24:27], v[32:35]
	v_mfma_f32_16x16x32_bf16 v[60:63], v[222:225], v[242:245], v[16:19]
	s_barrier
	s_add_i32 s72, s67, s26
	s_mov_b32 m0, s72
	s_add_i32 s73, s72, 0x2000
	ds_read_b128 v[36:39], v150 offset:49152
	ds_read_b128 v[44:47], v150 offset:50176
	ds_read_b128 v[128:131], v150 offset:51200
	ds_read_b128 v[132:135], v150 offset:52224
	ds_read_b128 v[136:139], v150 offset:53248
	ds_read_b128 v[226:229], v150 offset:54272
	ds_read_b128 v[230:233], v150 offset:55296
	ds_read_b128 v[234:237], v150 offset:56320
	global_load_lds_dwordx4 v144, s[50:51]
	s_mov_b32 m0, s73
	s_nop 0
	global_load_lds_dwordx4 v146, s[50:51]
	s_add_u32 s50, s44, 0x80180
	s_addc_u32 s51, s45, 0
	s_add_i32 s74, s68, s26
	s_mov_b32 m0, s74
	s_add_i32 s75, s74, 0x2000
	s_nop 0
	global_load_lds_dwordx4 v144, s[50:51]
	s_mov_b32 m0, s75
	s_nop 0
	global_load_lds_dwordx4 v146, s[50:51]
	s_mov_b32 m0, s60
	s_nop 0
	global_load_lds_dwordx4 v143, s[48:49]
	s_mov_b32 m0, s61
	s_nop 0
	global_load_lds_dwordx4 v145, s[48:49]
	s_waitcnt vmcnt(8)
	s_waitcnt lgkmcnt(0)
	s_barrier
	v_mfma_f32_16x16x32_bf16 v[16:19], v[0:3], v[36:39], v[154:157]
	v_mfma_f32_16x16x32_bf16 v[64:67], v[8:11], v[44:47], v[16:19]
	v_mfma_f32_16x16x32_bf16 v[16:19], v[12:15], v[36:39], v[158:161]
	v_mfma_f32_16x16x32_bf16 v[48:51], v[206:209], v[44:47], v[16:19]
	v_mfma_f32_16x16x32_bf16 v[16:19], v[0:3], v[128:131], v[162:165]
	v_mfma_f32_16x16x32_bf16 v[40:43], v[8:11], v[132:135], v[16:19]
	v_mfma_f32_16x16x32_bf16 v[16:19], v[12:15], v[128:131], v[166:169]
	v_mfma_f32_16x16x32_bf16 v[32:35], v[206:209], v[132:135], v[16:19]
	v_mfma_f32_16x16x32_bf16 v[16:19], v[0:3], v[136:139], v[170:173]
	v_mfma_f32_16x16x32_bf16 v[0:3], v[0:3], v[230:233], v[20:23]
	v_mfma_f32_16x16x32_bf16 v[24:27], v[8:11], v[226:229], v[16:19]
	v_mfma_f32_16x16x32_bf16 v[16:19], v[12:15], v[136:139], v[174:177]
	v_mfma_f32_16x16x32_bf16 v[8:11], v[8:11], v[234:237], v[0:3]
	v_mfma_f32_16x16x32_bf16 v[0:3], v[12:15], v[230:233], v[28:31]
	v_mfma_f32_16x16x32_bf16 v[16:19], v[206:209], v[226:229], v[16:19]
	v_mfma_f32_16x16x32_bf16 v[0:3], v[206:209], v[234:237], v[0:3]
	v_mfma_f32_16x16x32_bf16 v[12:15], v[210:213], v[36:39], v[178:181]
	v_mfma_f32_16x16x32_bf16 v[72:75], v[214:217], v[44:47], v[12:15]
	v_mfma_f32_16x16x32_bf16 v[12:15], v[218:221], v[36:39], v[182:185]
	v_mfma_f32_16x16x32_bf16 v[56:59], v[222:225], v[44:47], v[12:15]
	v_mfma_f32_16x16x32_bf16 v[12:15], v[210:213], v[128:131], v[186:189]
	v_mfma_f32_16x16x32_bf16 v[44:47], v[214:217], v[132:135], v[12:15]
	v_mfma_f32_16x16x32_bf16 v[12:15], v[218:221], v[128:131], v[190:193]
	v_mfma_f32_16x16x32_bf16 v[36:39], v[222:225], v[132:135], v[12:15]
	v_mfma_f32_16x16x32_bf16 v[12:15], v[210:213], v[136:139], v[194:197]
	v_mfma_f32_16x16x32_bf16 v[28:31], v[214:217], v[226:229], v[12:15]
	v_mfma_f32_16x16x32_bf16 v[12:15], v[218:221], v[136:139], v[198:201]
	v_mfma_f32_16x16x32_bf16 v[4:7], v[210:213], v[230:233], v[4:7]
	v_mfma_f32_16x16x32_bf16 v[20:23], v[222:225], v[226:229], v[12:15]
	v_mfma_f32_16x16x32_bf16 v[12:15], v[214:217], v[234:237], v[4:7]
	v_mfma_f32_16x16x32_bf16 v[4:7], v[218:221], v[230:233], v[202:205]
	v_mfma_f32_16x16x32_bf16 v[4:7], v[222:225], v[234:237], v[4:7]
	s_barrier
	s_add_u32 s52, s46, 0x100
	s_addc_u32 s53, s47, 0
	s_add_u32 s76, s44, 0x200
	s_addc_u32 s77, s45, 0
	s_mov_b32 s78, 0
.LBB0_802:
	s_add_u32 s44, s52, 0x100
	s_addc_u32 s45, s53, 0
	s_cmp_eq_u32 s78, 28
	s_cselect_b32 s50, s21, s44
	s_cselect_b32 s51, s20, s45
	s_cselect_b32 s48, s12, s76
	s_cselect_b32 s49, s9, s77
	s_add_u32 s46, s50, 0x80
	s_addc_u32 s47, s51, 0
	s_add_i32 s79, 0, 0x10000
	s_add_i32 s80, 0, 0x14000
	v_add_u32_e32 v154, s79, v147
	v_add_u32_e32 v170, s80, v147
	ds_read_b128 v[128:131], v154
	ds_read_b128 v[132:135], v154 offset:1024
	ds_read_b128 v[136:139], v154 offset:2048
	ds_read_b128 v[154:157], v154 offset:3072
	ds_read_b128 v[158:161], v170
	ds_read_b128 v[162:165], v170 offset:1024
	ds_read_b128 v[166:169], v170 offset:2048
	ds_read_b128 v[170:173], v170 offset:3072
	s_add_u32 s52, s52, 0x80080
	s_addc_u32 s53, s53, 0
	s_mov_b32 m0, s0
	ds_read_b128 v[174:177], v150
	ds_read_b128 v[178:181], v150 offset:1024
	ds_read_b128 v[182:185], v150 offset:2048
	ds_read_b128 v[186:189], v150 offset:3072
	ds_read_b128 v[190:193], v150 offset:4096
	ds_read_b128 v[194:197], v150 offset:5120
	ds_read_b128 v[198:201], v150 offset:6144
	ds_read_b128 v[202:205], v150 offset:7168
	global_load_lds_dwordx4 v143, s[52:53]
	s_mov_b32 m0, s1
	s_nop 0
	global_load_lds_dwordx4 v145, s[52:53]
	s_waitcnt vmcnt(8)
	s_waitcnt lgkmcnt(0)
	s_barrier
	v_mfma_f32_16x16x32_bf16 v[120:123], v[128:131], v[174:177], v[120:123]
	v_mfma_f32_16x16x32_bf16 v[112:115], v[136:139], v[174:177], v[112:115]
	v_mfma_f32_16x16x32_bf16 v[104:107], v[128:131], v[182:185], v[104:107]
	v_mfma_f32_16x16x32_bf16 v[96:99], v[136:139], v[182:185], v[96:99]
	v_mfma_f32_16x16x32_bf16 v[88:91], v[128:131], v[190:193], v[88:91]
	v_mfma_f32_16x16x32_bf16 v[80:83], v[136:139], v[190:193], v[80:83]
	v_mfma_f32_16x16x32_bf16 v[68:71], v[128:131], v[198:201], v[68:71]
	v_mfma_f32_16x16x32_bf16 v[52:55], v[136:139], v[198:201], v[52:55]
	v_mfma_f32_16x16x32_bf16 v[120:123], v[132:135], v[178:181], v[120:123]
	v_mfma_f32_16x16x32_bf16 v[112:115], v[154:157], v[178:181], v[112:115]
	v_mfma_f32_16x16x32_bf16 v[104:107], v[132:135], v[186:189], v[104:107]
	v_mfma_f32_16x16x32_bf16 v[96:99], v[154:157], v[186:189], v[96:99]
	v_mfma_f32_16x16x32_bf16 v[88:91], v[132:135], v[194:197], v[88:91]
	v_mfma_f32_16x16x32_bf16 v[80:83], v[154:157], v[194:197], v[80:83]
	v_mfma_f32_16x16x32_bf16 v[68:71], v[132:135], v[202:205], v[68:71]
	v_mfma_f32_16x16x32_bf16 v[52:55], v[154:157], v[202:205], v[52:55]
	v_mfma_f32_16x16x32_bf16 v[124:127], v[158:161], v[174:177], v[124:127]
	v_mfma_f32_16x16x32_bf16 v[116:119], v[166:169], v[174:177], v[116:119]
	v_mfma_f32_16x16x32_bf16 v[108:111], v[158:161], v[182:185], v[108:111]
	v_mfma_f32_16x16x32_bf16 v[100:103], v[166:169], v[182:185], v[100:103]
	v_mfma_f32_16x16x32_bf16 v[92:95], v[158:161], v[190:193], v[92:95]
	v_mfma_f32_16x16x32_bf16 v[84:87], v[166:169], v[190:193], v[84:87]
	v_mfma_f32_16x16x32_bf16 v[76:79], v[158:161], v[198:201], v[76:79]
	v_mfma_f32_16x16x32_bf16 v[60:63], v[166:169], v[198:201], v[60:63]
	v_mfma_f32_16x16x32_bf16 v[124:127], v[162:165], v[178:181], v[124:127]
	v_mfma_f32_16x16x32_bf16 v[116:119], v[170:173], v[178:181], v[116:119]
	v_mfma_f32_16x16x32_bf16 v[108:111], v[162:165], v[186:189], v[108:111]
	v_mfma_f32_16x16x32_bf16 v[100:103], v[170:173], v[186:189], v[100:103]
	v_mfma_f32_16x16x32_bf16 v[92:95], v[162:165], v[194:197], v[92:95]
	v_mfma_f32_16x16x32_bf16 v[84:87], v[170:173], v[194:197], v[84:87]
	v_mfma_f32_16x16x32_bf16 v[76:79], v[162:165], v[202:205], v[76:79]
	v_mfma_f32_16x16x32_bf16 v[60:63], v[170:173], v[202:205], v[60:63]
	s_barrier
	s_add_i32 s52, s79, s26
	s_mov_b32 m0, s52
	ds_read_b128 v[174:177], v150 offset:16384
	ds_read_b128 v[178:181], v150 offset:17408
	ds_read_b128 v[182:185], v150 offset:18432
	ds_read_b128 v[186:189], v150 offset:19456
	ds_read_b128 v[190:193], v150 offset:20480
	ds_read_b128 v[194:197], v150 offset:21504
	ds_read_b128 v[198:201], v150 offset:22528
	ds_read_b128 v[202:205], v150 offset:23552
	global_load_lds_dwordx4 v144, s[48:49]
	s_add_i32 m0, s52, 0x2000
	s_add_u32 s52, s48, 0x80000
	s_addc_u32 s53, s49, 0
	s_add_i32 s79, s80, s26
	s_nop 0
	global_load_lds_dwordx4 v146, s[48:49]
	s_mov_b32 m0, s79
	s_nop 0
	global_load_lds_dwordx4 v144, s[52:53]
	s_add_i32 m0, s79, 0x2000
	s_nop 0
	global_load_lds_dwordx4 v146, s[52:53]
	s_mov_b32 m0, s27
	s_nop 0
	global_load_lds_dwordx4 v143, s[50:51]
	s_mov_b32 m0, s57
	s_nop 0
	global_load_lds_dwordx4 v145, s[50:51]
	s_waitcnt vmcnt(8)
	s_waitcnt lgkmcnt(0)
	s_barrier
	v_mfma_f32_16x16x32_bf16 v[64:67], v[128:131], v[174:177], v[64:67]
	v_mfma_f32_16x16x32_bf16 v[48:51], v[136:139], v[174:177], v[48:51]
	v_mfma_f32_16x16x32_bf16 v[40:43], v[128:131], v[182:185], v[40:43]
	v_mfma_f32_16x16x32_bf16 v[32:35], v[136:139], v[182:185], v[32:35]
	v_mfma_f32_16x16x32_bf16 v[24:27], v[128:131], v[190:193], v[24:27]
	v_mfma_f32_16x16x32_bf16 v[16:19], v[136:139], v[190:193], v[16:19]
	v_mfma_f32_16x16x32_bf16 v[8:11], v[128:131], v[198:201], v[8:11]
	v_mfma_f32_16x16x32_bf16 v[0:3], v[136:139], v[198:201], v[0:3]
	v_mfma_f32_16x16x32_bf16 v[64:67], v[132:135], v[178:181], v[64:67]
	v_mfma_f32_16x16x32_bf16 v[48:51], v[154:157], v[178:181], v[48:51]
	v_mfma_f32_16x16x32_bf16 v[40:43], v[132:135], v[186:189], v[40:43]
	v_mfma_f32_16x16x32_bf16 v[32:35], v[154:157], v[186:189], v[32:35]
	v_mfma_f32_16x16x32_bf16 v[24:27], v[132:135], v[194:197], v[24:27]
	v_mfma_f32_16x16x32_bf16 v[16:19], v[154:157], v[194:197], v[16:19]
	v_mfma_f32_16x16x32_bf16 v[8:11], v[132:135], v[202:205], v[8:11]
	v_mfma_f32_16x16x32_bf16 v[0:3], v[154:157], v[202:205], v[0:3]
	v_mfma_f32_16x16x32_bf16 v[72:75], v[158:161], v[174:177], v[72:75]
	v_mfma_f32_16x16x32_bf16 v[56:59], v[166:169], v[174:177], v[56:59]
	v_mfma_f32_16x16x32_bf16 v[44:47], v[158:161], v[182:185], v[44:47]
	v_mfma_f32_16x16x32_bf16 v[36:39], v[166:169], v[182:185], v[36:39]
	v_mfma_f32_16x16x32_bf16 v[28:31], v[158:161], v[190:193], v[28:31]
	v_mfma_f32_16x16x32_bf16 v[20:23], v[166:169], v[190:193], v[20:23]
	v_mfma_f32_16x16x32_bf16 v[12:15], v[158:161], v[198:201], v[12:15]
	v_mfma_f32_16x16x32_bf16 v[4:7], v[166:169], v[198:201], v[4:7]
	v_mfma_f32_16x16x32_bf16 v[72:75], v[162:165], v[178:181], v[72:75]
	v_mfma_f32_16x16x32_bf16 v[56:59], v[170:173], v[178:181], v[56:59]
	v_mfma_f32_16x16x32_bf16 v[44:47], v[162:165], v[186:189], v[44:47]
	v_mfma_f32_16x16x32_bf16 v[36:39], v[170:173], v[186:189], v[36:39]
	v_mfma_f32_16x16x32_bf16 v[28:31], v[162:165], v[194:197], v[28:31]
	v_mfma_f32_16x16x32_bf16 v[20:23], v[170:173], v[194:197], v[20:23]
	v_mfma_f32_16x16x32_bf16 v[12:15], v[162:165], v[202:205], v[12:15]
	v_mfma_f32_16x16x32_bf16 v[4:7], v[170:173], v[202:205], v[4:7]
	s_barrier
	ds_read_b128 v[128:131], v152
	ds_read_b128 v[132:135], v152 offset:1024
	ds_read_b128 v[136:139], v152 offset:2048
	ds_read_b128 v[154:157], v152 offset:3072
	ds_read_b128 v[158:161], v153
	ds_read_b128 v[162:165], v153 offset:1024
	ds_read_b128 v[166:169], v153 offset:2048
	ds_read_b128 v[170:173], v153 offset:3072
	s_add_u32 s50, s50, 0x80000
	s_addc_u32 s51, s51, 0
	s_mov_b32 m0, s58
	ds_read_b128 v[174:177], v150 offset:32768
	ds_read_b128 v[178:181], v150 offset:33792
	ds_read_b128 v[182:185], v150 offset:34816
	ds_read_b128 v[186:189], v150 offset:35840
	ds_read_b128 v[190:193], v150 offset:36864
	ds_read_b128 v[194:197], v150 offset:37888
	ds_read_b128 v[198:201], v150 offset:38912
	ds_read_b128 v[202:205], v150 offset:39936
	global_load_lds_dwordx4 v143, s[50:51]
	s_mov_b32 m0, s59
	s_nop 0
	global_load_lds_dwordx4 v145, s[50:51]
	s_waitcnt vmcnt(8)
	s_waitcnt lgkmcnt(0)
	s_barrier
	v_mfma_f32_16x16x32_bf16 v[120:123], v[128:131], v[174:177], v[120:123]
	v_mfma_f32_16x16x32_bf16 v[112:115], v[136:139], v[174:177], v[112:115]
	v_mfma_f32_16x16x32_bf16 v[104:107], v[128:131], v[182:185], v[104:107]
	v_mfma_f32_16x16x32_bf16 v[96:99], v[136:139], v[182:185], v[96:99]
	v_mfma_f32_16x16x32_bf16 v[88:91], v[128:131], v[190:193], v[88:91]
	v_mfma_f32_16x16x32_bf16 v[80:83], v[136:139], v[190:193], v[80:83]
	v_mfma_f32_16x16x32_bf16 v[68:71], v[128:131], v[198:201], v[68:71]
	v_mfma_f32_16x16x32_bf16 v[52:55], v[136:139], v[198:201], v[52:55]
	v_mfma_f32_16x16x32_bf16 v[120:123], v[132:135], v[178:181], v[120:123]
	v_mfma_f32_16x16x32_bf16 v[112:115], v[154:157], v[178:181], v[112:115]
	v_mfma_f32_16x16x32_bf16 v[104:107], v[132:135], v[186:189], v[104:107]
	v_mfma_f32_16x16x32_bf16 v[96:99], v[154:157], v[186:189], v[96:99]
	v_mfma_f32_16x16x32_bf16 v[88:91], v[132:135], v[194:197], v[88:91]
	v_mfma_f32_16x16x32_bf16 v[80:83], v[154:157], v[194:197], v[80:83]
	v_mfma_f32_16x16x32_bf16 v[68:71], v[132:135], v[202:205], v[68:71]
	v_mfma_f32_16x16x32_bf16 v[52:55], v[154:157], v[202:205], v[52:55]
	v_mfma_f32_16x16x32_bf16 v[124:127], v[158:161], v[174:177], v[124:127]
	v_mfma_f32_16x16x32_bf16 v[116:119], v[166:169], v[174:177], v[116:119]
	v_mfma_f32_16x16x32_bf16 v[108:111], v[158:161], v[182:185], v[108:111]
	v_mfma_f32_16x16x32_bf16 v[100:103], v[166:169], v[182:185], v[100:103]
	v_mfma_f32_16x16x32_bf16 v[92:95], v[158:161], v[190:193], v[92:95]
	v_mfma_f32_16x16x32_bf16 v[84:87], v[166:169], v[190:193], v[84:87]
	v_mfma_f32_16x16x32_bf16 v[76:79], v[158:161], v[198:201], v[76:79]
	v_mfma_f32_16x16x32_bf16 v[60:63], v[166:169], v[198:201], v[60:63]
	v_mfma_f32_16x16x32_bf16 v[124:127], v[162:165], v[178:181], v[124:127]
	v_mfma_f32_16x16x32_bf16 v[116:119], v[170:173], v[178:181], v[116:119]
	v_mfma_f32_16x16x32_bf16 v[108:111], v[162:165], v[186:189], v[108:111]
	v_mfma_f32_16x16x32_bf16 v[100:103], v[170:173], v[186:189], v[100:103]
	v_mfma_f32_16x16x32_bf16 v[92:95], v[162:165], v[194:197], v[92:95]
	v_mfma_f32_16x16x32_bf16 v[84:87], v[170:173], v[194:197], v[84:87]
	v_mfma_f32_16x16x32_bf16 v[76:79], v[162:165], v[202:205], v[76:79]
	v_mfma_f32_16x16x32_bf16 v[60:63], v[170:173], v[202:205], v[60:63]
	s_barrier
	s_add_u32 s50, s48, 0x80
	s_mov_b32 m0, s72
	s_addc_u32 s51, s49, 0
	ds_read_b128 v[174:177], v150 offset:49152
	ds_read_b128 v[178:181], v150 offset:50176
	ds_read_b128 v[182:185], v150 offset:51200
	ds_read_b128 v[186:189], v150 offset:52224
	ds_read_b128 v[190:193], v150 offset:53248
	ds_read_b128 v[194:197], v150 offset:54272
	ds_read_b128 v[198:201], v150 offset:55296
	ds_read_b128 v[202:205], v150 offset:56320
	s_add_u32 s48, s48, 0x80080
	global_load_lds_dwordx4 v144, s[50:51]
	s_mov_b32 m0, s73
	s_addc_u32 s49, s49, 0
	global_load_lds_dwordx4 v146, s[50:51]
	s_mov_b32 m0, s74
	s_nop 0
	global_load_lds_dwordx4 v144, s[48:49]
	s_mov_b32 m0, s75
	s_nop 0
	global_load_lds_dwordx4 v146, s[48:49]
	s_mov_b32 m0, s60
	s_nop 0
	global_load_lds_dwordx4 v143, s[46:47]
	s_mov_b32 m0, s61
	s_nop 0
	global_load_lds_dwordx4 v145, s[46:47]
	s_waitcnt vmcnt(8)
	s_waitcnt lgkmcnt(0)
	s_barrier
	v_mfma_f32_16x16x32_bf16 v[64:67], v[128:131], v[174:177], v[64:67]
	v_mfma_f32_16x16x32_bf16 v[48:51], v[136:139], v[174:177], v[48:51]
	v_mfma_f32_16x16x32_bf16 v[40:43], v[128:131], v[182:185], v[40:43]
	v_mfma_f32_16x16x32_bf16 v[32:35], v[136:139], v[182:185], v[32:35]
	v_mfma_f32_16x16x32_bf16 v[24:27], v[128:131], v[190:193], v[24:27]
	v_mfma_f32_16x16x32_bf16 v[16:19], v[136:139], v[190:193], v[16:19]
	v_mfma_f32_16x16x32_bf16 v[8:11], v[128:131], v[198:201], v[8:11]
	v_mfma_f32_16x16x32_bf16 v[0:3], v[136:139], v[198:201], v[0:3]
	v_mfma_f32_16x16x32_bf16 v[64:67], v[132:135], v[178:181], v[64:67]
	v_mfma_f32_16x16x32_bf16 v[48:51], v[154:157], v[178:181], v[48:51]
	v_mfma_f32_16x16x32_bf16 v[40:43], v[132:135], v[186:189], v[40:43]
	v_mfma_f32_16x16x32_bf16 v[32:35], v[154:157], v[186:189], v[32:35]
	v_mfma_f32_16x16x32_bf16 v[24:27], v[132:135], v[194:197], v[24:27]
	v_mfma_f32_16x16x32_bf16 v[16:19], v[154:157], v[194:197], v[16:19]
	v_mfma_f32_16x16x32_bf16 v[8:11], v[132:135], v[202:205], v[8:11]
	v_mfma_f32_16x16x32_bf16 v[0:3], v[154:157], v[202:205], v[0:3]
	v_mfma_f32_16x16x32_bf16 v[72:75], v[158:161], v[174:177], v[72:75]
	v_mfma_f32_16x16x32_bf16 v[56:59], v[166:169], v[174:177], v[56:59]
	v_mfma_f32_16x16x32_bf16 v[44:47], v[158:161], v[182:185], v[44:47]
	v_mfma_f32_16x16x32_bf16 v[36:39], v[166:169], v[182:185], v[36:39]
	v_mfma_f32_16x16x32_bf16 v[28:31], v[158:161], v[190:193], v[28:31]
	v_mfma_f32_16x16x32_bf16 v[20:23], v[166:169], v[190:193], v[20:23]
	v_mfma_f32_16x16x32_bf16 v[12:15], v[158:161], v[198:201], v[12:15]
	v_mfma_f32_16x16x32_bf16 v[4:7], v[166:169], v[198:201], v[4:7]
	v_mfma_f32_16x16x32_bf16 v[72:75], v[162:165], v[178:181], v[72:75]
	v_mfma_f32_16x16x32_bf16 v[56:59], v[170:173], v[178:181], v[56:59]
	v_mfma_f32_16x16x32_bf16 v[44:47], v[162:165], v[186:189], v[44:47]
	v_mfma_f32_16x16x32_bf16 v[36:39], v[170:173], v[186:189], v[36:39]
	v_mfma_f32_16x16x32_bf16 v[28:31], v[162:165], v[194:197], v[28:31]
	v_mfma_f32_16x16x32_bf16 v[20:23], v[170:173], v[194:197], v[20:23]
	v_mfma_f32_16x16x32_bf16 v[12:15], v[162:165], v[202:205], v[12:15]
	v_mfma_f32_16x16x32_bf16 v[4:7], v[170:173], v[202:205], v[4:7]
	s_barrier
	s_add_i32 s78, s78, 2
	s_add_u32 s76, s76, 0x100
	s_addc_u32 s77, s77, 0
	s_cmp_gt_u32 s78, 29
	s_mov_b64 s[52:53], s[44:45]
	s_cbranch_scc0 .LBB0_802
	s_and_b64 vcc, exec, s[4:5]
	s_cbranch_vccz .LBB0_805
	s_barrier

.LBB0_895:
	s_add_u32 s20, s48, 0x100
	s_addc_u32 s21, s49, 0
	s_waitcnt lgkmcnt(0)
	s_add_u32 s52, s4, 0x100
	s_addc_u32 s53, s5, 0
	s_barrier
	v_mfma_f32_16x16x32_bf16 v[32:35], v[16:19], v[68:71], 0
	v_mfma_f32_16x16x32_bf16 v[36:39], v[24:27], v[68:71], 0
	s_waitcnt lgkmcnt(0)
	v_mfma_f32_16x16x32_bf16 v[40:43], v[16:19], v[84:87], 0
	v_mfma_f32_16x16x32_bf16 v[44:47], v[24:27], v[84:87], 0
	v_mfma_f32_16x16x32_bf16 v[48:51], v[16:19], v[92:95], 0
	v_mfma_f32_16x16x32_bf16 v[52:55], v[24:27], v[92:95], 0
	v_mfma_f32_16x16x32_bf16 v[56:59], v[16:19], v[76:79], 0
	v_mfma_f32_16x16x32_bf16 v[60:63], v[24:27], v[76:79], 0
	v_mfma_f32_16x16x32_bf16 v[138:141], v[20:23], v[72:75], v[32:35]
	v_mfma_f32_16x16x32_bf16 v[36:39], v[28:31], v[72:75], v[36:39]
	v_mfma_f32_16x16x32_bf16 v[40:43], v[20:23], v[88:91], v[40:43]
	v_mfma_f32_16x16x32_bf16 v[44:47], v[28:31], v[88:91], v[44:47]
	v_mfma_f32_16x16x32_bf16 v[48:51], v[20:23], v[96:99], v[48:51]
	v_mfma_f32_16x16x32_bf16 v[52:55], v[28:31], v[96:99], v[52:55]
	v_mfma_f32_16x16x32_bf16 v[56:59], v[20:23], v[80:83], v[56:59]
	v_mfma_f32_16x16x32_bf16 v[60:63], v[28:31], v[80:83], v[60:63]
	v_mfma_f32_16x16x32_bf16 v[64:67], v[0:3], v[68:71], 0
	v_mfma_f32_16x16x32_bf16 v[68:71], v[8:11], v[68:71], 0
	v_mfma_f32_16x16x32_bf16 v[64:67], v[4:7], v[72:75], v[64:67]
	v_mfma_f32_16x16x32_bf16 v[68:71], v[12:15], v[72:75], v[68:71]
	v_mfma_f32_16x16x32_bf16 v[72:75], v[0:3], v[84:87], 0
	v_mfma_f32_16x16x32_bf16 v[84:87], v[8:11], v[84:87], 0
	v_mfma_f32_16x16x32_bf16 v[72:75], v[4:7], v[88:91], v[72:75]
	v_mfma_f32_16x16x32_bf16 v[84:87], v[12:15], v[88:91], v[84:87]
	v_mfma_f32_16x16x32_bf16 v[88:91], v[0:3], v[92:95], 0
	v_mfma_f32_16x16x32_bf16 v[92:95], v[8:11], v[92:95], 0
	v_mfma_f32_16x16x32_bf16 v[88:91], v[4:7], v[96:99], v[88:91]
	v_mfma_f32_16x16x32_bf16 v[92:95], v[12:15], v[96:99], v[92:95]
	v_mfma_f32_16x16x32_bf16 v[96:99], v[0:3], v[76:79], 0
	v_mfma_f32_16x16x32_bf16 v[76:79], v[8:11], v[76:79], 0
	v_mfma_f32_16x16x32_bf16 v[108:111], v[4:7], v[80:83], v[96:99]
	v_mfma_f32_16x16x32_bf16 v[112:115], v[12:15], v[80:83], v[76:79]
	s_barrier
	s_mov_b32 m0, s54
	ds_read_b128 v[120:123], v209 offset:16384
	ds_read_b128 v[124:127], v209 offset:17408
	ds_read_b128 v[104:107], v209 offset:18432
	ds_read_b128 v[116:119], v209 offset:19456
	ds_read_b128 v[96:99], v209 offset:20480
	ds_read_b128 v[100:103], v209 offset:21504
	ds_read_b128 v[76:79], v209 offset:22528
	ds_read_b128 v[80:83], v209 offset:23552
	global_load_lds_dwordx4 v203, s[52:53]
	s_mov_b32 m0, s55
	s_nop 0
	global_load_lds_dwordx4 v205, s[52:53]
	s_add_u32 s52, s4, 0x160100
	s_addc_u32 s53, s5, 0
	s_mov_b32 m0, s56
	s_and_b64 vcc, exec, s[50:51]
	global_load_lds_dwordx4 v203, s[52:53]
	s_mov_b32 m0, s57
	s_nop 0
	global_load_lds_dwordx4 v205, s[52:53]
	s_mov_b32 m0, s27
	s_mov_b64 s[52:53], -1
	global_load_lds_dwordx4 v202, s[20:21]
	s_mov_b32 m0, s58
	s_nop 0
	global_load_lds_dwordx4 v204, s[20:21]
	s_cbranch_vccz .LBB0_897
	s_waitcnt vmcnt(8)
	s_mov_b64 s[52:53], 0

.LBB0_899:
	s_add_u32 s50, s48, 0x180
	s_waitcnt lgkmcnt(0)
	s_addc_u32 s51, s49, 0
	s_add_u32 s52, s4, 0x180
	s_addc_u32 s53, s5, 0
	s_barrier
	s_waitcnt lgkmcnt(0)
	v_mfma_f32_16x16x32_bf16 v[128:131], v[16:19], v[120:123], 0
	v_mfma_f32_16x16x32_bf16 v[134:137], v[20:23], v[124:127], v[128:131]
	v_mfma_f32_16x16x32_bf16 v[128:131], v[24:27], v[120:123], 0
	v_mfma_f32_16x16x32_bf16 v[156:159], v[28:31], v[124:127], v[128:131]
	v_mfma_f32_16x16x32_bf16 v[128:131], v[16:19], v[104:107], 0
	v_mfma_f32_16x16x32_bf16 v[160:163], v[20:23], v[116:119], v[128:131]
	v_mfma_f32_16x16x32_bf16 v[128:131], v[24:27], v[104:107], 0
	v_mfma_f32_16x16x32_bf16 v[164:167], v[28:31], v[116:119], v[128:131]
	v_mfma_f32_16x16x32_bf16 v[128:131], v[16:19], v[96:99], 0
	v_mfma_f32_16x16x32_bf16 v[16:19], v[16:19], v[76:79], 0
	v_mfma_f32_16x16x32_bf16 v[168:171], v[20:23], v[100:103], v[128:131]
	v_mfma_f32_16x16x32_bf16 v[16:19], v[20:23], v[80:83], v[16:19]
	v_mfma_f32_16x16x32_bf16 v[20:23], v[24:27], v[76:79], 0
	v_mfma_f32_16x16x32_bf16 v[128:131], v[24:27], v[96:99], 0
	v_mfma_f32_16x16x32_bf16 v[20:23], v[28:31], v[80:83], v[20:23]
	v_mfma_f32_16x16x32_bf16 v[172:175], v[28:31], v[100:103], v[128:131]
	v_mfma_f32_16x16x32_bf16 v[24:27], v[0:3], v[120:123], 0
	v_mfma_f32_16x16x32_bf16 v[176:179], v[4:7], v[124:127], v[24:27]
	v_mfma_f32_16x16x32_bf16 v[24:27], v[8:11], v[120:123], 0
	v_mfma_f32_16x16x32_bf16 v[180:183], v[12:15], v[124:127], v[24:27]
	v_mfma_f32_16x16x32_bf16 v[24:27], v[0:3], v[104:107], 0
	v_mfma_f32_16x16x32_bf16 v[186:189], v[4:7], v[116:119], v[24:27]
	v_mfma_f32_16x16x32_bf16 v[24:27], v[8:11], v[104:107], 0
	v_mfma_f32_16x16x32_bf16 v[190:193], v[12:15], v[116:119], v[24:27]
	v_mfma_f32_16x16x32_bf16 v[24:27], v[0:3], v[96:99], 0
	v_mfma_f32_16x16x32_bf16 v[0:3], v[0:3], v[76:79], 0
	v_mfma_f32_16x16x32_bf16 v[194:197], v[4:7], v[100:103], v[24:27]
	v_mfma_f32_16x16x32_bf16 v[24:27], v[8:11], v[96:99], 0
	v_mfma_f32_16x16x32_bf16 v[0:3], v[4:7], v[80:83], v[0:3]
	v_mfma_f32_16x16x32_bf16 v[4:7], v[8:11], v[76:79], 0
	v_mfma_f32_16x16x32_bf16 v[198:201], v[12:15], v[100:103], v[24:27]
	v_mfma_f32_16x16x32_bf16 v[212:215], v[12:15], v[80:83], v[4:7]
	s_barrier
	v_add_u32_e32 v132, s68, v206
	v_add_u32_e32 v133, s69, v206
	s_nop 1
	ds_read_b128 v[4:7], v132
	ds_read_b128 v[8:11], v132 offset:1024
	ds_read_b128 v[216:219], v132 offset:2048
	ds_read_b128 v[220:223], v132 offset:3072
	ds_read_b128 v[224:227], v133
	ds_read_b128 v[228:231], v133 offset:1024
	ds_read_b128 v[232:235], v133 offset:2048
	ds_read_b128 v[236:239], v133 offset:3072
	s_add_u32 s20, s48, 0x160100
	s_addc_u32 s21, s49, 0
	s_mov_b32 m0, s59
	ds_read_b128 v[12:15], v209 offset:32768
	ds_read_b128 v[24:27], v209 offset:33792
	ds_read_b128 v[28:31], v209 offset:34816
	ds_read_b128 v[96:99], v209 offset:35840
	ds_read_b128 v[240:243], v209 offset:36864
	ds_read_b128 v[244:247], v209 offset:37888
	ds_read_b128 v[248:251], v209 offset:38912
	ds_read_b128 v[32:35], v209 offset:39936
	global_load_lds_dwordx4 v202, s[20:21]
	s_mov_b32 m0, s60
	s_nop 0
	global_load_lds_dwordx4 v204, s[20:21]
	s_waitcnt vmcnt(8)
	s_waitcnt lgkmcnt(0)
	s_barrier
	v_mfma_f32_16x16x32_bf16 v[36:39], v[216:219], v[12:15], v[36:39]
	v_mfma_f32_16x16x32_bf16 v[148:151], v[220:223], v[24:27], v[36:39]
	v_mfma_f32_16x16x32_bf16 v[36:39], v[4:7], v[28:31], v[40:43]
	v_mfma_f32_16x16x32_bf16 v[128:131], v[8:11], v[96:99], v[36:39]
	v_mfma_f32_16x16x32_bf16 v[36:39], v[216:219], v[28:31], v[44:47]
	v_mfma_f32_16x16x32_bf16 v[124:127], v[220:223], v[96:99], v[36:39]
	v_mfma_f32_16x16x32_bf16 v[36:39], v[4:7], v[240:243], v[48:51]
	v_mfma_f32_16x16x32_bf16 v[104:107], v[8:11], v[244:247], v[36:39]
	v_mfma_f32_16x16x32_bf16 v[36:39], v[216:219], v[240:243], v[52:55]
	v_mfma_f32_16x16x32_bf16 v[100:103], v[220:223], v[244:247], v[36:39]
	v_mfma_f32_16x16x32_bf16 v[36:39], v[4:7], v[248:251], v[56:59]
	v_mfma_f32_16x16x32_bf16 v[76:79], v[4:7], v[12:15], v[138:141]
	v_mfma_f32_16x16x32_bf16 v[80:83], v[8:11], v[32:35], v[36:39]
	v_mfma_f32_16x16x32_bf16 v[36:39], v[216:219], v[248:251], v[60:63]
	v_mfma_f32_16x16x32_bf16 v[152:155], v[8:11], v[24:27], v[76:79]
	v_mfma_f32_16x16x32_bf16 v[76:79], v[220:223], v[32:35], v[36:39]
	v_mfma_f32_16x16x32_bf16 v[36:39], v[224:227], v[12:15], v[64:67]
	v_mfma_f32_16x16x32_bf16 v[12:15], v[232:235], v[12:15], v[68:71]
	v_mfma_f32_16x16x32_bf16 v[140:143], v[236:239], v[24:27], v[12:15]
	v_mfma_f32_16x16x32_bf16 v[12:15], v[224:227], v[28:31], v[72:75]
	v_mfma_f32_16x16x32_bf16 v[120:123], v[228:231], v[96:99], v[12:15]
	v_mfma_f32_16x16x32_bf16 v[12:15], v[232:235], v[28:31], v[84:87]
	v_mfma_f32_16x16x32_bf16 v[116:119], v[236:239], v[96:99], v[12:15]
	v_mfma_f32_16x16x32_bf16 v[12:15], v[224:227], v[240:243], v[88:91]
	v_mfma_f32_16x16x32_bf16 v[96:99], v[228:231], v[244:247], v[12:15]
	v_mfma_f32_16x16x32_bf16 v[12:15], v[232:235], v[240:243], v[92:95]
	v_mfma_f32_16x16x32_bf16 v[92:95], v[236:239], v[244:247], v[12:15]
	v_mfma_f32_16x16x32_bf16 v[12:15], v[224:227], v[248:251], v[108:111]
	v_mfma_f32_16x16x32_bf16 v[72:75], v[228:231], v[32:35], v[12:15]
	v_mfma_f32_16x16x32_bf16 v[12:15], v[232:235], v[248:251], v[112:115]
	v_mfma_f32_16x16x32_bf16 v[144:147], v[228:231], v[24:27], v[36:39]
	v_mfma_f32_16x16x32_bf16 v[68:71], v[236:239], v[32:35], v[12:15]
	s_barrier
	s_add_i32 s12, s68, s26
	s_mov_b32 m0, s12
	s_add_i32 s20, s12, 0x2000
	ds_read_b128 v[32:35], v209 offset:49152
	ds_read_b128 v[36:39], v209 offset:50176
	ds_read_b128 v[60:63], v209 offset:51200
	ds_read_b128 v[84:87], v209 offset:52224
	ds_read_b128 v[88:91], v209 offset:53248
	ds_read_b128 v[108:111], v209 offset:54272
	ds_read_b128 v[112:115], v209 offset:55296
	ds_read_b128 v[240:243], v209 offset:56320
	global_load_lds_dwordx4 v203, s[52:53]
	s_mov_b32 m0, s20
	s_nop 0
	global_load_lds_dwordx4 v205, s[52:53]
	s_add_u32 s52, s4, 0x160180
	s_addc_u32 s53, s5, 0
	s_add_i32 s21, s69, s26
	s_mov_b32 m0, s21
	s_add_i32 s74, s21, 0x2000
	s_nop 0
	global_load_lds_dwordx4 v203, s[52:53]
	s_mov_b32 m0, s74
	s_nop 0
	global_load_lds_dwordx4 v205, s[52:53]
	s_mov_b32 m0, s61
	s_nop 0
	global_load_lds_dwordx4 v202, s[50:51]
	s_mov_b32 m0, s62
	s_nop 0
	global_load_lds_dwordx4 v204, s[50:51]
	s_waitcnt vmcnt(8)
	s_waitcnt lgkmcnt(0)
	s_barrier
	v_mfma_f32_16x16x32_bf16 v[12:15], v[4:7], v[32:35], v[134:137]
	v_mfma_f32_16x16x32_bf16 v[64:67], v[8:11], v[36:39], v[12:15]
	v_mfma_f32_16x16x32_bf16 v[12:15], v[216:219], v[32:35], v[156:159]
	v_mfma_f32_16x16x32_bf16 v[56:59], v[220:223], v[36:39], v[12:15]
	v_mfma_f32_16x16x32_bf16 v[12:15], v[4:7], v[60:63], v[160:163]
	v_mfma_f32_16x16x32_bf16 v[44:47], v[8:11], v[84:87], v[12:15]
	v_mfma_f32_16x16x32_bf16 v[12:15], v[216:219], v[60:63], v[164:167]
	v_mfma_f32_16x16x32_bf16 v[40:43], v[220:223], v[84:87], v[12:15]
	v_mfma_f32_16x16x32_bf16 v[12:15], v[4:7], v[88:91], v[168:171]
	v_mfma_f32_16x16x32_bf16 v[28:31], v[8:11], v[108:111], v[12:15]
	v_mfma_f32_16x16x32_bf16 v[12:15], v[216:219], v[88:91], v[172:175]
	v_mfma_f32_16x16x32_bf16 v[4:7], v[4:7], v[112:115], v[16:19]
	v_mfma_f32_16x16x32_bf16 v[24:27], v[220:223], v[108:111], v[12:15]
	v_mfma_f32_16x16x32_bf16 v[12:15], v[8:11], v[240:243], v[4:7]
	v_mfma_f32_16x16x32_bf16 v[4:7], v[216:219], v[112:115], v[20:23]
	v_mfma_f32_16x16x32_bf16 v[8:11], v[220:223], v[240:243], v[4:7]
	v_mfma_f32_16x16x32_bf16 v[4:7], v[224:227], v[32:35], v[176:179]
	v_mfma_f32_16x16x32_bf16 v[52:55], v[228:231], v[36:39], v[4:7]
	v_mfma_f32_16x16x32_bf16 v[4:7], v[232:235], v[32:35], v[180:183]
	v_mfma_f32_16x16x32_bf16 v[48:51], v[236:239], v[36:39], v[4:7]
	v_mfma_f32_16x16x32_bf16 v[4:7], v[224:227], v[60:63], v[186:189]
	v_mfma_f32_16x16x32_bf16 v[36:39], v[228:231], v[84:87], v[4:7]
	v_mfma_f32_16x16x32_bf16 v[4:7], v[232:235], v[60:63], v[190:193]
	v_mfma_f32_16x16x32_bf16 v[32:35], v[236:239], v[84:87], v[4:7]
	v_mfma_f32_16x16x32_bf16 v[4:7], v[224:227], v[88:91], v[194:197]
	v_mfma_f32_16x16x32_bf16 v[20:23], v[228:231], v[108:111], v[4:7]
	v_mfma_f32_16x16x32_bf16 v[4:7], v[232:235], v[88:91], v[198:201]
	v_mfma_f32_16x16x32_bf16 v[0:3], v[224:227], v[112:115], v[0:3]
	v_mfma_f32_16x16x32_bf16 v[16:19], v[236:239], v[108:111], v[4:7]
	v_mfma_f32_16x16x32_bf16 v[4:7], v[228:231], v[240:243], v[0:3]
	v_mfma_f32_16x16x32_bf16 v[0:3], v[232:235], v[112:115], v[212:215]
	v_mfma_f32_16x16x32_bf16 v[0:3], v[236:239], v[240:243], v[0:3]
	s_barrier
	s_add_u32 s75, s48, 0x200
	s_addc_u32 s76, s49, 0
	s_add_u32 s77, s4, 0x200
	s_addc_u32 s78, s5, 0
	s_add_u32 s4, s48, 0x160180
	s_addc_u32 s5, s49, 0
	s_mov_b32 s79, 0
.LBB0_900:
	s_cmpk_eq_i32 s79, 0x54
	s_cselect_b32 s52, s44, s75
	s_cselect_b32 s53, s45, s76
	s_cselect_b32 s50, s46, s77
	s_cselect_b32 s51, s47, s78
	s_add_u32 s48, s52, 0x80
	s_addc_u32 s49, s53, 0
	s_add_i32 s80, 0, 0x10000
	s_add_i32 s83, 0, 0x14000
	v_add_u32_e32 v108, s80, v206
	v_add_u32_e32 v138, s83, v206
	ds_read_b128 v[60:63], v108
	ds_read_b128 v[84:87], v108 offset:1024
	ds_read_b128 v[88:91], v108 offset:2048
	ds_read_b128 v[108:111], v108 offset:3072
	ds_read_b128 v[112:115], v138
	ds_read_b128 v[134:137], v138 offset:1024
	ds_read_b128 v[156:159], v138 offset:2048
	ds_read_b128 v[160:163], v138 offset:3072
	s_mov_b32 m0, s0
	ds_read_b128 v[164:167], v209
	ds_read_b128 v[168:171], v209 offset:1024
	ds_read_b128 v[172:175], v209 offset:2048
	ds_read_b128 v[176:179], v209 offset:3072
	ds_read_b128 v[180:183], v209 offset:4096
	ds_read_b128 v[186:189], v209 offset:5120
	ds_read_b128 v[190:193], v209 offset:6144
	ds_read_b128 v[194:197], v209 offset:7168
	global_load_lds_dwordx4 v202, s[4:5]
	s_mov_b32 m0, s1
	s_nop 0
	global_load_lds_dwordx4 v204, s[4:5]
	s_waitcnt vmcnt(8)
	s_waitcnt lgkmcnt(0)
	s_barrier
	v_mfma_f32_16x16x32_bf16 v[152:155], v[60:63], v[164:167], v[152:155]
	v_mfma_f32_16x16x32_bf16 v[148:151], v[88:91], v[164:167], v[148:151]
	v_mfma_f32_16x16x32_bf16 v[128:131], v[60:63], v[172:175], v[128:131]
	v_mfma_f32_16x16x32_bf16 v[124:127], v[88:91], v[172:175], v[124:127]
	v_mfma_f32_16x16x32_bf16 v[104:107], v[60:63], v[180:183], v[104:107]
	v_mfma_f32_16x16x32_bf16 v[100:103], v[88:91], v[180:183], v[100:103]
	v_mfma_f32_16x16x32_bf16 v[80:83], v[60:63], v[190:193], v[80:83]
	v_mfma_f32_16x16x32_bf16 v[76:79], v[88:91], v[190:193], v[76:79]
	v_mfma_f32_16x16x32_bf16 v[152:155], v[84:87], v[168:171], v[152:155]
	v_mfma_f32_16x16x32_bf16 v[148:151], v[108:111], v[168:171], v[148:151]
	v_mfma_f32_16x16x32_bf16 v[128:131], v[84:87], v[176:179], v[128:131]
	v_mfma_f32_16x16x32_bf16 v[124:127], v[108:111], v[176:179], v[124:127]
	v_mfma_f32_16x16x32_bf16 v[104:107], v[84:87], v[186:189], v[104:107]
	v_mfma_f32_16x16x32_bf16 v[100:103], v[108:111], v[186:189], v[100:103]
	v_mfma_f32_16x16x32_bf16 v[80:83], v[84:87], v[194:197], v[80:83]
	v_mfma_f32_16x16x32_bf16 v[76:79], v[108:111], v[194:197], v[76:79]
	v_mfma_f32_16x16x32_bf16 v[144:147], v[112:115], v[164:167], v[144:147]
	v_mfma_f32_16x16x32_bf16 v[138:141], v[156:159], v[164:167], v[140:143]
	v_mfma_f32_16x16x32_bf16 v[120:123], v[112:115], v[172:175], v[120:123]
	v_mfma_f32_16x16x32_bf16 v[116:119], v[156:159], v[172:175], v[116:119]
	v_mfma_f32_16x16x32_bf16 v[96:99], v[112:115], v[180:183], v[96:99]
	v_mfma_f32_16x16x32_bf16 v[92:95], v[156:159], v[180:183], v[92:95]
	v_mfma_f32_16x16x32_bf16 v[72:75], v[112:115], v[190:193], v[72:75]
	v_mfma_f32_16x16x32_bf16 v[68:71], v[156:159], v[190:193], v[68:71]
	v_mfma_f32_16x16x32_bf16 v[144:147], v[134:137], v[168:171], v[144:147]
	v_mfma_f32_16x16x32_bf16 v[138:141], v[160:163], v[168:171], v[138:141]
	v_mfma_f32_16x16x32_bf16 v[120:123], v[134:137], v[176:179], v[120:123]
	v_mfma_f32_16x16x32_bf16 v[116:119], v[160:163], v[176:179], v[116:119]
	v_mfma_f32_16x16x32_bf16 v[96:99], v[134:137], v[186:189], v[96:99]
	v_mfma_f32_16x16x32_bf16 v[92:95], v[160:163], v[186:189], v[92:95]
	v_mfma_f32_16x16x32_bf16 v[72:75], v[134:137], v[194:197], v[72:75]
	v_mfma_f32_16x16x32_bf16 v[68:71], v[160:163], v[194:197], v[68:71]
	s_barrier
	s_add_i32 s80, s80, s26
	s_mov_b32 m0, s80
	ds_read_b128 v[164:167], v209 offset:16384
	ds_read_b128 v[168:171], v209 offset:17408
	ds_read_b128 v[172:175], v209 offset:18432
	ds_read_b128 v[176:179], v209 offset:19456
	ds_read_b128 v[180:183], v209 offset:20480
	ds_read_b128 v[186:189], v209 offset:21504
	ds_read_b128 v[190:193], v209 offset:22528
	ds_read_b128 v[194:197], v209 offset:23552
	global_load_lds_dwordx4 v203, s[50:51]
	s_add_i32 m0, s80, 0x2000
	s_add_u32 s84, s50, 0x160000
	s_addc_u32 s85, s51, 0
	s_add_i32 s80, s83, s26
	s_nop 0
	global_load_lds_dwordx4 v205, s[50:51]
	s_mov_b32 m0, s80
	s_nop 0
	global_load_lds_dwordx4 v203, s[84:85]
	s_add_i32 m0, s80, 0x2000
	s_nop 0
	global_load_lds_dwordx4 v205, s[84:85]
	s_mov_b32 m0, s27
	s_nop 0
	global_load_lds_dwordx4 v202, s[52:53]
	s_mov_b32 m0, s58
	s_nop 0
	global_load_lds_dwordx4 v204, s[52:53]
	s_waitcnt vmcnt(8)
	s_waitcnt lgkmcnt(0)
	s_barrier
	v_mfma_f32_16x16x32_bf16 v[64:67], v[60:63], v[164:167], v[64:67]
	v_mfma_f32_16x16x32_bf16 v[56:59], v[88:91], v[164:167], v[56:59]
	v_mfma_f32_16x16x32_bf16 v[44:47], v[60:63], v[172:175], v[44:47]
	v_mfma_f32_16x16x32_bf16 v[40:43], v[88:91], v[172:175], v[40:43]
	v_mfma_f32_16x16x32_bf16 v[28:31], v[60:63], v[180:183], v[28:31]
	v_mfma_f32_16x16x32_bf16 v[24:27], v[88:91], v[180:183], v[24:27]
	v_mfma_f32_16x16x32_bf16 v[12:15], v[60:63], v[190:193], v[12:15]
	v_mfma_f32_16x16x32_bf16 v[8:11], v[88:91], v[190:193], v[8:11]
	v_mfma_f32_16x16x32_bf16 v[64:67], v[84:87], v[168:171], v[64:67]
	v_mfma_f32_16x16x32_bf16 v[56:59], v[108:111], v[168:171], v[56:59]
	v_mfma_f32_16x16x32_bf16 v[44:47], v[84:87], v[176:179], v[44:47]
	v_mfma_f32_16x16x32_bf16 v[40:43], v[108:111], v[176:179], v[40:43]
	v_mfma_f32_16x16x32_bf16 v[28:31], v[84:87], v[186:189], v[28:31]
	v_mfma_f32_16x16x32_bf16 v[24:27], v[108:111], v[186:189], v[24:27]
	v_mfma_f32_16x16x32_bf16 v[12:15], v[84:87], v[194:197], v[12:15]
	v_mfma_f32_16x16x32_bf16 v[8:11], v[108:111], v[194:197], v[8:11]
	v_mfma_f32_16x16x32_bf16 v[52:55], v[112:115], v[164:167], v[52:55]
	v_mfma_f32_16x16x32_bf16 v[48:51], v[156:159], v[164:167], v[48:51]
	v_mfma_f32_16x16x32_bf16 v[36:39], v[112:115], v[172:175], v[36:39]
	v_mfma_f32_16x16x32_bf16 v[32:35], v[156:159], v[172:175], v[32:35]
	v_mfma_f32_16x16x32_bf16 v[20:23], v[112:115], v[180:183], v[20:23]
	v_mfma_f32_16x16x32_bf16 v[16:19], v[156:159], v[180:183], v[16:19]
	v_mfma_f32_16x16x32_bf16 v[4:7], v[112:115], v[190:193], v[4:7]
	v_mfma_f32_16x16x32_bf16 v[0:3], v[156:159], v[190:193], v[0:3]
	v_mfma_f32_16x16x32_bf16 v[52:55], v[134:137], v[168:171], v[52:55]
	v_mfma_f32_16x16x32_bf16 v[48:51], v[160:163], v[168:171], v[48:51]
	v_mfma_f32_16x16x32_bf16 v[36:39], v[134:137], v[176:179], v[36:39]
	v_mfma_f32_16x16x32_bf16 v[32:35], v[160:163], v[176:179], v[32:35]
	v_mfma_f32_16x16x32_bf16 v[20:23], v[134:137], v[186:189], v[20:23]
	v_mfma_f32_16x16x32_bf16 v[16:19], v[160:163], v[186:189], v[16:19]
	v_mfma_f32_16x16x32_bf16 v[4:7], v[134:137], v[194:197], v[4:7]
	v_mfma_f32_16x16x32_bf16 v[0:3], v[160:163], v[194:197], v[0:3]
	s_barrier
	ds_read_b128 v[60:63], v132
	ds_read_b128 v[84:87], v132 offset:1024
	ds_read_b128 v[88:91], v132 offset:2048
	ds_read_b128 v[108:111], v132 offset:3072
	ds_read_b128 v[112:115], v133
	ds_read_b128 v[134:137], v133 offset:1024
	ds_read_b128 v[156:159], v133 offset:2048
	ds_read_b128 v[160:163], v133 offset:3072
	s_add_u32 s52, s52, 0x160000
	s_addc_u32 s53, s53, 0
	s_mov_b32 m0, s59
	ds_read_b128 v[164:167], v209 offset:32768
	ds_read_b128 v[168:171], v209 offset:33792
	ds_read_b128 v[172:175], v209 offset:34816
	ds_read_b128 v[176:179], v209 offset:35840
	ds_read_b128 v[180:183], v209 offset:36864
	ds_read_b128 v[186:189], v209 offset:37888
	ds_read_b128 v[190:193], v209 offset:38912
	ds_read_b128 v[194:197], v209 offset:39936
	global_load_lds_dwordx4 v202, s[52:53]
	s_mov_b32 m0, s60
	s_nop 0
	global_load_lds_dwordx4 v204, s[52:53]
	s_waitcnt vmcnt(8)
	s_waitcnt lgkmcnt(0)
	s_barrier
	v_mfma_f32_16x16x32_bf16 v[152:155], v[60:63], v[164:167], v[152:155]
	v_mfma_f32_16x16x32_bf16 v[148:151], v[88:91], v[164:167], v[148:151]
	v_mfma_f32_16x16x32_bf16 v[128:131], v[60:63], v[172:175], v[128:131]
	v_mfma_f32_16x16x32_bf16 v[124:127], v[88:91], v[172:175], v[124:127]
	v_mfma_f32_16x16x32_bf16 v[104:107], v[60:63], v[180:183], v[104:107]
	v_mfma_f32_16x16x32_bf16 v[100:103], v[88:91], v[180:183], v[100:103]
	v_mfma_f32_16x16x32_bf16 v[80:83], v[60:63], v[190:193], v[80:83]
	v_mfma_f32_16x16x32_bf16 v[76:79], v[88:91], v[190:193], v[76:79]
	v_mfma_f32_16x16x32_bf16 v[152:155], v[84:87], v[168:171], v[152:155]
	v_mfma_f32_16x16x32_bf16 v[148:151], v[108:111], v[168:171], v[148:151]
	v_mfma_f32_16x16x32_bf16 v[128:131], v[84:87], v[176:179], v[128:131]
	v_mfma_f32_16x16x32_bf16 v[124:127], v[108:111], v[176:179], v[124:127]
	v_mfma_f32_16x16x32_bf16 v[104:107], v[84:87], v[186:189], v[104:107]
	v_mfma_f32_16x16x32_bf16 v[100:103], v[108:111], v[186:189], v[100:103]
	v_mfma_f32_16x16x32_bf16 v[80:83], v[84:87], v[194:197], v[80:83]
	v_mfma_f32_16x16x32_bf16 v[76:79], v[108:111], v[194:197], v[76:79]
	v_mfma_f32_16x16x32_bf16 v[142:145], v[112:115], v[164:167], v[144:147]
	v_mfma_f32_16x16x32_bf16 v[138:141], v[156:159], v[164:167], v[138:141]
	v_mfma_f32_16x16x32_bf16 v[120:123], v[112:115], v[172:175], v[120:123]
	v_mfma_f32_16x16x32_bf16 v[116:119], v[156:159], v[172:175], v[116:119]
	v_mfma_f32_16x16x32_bf16 v[96:99], v[112:115], v[180:183], v[96:99]
	v_mfma_f32_16x16x32_bf16 v[92:95], v[156:159], v[180:183], v[92:95]
	v_mfma_f32_16x16x32_bf16 v[72:75], v[112:115], v[190:193], v[72:75]
	v_mfma_f32_16x16x32_bf16 v[68:71], v[156:159], v[190:193], v[68:71]
	v_mfma_f32_16x16x32_bf16 v[144:147], v[134:137], v[168:171], v[142:145]
	v_mfma_f32_16x16x32_bf16 v[140:143], v[160:163], v[168:171], v[138:141]
	v_mfma_f32_16x16x32_bf16 v[120:123], v[134:137], v[176:179], v[120:123]
	v_mfma_f32_16x16x32_bf16 v[116:119], v[160:163], v[176:179], v[116:119]
	v_mfma_f32_16x16x32_bf16 v[96:99], v[134:137], v[186:189], v[96:99]
	v_mfma_f32_16x16x32_bf16 v[92:95], v[160:163], v[186:189], v[92:95]
	v_mfma_f32_16x16x32_bf16 v[72:75], v[134:137], v[194:197], v[72:75]
	v_mfma_f32_16x16x32_bf16 v[68:71], v[160:163], v[194:197], v[68:71]
	s_barrier
	s_add_u32 s52, s50, 0x80
	s_mov_b32 m0, s12
	s_addc_u32 s53, s51, 0
	ds_read_b128 v[164:167], v209 offset:49152
	ds_read_b128 v[168:171], v209 offset:50176
	ds_read_b128 v[172:175], v209 offset:51200
	ds_read_b128 v[176:179], v209 offset:52224
	ds_read_b128 v[180:183], v209 offset:53248
	ds_read_b128 v[186:189], v209 offset:54272
	ds_read_b128 v[190:193], v209 offset:55296
	ds_read_b128 v[194:197], v209 offset:56320
	s_add_u32 s50, s50, 0x160080
	global_load_lds_dwordx4 v203, s[52:53]
	s_mov_b32 m0, s20
	s_addc_u32 s51, s51, 0
	global_load_lds_dwordx4 v205, s[52:53]
	s_mov_b32 m0, s21
	s_nop 0
	global_load_lds_dwordx4 v203, s[50:51]
	s_mov_b32 m0, s74
	s_nop 0
	global_load_lds_dwordx4 v205, s[50:51]
	s_mov_b32 m0, s61
	s_nop 0
	global_load_lds_dwordx4 v202, s[48:49]
	s_mov_b32 m0, s62
	s_nop 0
	global_load_lds_dwordx4 v204, s[48:49]
	s_waitcnt vmcnt(8)
	s_waitcnt lgkmcnt(0)
	s_barrier
	v_mfma_f32_16x16x32_bf16 v[64:67], v[60:63], v[164:167], v[64:67]
	v_mfma_f32_16x16x32_bf16 v[56:59], v[88:91], v[164:167], v[56:59]
	v_mfma_f32_16x16x32_bf16 v[44:47], v[60:63], v[172:175], v[44:47]
	v_mfma_f32_16x16x32_bf16 v[40:43], v[88:91], v[172:175], v[40:43]
	v_mfma_f32_16x16x32_bf16 v[28:31], v[60:63], v[180:183], v[28:31]
	v_mfma_f32_16x16x32_bf16 v[24:27], v[88:91], v[180:183], v[24:27]
	v_mfma_f32_16x16x32_bf16 v[12:15], v[60:63], v[190:193], v[12:15]
	v_mfma_f32_16x16x32_bf16 v[8:11], v[88:91], v[190:193], v[8:11]
	v_mfma_f32_16x16x32_bf16 v[64:67], v[84:87], v[168:171], v[64:67]
	v_mfma_f32_16x16x32_bf16 v[56:59], v[108:111], v[168:171], v[56:59]
	v_mfma_f32_16x16x32_bf16 v[44:47], v[84:87], v[176:179], v[44:47]
	v_mfma_f32_16x16x32_bf16 v[40:43], v[108:111], v[176:179], v[40:43]
	v_mfma_f32_16x16x32_bf16 v[28:31], v[84:87], v[186:189], v[28:31]
	v_mfma_f32_16x16x32_bf16 v[24:27], v[108:111], v[186:189], v[24:27]
	v_mfma_f32_16x16x32_bf16 v[12:15], v[84:87], v[194:197], v[12:15]
	v_mfma_f32_16x16x32_bf16 v[8:11], v[108:111], v[194:197], v[8:11]
	v_mfma_f32_16x16x32_bf16 v[52:55], v[112:115], v[164:167], v[52:55]
	v_mfma_f32_16x16x32_bf16 v[48:51], v[156:159], v[164:167], v[48:51]
	v_mfma_f32_16x16x32_bf16 v[36:39], v[112:115], v[172:175], v[36:39]
	v_mfma_f32_16x16x32_bf16 v[32:35], v[156:159], v[172:175], v[32:35]
	v_mfma_f32_16x16x32_bf16 v[20:23], v[112:115], v[180:183], v[20:23]
	v_mfma_f32_16x16x32_bf16 v[16:19], v[156:159], v[180:183], v[16:19]
	v_mfma_f32_16x16x32_bf16 v[4:7], v[112:115], v[190:193], v[4:7]
	v_mfma_f32_16x16x32_bf16 v[0:3], v[156:159], v[190:193], v[0:3]
	v_mfma_f32_16x16x32_bf16 v[52:55], v[134:137], v[168:171], v[52:55]
	v_mfma_f32_16x16x32_bf16 v[48:51], v[160:163], v[168:171], v[48:51]
	v_mfma_f32_16x16x32_bf16 v[36:39], v[134:137], v[176:179], v[36:39]
	v_mfma_f32_16x16x32_bf16 v[32:35], v[160:163], v[176:179], v[32:35]
	v_mfma_f32_16x16x32_bf16 v[20:23], v[134:137], v[186:189], v[20:23]
	v_mfma_f32_16x16x32_bf16 v[16:19], v[160:163], v[186:189], v[16:19]
	v_mfma_f32_16x16x32_bf16 v[4:7], v[134:137], v[194:197], v[4:7]
	v_mfma_f32_16x16x32_bf16 v[0:3], v[160:163], v[194:197], v[0:3]
	s_barrier
	s_add_i32 s79, s79, 2
	s_add_u32 s75, s75, 0x100
	s_addc_u32 s76, s76, 0
	s_add_u32 s77, s77, 0x100
	s_addc_u32 s78, s78, 0
	s_add_u32 s4, s4, 0x100
	s_addc_u32 s5, s5, 0
	s_cmpk_gt_u32 s79, 0x55
	s_cbranch_scc0 .LBB0_900
	s_and_b64 vcc, exec, s[34:35]
	s_cbranch_vccz .LBB0_903
	s_barrier

.LBB0_1005:
	s_add_u32 s20, s46, 0x100
	s_addc_u32 s21, s47, 0
	s_waitcnt lgkmcnt(0)
	s_add_u32 s42, s44, 0x100
	s_addc_u32 s43, s45, 0
	s_barrier
	s_waitcnt lgkmcnt(0)
	v_mfma_f32_16x16x32_bf16 v[32:35], v[16:19], v[72:75], 0
	v_mfma_f32_16x16x32_bf16 v[36:39], v[24:27], v[72:75], 0
	v_mfma_f32_16x16x32_bf16 v[40:43], v[16:19], v[80:83], 0
	v_mfma_f32_16x16x32_bf16 v[44:47], v[24:27], v[80:83], 0
	v_mfma_f32_16x16x32_bf16 v[48:51], v[16:19], v[92:95], 0
	v_mfma_f32_16x16x32_bf16 v[52:55], v[24:27], v[92:95], 0
	v_mfma_f32_16x16x32_bf16 v[56:59], v[16:19], v[60:63], 0
	v_mfma_f32_16x16x32_bf16 v[64:67], v[24:27], v[60:63], 0
	v_mfma_f32_16x16x32_bf16 v[32:35], v[20:23], v[76:79], v[32:35]
	v_mfma_f32_16x16x32_bf16 v[36:39], v[28:31], v[76:79], v[36:39]
	v_mfma_f32_16x16x32_bf16 v[40:43], v[20:23], v[84:87], v[40:43]
	v_mfma_f32_16x16x32_bf16 v[44:47], v[28:31], v[84:87], v[44:47]
	v_mfma_f32_16x16x32_bf16 v[48:51], v[20:23], v[96:99], v[48:51]
	v_mfma_f32_16x16x32_bf16 v[52:55], v[28:31], v[96:99], v[52:55]
	v_mfma_f32_16x16x32_bf16 v[56:59], v[20:23], v[88:91], v[56:59]
	v_mfma_f32_16x16x32_bf16 v[64:67], v[28:31], v[88:91], v[64:67]
	v_mfma_f32_16x16x32_bf16 v[68:71], v[0:3], v[72:75], 0
	v_mfma_f32_16x16x32_bf16 v[72:75], v[8:11], v[72:75], 0
	v_mfma_f32_16x16x32_bf16 v[68:71], v[4:7], v[76:79], v[68:71]
	v_mfma_f32_16x16x32_bf16 v[72:75], v[12:15], v[76:79], v[72:75]
	v_mfma_f32_16x16x32_bf16 v[76:79], v[0:3], v[80:83], 0
	v_mfma_f32_16x16x32_bf16 v[80:83], v[8:11], v[80:83], 0
	v_mfma_f32_16x16x32_bf16 v[76:79], v[4:7], v[84:87], v[76:79]
	v_mfma_f32_16x16x32_bf16 v[80:83], v[12:15], v[84:87], v[80:83]
	v_mfma_f32_16x16x32_bf16 v[84:87], v[0:3], v[92:95], 0
	v_mfma_f32_16x16x32_bf16 v[92:95], v[8:11], v[92:95], 0
	v_mfma_f32_16x16x32_bf16 v[128:131], v[12:15], v[96:99], v[92:95]
	v_mfma_f32_16x16x32_bf16 v[92:95], v[0:3], v[60:63], 0
	v_mfma_f32_16x16x32_bf16 v[60:63], v[8:11], v[60:63], 0
	v_mfma_f32_16x16x32_bf16 v[84:87], v[4:7], v[96:99], v[84:87]
	v_mfma_f32_16x16x32_bf16 v[132:135], v[4:7], v[88:91], v[92:95]
	v_mfma_f32_16x16x32_bf16 v[136:139], v[12:15], v[88:91], v[60:63]
	s_barrier
	s_mov_b32 m0, s37
	ds_read_b128 v[108:111], v150 offset:16384
	ds_read_b128 v[112:115], v150 offset:17408
	ds_read_b128 v[100:103], v150 offset:18432
	ds_read_b128 v[104:107], v150 offset:19456
	ds_read_b128 v[92:95], v150 offset:20480
	ds_read_b128 v[96:99], v150 offset:21504
	ds_read_b128 v[60:63], v150 offset:22528
	ds_read_b128 v[88:91], v150 offset:23552
	global_load_lds_dwordx4 v144, s[42:43]
	s_mov_b32 m0, s55
	s_nop 0
	global_load_lds_dwordx4 v146, s[42:43]
	s_add_u32 s42, s44, 0x80100
	s_addc_u32 s43, s45, 0
	s_mov_b32 m0, s56
	s_and_b64 vcc, exec, s[40:41]
	global_load_lds_dwordx4 v144, s[42:43]
	s_mov_b32 m0, s57
	s_nop 0
	global_load_lds_dwordx4 v146, s[42:43]
	s_mov_b32 m0, s27
	s_mov_b64 s[42:43], -1
	global_load_lds_dwordx4 v143, s[20:21]
	s_mov_b32 m0, s58
	s_nop 0
	global_load_lds_dwordx4 v145, s[20:21]
	s_cbranch_vccz .LBB0_1007
	s_waitcnt vmcnt(8)
	s_mov_b64 s[42:43], 0

.LBB0_1009:
	s_ashr_i32 s7, s6, 31
	s_lshl_b64 s[20:21], s[6:7], 20
	s_add_u32 s40, s14, s20
	s_addc_u32 s41, s15, s21
	s_ashr_i32 s9, s8, 31
	s_lshl_b64 s[20:21], s[8:9], 20
	s_add_u32 s42, s24, s20
	s_addc_u32 s43, s25, s21
	s_add_u32 s48, s46, 0x180
	s_addc_u32 s49, s47, 0
	s_waitcnt lgkmcnt(0)
	s_and_b64 s[20:21], s[38:39], exec
	s_cselect_b32 s9, s43, s45
	s_cselect_b32 s12, s42, s44
	s_cselect_b32 s20, s41, s47
	s_cselect_b32 s21, s40, s46
	s_add_u32 s50, s44, 0x180
	s_addc_u32 s51, s45, 0
	s_barrier
	s_waitcnt lgkmcnt(0)
	v_mfma_f32_16x16x32_bf16 v[116:119], v[16:19], v[108:111], 0
	v_mfma_f32_16x16x32_bf16 v[156:159], v[20:23], v[112:115], v[116:119]
	v_mfma_f32_16x16x32_bf16 v[116:119], v[24:27], v[108:111], 0
	v_mfma_f32_16x16x32_bf16 v[160:163], v[28:31], v[112:115], v[116:119]
	v_mfma_f32_16x16x32_bf16 v[116:119], v[16:19], v[100:103], 0
	v_mfma_f32_16x16x32_bf16 v[164:167], v[20:23], v[104:107], v[116:119]
	v_mfma_f32_16x16x32_bf16 v[116:119], v[24:27], v[100:103], 0
	v_mfma_f32_16x16x32_bf16 v[168:171], v[28:31], v[104:107], v[116:119]
	v_mfma_f32_16x16x32_bf16 v[116:119], v[16:19], v[92:95], 0
	v_mfma_f32_16x16x32_bf16 v[16:19], v[16:19], v[60:63], 0
	v_mfma_f32_16x16x32_bf16 v[172:175], v[20:23], v[96:99], v[116:119]
	v_mfma_f32_16x16x32_bf16 v[16:19], v[20:23], v[88:91], v[16:19]
	v_mfma_f32_16x16x32_bf16 v[20:23], v[24:27], v[60:63], 0
	v_mfma_f32_16x16x32_bf16 v[116:119], v[24:27], v[92:95], 0
	v_mfma_f32_16x16x32_bf16 v[20:23], v[28:31], v[88:91], v[20:23]
	v_mfma_f32_16x16x32_bf16 v[176:179], v[28:31], v[96:99], v[116:119]
	v_mfma_f32_16x16x32_bf16 v[24:27], v[0:3], v[108:111], 0
	v_mfma_f32_16x16x32_bf16 v[180:183], v[4:7], v[112:115], v[24:27]
	v_mfma_f32_16x16x32_bf16 v[24:27], v[8:11], v[108:111], 0
	v_mfma_f32_16x16x32_bf16 v[184:187], v[12:15], v[112:115], v[24:27]
	v_mfma_f32_16x16x32_bf16 v[24:27], v[0:3], v[100:103], 0
	v_mfma_f32_16x16x32_bf16 v[188:191], v[4:7], v[104:107], v[24:27]
	v_mfma_f32_16x16x32_bf16 v[24:27], v[8:11], v[100:103], 0
	v_mfma_f32_16x16x32_bf16 v[192:195], v[12:15], v[104:107], v[24:27]
	v_mfma_f32_16x16x32_bf16 v[24:27], v[0:3], v[92:95], 0
	v_mfma_f32_16x16x32_bf16 v[0:3], v[0:3], v[60:63], 0
	v_mfma_f32_16x16x32_bf16 v[196:199], v[4:7], v[96:99], v[24:27]
	v_mfma_f32_16x16x32_bf16 v[24:27], v[8:11], v[92:95], 0
	v_mfma_f32_16x16x32_bf16 v[0:3], v[4:7], v[88:91], v[0:3]
	v_mfma_f32_16x16x32_bf16 v[4:7], v[8:11], v[60:63], 0
	v_mfma_f32_16x16x32_bf16 v[200:203], v[12:15], v[96:99], v[24:27]
	v_mfma_f32_16x16x32_bf16 v[204:207], v[12:15], v[88:91], v[4:7]
	s_barrier
	v_add_u32_e32 v153, s68, v147
	v_add_u32_e32 v154, s69, v147
	s_nop 1
	ds_read_b128 v[4:7], v153
	ds_read_b128 v[8:11], v153 offset:1024
	ds_read_b128 v[208:211], v153 offset:2048
	ds_read_b128 v[212:215], v153 offset:3072
	ds_read_b128 v[216:219], v154
	ds_read_b128 v[220:223], v154 offset:1024
	ds_read_b128 v[224:227], v154 offset:2048
	ds_read_b128 v[228:231], v154 offset:3072
	s_add_u32 s52, s46, 0x80100
	s_addc_u32 s53, s47, 0
	s_mov_b32 m0, s59
	ds_read_b128 v[12:15], v150 offset:32768
	ds_read_b128 v[24:27], v150 offset:33792
	ds_read_b128 v[28:31], v150 offset:34816
	ds_read_b128 v[96:99], v150 offset:35840
	ds_read_b128 v[232:235], v150 offset:36864
	ds_read_b128 v[236:239], v150 offset:37888
	ds_read_b128 v[240:243], v150 offset:38912
	ds_read_b128 v[244:247], v150 offset:39936
	global_load_lds_dwordx4 v143, s[52:53]
	s_mov_b32 m0, s60
	s_nop 0
	global_load_lds_dwordx4 v145, s[52:53]
	s_waitcnt vmcnt(8)
	s_waitcnt lgkmcnt(0)
	s_barrier
	v_mfma_f32_16x16x32_bf16 v[32:35], v[4:7], v[12:15], v[32:35]
	v_mfma_f32_16x16x32_bf16 v[124:127], v[8:11], v[24:27], v[32:35]
	v_mfma_f32_16x16x32_bf16 v[32:35], v[208:211], v[12:15], v[36:39]
	v_mfma_f32_16x16x32_bf16 v[120:123], v[212:215], v[24:27], v[32:35]
	v_mfma_f32_16x16x32_bf16 v[32:35], v[4:7], v[28:31], v[40:43]
	v_mfma_f32_16x16x32_bf16 v[108:111], v[8:11], v[96:99], v[32:35]
	v_mfma_f32_16x16x32_bf16 v[32:35], v[208:211], v[28:31], v[44:47]
	v_mfma_f32_16x16x32_bf16 v[104:107], v[212:215], v[96:99], v[32:35]
	v_mfma_f32_16x16x32_bf16 v[32:35], v[4:7], v[232:235], v[48:51]
	v_mfma_f32_16x16x32_bf16 v[92:95], v[8:11], v[236:239], v[32:35]
	v_mfma_f32_16x16x32_bf16 v[32:35], v[208:211], v[232:235], v[52:55]
	v_mfma_f32_16x16x32_bf16 v[88:91], v[212:215], v[236:239], v[32:35]
	v_mfma_f32_16x16x32_bf16 v[32:35], v[4:7], v[240:243], v[56:59]
	v_mfma_f32_16x16x32_bf16 v[60:63], v[8:11], v[244:247], v[32:35]
	v_mfma_f32_16x16x32_bf16 v[32:35], v[208:211], v[240:243], v[64:67]
	v_mfma_f32_16x16x32_bf16 v[56:59], v[212:215], v[244:247], v[32:35]
	v_mfma_f32_16x16x32_bf16 v[32:35], v[216:219], v[12:15], v[68:71]
	v_mfma_f32_16x16x32_bf16 v[12:15], v[224:227], v[12:15], v[72:75]
	v_mfma_f32_16x16x32_bf16 v[112:115], v[228:231], v[24:27], v[12:15]
	v_mfma_f32_16x16x32_bf16 v[12:15], v[216:219], v[28:31], v[76:79]
	v_mfma_f32_16x16x32_bf16 v[100:103], v[220:223], v[96:99], v[12:15]
	v_mfma_f32_16x16x32_bf16 v[12:15], v[224:227], v[28:31], v[80:83]
	v_mfma_f32_16x16x32_bf16 v[96:99], v[228:231], v[96:99], v[12:15]
	v_mfma_f32_16x16x32_bf16 v[12:15], v[216:219], v[232:235], v[84:87]
	v_mfma_f32_16x16x32_bf16 v[84:87], v[220:223], v[236:239], v[12:15]
	v_mfma_f32_16x16x32_bf16 v[12:15], v[224:227], v[232:235], v[128:131]
	v_mfma_f32_16x16x32_bf16 v[80:83], v[228:231], v[236:239], v[12:15]
	v_mfma_f32_16x16x32_bf16 v[12:15], v[216:219], v[240:243], v[132:135]
	v_mfma_f32_16x16x32_bf16 v[52:55], v[220:223], v[244:247], v[12:15]
	v_mfma_f32_16x16x32_bf16 v[12:15], v[224:227], v[240:243], v[136:139]
	v_mfma_f32_16x16x32_bf16 v[116:119], v[220:223], v[24:27], v[32:35]
	v_mfma_f32_16x16x32_bf16 v[48:51], v[228:231], v[244:247], v[12:15]
	s_barrier
	s_add_i32 s35, s68, s26
	s_mov_b32 m0, s35
	s_add_i32 s73, s35, 0x2000
	ds_read_b128 v[32:35], v150 offset:49152
	ds_read_b128 v[36:39], v150 offset:50176
	ds_read_b128 v[128:131], v150 offset:51200
	ds_read_b128 v[132:135], v150 offset:52224
	ds_read_b128 v[136:139], v150 offset:53248
	ds_read_b128 v[232:235], v150 offset:54272
	ds_read_b128 v[236:239], v150 offset:55296
	ds_read_b128 v[240:243], v150 offset:56320
	global_load_lds_dwordx4 v144, s[50:51]
	s_mov_b32 m0, s73
	s_nop 0
	global_load_lds_dwordx4 v146, s[50:51]
	s_add_u32 s50, s44, 0x80180
	s_addc_u32 s51, s45, 0
	s_add_i32 s74, s69, s26
	s_mov_b32 m0, s74
	s_add_i32 s75, s74, 0x2000
	s_nop 0
	global_load_lds_dwordx4 v144, s[50:51]
	s_mov_b32 m0, s75
	s_nop 0
	global_load_lds_dwordx4 v146, s[50:51]
	s_mov_b32 m0, s61
	s_nop 0
	global_load_lds_dwordx4 v143, s[48:49]
	s_mov_b32 m0, s62
	s_nop 0
	global_load_lds_dwordx4 v145, s[48:49]
	s_waitcnt vmcnt(8)
	s_waitcnt lgkmcnt(0)
	s_barrier
	v_mfma_f32_16x16x32_bf16 v[12:15], v[4:7], v[32:35], v[156:159]
	v_mfma_f32_16x16x32_bf16 v[76:79], v[8:11], v[36:39], v[12:15]
	v_mfma_f32_16x16x32_bf16 v[12:15], v[208:211], v[32:35], v[160:163]
	v_mfma_f32_16x16x32_bf16 v[72:75], v[212:215], v[36:39], v[12:15]
	v_mfma_f32_16x16x32_bf16 v[12:15], v[4:7], v[128:131], v[164:167]
	v_mfma_f32_16x16x32_bf16 v[44:47], v[8:11], v[132:135], v[12:15]
	v_mfma_f32_16x16x32_bf16 v[12:15], v[208:211], v[128:131], v[168:171]
	v_mfma_f32_16x16x32_bf16 v[40:43], v[212:215], v[132:135], v[12:15]
	v_mfma_f32_16x16x32_bf16 v[12:15], v[4:7], v[136:139], v[172:175]
	v_mfma_f32_16x16x32_bf16 v[28:31], v[8:11], v[232:235], v[12:15]
	v_mfma_f32_16x16x32_bf16 v[12:15], v[208:211], v[136:139], v[176:179]
	v_mfma_f32_16x16x32_bf16 v[4:7], v[4:7], v[236:239], v[16:19]
	v_mfma_f32_16x16x32_bf16 v[24:27], v[212:215], v[232:235], v[12:15]
	v_mfma_f32_16x16x32_bf16 v[12:15], v[8:11], v[240:243], v[4:7]
	v_mfma_f32_16x16x32_bf16 v[4:7], v[208:211], v[236:239], v[20:23]
	v_mfma_f32_16x16x32_bf16 v[8:11], v[212:215], v[240:243], v[4:7]
	v_mfma_f32_16x16x32_bf16 v[4:7], v[216:219], v[32:35], v[180:183]
	v_mfma_f32_16x16x32_bf16 v[68:71], v[220:223], v[36:39], v[4:7]
	v_mfma_f32_16x16x32_bf16 v[4:7], v[224:227], v[32:35], v[184:187]
	v_mfma_f32_16x16x32_bf16 v[64:67], v[228:231], v[36:39], v[4:7]
	v_mfma_f32_16x16x32_bf16 v[4:7], v[216:219], v[128:131], v[188:191]
	v_mfma_f32_16x16x32_bf16 v[36:39], v[220:223], v[132:135], v[4:7]
	v_mfma_f32_16x16x32_bf16 v[4:7], v[224:227], v[128:131], v[192:195]
	v_mfma_f32_16x16x32_bf16 v[32:35], v[228:231], v[132:135], v[4:7]
	v_mfma_f32_16x16x32_bf16 v[4:7], v[216:219], v[136:139], v[196:199]
	v_mfma_f32_16x16x32_bf16 v[20:23], v[220:223], v[232:235], v[4:7]
	v_mfma_f32_16x16x32_bf16 v[4:7], v[224:227], v[136:139], v[200:203]
	v_mfma_f32_16x16x32_bf16 v[0:3], v[216:219], v[236:239], v[0:3]
	v_mfma_f32_16x16x32_bf16 v[16:19], v[228:231], v[232:235], v[4:7]
	v_mfma_f32_16x16x32_bf16 v[4:7], v[220:223], v[240:243], v[0:3]
	v_mfma_f32_16x16x32_bf16 v[0:3], v[224:227], v[236:239], v[204:207]
	v_mfma_f32_16x16x32_bf16 v[0:3], v[228:231], v[240:243], v[0:3]
	s_barrier
	s_add_u32 s52, s46, 0x100
	s_addc_u32 s53, s47, 0
	s_add_u32 s76, s44, 0x200
	s_addc_u32 s77, s45, 0
	s_mov_b32 s78, 0
.LBB0_1010:
	s_add_u32 s44, s52, 0x100
	s_addc_u32 s45, s53, 0
	s_cmp_eq_u32 s78, 28
	s_cselect_b32 s50, s21, s44
	s_cselect_b32 s51, s20, s45
	s_cselect_b32 s48, s12, s76
	s_cselect_b32 s49, s9, s77
	s_add_u32 s46, s50, 0x80
	s_addc_u32 s47, s51, 0
	s_add_i32 s79, 0, 0x10000
	v_add_u32_e32 v155, s79, v147
	s_add_i32 s80, 0, 0x14000
	ds_read_b128 v[128:131], v155
	ds_read_b128 v[132:135], v155 offset:1024
	ds_read_b128 v[136:139], v155 offset:2048
	ds_read_b128 v[156:159], v155 offset:3072
	v_add_u32_e32 v155, s80, v147
	ds_read_b128 v[160:163], v155
	ds_read_b128 v[164:167], v155 offset:1024
	ds_read_b128 v[168:171], v155 offset:2048
	ds_read_b128 v[172:175], v155 offset:3072
	s_add_u32 s52, s52, 0x80080
	s_addc_u32 s53, s53, 0
	s_mov_b32 m0, s0
	ds_read_b128 v[176:179], v150
	ds_read_b128 v[180:183], v150 offset:1024
	ds_read_b128 v[184:187], v150 offset:2048
	ds_read_b128 v[188:191], v150 offset:3072
	ds_read_b128 v[192:195], v150 offset:4096
	ds_read_b128 v[196:199], v150 offset:5120
	ds_read_b128 v[200:203], v150 offset:6144
	ds_read_b128 v[204:207], v150 offset:7168
	global_load_lds_dwordx4 v143, s[52:53]
	s_mov_b32 m0, s1
	s_nop 0
	global_load_lds_dwordx4 v145, s[52:53]
	s_waitcnt vmcnt(8)
	s_waitcnt lgkmcnt(0)
	s_barrier
	v_mfma_f32_16x16x32_bf16 v[124:127], v[128:131], v[176:179], v[124:127]
	v_mfma_f32_16x16x32_bf16 v[120:123], v[136:139], v[176:179], v[120:123]
	v_mfma_f32_16x16x32_bf16 v[108:111], v[128:131], v[184:187], v[108:111]
	v_mfma_f32_16x16x32_bf16 v[104:107], v[136:139], v[184:187], v[104:107]
	v_mfma_f32_16x16x32_bf16 v[92:95], v[128:131], v[192:195], v[92:95]
	v_mfma_f32_16x16x32_bf16 v[88:91], v[136:139], v[192:195], v[88:91]
	v_mfma_f32_16x16x32_bf16 v[60:63], v[128:131], v[200:203], v[60:63]
	v_mfma_f32_16x16x32_bf16 v[56:59], v[136:139], v[200:203], v[56:59]
	v_mfma_f32_16x16x32_bf16 v[124:127], v[132:135], v[180:183], v[124:127]
	v_mfma_f32_16x16x32_bf16 v[120:123], v[156:159], v[180:183], v[120:123]
	v_mfma_f32_16x16x32_bf16 v[108:111], v[132:135], v[188:191], v[108:111]
	v_mfma_f32_16x16x32_bf16 v[104:107], v[156:159], v[188:191], v[104:107]
	v_mfma_f32_16x16x32_bf16 v[92:95], v[132:135], v[196:199], v[92:95]
	v_mfma_f32_16x16x32_bf16 v[88:91], v[156:159], v[196:199], v[88:91]
	v_mfma_f32_16x16x32_bf16 v[60:63], v[132:135], v[204:207], v[60:63]
	v_mfma_f32_16x16x32_bf16 v[56:59], v[156:159], v[204:207], v[56:59]
	v_mfma_f32_16x16x32_bf16 v[116:119], v[160:163], v[176:179], v[116:119]
	v_mfma_f32_16x16x32_bf16 v[112:115], v[168:171], v[176:179], v[112:115]
	v_mfma_f32_16x16x32_bf16 v[100:103], v[160:163], v[184:187], v[100:103]
	v_mfma_f32_16x16x32_bf16 v[96:99], v[168:171], v[184:187], v[96:99]
	v_mfma_f32_16x16x32_bf16 v[84:87], v[160:163], v[192:195], v[84:87]
	v_mfma_f32_16x16x32_bf16 v[80:83], v[168:171], v[192:195], v[80:83]
	v_mfma_f32_16x16x32_bf16 v[52:55], v[160:163], v[200:203], v[52:55]
	v_mfma_f32_16x16x32_bf16 v[48:51], v[168:171], v[200:203], v[48:51]
	v_mfma_f32_16x16x32_bf16 v[116:119], v[164:167], v[180:183], v[116:119]
	v_mfma_f32_16x16x32_bf16 v[112:115], v[172:175], v[180:183], v[112:115]
	v_mfma_f32_16x16x32_bf16 v[100:103], v[164:167], v[188:191], v[100:103]
	v_mfma_f32_16x16x32_bf16 v[96:99], v[172:175], v[188:191], v[96:99]
	v_mfma_f32_16x16x32_bf16 v[84:87], v[164:167], v[196:199], v[84:87]
	v_mfma_f32_16x16x32_bf16 v[80:83], v[172:175], v[196:199], v[80:83]
	v_mfma_f32_16x16x32_bf16 v[52:55], v[164:167], v[204:207], v[52:55]
	v_mfma_f32_16x16x32_bf16 v[48:51], v[172:175], v[204:207], v[48:51]
	s_barrier
	s_add_i32 s52, s79, s26
	s_mov_b32 m0, s52
	ds_read_b128 v[176:179], v150 offset:16384
	ds_read_b128 v[180:183], v150 offset:17408
	ds_read_b128 v[184:187], v150 offset:18432
	ds_read_b128 v[188:191], v150 offset:19456
	ds_read_b128 v[192:195], v150 offset:20480
	ds_read_b128 v[196:199], v150 offset:21504
	ds_read_b128 v[200:203], v150 offset:22528
	ds_read_b128 v[204:207], v150 offset:23552
	global_load_lds_dwordx4 v144, s[48:49]
	s_add_i32 m0, s52, 0x2000
	s_add_u32 s52, s48, 0x80000
	s_addc_u32 s53, s49, 0
	s_add_i32 s79, s80, s26
	s_nop 0
	global_load_lds_dwordx4 v146, s[48:49]
	s_mov_b32 m0, s79
	s_nop 0
	global_load_lds_dwordx4 v144, s[52:53]
	s_add_i32 m0, s79, 0x2000
	s_nop 0
	global_load_lds_dwordx4 v146, s[52:53]
	s_mov_b32 m0, s27
	s_nop 0
	global_load_lds_dwordx4 v143, s[50:51]
	s_mov_b32 m0, s58
	s_nop 0
	global_load_lds_dwordx4 v145, s[50:51]
	s_waitcnt vmcnt(8)
	s_waitcnt lgkmcnt(0)
	s_barrier
	v_mfma_f32_16x16x32_bf16 v[76:79], v[128:131], v[176:179], v[76:79]
	v_mfma_f32_16x16x32_bf16 v[72:75], v[136:139], v[176:179], v[72:75]
	v_mfma_f32_16x16x32_bf16 v[44:47], v[128:131], v[184:187], v[44:47]
	v_mfma_f32_16x16x32_bf16 v[40:43], v[136:139], v[184:187], v[40:43]
	v_mfma_f32_16x16x32_bf16 v[28:31], v[128:131], v[192:195], v[28:31]
	v_mfma_f32_16x16x32_bf16 v[24:27], v[136:139], v[192:195], v[24:27]
	v_mfma_f32_16x16x32_bf16 v[12:15], v[128:131], v[200:203], v[12:15]
	v_mfma_f32_16x16x32_bf16 v[8:11], v[136:139], v[200:203], v[8:11]
	v_mfma_f32_16x16x32_bf16 v[76:79], v[132:135], v[180:183], v[76:79]
	v_mfma_f32_16x16x32_bf16 v[72:75], v[156:159], v[180:183], v[72:75]
	v_mfma_f32_16x16x32_bf16 v[44:47], v[132:135], v[188:191], v[44:47]
	v_mfma_f32_16x16x32_bf16 v[40:43], v[156:159], v[188:191], v[40:43]
	v_mfma_f32_16x16x32_bf16 v[28:31], v[132:135], v[196:199], v[28:31]
	v_mfma_f32_16x16x32_bf16 v[24:27], v[156:159], v[196:199], v[24:27]
	v_mfma_f32_16x16x32_bf16 v[12:15], v[132:135], v[204:207], v[12:15]
	v_mfma_f32_16x16x32_bf16 v[8:11], v[156:159], v[204:207], v[8:11]
	v_mfma_f32_16x16x32_bf16 v[68:71], v[160:163], v[176:179], v[68:71]
	v_mfma_f32_16x16x32_bf16 v[64:67], v[168:171], v[176:179], v[64:67]
	v_mfma_f32_16x16x32_bf16 v[36:39], v[160:163], v[184:187], v[36:39]
	v_mfma_f32_16x16x32_bf16 v[32:35], v[168:171], v[184:187], v[32:35]
	v_mfma_f32_16x16x32_bf16 v[20:23], v[160:163], v[192:195], v[20:23]
	v_mfma_f32_16x16x32_bf16 v[16:19], v[168:171], v[192:195], v[16:19]
	v_mfma_f32_16x16x32_bf16 v[4:7], v[160:163], v[200:203], v[4:7]
	v_mfma_f32_16x16x32_bf16 v[0:3], v[168:171], v[200:203], v[0:3]
	v_mfma_f32_16x16x32_bf16 v[68:71], v[164:167], v[180:183], v[68:71]
	v_mfma_f32_16x16x32_bf16 v[64:67], v[172:175], v[180:183], v[64:67]
	v_mfma_f32_16x16x32_bf16 v[36:39], v[164:167], v[188:191], v[36:39]
	v_mfma_f32_16x16x32_bf16 v[32:35], v[172:175], v[188:191], v[32:35]
	v_mfma_f32_16x16x32_bf16 v[20:23], v[164:167], v[196:199], v[20:23]
	v_mfma_f32_16x16x32_bf16 v[16:19], v[172:175], v[196:199], v[16:19]
	v_mfma_f32_16x16x32_bf16 v[4:7], v[164:167], v[204:207], v[4:7]
	v_mfma_f32_16x16x32_bf16 v[0:3], v[172:175], v[204:207], v[0:3]
	s_barrier
	ds_read_b128 v[128:131], v153
	ds_read_b128 v[132:135], v153 offset:1024
	ds_read_b128 v[136:139], v153 offset:2048
	ds_read_b128 v[156:159], v153 offset:3072
	ds_read_b128 v[160:163], v154
	ds_read_b128 v[164:167], v154 offset:1024
	ds_read_b128 v[168:171], v154 offset:2048
	ds_read_b128 v[172:175], v154 offset:3072
	s_add_u32 s50, s50, 0x80000
	s_addc_u32 s51, s51, 0
	s_mov_b32 m0, s59
	ds_read_b128 v[176:179], v150 offset:32768
	ds_read_b128 v[180:183], v150 offset:33792
	ds_read_b128 v[184:187], v150 offset:34816
	ds_read_b128 v[188:191], v150 offset:35840
	ds_read_b128 v[192:195], v150 offset:36864
	ds_read_b128 v[196:199], v150 offset:37888
	ds_read_b128 v[200:203], v150 offset:38912
	ds_read_b128 v[204:207], v150 offset:39936
	global_load_lds_dwordx4 v143, s[50:51]
	s_mov_b32 m0, s60
	s_nop 0
	global_load_lds_dwordx4 v145, s[50:51]
	s_waitcnt vmcnt(8)
	s_waitcnt lgkmcnt(0)
	s_barrier
	v_mfma_f32_16x16x32_bf16 v[124:127], v[128:131], v[176:179], v[124:127]
	v_mfma_f32_16x16x32_bf16 v[120:123], v[136:139], v[176:179], v[120:123]
	v_mfma_f32_16x16x32_bf16 v[108:111], v[128:131], v[184:187], v[108:111]
	v_mfma_f32_16x16x32_bf16 v[104:107], v[136:139], v[184:187], v[104:107]
	v_mfma_f32_16x16x32_bf16 v[92:95], v[128:131], v[192:195], v[92:95]
	v_mfma_f32_16x16x32_bf16 v[88:91], v[136:139], v[192:195], v[88:91]
	v_mfma_f32_16x16x32_bf16 v[60:63], v[128:131], v[200:203], v[60:63]
	v_mfma_f32_16x16x32_bf16 v[56:59], v[136:139], v[200:203], v[56:59]
	v_mfma_f32_16x16x32_bf16 v[124:127], v[132:135], v[180:183], v[124:127]
	v_mfma_f32_16x16x32_bf16 v[120:123], v[156:159], v[180:183], v[120:123]
	v_mfma_f32_16x16x32_bf16 v[108:111], v[132:135], v[188:191], v[108:111]
	v_mfma_f32_16x16x32_bf16 v[104:107], v[156:159], v[188:191], v[104:107]
	v_mfma_f32_16x16x32_bf16 v[92:95], v[132:135], v[196:199], v[92:95]
	v_mfma_f32_16x16x32_bf16 v[88:91], v[156:159], v[196:199], v[88:91]
	v_mfma_f32_16x16x32_bf16 v[60:63], v[132:135], v[204:207], v[60:63]
	v_mfma_f32_16x16x32_bf16 v[56:59], v[156:159], v[204:207], v[56:59]
	v_mfma_f32_16x16x32_bf16 v[116:119], v[160:163], v[176:179], v[116:119]
	v_mfma_f32_16x16x32_bf16 v[112:115], v[168:171], v[176:179], v[112:115]
	v_mfma_f32_16x16x32_bf16 v[100:103], v[160:163], v[184:187], v[100:103]
	v_mfma_f32_16x16x32_bf16 v[96:99], v[168:171], v[184:187], v[96:99]
	v_mfma_f32_16x16x32_bf16 v[84:87], v[160:163], v[192:195], v[84:87]
	v_mfma_f32_16x16x32_bf16 v[80:83], v[168:171], v[192:195], v[80:83]
	v_mfma_f32_16x16x32_bf16 v[52:55], v[160:163], v[200:203], v[52:55]
	v_mfma_f32_16x16x32_bf16 v[48:51], v[168:171], v[200:203], v[48:51]
	v_mfma_f32_16x16x32_bf16 v[116:119], v[164:167], v[180:183], v[116:119]
	v_mfma_f32_16x16x32_bf16 v[112:115], v[172:175], v[180:183], v[112:115]
	v_mfma_f32_16x16x32_bf16 v[100:103], v[164:167], v[188:191], v[100:103]
	v_mfma_f32_16x16x32_bf16 v[96:99], v[172:175], v[188:191], v[96:99]
	v_mfma_f32_16x16x32_bf16 v[84:87], v[164:167], v[196:199], v[84:87]
	v_mfma_f32_16x16x32_bf16 v[80:83], v[172:175], v[196:199], v[80:83]
	v_mfma_f32_16x16x32_bf16 v[52:55], v[164:167], v[204:207], v[52:55]
	v_mfma_f32_16x16x32_bf16 v[48:51], v[172:175], v[204:207], v[48:51]
	s_barrier
	s_add_u32 s50, s48, 0x80
	s_mov_b32 m0, s35
	s_addc_u32 s51, s49, 0
	ds_read_b128 v[176:179], v150 offset:49152
	ds_read_b128 v[180:183], v150 offset:50176
	ds_read_b128 v[184:187], v150 offset:51200
	ds_read_b128 v[188:191], v150 offset:52224
	ds_read_b128 v[192:195], v150 offset:53248
	ds_read_b128 v[196:199], v150 offset:54272
	ds_read_b128 v[200:203], v150 offset:55296
	ds_read_b128 v[204:207], v150 offset:56320
	s_add_u32 s48, s48, 0x80080
	global_load_lds_dwordx4 v144, s[50:51]
	s_mov_b32 m0, s73
	s_addc_u32 s49, s49, 0
	global_load_lds_dwordx4 v146, s[50:51]
	s_mov_b32 m0, s74
	s_nop 0
	global_load_lds_dwordx4 v144, s[48:49]
	s_mov_b32 m0, s75
	s_nop 0
	global_load_lds_dwordx4 v146, s[48:49]
	s_mov_b32 m0, s61
	s_nop 0
	global_load_lds_dwordx4 v143, s[46:47]
	s_mov_b32 m0, s62
	s_nop 0
	global_load_lds_dwordx4 v145, s[46:47]
	s_waitcnt vmcnt(8)
	s_waitcnt lgkmcnt(0)
	s_barrier
	v_mfma_f32_16x16x32_bf16 v[76:79], v[128:131], v[176:179], v[76:79]
	v_mfma_f32_16x16x32_bf16 v[72:75], v[136:139], v[176:179], v[72:75]
	v_mfma_f32_16x16x32_bf16 v[44:47], v[128:131], v[184:187], v[44:47]
	v_mfma_f32_16x16x32_bf16 v[40:43], v[136:139], v[184:187], v[40:43]
	v_mfma_f32_16x16x32_bf16 v[28:31], v[128:131], v[192:195], v[28:31]
	v_mfma_f32_16x16x32_bf16 v[24:27], v[136:139], v[192:195], v[24:27]
	v_mfma_f32_16x16x32_bf16 v[12:15], v[128:131], v[200:203], v[12:15]
	v_mfma_f32_16x16x32_bf16 v[8:11], v[136:139], v[200:203], v[8:11]
	v_mfma_f32_16x16x32_bf16 v[76:79], v[132:135], v[180:183], v[76:79]
	v_mfma_f32_16x16x32_bf16 v[72:75], v[156:159], v[180:183], v[72:75]
	v_mfma_f32_16x16x32_bf16 v[44:47], v[132:135], v[188:191], v[44:47]
	v_mfma_f32_16x16x32_bf16 v[40:43], v[156:159], v[188:191], v[40:43]
	v_mfma_f32_16x16x32_bf16 v[28:31], v[132:135], v[196:199], v[28:31]
	v_mfma_f32_16x16x32_bf16 v[24:27], v[156:159], v[196:199], v[24:27]
	v_mfma_f32_16x16x32_bf16 v[12:15], v[132:135], v[204:207], v[12:15]
	v_mfma_f32_16x16x32_bf16 v[8:11], v[156:159], v[204:207], v[8:11]
	v_mfma_f32_16x16x32_bf16 v[68:71], v[160:163], v[176:179], v[68:71]
	v_mfma_f32_16x16x32_bf16 v[64:67], v[168:171], v[176:179], v[64:67]
	v_mfma_f32_16x16x32_bf16 v[36:39], v[160:163], v[184:187], v[36:39]
	v_mfma_f32_16x16x32_bf16 v[32:35], v[168:171], v[184:187], v[32:35]
	v_mfma_f32_16x16x32_bf16 v[20:23], v[160:163], v[192:195], v[20:23]
	v_mfma_f32_16x16x32_bf16 v[16:19], v[168:171], v[192:195], v[16:19]
	v_mfma_f32_16x16x32_bf16 v[4:7], v[160:163], v[200:203], v[4:7]
	v_mfma_f32_16x16x32_bf16 v[0:3], v[168:171], v[200:203], v[0:3]
	v_mfma_f32_16x16x32_bf16 v[68:71], v[164:167], v[180:183], v[68:71]
	v_mfma_f32_16x16x32_bf16 v[64:67], v[172:175], v[180:183], v[64:67]
	v_mfma_f32_16x16x32_bf16 v[36:39], v[164:167], v[188:191], v[36:39]
	v_mfma_f32_16x16x32_bf16 v[32:35], v[172:175], v[188:191], v[32:35]
	v_mfma_f32_16x16x32_bf16 v[20:23], v[164:167], v[196:199], v[20:23]
	v_mfma_f32_16x16x32_bf16 v[16:19], v[172:175], v[196:199], v[16:19]
	v_mfma_f32_16x16x32_bf16 v[4:7], v[164:167], v[204:207], v[4:7]
	v_mfma_f32_16x16x32_bf16 v[0:3], v[172:175], v[204:207], v[0:3]
	s_barrier
	s_add_i32 s78, s78, 2
	s_add_u32 s76, s76, 0x100
	s_addc_u32 s77, s77, 0
	s_cmp_gt_u32 s78, 29
	s_mov_b64 s[52:53], s[44:45]
	s_cbranch_scc0 .LBB0_1010
	s_and_b64 vcc, exec, s[4:5]
	s_cbranch_vccz .LBB0_1013
	s_barrier

.LBB0_1077:
	s_or_b64 exec, exec, s[2:3]
	v_lshlrev_b32_e32 v0, 11, v149
	v_lshlrev_b32_e32 v20, 4, v18
	v_or_b32_e32 v4, v20, v0
	v_ashrrev_i32_e32 v4, 8, v4
	v_xor_b32_e32 v5, v4, v2
	v_and_b32_e32 v6, 3, v4
	v_lshrrev_b32_e32 v4, 1, v4
	v_and_b32_e32 v3, 0x7ffffff0, v19
	v_and_b32_e32 v4, 12, v4
	v_or3_b32 v4, v6, v4, v3
	v_mul_lo_u32 v4, v4, s25
	v_lshlrev_b32_e32 v5, 3, v5
	v_and_or_b32 v4, v5, s26, v4
	v_lshlrev_b32_e32 v158, 1, v4
	v_or_b32_e32 v4, 0x400, v20
	v_or_b32_e32 v0, v4, v0
	s_lshl_b32 s2, s4, 2
	v_ashrrev_i32_e32 v0, 8, v0
	s_add_i32 s74, s2, 4
	v_xor_b32_e32 v5, v0, v2
	v_and_b32_e32 v6, 3, v0
	v_lshrrev_b32_e32 v0, 1, v0
	s_or_b32 s2, s2, 3
	v_and_b32_e32 v0, 12, v0
	s_mul_i32 s3, s2, 0x50000
	v_or3_b32 v0, v6, v0, v3
	s_lshl_b32 s3, s3, 1
	v_mul_lo_u32 v0, v0, s25
	v_lshlrev_b32_e32 v5, 3, v5
	s_add_u32 s4, s67, s3
	s_mov_b32 m0, s54
	v_and_or_b32 v0, v5, s26, v0
	s_addc_u32 s5, s68, 0
	v_lshl_add_u32 v159, v0, 1, v148
	s_waitcnt lgkmcnt(0)
	s_barrier
	v_lshlrev_b32_e32 v6, 1, v2
	global_load_lds_dwordx4 v158, s[4:5]
	s_mov_b32 m0, s61
	v_and_b32_e32 v6, 32, v6
	global_load_lds_dwordx4 v159, s[4:5]
	v_bfe_u32 v0, v2, 2, 2
	v_and_b32_e32 v5, 12, v19
	v_add_u32_e32 v3, v6, v3
	v_lshlrev_b32_e32 v22, 3, v18
	v_or3_b32 v0, v0, v5, v3
	v_and_b32_e32 v21, 24, v22
	v_mul_lo_u32 v0, v0, s25
	v_or_b32_e32 v0, v0, v21
	v_and_b32_e32 v23, 32, v2
	s_and_b32 s8, s1, 0xffffff00
	v_or_b32_e32 v2, v0, v23
	s_waitcnt vmcnt(0)
	s_cmpk_eq_i32 s8, 0x100
	v_lshlrev_b32_e32 v160, 1, v2
	v_lshrrev_b32_e32 v2, 4, v4
	s_waitcnt lgkmcnt(0)
	s_barrier
	s_cselect_b64 s[4:5], -1, 0
	s_cmpk_lg_i32 s8, 0x100
	v_and_or_b32 v0, v2, s27, v0
	s_cselect_b64 s[38:39], -1, 0
	v_lshlrev_b32_e32 v161, 1, v0
	s_and_b64 vcc, exec, s[38:39]
	s_waitcnt vmcnt(0)
	s_cbranch_vccnz .LBB0_1079
	s_lshl_b32 s8, s74, 6
	s_addk_i32 s8, 0xff80
	s_mul_hi_u32 s9, s8, 0x2800
	s_mulk_i32 s8, 0x2800
	s_add_u32 s8, s67, s8
	s_mov_b32 m0, s55
	s_addc_u32 s9, s68, s9
	global_load_lds_dwordx4 v158, s[8:9]
	s_mov_b32 m0, s56
	s_nop 0
	global_load_lds_dwordx4 v159, s[8:9]
	s_add_u32 s8, s69, s3
	s_addc_u32 s9, s70, 0
	s_mov_b32 m0, s57
	s_nop 0
	global_load_lds_dwordx4 v160, s[8:9]
	s_mov_b32 m0, s58
	s_nop 0
	global_load_lds_dwordx4 v161, s[8:9]
	s_waitcnt lgkmcnt(0)
	s_barrier
.LBB0_1079:
	s_cmpk_lt_u32 s1, 0x100
	s_cselect_b64 s[40:41], -1, 0
	s_cmpk_gt_u32 s1, 0xff
	s_cselect_b64 s[42:43], -1, 0
	s_and_b64 vcc, exec, s[42:43]
	s_cbranch_vccnz .LBB0_1081
	s_lshl_b32 s1, s74, 6
	s_addk_i32 s1, 0xff80
	s_mul_hi_u32 s9, s1, 0x2800
	s_mulk_i32 s1, 0x2800
	s_add_u32 s8, s67, s1
	s_mov_b32 m0, s55
	s_addc_u32 s9, s68, s9
	global_load_lds_dwordx4 v158, s[8:9]
	s_mov_b32 m0, s56
	s_nop 0
	global_load_lds_dwordx4 v159, s[8:9]
	s_add_u32 s8, s69, s3
	s_addc_u32 s9, s70, 0
	s_mov_b32 m0, s57
	s_nop 0
	global_load_lds_dwordx4 v160, s[8:9]
	s_mov_b32 m0, s58
	s_nop 0
	global_load_lds_dwordx4 v161, s[8:9]

.LBB0_1088:
	s_waitcnt lgkmcnt(0)
	s_barrier
	s_and_b64 vcc, exec, s[2:3]
	s_cbranch_vccnz .LBB0_1090
	s_lshl_b32 s8, s74, 6
	s_mul_i32 s5, s74, 0xa0000
	s_add_i32 s4, s8, 0xffffff40
	s_add_i32 s5, s5, 0xffe20000
	s_mul_hi_u32 s9, s4, 0x2800
	s_add_u32 s4, s67, s5
	s_mov_b32 m0, s54
	s_addc_u32 s5, s68, s9
	global_load_lds_dwordx4 v158, s[4:5]
	s_mov_b32 m0, s61
	s_nop 0
	global_load_lds_dwordx4 v159, s[4:5]
	s_add_i32 s4, s8, 0xffffff80
	s_mul_hi_u32 s5, s4, 0x2800
	s_mulk_i32 s4, 0x2800
	s_add_u32 s4, s69, s4
	s_addc_u32 s5, s70, s5
	s_add_i32 m0, s54, 0x10000
	s_nop 0
	global_load_lds_dwordx4 v160, s[4:5]
	s_add_i32 m0, s54, 0x10400
	s_nop 0
	global_load_lds_dwordx4 v161, s[4:5]

.LBB0_1149:
	s_waitcnt lgkmcnt(0)
	s_barrier
	s_and_b64 vcc, exec, s[2:3]
	s_cbranch_vccnz .LBB0_1151
	s_add_u32 s0, s8, 0x100000
	s_mov_b32 m0, s54
	s_addc_u32 s1, s9, 0
	global_load_lds_dwordx4 v165, s[0:1]
	s_mov_b32 m0, s36
	s_nop 0
	global_load_lds_dwordx4 v166, s[0:1]
	s_add_u32 s0, s8, 0x80400
	s_addc_u32 s1, s9, 0
	s_mov_b32 m0, s43
	s_nop 0
	global_load_lds_dwordx4 v146, s[0:1]
	s_mov_b32 m0, s44
	s_nop 0
	global_load_lds_dwordx4 v144, s[0:1]

.LBB0_1153:
	v_lshlrev_b32_e32 v4, 1, v32
	v_and_b32_e32 v4, 32, v4
	v_and_b32_e32 v5, 0xc0, v33
	v_and_b32_e32 v6, 0x100, v35
	s_waitcnt lgkmcnt(0)
	s_barrier
	v_add3_u32 v4, v4, s45, v5
	v_add3_u32 v147, v4, v6, v34
	ds_read_b64_tr_b16 v[16:17], v147 offset:0
	ds_read_b64_tr_b16 v[18:19], v147 offset:0x800
	ds_read_b64_tr_b16 v[12:13], v147 offset:0x1000
	ds_read_b64_tr_b16 v[14:15], v147 offset:0x1800
	ds_read_b64_tr_b16 v[8:9], v147 offset:0x2000
	ds_read_b64_tr_b16 v[10:11], v147 offset:0x2800
	ds_read_b64_tr_b16 v[4:5], v147 offset:0x3000
	ds_read_b64_tr_b16 v[6:7], v147 offset:0x3800
	s_and_b64 vcc, exec, s[4:5]
	s_cbranch_vccnz .LBB0_1155
	s_add_u32 s0, s8, 0x100000
	s_mov_b32 m0, s54
	s_addc_u32 s1, s9, 0
	global_load_lds_dwordx4 v165, s[0:1]
	s_mov_b32 m0, s36
	s_nop 0
	global_load_lds_dwordx4 v166, s[0:1]
	s_add_u32 s0, s8, 0x80400
	s_addc_u32 s1, s9, 0
	s_mov_b32 m0, s43
	s_nop 0
	global_load_lds_dwordx4 v146, s[0:1]
	s_mov_b32 m0, s44
	s_nop 0
	global_load_lds_dwordx4 v144, s[0:1]

.LBB0_1157:
	s_waitcnt lgkmcnt(0)
	s_barrier
	s_and_b64 vcc, exec, s[2:3]
	s_cbranch_vccnz .LBB0_1159
	s_add_u32 s0, s8, 0x180000
	s_mov_b32 m0, s37
	s_addc_u32 s1, s9, 0
	global_load_lds_dwordx4 v165, s[0:1]
	s_mov_b32 m0, s38
	s_nop 0
	global_load_lds_dwordx4 v166, s[0:1]
	s_add_u32 s0, s8, 0x100400
	s_addc_u32 s1, s9, 0
	s_mov_b32 m0, s39
	s_nop 0
	global_load_lds_dwordx4 v146, s[0:1]
	s_mov_b32 m0, s40
	s_nop 0
	global_load_lds_dwordx4 v144, s[0:1]

.LBB0_1163:
	s_waitcnt lgkmcnt(0)
	s_barrier
	v_add_u32_e32 v148, 0x4000, v147
	ds_read_b64_tr_b16 v[108:109], v148 offset:0
	ds_read_b64_tr_b16 v[110:111], v148 offset:0x800
	ds_read_b64_tr_b16 v[104:105], v148 offset:0x1000
	ds_read_b64_tr_b16 v[106:107], v148 offset:0x1800
	ds_read_b64_tr_b16 v[100:101], v148 offset:0x2000
	ds_read_b64_tr_b16 v[102:103], v148 offset:0x2800
	ds_read_b64_tr_b16 v[96:97], v148 offset:0x3000
	ds_read_b64_tr_b16 v[98:99], v148 offset:0x3800
	s_and_b64 vcc, exec, s[4:5]
	s_cbranch_vccnz .LBB0_1165
	s_add_u32 s0, s8, 0x180000
	s_mov_b32 m0, s37
	s_addc_u32 s1, s9, 0
	global_load_lds_dwordx4 v165, s[0:1]
	s_mov_b32 m0, s38
	s_nop 0
	global_load_lds_dwordx4 v166, s[0:1]
	s_add_u32 s0, s8, 0x100400
	s_addc_u32 s1, s9, 0
	s_mov_b32 m0, s39
	s_nop 0
	global_load_lds_dwordx4 v146, s[0:1]
	s_mov_b32 m0, s40
	s_nop 0
	global_load_lds_dwordx4 v144, s[0:1]

.LBB0_1585:
	s_add_u32 s20, s52, 0x100
	s_addc_u32 s21, s53, 0
	s_waitcnt lgkmcnt(0)
	s_add_u32 s44, s50, 0x100
	s_addc_u32 s45, s51, 0
	s_barrier
	v_mfma_f32_16x16x32_bf16 v[32:35], v[16:19], v[68:71], 0
	v_mfma_f32_16x16x32_bf16 v[36:39], v[24:27], v[68:71], 0
	s_waitcnt lgkmcnt(0)
	v_mfma_f32_16x16x32_bf16 v[40:43], v[16:19], v[84:87], 0
	v_mfma_f32_16x16x32_bf16 v[44:47], v[24:27], v[84:87], 0
	v_mfma_f32_16x16x32_bf16 v[48:51], v[16:19], v[88:91], 0
	v_mfma_f32_16x16x32_bf16 v[52:55], v[24:27], v[88:91], 0
	v_mfma_f32_16x16x32_bf16 v[56:59], v[16:19], v[72:75], 0
	v_mfma_f32_16x16x32_bf16 v[60:63], v[24:27], v[72:75], 0
	v_mfma_f32_16x16x32_bf16 v[116:119], v[20:23], v[80:83], v[32:35]
	v_mfma_f32_16x16x32_bf16 v[36:39], v[28:31], v[80:83], v[36:39]
	v_mfma_f32_16x16x32_bf16 v[40:43], v[20:23], v[96:99], v[40:43]
	v_mfma_f32_16x16x32_bf16 v[44:47], v[28:31], v[96:99], v[44:47]
	v_mfma_f32_16x16x32_bf16 v[48:51], v[20:23], v[92:95], v[48:51]
	v_mfma_f32_16x16x32_bf16 v[52:55], v[28:31], v[92:95], v[52:55]
	v_mfma_f32_16x16x32_bf16 v[56:59], v[20:23], v[76:79], v[56:59]
	v_mfma_f32_16x16x32_bf16 v[60:63], v[28:31], v[76:79], v[60:63]
	v_mfma_f32_16x16x32_bf16 v[64:67], v[0:3], v[68:71], 0
	v_mfma_f32_16x16x32_bf16 v[68:71], v[8:11], v[68:71], 0
	v_mfma_f32_16x16x32_bf16 v[64:67], v[4:7], v[80:83], v[64:67]
	v_mfma_f32_16x16x32_bf16 v[68:71], v[12:15], v[80:83], v[68:71]
	v_mfma_f32_16x16x32_bf16 v[80:83], v[0:3], v[84:87], 0
	v_mfma_f32_16x16x32_bf16 v[84:87], v[8:11], v[84:87], 0
	v_mfma_f32_16x16x32_bf16 v[80:83], v[4:7], v[96:99], v[80:83]
	v_mfma_f32_16x16x32_bf16 v[84:87], v[12:15], v[96:99], v[84:87]
	v_mfma_f32_16x16x32_bf16 v[96:99], v[0:3], v[88:91], 0
	v_mfma_f32_16x16x32_bf16 v[88:91], v[8:11], v[88:91], 0
	v_mfma_f32_16x16x32_bf16 v[132:135], v[12:15], v[92:95], v[88:91]
	v_mfma_f32_16x16x32_bf16 v[88:91], v[0:3], v[72:75], 0
	v_mfma_f32_16x16x32_bf16 v[72:75], v[8:11], v[72:75], 0
	v_mfma_f32_16x16x32_bf16 v[128:131], v[4:7], v[92:95], v[96:99]
	v_mfma_f32_16x16x32_bf16 v[136:139], v[4:7], v[76:79], v[88:91]
	v_mfma_f32_16x16x32_bf16 v[140:143], v[12:15], v[76:79], v[72:75]
	s_barrier
	s_mov_b32 m0, s61
	ds_read_b128 v[104:107], v162 offset:16384
	ds_read_b128 v[108:111], v162 offset:17408
	ds_read_b128 v[96:99], v162 offset:18432
	ds_read_b128 v[100:103], v162 offset:19456
	ds_read_b128 v[88:91], v162 offset:20480
	ds_read_b128 v[92:95], v162 offset:21504
	ds_read_b128 v[72:75], v162 offset:22528
	ds_read_b128 v[76:79], v162 offset:23552
	global_load_lds_dwordx4 v156, s[44:45]
	s_mov_b32 m0, s62
	s_nop 0
	global_load_lds_dwordx4 v158, s[44:45]
	s_add_u32 s44, s50, 0x80100
	s_addc_u32 s45, s51, 0
	s_mov_b32 m0, s63
	s_and_b64 vcc, exec, s[42:43]
	global_load_lds_dwordx4 v156, s[44:45]
	s_mov_b32 m0, s64
	s_nop 0
	global_load_lds_dwordx4 v158, s[44:45]
	s_mov_b32 m0, s27
	s_mov_b64 s[44:45], -1
	global_load_lds_dwordx4 v153, s[20:21]
	s_mov_b32 m0, s65
	s_nop 0
	global_load_lds_dwordx4 v157, s[20:21]
	s_cbranch_vccz .LBB0_1587
	s_waitcnt vmcnt(8)
	s_mov_b64 s[44:45], 0

.LBB0_1589:
	s_ashr_i32 s7, s6, 31
	s_lshl_b64 s[20:21], s[6:7], 20
	s_add_u32 s42, s14, s20
	s_addc_u32 s43, s15, s21
	s_ashr_i32 s35, s34, 31
	s_lshl_b64 s[20:21], s[34:35], 20
	s_add_u32 s44, s24, s20
	s_addc_u32 s45, s25, s21
	s_add_u32 s54, s52, 0x180
	s_addc_u32 s55, s53, 0
	s_waitcnt lgkmcnt(0)
	s_and_b64 s[20:21], s[36:37], exec
	s_cselect_b32 s20, s45, s51
	s_cselect_b32 s21, s44, s50
	s_cselect_b32 s35, s43, s53
	s_cselect_b32 s47, s42, s52
	s_add_u32 s56, s50, 0x180
	s_addc_u32 s57, s51, 0
	s_barrier
	s_waitcnt lgkmcnt(0)
	v_mfma_f32_16x16x32_bf16 v[112:115], v[16:19], v[104:107], 0
	v_mfma_f32_16x16x32_bf16 v[166:169], v[20:23], v[108:111], v[112:115]
	v_mfma_f32_16x16x32_bf16 v[112:115], v[24:27], v[104:107], 0
	v_mfma_f32_16x16x32_bf16 v[170:173], v[28:31], v[108:111], v[112:115]
	v_mfma_f32_16x16x32_bf16 v[112:115], v[16:19], v[96:99], 0
	v_mfma_f32_16x16x32_bf16 v[174:177], v[20:23], v[100:103], v[112:115]
	v_mfma_f32_16x16x32_bf16 v[112:115], v[24:27], v[96:99], 0
	v_mfma_f32_16x16x32_bf16 v[178:181], v[28:31], v[100:103], v[112:115]
	v_mfma_f32_16x16x32_bf16 v[112:115], v[16:19], v[88:91], 0
	v_mfma_f32_16x16x32_bf16 v[16:19], v[16:19], v[72:75], 0
	v_mfma_f32_16x16x32_bf16 v[182:185], v[20:23], v[92:95], v[112:115]
	v_mfma_f32_16x16x32_bf16 v[16:19], v[20:23], v[76:79], v[16:19]
	v_mfma_f32_16x16x32_bf16 v[20:23], v[24:27], v[72:75], 0
	v_mfma_f32_16x16x32_bf16 v[112:115], v[24:27], v[88:91], 0
	v_mfma_f32_16x16x32_bf16 v[20:23], v[28:31], v[76:79], v[20:23]
	v_mfma_f32_16x16x32_bf16 v[186:189], v[28:31], v[92:95], v[112:115]
	v_mfma_f32_16x16x32_bf16 v[24:27], v[0:3], v[104:107], 0
	v_mfma_f32_16x16x32_bf16 v[190:193], v[4:7], v[108:111], v[24:27]
	v_mfma_f32_16x16x32_bf16 v[24:27], v[8:11], v[104:107], 0
	v_mfma_f32_16x16x32_bf16 v[194:197], v[12:15], v[108:111], v[24:27]
	v_mfma_f32_16x16x32_bf16 v[24:27], v[0:3], v[96:99], 0
	v_mfma_f32_16x16x32_bf16 v[198:201], v[4:7], v[100:103], v[24:27]
	v_mfma_f32_16x16x32_bf16 v[24:27], v[8:11], v[96:99], 0
	v_mfma_f32_16x16x32_bf16 v[202:205], v[12:15], v[100:103], v[24:27]
	v_mfma_f32_16x16x32_bf16 v[24:27], v[0:3], v[88:91], 0
	v_mfma_f32_16x16x32_bf16 v[0:3], v[0:3], v[72:75], 0
	v_mfma_f32_16x16x32_bf16 v[206:209], v[4:7], v[92:95], v[24:27]
	v_mfma_f32_16x16x32_bf16 v[24:27], v[8:11], v[88:91], 0
	v_mfma_f32_16x16x32_bf16 v[0:3], v[4:7], v[76:79], v[0:3]
	v_mfma_f32_16x16x32_bf16 v[4:7], v[8:11], v[72:75], 0
	v_mfma_f32_16x16x32_bf16 v[210:213], v[12:15], v[92:95], v[24:27]
	v_mfma_f32_16x16x32_bf16 v[214:217], v[12:15], v[76:79], v[4:7]
	s_barrier
	v_add_u32_e32 v144, s74, v159
	v_add_u32_e32 v148, s75, v159
	s_nop 1
	ds_read_b128 v[4:7], v144
	ds_read_b128 v[8:11], v144 offset:1024
	ds_read_b128 v[218:221], v144 offset:2048
	ds_read_b128 v[222:225], v144 offset:3072
	ds_read_b128 v[226:229], v148
	ds_read_b128 v[230:233], v148 offset:1024
	ds_read_b128 v[234:237], v148 offset:2048
	ds_read_b128 v[238:241], v148 offset:3072
	s_add_u32 s58, s52, 0x80100
	s_addc_u32 s59, s53, 0
	s_mov_b32 m0, s66
	ds_read_b128 v[12:15], v162 offset:32768
	ds_read_b128 v[24:27], v162 offset:33792
	ds_read_b128 v[28:31], v162 offset:34816
	ds_read_b128 v[96:99], v162 offset:35840
	ds_read_b128 v[242:245], v162 offset:36864
	ds_read_b128 v[246:249], v162 offset:37888
	ds_read_b128 v[250:253], v162 offset:38912
	ds_read_b128 v[32:35], v162 offset:39936
	global_load_lds_dwordx4 v153, s[58:59]
	s_mov_b32 m0, s67
	s_nop 0
	global_load_lds_dwordx4 v157, s[58:59]
	s_waitcnt vmcnt(8)
	s_waitcnt lgkmcnt(0)
	s_barrier
	v_mfma_f32_16x16x32_bf16 v[36:39], v[218:221], v[12:15], v[36:39]
	v_mfma_f32_16x16x32_bf16 v[120:123], v[222:225], v[24:27], v[36:39]
	v_mfma_f32_16x16x32_bf16 v[36:39], v[4:7], v[28:31], v[40:43]
	v_mfma_f32_16x16x32_bf16 v[108:111], v[8:11], v[96:99], v[36:39]
	v_mfma_f32_16x16x32_bf16 v[36:39], v[218:221], v[28:31], v[44:47]
	v_mfma_f32_16x16x32_bf16 v[104:107], v[222:225], v[96:99], v[36:39]
	v_mfma_f32_16x16x32_bf16 v[36:39], v[4:7], v[242:245], v[48:51]
	v_mfma_f32_16x16x32_bf16 v[92:95], v[8:11], v[246:249], v[36:39]
	v_mfma_f32_16x16x32_bf16 v[36:39], v[218:221], v[242:245], v[52:55]
	v_mfma_f32_16x16x32_bf16 v[88:91], v[222:225], v[246:249], v[36:39]
	v_mfma_f32_16x16x32_bf16 v[36:39], v[4:7], v[250:253], v[56:59]
	v_mfma_f32_16x16x32_bf16 v[72:75], v[4:7], v[12:15], v[116:119]
	v_mfma_f32_16x16x32_bf16 v[76:79], v[8:11], v[32:35], v[36:39]
	v_mfma_f32_16x16x32_bf16 v[36:39], v[218:221], v[250:253], v[60:63]
	v_mfma_f32_16x16x32_bf16 v[124:127], v[8:11], v[24:27], v[72:75]
	v_mfma_f32_16x16x32_bf16 v[72:75], v[222:225], v[32:35], v[36:39]
	v_mfma_f32_16x16x32_bf16 v[36:39], v[226:229], v[12:15], v[64:67]
	v_mfma_f32_16x16x32_bf16 v[12:15], v[234:237], v[12:15], v[68:71]
	v_mfma_f32_16x16x32_bf16 v[112:115], v[238:241], v[24:27], v[12:15]
	v_mfma_f32_16x16x32_bf16 v[12:15], v[226:229], v[28:31], v[80:83]
	v_mfma_f32_16x16x32_bf16 v[100:103], v[230:233], v[96:99], v[12:15]
	v_mfma_f32_16x16x32_bf16 v[12:15], v[234:237], v[28:31], v[84:87]
	v_mfma_f32_16x16x32_bf16 v[96:99], v[238:241], v[96:99], v[12:15]
	v_mfma_f32_16x16x32_bf16 v[12:15], v[226:229], v[242:245], v[128:131]
	v_mfma_f32_16x16x32_bf16 v[84:87], v[230:233], v[246:249], v[12:15]
	v_mfma_f32_16x16x32_bf16 v[12:15], v[234:237], v[242:245], v[132:135]
	v_mfma_f32_16x16x32_bf16 v[80:83], v[238:241], v[246:249], v[12:15]
	v_mfma_f32_16x16x32_bf16 v[12:15], v[226:229], v[250:253], v[136:139]
	v_mfma_f32_16x16x32_bf16 v[68:71], v[230:233], v[32:35], v[12:15]
	v_mfma_f32_16x16x32_bf16 v[12:15], v[234:237], v[250:253], v[140:143]
	v_mfma_f32_16x16x32_bf16 v[116:119], v[230:233], v[24:27], v[36:39]
	v_mfma_f32_16x16x32_bf16 v[60:63], v[238:241], v[32:35], v[12:15]
	s_barrier
	s_add_i32 s49, s74, s26
	s_mov_b32 m0, s49
	s_add_i32 s79, s49, 0x2000
	ds_read_b128 v[32:35], v162 offset:49152
	ds_read_b128 v[36:39], v162 offset:50176
	ds_read_b128 v[128:131], v162 offset:51200
	ds_read_b128 v[132:135], v162 offset:52224
	ds_read_b128 v[136:139], v162 offset:53248
	ds_read_b128 v[140:143], v162 offset:54272
	ds_read_b128 v[242:245], v162 offset:55296
	ds_read_b128 v[246:249], v162 offset:56320
	global_load_lds_dwordx4 v156, s[56:57]
	s_mov_b32 m0, s79
	s_nop 0
	global_load_lds_dwordx4 v158, s[56:57]
	s_add_u32 s56, s50, 0x80180
	s_addc_u32 s57, s51, 0
	s_add_i32 s80, s75, s26
	s_mov_b32 m0, s80
	s_add_i32 s83, s80, 0x2000
	s_nop 0
	global_load_lds_dwordx4 v156, s[56:57]
	s_mov_b32 m0, s83
	s_nop 0
	global_load_lds_dwordx4 v158, s[56:57]
	s_mov_b32 m0, s68
	s_nop 0
	global_load_lds_dwordx4 v153, s[54:55]
	s_mov_b32 m0, s69
	s_nop 0
	global_load_lds_dwordx4 v157, s[54:55]
	s_waitcnt vmcnt(8)
	s_waitcnt lgkmcnt(0)
	s_barrier
	v_mfma_f32_16x16x32_bf16 v[12:15], v[4:7], v[32:35], v[166:169]
	v_mfma_f32_16x16x32_bf16 v[64:67], v[8:11], v[36:39], v[12:15]
	v_mfma_f32_16x16x32_bf16 v[12:15], v[218:221], v[32:35], v[170:173]
	v_mfma_f32_16x16x32_bf16 v[56:59], v[222:225], v[36:39], v[12:15]
	v_mfma_f32_16x16x32_bf16 v[12:15], v[4:7], v[128:131], v[174:177]
	v_mfma_f32_16x16x32_bf16 v[44:47], v[8:11], v[132:135], v[12:15]
	v_mfma_f32_16x16x32_bf16 v[12:15], v[218:221], v[128:131], v[178:181]
	v_mfma_f32_16x16x32_bf16 v[40:43], v[222:225], v[132:135], v[12:15]
	v_mfma_f32_16x16x32_bf16 v[12:15], v[4:7], v[136:139], v[182:185]
	v_mfma_f32_16x16x32_bf16 v[28:31], v[8:11], v[140:143], v[12:15]
	v_mfma_f32_16x16x32_bf16 v[12:15], v[218:221], v[136:139], v[186:189]
	v_mfma_f32_16x16x32_bf16 v[4:7], v[4:7], v[242:245], v[16:19]
	v_mfma_f32_16x16x32_bf16 v[24:27], v[222:225], v[140:143], v[12:15]
	v_mfma_f32_16x16x32_bf16 v[12:15], v[8:11], v[246:249], v[4:7]
	v_mfma_f32_16x16x32_bf16 v[4:7], v[218:221], v[242:245], v[20:23]
	v_mfma_f32_16x16x32_bf16 v[8:11], v[222:225], v[246:249], v[4:7]
	v_mfma_f32_16x16x32_bf16 v[4:7], v[226:229], v[32:35], v[190:193]
	v_mfma_f32_16x16x32_bf16 v[52:55], v[230:233], v[36:39], v[4:7]
	v_mfma_f32_16x16x32_bf16 v[4:7], v[234:237], v[32:35], v[194:197]
	v_mfma_f32_16x16x32_bf16 v[48:51], v[238:241], v[36:39], v[4:7]
	v_mfma_f32_16x16x32_bf16 v[4:7], v[226:229], v[128:131], v[198:201]
	v_mfma_f32_16x16x32_bf16 v[36:39], v[230:233], v[132:135], v[4:7]
	v_mfma_f32_16x16x32_bf16 v[4:7], v[234:237], v[128:131], v[202:205]
	v_mfma_f32_16x16x32_bf16 v[32:35], v[238:241], v[132:135], v[4:7]
	v_mfma_f32_16x16x32_bf16 v[4:7], v[226:229], v[136:139], v[206:209]
	v_mfma_f32_16x16x32_bf16 v[20:23], v[230:233], v[140:143], v[4:7]
	v_mfma_f32_16x16x32_bf16 v[4:7], v[234:237], v[136:139], v[210:213]
	v_mfma_f32_16x16x32_bf16 v[0:3], v[226:229], v[242:245], v[0:3]
	v_mfma_f32_16x16x32_bf16 v[16:19], v[238:241], v[140:143], v[4:7]
	v_mfma_f32_16x16x32_bf16 v[4:7], v[230:233], v[246:249], v[0:3]
	v_mfma_f32_16x16x32_bf16 v[0:3], v[234:237], v[242:245], v[214:217]
	v_mfma_f32_16x16x32_bf16 v[0:3], v[238:241], v[246:249], v[0:3]
	s_barrier
	s_add_u32 s58, s52, 0x100
	s_addc_u32 s59, s53, 0
	s_add_u32 s86, s50, 0x200
	s_addc_u32 s88, s51, 0
	s_mov_b32 s89, 0
.LBB0_1590:
	s_add_u32 s50, s58, 0x100
	s_addc_u32 s51, s59, 0
	s_cmp_eq_u32 s89, 28
	s_cselect_b32 s56, s47, s50
	s_cselect_b32 s57, s35, s51
	s_cselect_b32 s54, s21, s86
	s_cselect_b32 s55, s20, s88
	s_add_u32 s52, s56, 0x80
	s_addc_u32 s53, s57, 0
	s_add_i32 s90, 0, 0x10000
	s_add_i32 s91, 0, 0x14000
	v_add_u32_e32 v140, s90, v159
	v_add_u32_e32 v149, s91, v159
	ds_read_b128 v[128:131], v140
	ds_read_b128 v[132:135], v140 offset:1024
	ds_read_b128 v[136:139], v140 offset:2048
	ds_read_b128 v[140:143], v140 offset:3072
	ds_read_b128 v[166:169], v149
	ds_read_b128 v[170:173], v149 offset:1024
	ds_read_b128 v[174:177], v149 offset:2048
	ds_read_b128 v[178:181], v149 offset:3072
	s_add_u32 s58, s58, 0x80080
	s_addc_u32 s59, s59, 0
	s_mov_b32 m0, s1
	ds_read_b128 v[182:185], v162
	ds_read_b128 v[186:189], v162 offset:1024
	ds_read_b128 v[190:193], v162 offset:2048
	ds_read_b128 v[194:197], v162 offset:3072
	ds_read_b128 v[198:201], v162 offset:4096
	ds_read_b128 v[202:205], v162 offset:5120
	ds_read_b128 v[206:209], v162 offset:6144
	ds_read_b128 v[210:213], v162 offset:7168
	global_load_lds_dwordx4 v153, s[58:59]
	s_mov_b32 m0, s12
	s_nop 0
	global_load_lds_dwordx4 v157, s[58:59]
	s_waitcnt vmcnt(8)
	s_waitcnt lgkmcnt(0)
	s_barrier
	v_mfma_f32_16x16x32_bf16 v[124:127], v[128:131], v[182:185], v[124:127]
	v_mfma_f32_16x16x32_bf16 v[120:123], v[136:139], v[182:185], v[120:123]
	v_mfma_f32_16x16x32_bf16 v[108:111], v[128:131], v[190:193], v[108:111]
	v_mfma_f32_16x16x32_bf16 v[104:107], v[136:139], v[190:193], v[104:107]
	v_mfma_f32_16x16x32_bf16 v[92:95], v[128:131], v[198:201], v[92:95]
	v_mfma_f32_16x16x32_bf16 v[88:91], v[136:139], v[198:201], v[88:91]
	v_mfma_f32_16x16x32_bf16 v[76:79], v[128:131], v[206:209], v[76:79]
	v_mfma_f32_16x16x32_bf16 v[72:75], v[136:139], v[206:209], v[72:75]
	v_mfma_f32_16x16x32_bf16 v[124:127], v[132:135], v[186:189], v[124:127]
	v_mfma_f32_16x16x32_bf16 v[120:123], v[140:143], v[186:189], v[120:123]
	v_mfma_f32_16x16x32_bf16 v[108:111], v[132:135], v[194:197], v[108:111]
	v_mfma_f32_16x16x32_bf16 v[104:107], v[140:143], v[194:197], v[104:107]
	v_mfma_f32_16x16x32_bf16 v[92:95], v[132:135], v[202:205], v[92:95]
	v_mfma_f32_16x16x32_bf16 v[88:91], v[140:143], v[202:205], v[88:91]
	v_mfma_f32_16x16x32_bf16 v[76:79], v[132:135], v[210:213], v[76:79]
	v_mfma_f32_16x16x32_bf16 v[72:75], v[140:143], v[210:213], v[72:75]
	v_mfma_f32_16x16x32_bf16 v[116:119], v[166:169], v[182:185], v[116:119]
	v_mfma_f32_16x16x32_bf16 v[112:115], v[174:177], v[182:185], v[112:115]
	v_mfma_f32_16x16x32_bf16 v[100:103], v[166:169], v[190:193], v[100:103]
	v_mfma_f32_16x16x32_bf16 v[96:99], v[174:177], v[190:193], v[96:99]
	v_mfma_f32_16x16x32_bf16 v[84:87], v[166:169], v[198:201], v[84:87]
	v_mfma_f32_16x16x32_bf16 v[80:83], v[174:177], v[198:201], v[80:83]
	v_mfma_f32_16x16x32_bf16 v[68:71], v[166:169], v[206:209], v[68:71]
	v_mfma_f32_16x16x32_bf16 v[60:63], v[174:177], v[206:209], v[60:63]
	v_mfma_f32_16x16x32_bf16 v[116:119], v[170:173], v[186:189], v[116:119]
	v_mfma_f32_16x16x32_bf16 v[112:115], v[178:181], v[186:189], v[112:115]
	v_mfma_f32_16x16x32_bf16 v[100:103], v[170:173], v[194:197], v[100:103]
	v_mfma_f32_16x16x32_bf16 v[96:99], v[178:181], v[194:197], v[96:99]
	v_mfma_f32_16x16x32_bf16 v[84:87], v[170:173], v[202:205], v[84:87]
	v_mfma_f32_16x16x32_bf16 v[80:83], v[178:181], v[202:205], v[80:83]
	v_mfma_f32_16x16x32_bf16 v[68:71], v[170:173], v[210:213], v[68:71]
	v_mfma_f32_16x16x32_bf16 v[60:63], v[178:181], v[210:213], v[60:63]
	s_barrier
	s_add_i32 s58, s90, s26
	s_mov_b32 m0, s58
	ds_read_b128 v[182:185], v162 offset:16384
	ds_read_b128 v[186:189], v162 offset:17408
	ds_read_b128 v[190:193], v162 offset:18432
	ds_read_b128 v[194:197], v162 offset:19456
	ds_read_b128 v[198:201], v162 offset:20480
	ds_read_b128 v[202:205], v162 offset:21504
	ds_read_b128 v[206:209], v162 offset:22528
	ds_read_b128 v[210:213], v162 offset:23552
	global_load_lds_dwordx4 v156, s[54:55]
	s_add_i32 m0, s58, 0x2000
	s_add_u32 s58, s54, 0x80000
	s_addc_u32 s59, s55, 0
	s_add_i32 s90, s91, s26
	s_nop 0
	global_load_lds_dwordx4 v158, s[54:55]
	s_mov_b32 m0, s90
	s_nop 0
	global_load_lds_dwordx4 v156, s[58:59]
	s_add_i32 m0, s90, 0x2000
	s_nop 0
	global_load_lds_dwordx4 v158, s[58:59]
	s_mov_b32 m0, s27
	s_nop 0
	global_load_lds_dwordx4 v153, s[56:57]
	s_mov_b32 m0, s65
	s_nop 0
	global_load_lds_dwordx4 v157, s[56:57]
	s_waitcnt vmcnt(8)
	s_waitcnt lgkmcnt(0)
	s_barrier
	v_mfma_f32_16x16x32_bf16 v[64:67], v[128:131], v[182:185], v[64:67]
	v_mfma_f32_16x16x32_bf16 v[56:59], v[136:139], v[182:185], v[56:59]
	v_mfma_f32_16x16x32_bf16 v[44:47], v[128:131], v[190:193], v[44:47]
	v_mfma_f32_16x16x32_bf16 v[40:43], v[136:139], v[190:193], v[40:43]
	v_mfma_f32_16x16x32_bf16 v[28:31], v[128:131], v[198:201], v[28:31]
	v_mfma_f32_16x16x32_bf16 v[24:27], v[136:139], v[198:201], v[24:27]
	v_mfma_f32_16x16x32_bf16 v[12:15], v[128:131], v[206:209], v[12:15]
	v_mfma_f32_16x16x32_bf16 v[8:11], v[136:139], v[206:209], v[8:11]
	v_mfma_f32_16x16x32_bf16 v[64:67], v[132:135], v[186:189], v[64:67]
	v_mfma_f32_16x16x32_bf16 v[56:59], v[140:143], v[186:189], v[56:59]
	v_mfma_f32_16x16x32_bf16 v[44:47], v[132:135], v[194:197], v[44:47]
	v_mfma_f32_16x16x32_bf16 v[40:43], v[140:143], v[194:197], v[40:43]
	v_mfma_f32_16x16x32_bf16 v[28:31], v[132:135], v[202:205], v[28:31]
	v_mfma_f32_16x16x32_bf16 v[24:27], v[140:143], v[202:205], v[24:27]
	v_mfma_f32_16x16x32_bf16 v[12:15], v[132:135], v[210:213], v[12:15]
	v_mfma_f32_16x16x32_bf16 v[8:11], v[140:143], v[210:213], v[8:11]
	v_mfma_f32_16x16x32_bf16 v[52:55], v[166:169], v[182:185], v[52:55]
	v_mfma_f32_16x16x32_bf16 v[48:51], v[174:177], v[182:185], v[48:51]
	v_mfma_f32_16x16x32_bf16 v[36:39], v[166:169], v[190:193], v[36:39]
	v_mfma_f32_16x16x32_bf16 v[32:35], v[174:177], v[190:193], v[32:35]
	v_mfma_f32_16x16x32_bf16 v[20:23], v[166:169], v[198:201], v[20:23]
	v_mfma_f32_16x16x32_bf16 v[16:19], v[174:177], v[198:201], v[16:19]
	v_mfma_f32_16x16x32_bf16 v[4:7], v[166:169], v[206:209], v[4:7]
	v_mfma_f32_16x16x32_bf16 v[0:3], v[174:177], v[206:209], v[0:3]
	v_mfma_f32_16x16x32_bf16 v[52:55], v[170:173], v[186:189], v[52:55]
	v_mfma_f32_16x16x32_bf16 v[48:51], v[178:181], v[186:189], v[48:51]
	v_mfma_f32_16x16x32_bf16 v[36:39], v[170:173], v[194:197], v[36:39]
	v_mfma_f32_16x16x32_bf16 v[32:35], v[178:181], v[194:197], v[32:35]
	v_mfma_f32_16x16x32_bf16 v[20:23], v[170:173], v[202:205], v[20:23]
	v_mfma_f32_16x16x32_bf16 v[16:19], v[178:181], v[202:205], v[16:19]
	v_mfma_f32_16x16x32_bf16 v[4:7], v[170:173], v[210:213], v[4:7]
	v_mfma_f32_16x16x32_bf16 v[0:3], v[178:181], v[210:213], v[0:3]
	s_barrier
	ds_read_b128 v[128:131], v144
	ds_read_b128 v[132:135], v144 offset:1024
	ds_read_b128 v[136:139], v144 offset:2048
	ds_read_b128 v[140:143], v144 offset:3072
	ds_read_b128 v[166:169], v148
	ds_read_b128 v[170:173], v148 offset:1024
	ds_read_b128 v[174:177], v148 offset:2048
	ds_read_b128 v[178:181], v148 offset:3072
	s_add_u32 s56, s56, 0x80000
	s_addc_u32 s57, s57, 0
	s_mov_b32 m0, s66
	ds_read_b128 v[182:185], v162 offset:32768
	ds_read_b128 v[186:189], v162 offset:33792
	ds_read_b128 v[190:193], v162 offset:34816
	ds_read_b128 v[194:197], v162 offset:35840
	ds_read_b128 v[198:201], v162 offset:36864
	ds_read_b128 v[202:205], v162 offset:37888
	ds_read_b128 v[206:209], v162 offset:38912
	ds_read_b128 v[210:213], v162 offset:39936
	global_load_lds_dwordx4 v153, s[56:57]
	s_mov_b32 m0, s67
	s_nop 0
	global_load_lds_dwordx4 v157, s[56:57]
	s_waitcnt vmcnt(8)
	s_waitcnt lgkmcnt(0)
	s_barrier
	v_mfma_f32_16x16x32_bf16 v[124:127], v[128:131], v[182:185], v[124:127]
	v_mfma_f32_16x16x32_bf16 v[120:123], v[136:139], v[182:185], v[120:123]
	v_mfma_f32_16x16x32_bf16 v[108:111], v[128:131], v[190:193], v[108:111]
	v_mfma_f32_16x16x32_bf16 v[104:107], v[136:139], v[190:193], v[104:107]
	v_mfma_f32_16x16x32_bf16 v[92:95], v[128:131], v[198:201], v[92:95]
	v_mfma_f32_16x16x32_bf16 v[88:91], v[136:139], v[198:201], v[88:91]
	v_mfma_f32_16x16x32_bf16 v[76:79], v[128:131], v[206:209], v[76:79]
	v_mfma_f32_16x16x32_bf16 v[72:75], v[136:139], v[206:209], v[72:75]
	v_mfma_f32_16x16x32_bf16 v[124:127], v[132:135], v[186:189], v[124:127]
	v_mfma_f32_16x16x32_bf16 v[120:123], v[140:143], v[186:189], v[120:123]
	v_mfma_f32_16x16x32_bf16 v[108:111], v[132:135], v[194:197], v[108:111]
	v_mfma_f32_16x16x32_bf16 v[104:107], v[140:143], v[194:197], v[104:107]
	v_mfma_f32_16x16x32_bf16 v[92:95], v[132:135], v[202:205], v[92:95]
	v_mfma_f32_16x16x32_bf16 v[88:91], v[140:143], v[202:205], v[88:91]
	v_mfma_f32_16x16x32_bf16 v[76:79], v[132:135], v[210:213], v[76:79]
	v_mfma_f32_16x16x32_bf16 v[72:75], v[140:143], v[210:213], v[72:75]
	v_mfma_f32_16x16x32_bf16 v[116:119], v[166:169], v[182:185], v[116:119]
	v_mfma_f32_16x16x32_bf16 v[112:115], v[174:177], v[182:185], v[112:115]
	v_mfma_f32_16x16x32_bf16 v[100:103], v[166:169], v[190:193], v[100:103]
	v_mfma_f32_16x16x32_bf16 v[96:99], v[174:177], v[190:193], v[96:99]
	v_mfma_f32_16x16x32_bf16 v[84:87], v[166:169], v[198:201], v[84:87]
	v_mfma_f32_16x16x32_bf16 v[80:83], v[174:177], v[198:201], v[80:83]
	v_mfma_f32_16x16x32_bf16 v[68:71], v[166:169], v[206:209], v[68:71]
	v_mfma_f32_16x16x32_bf16 v[60:63], v[174:177], v[206:209], v[60:63]
	v_mfma_f32_16x16x32_bf16 v[116:119], v[170:173], v[186:189], v[116:119]
	v_mfma_f32_16x16x32_bf16 v[112:115], v[178:181], v[186:189], v[112:115]
	v_mfma_f32_16x16x32_bf16 v[100:103], v[170:173], v[194:197], v[100:103]
	v_mfma_f32_16x16x32_bf16 v[96:99], v[178:181], v[194:197], v[96:99]
	v_mfma_f32_16x16x32_bf16 v[84:87], v[170:173], v[202:205], v[84:87]
	v_mfma_f32_16x16x32_bf16 v[80:83], v[178:181], v[202:205], v[80:83]
	v_mfma_f32_16x16x32_bf16 v[68:71], v[170:173], v[210:213], v[68:71]
	v_mfma_f32_16x16x32_bf16 v[60:63], v[178:181], v[210:213], v[60:63]
	s_barrier
	s_add_u32 s56, s54, 0x80
	s_mov_b32 m0, s49
	s_addc_u32 s57, s55, 0
	ds_read_b128 v[182:185], v162 offset:49152
	ds_read_b128 v[186:189], v162 offset:50176
	ds_read_b128 v[190:193], v162 offset:51200
	ds_read_b128 v[194:197], v162 offset:52224
	ds_read_b128 v[198:201], v162 offset:53248
	ds_read_b128 v[202:205], v162 offset:54272
	ds_read_b128 v[206:209], v162 offset:55296
	ds_read_b128 v[210:213], v162 offset:56320
	s_add_u32 s54, s54, 0x80080
	global_load_lds_dwordx4 v156, s[56:57]
	s_mov_b32 m0, s79
	s_addc_u32 s55, s55, 0
	global_load_lds_dwordx4 v158, s[56:57]
	s_mov_b32 m0, s80
	s_nop 0
	global_load_lds_dwordx4 v156, s[54:55]
	s_mov_b32 m0, s83
	s_nop 0
	global_load_lds_dwordx4 v158, s[54:55]
	s_mov_b32 m0, s68
	s_nop 0
	global_load_lds_dwordx4 v153, s[52:53]
	s_mov_b32 m0, s69
	s_nop 0
	global_load_lds_dwordx4 v157, s[52:53]
	s_waitcnt vmcnt(8)
	s_waitcnt lgkmcnt(0)
	s_barrier
	v_mfma_f32_16x16x32_bf16 v[64:67], v[128:131], v[182:185], v[64:67]
	v_mfma_f32_16x16x32_bf16 v[56:59], v[136:139], v[182:185], v[56:59]
	v_mfma_f32_16x16x32_bf16 v[44:47], v[128:131], v[190:193], v[44:47]
	v_mfma_f32_16x16x32_bf16 v[40:43], v[136:139], v[190:193], v[40:43]
	v_mfma_f32_16x16x32_bf16 v[28:31], v[128:131], v[198:201], v[28:31]
	v_mfma_f32_16x16x32_bf16 v[24:27], v[136:139], v[198:201], v[24:27]
	v_mfma_f32_16x16x32_bf16 v[12:15], v[128:131], v[206:209], v[12:15]
	v_mfma_f32_16x16x32_bf16 v[8:11], v[136:139], v[206:209], v[8:11]
	v_mfma_f32_16x16x32_bf16 v[64:67], v[132:135], v[186:189], v[64:67]
	v_mfma_f32_16x16x32_bf16 v[56:59], v[140:143], v[186:189], v[56:59]
	v_mfma_f32_16x16x32_bf16 v[44:47], v[132:135], v[194:197], v[44:47]
	v_mfma_f32_16x16x32_bf16 v[40:43], v[140:143], v[194:197], v[40:43]
	v_mfma_f32_16x16x32_bf16 v[28:31], v[132:135], v[202:205], v[28:31]
	v_mfma_f32_16x16x32_bf16 v[24:27], v[140:143], v[202:205], v[24:27]
	v_mfma_f32_16x16x32_bf16 v[12:15], v[132:135], v[210:213], v[12:15]
	v_mfma_f32_16x16x32_bf16 v[8:11], v[140:143], v[210:213], v[8:11]
	v_mfma_f32_16x16x32_bf16 v[52:55], v[166:169], v[182:185], v[52:55]
	v_mfma_f32_16x16x32_bf16 v[48:51], v[174:177], v[182:185], v[48:51]
	v_mfma_f32_16x16x32_bf16 v[36:39], v[166:169], v[190:193], v[36:39]
	v_mfma_f32_16x16x32_bf16 v[32:35], v[174:177], v[190:193], v[32:35]
	v_mfma_f32_16x16x32_bf16 v[20:23], v[166:169], v[198:201], v[20:23]
	v_mfma_f32_16x16x32_bf16 v[16:19], v[174:177], v[198:201], v[16:19]
	v_mfma_f32_16x16x32_bf16 v[4:7], v[166:169], v[206:209], v[4:7]
	v_mfma_f32_16x16x32_bf16 v[0:3], v[174:177], v[206:209], v[0:3]
	v_mfma_f32_16x16x32_bf16 v[52:55], v[170:173], v[186:189], v[52:55]
	v_mfma_f32_16x16x32_bf16 v[48:51], v[178:181], v[186:189], v[48:51]
	v_mfma_f32_16x16x32_bf16 v[36:39], v[170:173], v[194:197], v[36:39]
	v_mfma_f32_16x16x32_bf16 v[32:35], v[178:181], v[194:197], v[32:35]
	v_mfma_f32_16x16x32_bf16 v[20:23], v[170:173], v[202:205], v[20:23]
	v_mfma_f32_16x16x32_bf16 v[16:19], v[178:181], v[202:205], v[16:19]
	v_mfma_f32_16x16x32_bf16 v[4:7], v[170:173], v[210:213], v[4:7]
	v_mfma_f32_16x16x32_bf16 v[0:3], v[178:181], v[210:213], v[0:3]
	s_barrier
	s_add_i32 s89, s89, 2
	s_add_u32 s86, s86, 0x100
	s_addc_u32 s88, s88, 0
	s_cmp_gt_u32 s89, 29
	s_mov_b64 s[58:59], s[50:51]
	s_cbranch_scc0 .LBB0_1590
	s_and_b64 vcc, exec, s[4:5]
	s_cbranch_vccz .LBB0_1593
	s_barrier

.LBB0_1701:
	s_add_u32 s20, s56, 0x100
	s_addc_u32 s21, s57, 0
	s_waitcnt lgkmcnt(0)
	s_add_u32 s60, s54, 0x100
	s_addc_u32 s61, s55, 0
	s_barrier
	s_waitcnt lgkmcnt(0)
	v_mfma_f32_16x16x32_bf16 v[32:35], v[16:19], v[68:71], 0
	v_mfma_f32_16x16x32_bf16 v[36:39], v[24:27], v[68:71], 0
	v_mfma_f32_16x16x32_bf16 v[40:43], v[16:19], v[76:79], 0
	v_mfma_f32_16x16x32_bf16 v[44:47], v[24:27], v[76:79], 0
	v_mfma_f32_16x16x32_bf16 v[48:51], v[16:19], v[84:87], 0
	v_mfma_f32_16x16x32_bf16 v[52:55], v[24:27], v[84:87], 0
	v_mfma_f32_16x16x32_bf16 v[56:59], v[16:19], v[88:91], 0
	v_mfma_f32_16x16x32_bf16 v[60:63], v[24:27], v[88:91], 0
	v_mfma_f32_16x16x32_bf16 v[136:139], v[20:23], v[72:75], v[32:35]
	v_mfma_f32_16x16x32_bf16 v[140:143], v[28:31], v[72:75], v[36:39]
	v_mfma_f32_16x16x32_bf16 v[40:43], v[20:23], v[80:83], v[40:43]
	v_mfma_f32_16x16x32_bf16 v[44:47], v[28:31], v[80:83], v[44:47]
	v_mfma_f32_16x16x32_bf16 v[48:51], v[20:23], v[96:99], v[48:51]
	v_mfma_f32_16x16x32_bf16 v[52:55], v[28:31], v[96:99], v[52:55]
	v_mfma_f32_16x16x32_bf16 v[56:59], v[20:23], v[92:95], v[56:59]
	v_mfma_f32_16x16x32_bf16 v[60:63], v[28:31], v[92:95], v[60:63]
	v_mfma_f32_16x16x32_bf16 v[64:67], v[0:3], v[68:71], 0
	v_mfma_f32_16x16x32_bf16 v[68:71], v[8:11], v[68:71], 0
	v_mfma_f32_16x16x32_bf16 v[64:67], v[4:7], v[72:75], v[64:67]
	v_mfma_f32_16x16x32_bf16 v[68:71], v[12:15], v[72:75], v[68:71]
	v_mfma_f32_16x16x32_bf16 v[72:75], v[0:3], v[76:79], 0
	v_mfma_f32_16x16x32_bf16 v[76:79], v[8:11], v[76:79], 0
	v_mfma_f32_16x16x32_bf16 v[72:75], v[4:7], v[80:83], v[72:75]
	v_mfma_f32_16x16x32_bf16 v[76:79], v[12:15], v[80:83], v[76:79]
	v_mfma_f32_16x16x32_bf16 v[80:83], v[0:3], v[84:87], 0
	v_mfma_f32_16x16x32_bf16 v[84:87], v[8:11], v[84:87], 0
	v_mfma_f32_16x16x32_bf16 v[80:83], v[4:7], v[96:99], v[80:83]
	v_mfma_f32_16x16x32_bf16 v[84:87], v[12:15], v[96:99], v[84:87]
	v_mfma_f32_16x16x32_bf16 v[96:99], v[0:3], v[88:91], 0
	v_mfma_f32_16x16x32_bf16 v[88:91], v[8:11], v[88:91], 0
	v_mfma_f32_16x16x32_bf16 v[100:103], v[4:7], v[92:95], v[96:99]
	v_mfma_f32_16x16x32_bf16 v[104:107], v[12:15], v[92:95], v[88:91]
	s_barrier
	s_mov_b32 m0, s65
	ds_read_b128 v[120:123], v206 offset:16384
	ds_read_b128 v[124:127], v206 offset:17408
	ds_read_b128 v[112:115], v206 offset:18432
	ds_read_b128 v[116:119], v206 offset:19456
	ds_read_b128 v[96:99], v206 offset:20480
	ds_read_b128 v[108:111], v206 offset:21504
	ds_read_b128 v[88:91], v206 offset:22528
	ds_read_b128 v[92:95], v206 offset:23552
	global_load_lds_dwordx4 v200, s[60:61]
	s_mov_b32 m0, s66
	s_nop 0
	global_load_lds_dwordx4 v202, s[60:61]
	s_add_u32 s60, s54, 0x20100
	s_addc_u32 s61, s55, 0
	s_mov_b32 m0, s67
	s_and_b64 vcc, exec, s[50:51]
	global_load_lds_dwordx4 v200, s[60:61]
	s_mov_b32 m0, s68
	s_nop 0
	global_load_lds_dwordx4 v202, s[60:61]
	s_mov_b32 m0, s27
	s_mov_b64 s[60:61], -1
	global_load_lds_dwordx4 v199, s[20:21]
	s_mov_b32 m0, s69
	s_nop 0
	global_load_lds_dwordx4 v201, s[20:21]
	s_cbranch_vccz .LBB0_1703
	s_waitcnt vmcnt(8)
	s_mov_b64 s[60:61], 0

.LBB0_1705:
	s_ashr_i32 s47, s46, 31
	s_lshl_b64 s[20:21], s[46:47], 18
	s_add_u32 s50, s24, s20
	s_addc_u32 s51, s25, s21
	s_add_u32 s60, s56, 0x180
	s_addc_u32 s61, s57, 0
	s_waitcnt lgkmcnt(0)
	s_and_b64 s[20:21], s[58:59], exec
	s_cselect_b32 s12, s51, s55
	s_cselect_b32 s20, s50, s54
	s_add_u32 s58, s54, 0x180
	s_addc_u32 s59, s55, 0
	s_barrier
	s_waitcnt lgkmcnt(0)
	v_mfma_f32_16x16x32_bf16 v[128:131], v[16:19], v[120:123], 0
	v_mfma_f32_16x16x32_bf16 v[132:135], v[20:23], v[124:127], v[128:131]
	v_mfma_f32_16x16x32_bf16 v[128:131], v[24:27], v[120:123], 0
	v_mfma_f32_16x16x32_bf16 v[144:147], v[28:31], v[124:127], v[128:131]
	v_mfma_f32_16x16x32_bf16 v[128:131], v[16:19], v[112:115], 0
	v_mfma_f32_16x16x32_bf16 v[152:155], v[20:23], v[116:119], v[128:131]
	v_mfma_f32_16x16x32_bf16 v[128:131], v[24:27], v[112:115], 0
	v_mfma_f32_16x16x32_bf16 v[168:171], v[28:31], v[116:119], v[128:131]
	v_mfma_f32_16x16x32_bf16 v[128:131], v[16:19], v[96:99], 0
	v_mfma_f32_16x16x32_bf16 v[16:19], v[16:19], v[88:91], 0
	v_mfma_f32_16x16x32_bf16 v[172:175], v[20:23], v[108:111], v[128:131]
	v_mfma_f32_16x16x32_bf16 v[16:19], v[20:23], v[92:95], v[16:19]
	v_mfma_f32_16x16x32_bf16 v[20:23], v[24:27], v[88:91], 0
	v_mfma_f32_16x16x32_bf16 v[128:131], v[24:27], v[96:99], 0
	v_mfma_f32_16x16x32_bf16 v[20:23], v[28:31], v[92:95], v[20:23]
	v_mfma_f32_16x16x32_bf16 v[176:179], v[28:31], v[108:111], v[128:131]
	v_mfma_f32_16x16x32_bf16 v[24:27], v[0:3], v[120:123], 0
	v_mfma_f32_16x16x32_bf16 v[180:183], v[4:7], v[124:127], v[24:27]
	v_mfma_f32_16x16x32_bf16 v[24:27], v[8:11], v[120:123], 0
	v_mfma_f32_16x16x32_bf16 v[188:191], v[12:15], v[124:127], v[24:27]
	v_mfma_f32_16x16x32_bf16 v[24:27], v[0:3], v[112:115], 0
	v_mfma_f32_16x16x32_bf16 v[192:195], v[4:7], v[116:119], v[24:27]
	v_mfma_f32_16x16x32_bf16 v[24:27], v[8:11], v[112:115], 0
	v_mfma_f32_16x16x32_bf16 v[208:211], v[12:15], v[116:119], v[24:27]
	v_mfma_f32_16x16x32_bf16 v[24:27], v[0:3], v[96:99], 0
	v_mfma_f32_16x16x32_bf16 v[0:3], v[0:3], v[88:91], 0
	v_mfma_f32_16x16x32_bf16 v[212:215], v[4:7], v[108:111], v[24:27]
	v_mfma_f32_16x16x32_bf16 v[24:27], v[8:11], v[96:99], 0
	v_mfma_f32_16x16x32_bf16 v[0:3], v[4:7], v[92:95], v[0:3]
	v_mfma_f32_16x16x32_bf16 v[4:7], v[8:11], v[88:91], 0
	v_mfma_f32_16x16x32_bf16 v[216:219], v[12:15], v[108:111], v[24:27]
	v_mfma_f32_16x16x32_bf16 v[220:223], v[12:15], v[92:95], v[4:7]
	s_barrier
	v_add_u32_e32 v124, s78, v203
	v_add_u32_e32 v125, s83, v203
	s_nop 1
	ds_read_b128 v[4:7], v124
	ds_read_b128 v[8:11], v124 offset:1024
	ds_read_b128 v[224:227], v124 offset:2048
	ds_read_b128 v[228:231], v124 offset:3072
	ds_read_b128 v[232:235], v125
	ds_read_b128 v[236:239], v125 offset:1024
	ds_read_b128 v[240:243], v125 offset:2048
	ds_read_b128 v[244:247], v125 offset:3072
	s_add_u32 s62, s56, 0x70100
	s_addc_u32 s63, s57, 0
	s_mov_b32 m0, s70
	ds_read_b128 v[12:15], v206 offset:32768
	ds_read_b128 v[24:27], v206 offset:33792
	ds_read_b128 v[28:31], v206 offset:34816
	ds_read_b128 v[96:99], v206 offset:35840
	ds_read_b128 v[248:251], v206 offset:36864
	ds_read_b128 v[184:187], v206 offset:37888
	ds_read_b128 v[32:35], v206 offset:38912
	ds_read_b128 v[36:39], v206 offset:39936
	global_load_lds_dwordx4 v199, s[62:63]
	s_mov_b32 m0, s71
	s_nop 0
	global_load_lds_dwordx4 v201, s[62:63]
	s_waitcnt vmcnt(8)
	s_waitcnt lgkmcnt(0)
	s_barrier
	v_mfma_f32_16x16x32_bf16 v[88:91], v[4:7], v[12:15], v[136:139]
	v_mfma_f32_16x16x32_bf16 v[40:43], v[4:7], v[28:31], v[40:43]
	v_mfma_f32_16x16x32_bf16 v[164:167], v[8:11], v[24:27], v[88:91]
	v_mfma_f32_16x16x32_bf16 v[88:91], v[224:227], v[12:15], v[140:143]
	v_mfma_f32_16x16x32_bf16 v[140:143], v[8:11], v[96:99], v[40:43]
	v_mfma_f32_16x16x32_bf16 v[40:43], v[224:227], v[28:31], v[44:47]
	v_mfma_f32_16x16x32_bf16 v[136:139], v[228:231], v[96:99], v[40:43]
	v_mfma_f32_16x16x32_bf16 v[40:43], v[4:7], v[248:251], v[48:51]
	v_mfma_f32_16x16x32_bf16 v[116:119], v[8:11], v[184:187], v[40:43]
	v_mfma_f32_16x16x32_bf16 v[40:43], v[224:227], v[248:251], v[52:55]
	v_mfma_f32_16x16x32_bf16 v[112:115], v[228:231], v[184:187], v[40:43]
	v_mfma_f32_16x16x32_bf16 v[40:43], v[4:7], v[32:35], v[56:59]
	v_mfma_f32_16x16x32_bf16 v[92:95], v[8:11], v[36:39], v[40:43]
	v_mfma_f32_16x16x32_bf16 v[40:43], v[224:227], v[32:35], v[60:63]
	v_mfma_f32_16x16x32_bf16 v[160:163], v[228:231], v[24:27], v[88:91]
	v_mfma_f32_16x16x32_bf16 v[88:91], v[228:231], v[36:39], v[40:43]
	v_mfma_f32_16x16x32_bf16 v[40:43], v[232:235], v[12:15], v[64:67]
	v_mfma_f32_16x16x32_bf16 v[12:15], v[240:243], v[12:15], v[68:71]
	v_mfma_f32_16x16x32_bf16 v[148:151], v[244:247], v[24:27], v[12:15]
	v_mfma_f32_16x16x32_bf16 v[12:15], v[232:235], v[28:31], v[72:75]
	v_mfma_f32_16x16x32_bf16 v[128:131], v[236:239], v[96:99], v[12:15]
	v_mfma_f32_16x16x32_bf16 v[12:15], v[240:243], v[28:31], v[76:79]
	v_mfma_f32_16x16x32_bf16 v[120:123], v[244:247], v[96:99], v[12:15]
	v_mfma_f32_16x16x32_bf16 v[12:15], v[232:235], v[248:251], v[80:83]
	v_mfma_f32_16x16x32_bf16 v[108:111], v[236:239], v[184:187], v[12:15]
	v_mfma_f32_16x16x32_bf16 v[12:15], v[240:243], v[248:251], v[84:87]
	v_mfma_f32_16x16x32_bf16 v[96:99], v[244:247], v[184:187], v[12:15]
	v_mfma_f32_16x16x32_bf16 v[12:15], v[232:235], v[32:35], v[100:103]
	v_mfma_f32_16x16x32_bf16 v[84:87], v[236:239], v[36:39], v[12:15]
	v_mfma_f32_16x16x32_bf16 v[12:15], v[240:243], v[32:35], v[104:107]
	v_mfma_f32_16x16x32_bf16 v[156:159], v[236:239], v[24:27], v[40:43]
	v_mfma_f32_16x16x32_bf16 v[72:75], v[244:247], v[36:39], v[12:15]
	s_barrier
	s_add_i32 s21, s78, s26
	s_mov_b32 m0, s21
	s_add_i32 s45, s21, 0x2000
	ds_read_b128 v[32:35], v206 offset:49152
	ds_read_b128 v[36:39], v206 offset:50176
	ds_read_b128 v[48:51], v206 offset:51200
	ds_read_b128 v[52:55], v206 offset:52224
	ds_read_b128 v[76:79], v206 offset:53248
	ds_read_b128 v[80:83], v206 offset:54272
	ds_read_b128 v[100:103], v206 offset:55296
	ds_read_b128 v[104:107], v206 offset:56320
	global_load_lds_dwordx4 v200, s[58:59]
	s_mov_b32 m0, s45
	s_nop 0
	global_load_lds_dwordx4 v202, s[58:59]
	s_add_u32 s58, s54, 0x20180
	s_addc_u32 s59, s55, 0
	s_add_i32 s47, s83, s26
	s_mov_b32 m0, s47
	s_add_i32 s53, s47, 0x2000
	s_nop 0
	global_load_lds_dwordx4 v200, s[58:59]
	s_mov_b32 m0, s53
	s_nop 0
	global_load_lds_dwordx4 v202, s[58:59]
	s_mov_b32 m0, s72
	s_nop 0
	global_load_lds_dwordx4 v199, s[60:61]
	s_mov_b32 m0, s73
	s_nop 0
	global_load_lds_dwordx4 v201, s[60:61]
	s_waitcnt vmcnt(8)
	s_waitcnt lgkmcnt(0)
	s_barrier
	v_mfma_f32_16x16x32_bf16 v[12:15], v[4:7], v[32:35], v[132:135]
	v_mfma_f32_16x16x32_bf16 v[68:71], v[8:11], v[36:39], v[12:15]
	v_mfma_f32_16x16x32_bf16 v[12:15], v[224:227], v[32:35], v[144:147]
	v_mfma_f32_16x16x32_bf16 v[64:67], v[228:231], v[36:39], v[12:15]
	v_mfma_f32_16x16x32_bf16 v[12:15], v[4:7], v[48:51], v[152:155]
	v_mfma_f32_16x16x32_bf16 v[44:47], v[8:11], v[52:55], v[12:15]
	v_mfma_f32_16x16x32_bf16 v[12:15], v[224:227], v[48:51], v[168:171]
	v_mfma_f32_16x16x32_bf16 v[40:43], v[228:231], v[52:55], v[12:15]
	v_mfma_f32_16x16x32_bf16 v[12:15], v[4:7], v[76:79], v[172:175]
	v_mfma_f32_16x16x32_bf16 v[28:31], v[8:11], v[80:83], v[12:15]
	v_mfma_f32_16x16x32_bf16 v[12:15], v[224:227], v[76:79], v[176:179]
	v_mfma_f32_16x16x32_bf16 v[4:7], v[4:7], v[100:103], v[16:19]
	v_mfma_f32_16x16x32_bf16 v[24:27], v[228:231], v[80:83], v[12:15]
	v_mfma_f32_16x16x32_bf16 v[12:15], v[8:11], v[104:107], v[4:7]
	v_mfma_f32_16x16x32_bf16 v[4:7], v[224:227], v[100:103], v[20:23]
	v_mfma_f32_16x16x32_bf16 v[8:11], v[228:231], v[104:107], v[4:7]
	v_mfma_f32_16x16x32_bf16 v[4:7], v[232:235], v[32:35], v[180:183]
	v_mfma_f32_16x16x32_bf16 v[60:63], v[236:239], v[36:39], v[4:7]
	v_mfma_f32_16x16x32_bf16 v[4:7], v[240:243], v[32:35], v[188:191]
	v_mfma_f32_16x16x32_bf16 v[56:59], v[244:247], v[36:39], v[4:7]
	v_mfma_f32_16x16x32_bf16 v[4:7], v[232:235], v[48:51], v[192:195]
	v_mfma_f32_16x16x32_bf16 v[36:39], v[236:239], v[52:55], v[4:7]
	v_mfma_f32_16x16x32_bf16 v[4:7], v[240:243], v[48:51], v[208:211]
	v_mfma_f32_16x16x32_bf16 v[32:35], v[244:247], v[52:55], v[4:7]
	v_mfma_f32_16x16x32_bf16 v[4:7], v[232:235], v[76:79], v[212:215]
	v_mfma_f32_16x16x32_bf16 v[20:23], v[236:239], v[80:83], v[4:7]
	v_mfma_f32_16x16x32_bf16 v[4:7], v[240:243], v[76:79], v[216:219]
	v_mfma_f32_16x16x32_bf16 v[0:3], v[232:235], v[100:103], v[0:3]
	v_mfma_f32_16x16x32_bf16 v[16:19], v[244:247], v[80:83], v[4:7]
	v_mfma_f32_16x16x32_bf16 v[4:7], v[236:239], v[104:107], v[0:3]
	v_mfma_f32_16x16x32_bf16 v[0:3], v[240:243], v[100:103], v[220:223]
	v_mfma_f32_16x16x32_bf16 v[0:3], v[244:247], v[104:107], v[0:3]
	s_barrier
	s_add_u32 s62, s56, 0x100
	s_addc_u32 s63, s57, 0
	s_add_u32 s79, s54, 0x200
	s_addc_u32 s80, s55, 0
	s_mov_b32 s86, 0
.LBB0_1706:
	s_add_u32 s54, s62, 0x100
	s_addc_u32 s55, s63, 0
	s_cmp_eq_u32 s86, 4
	s_cselect_b32 s60, s48, s54
	s_cselect_b32 s61, s49, s55
	s_cselect_b32 s58, s20, s79
	s_cselect_b32 s59, s12, s80
	s_add_u32 s56, s60, 0x80
	s_addc_u32 s57, s61, 0
	s_add_i32 s92, 0, 0x10000
	s_add_i32 s93, 0, 0x14000
	v_add_u32_e32 v80, s92, v203
	v_add_u32_e32 v126, s93, v203
	ds_read_b128 v[48:51], v80
	ds_read_b128 v[52:55], v80 offset:1024
	ds_read_b128 v[76:79], v80 offset:2048
	ds_read_b128 v[80:83], v80 offset:3072
	ds_read_b128 v[100:103], v126
	ds_read_b128 v[104:107], v126 offset:1024
	ds_read_b128 v[132:135], v126 offset:2048
	ds_read_b128 v[144:147], v126 offset:3072
	s_add_u32 s62, s62, 0x70080
	s_addc_u32 s63, s63, 0
	s_mov_b32 m0, s1
	ds_read_b128 v[152:155], v206
	ds_read_b128 v[168:171], v206 offset:1024
	ds_read_b128 v[172:175], v206 offset:2048
	ds_read_b128 v[176:179], v206 offset:3072
	ds_read_b128 v[180:183], v206 offset:4096
	ds_read_b128 v[184:187], v206 offset:5120
	ds_read_b128 v[188:191], v206 offset:6144
	ds_read_b128 v[192:195], v206 offset:7168
	global_load_lds_dwordx4 v199, s[62:63]
	s_mov_b32 m0, s5
	s_nop 0
	global_load_lds_dwordx4 v201, s[62:63]
	s_waitcnt vmcnt(8)
	s_waitcnt lgkmcnt(0)
	s_barrier
	v_mfma_f32_16x16x32_bf16 v[164:167], v[48:51], v[152:155], v[164:167]
	v_mfma_f32_16x16x32_bf16 v[160:163], v[76:79], v[152:155], v[160:163]
	v_mfma_f32_16x16x32_bf16 v[140:143], v[48:51], v[172:175], v[140:143]
	v_mfma_f32_16x16x32_bf16 v[136:139], v[76:79], v[172:175], v[136:139]
	v_mfma_f32_16x16x32_bf16 v[116:119], v[48:51], v[180:183], v[116:119]
	v_mfma_f32_16x16x32_bf16 v[112:115], v[76:79], v[180:183], v[112:115]
	v_mfma_f32_16x16x32_bf16 v[92:95], v[48:51], v[188:191], v[92:95]
	v_mfma_f32_16x16x32_bf16 v[88:91], v[76:79], v[188:191], v[88:91]
	v_mfma_f32_16x16x32_bf16 v[164:167], v[52:55], v[168:171], v[164:167]
	v_mfma_f32_16x16x32_bf16 v[160:163], v[80:83], v[168:171], v[160:163]
	v_mfma_f32_16x16x32_bf16 v[140:143], v[52:55], v[176:179], v[140:143]
	v_mfma_f32_16x16x32_bf16 v[136:139], v[80:83], v[176:179], v[136:139]
	v_mfma_f32_16x16x32_bf16 v[116:119], v[52:55], v[184:187], v[116:119]
	v_mfma_f32_16x16x32_bf16 v[112:115], v[80:83], v[184:187], v[112:115]
	v_mfma_f32_16x16x32_bf16 v[92:95], v[52:55], v[192:195], v[92:95]
	v_mfma_f32_16x16x32_bf16 v[88:91], v[80:83], v[192:195], v[88:91]
	v_mfma_f32_16x16x32_bf16 v[156:159], v[100:103], v[152:155], v[156:159]
	v_mfma_f32_16x16x32_bf16 v[148:151], v[132:135], v[152:155], v[148:151]
	v_mfma_f32_16x16x32_bf16 v[126:129], v[100:103], v[172:175], v[128:131]
	v_mfma_f32_16x16x32_bf16 v[120:123], v[132:135], v[172:175], v[120:123]
	v_mfma_f32_16x16x32_bf16 v[108:111], v[100:103], v[180:183], v[108:111]
	v_mfma_f32_16x16x32_bf16 v[96:99], v[132:135], v[180:183], v[96:99]
	v_mfma_f32_16x16x32_bf16 v[84:87], v[100:103], v[188:191], v[84:87]
	v_mfma_f32_16x16x32_bf16 v[72:75], v[132:135], v[188:191], v[72:75]
	v_mfma_f32_16x16x32_bf16 v[156:159], v[104:107], v[168:171], v[156:159]
	v_mfma_f32_16x16x32_bf16 v[148:151], v[144:147], v[168:171], v[148:151]
	v_mfma_f32_16x16x32_bf16 v[126:129], v[104:107], v[176:179], v[126:129]
	v_mfma_f32_16x16x32_bf16 v[120:123], v[144:147], v[176:179], v[120:123]
	v_mfma_f32_16x16x32_bf16 v[108:111], v[104:107], v[184:187], v[108:111]
	v_mfma_f32_16x16x32_bf16 v[96:99], v[144:147], v[184:187], v[96:99]
	v_mfma_f32_16x16x32_bf16 v[84:87], v[104:107], v[192:195], v[84:87]
	v_mfma_f32_16x16x32_bf16 v[72:75], v[144:147], v[192:195], v[72:75]
	s_barrier
	s_add_i32 s62, s92, s26
	s_mov_b32 m0, s62
	ds_read_b128 v[152:155], v206 offset:16384
	ds_read_b128 v[168:171], v206 offset:17408
	ds_read_b128 v[172:175], v206 offset:18432
	ds_read_b128 v[176:179], v206 offset:19456
	ds_read_b128 v[180:183], v206 offset:20480
	ds_read_b128 v[184:187], v206 offset:21504
	ds_read_b128 v[188:191], v206 offset:22528
	ds_read_b128 v[192:195], v206 offset:23552
	global_load_lds_dwordx4 v200, s[58:59]
	s_add_i32 m0, s62, 0x2000
	s_add_u32 s62, s58, 0x20000
	s_addc_u32 s63, s59, 0
	s_add_i32 s92, s93, s26
	s_nop 0
	global_load_lds_dwordx4 v202, s[58:59]
	s_mov_b32 m0, s92
	s_nop 0
	global_load_lds_dwordx4 v200, s[62:63]
	s_add_i32 m0, s92, 0x2000
	s_nop 0
	global_load_lds_dwordx4 v202, s[62:63]
	s_mov_b32 m0, s27
	s_nop 0
	global_load_lds_dwordx4 v199, s[60:61]
	s_mov_b32 m0, s69
	s_nop 0
	global_load_lds_dwordx4 v201, s[60:61]
	s_waitcnt vmcnt(8)
	s_waitcnt lgkmcnt(0)
	s_barrier
	v_mfma_f32_16x16x32_bf16 v[68:71], v[48:51], v[152:155], v[68:71]
	v_mfma_f32_16x16x32_bf16 v[64:67], v[76:79], v[152:155], v[64:67]
	v_mfma_f32_16x16x32_bf16 v[44:47], v[48:51], v[172:175], v[44:47]
	v_mfma_f32_16x16x32_bf16 v[40:43], v[76:79], v[172:175], v[40:43]
	v_mfma_f32_16x16x32_bf16 v[28:31], v[48:51], v[180:183], v[28:31]
	v_mfma_f32_16x16x32_bf16 v[24:27], v[76:79], v[180:183], v[24:27]
	v_mfma_f32_16x16x32_bf16 v[12:15], v[48:51], v[188:191], v[12:15]
	v_mfma_f32_16x16x32_bf16 v[8:11], v[76:79], v[188:191], v[8:11]
	v_mfma_f32_16x16x32_bf16 v[68:71], v[52:55], v[168:171], v[68:71]
	v_mfma_f32_16x16x32_bf16 v[64:67], v[80:83], v[168:171], v[64:67]
	v_mfma_f32_16x16x32_bf16 v[44:47], v[52:55], v[176:179], v[44:47]
	v_mfma_f32_16x16x32_bf16 v[40:43], v[80:83], v[176:179], v[40:43]
	v_mfma_f32_16x16x32_bf16 v[28:31], v[52:55], v[184:187], v[28:31]
	v_mfma_f32_16x16x32_bf16 v[24:27], v[80:83], v[184:187], v[24:27]
	v_mfma_f32_16x16x32_bf16 v[12:15], v[52:55], v[192:195], v[12:15]
	v_mfma_f32_16x16x32_bf16 v[8:11], v[80:83], v[192:195], v[8:11]
	v_mfma_f32_16x16x32_bf16 v[36:39], v[100:103], v[172:175], v[36:39]
	v_mfma_f32_16x16x32_bf16 v[32:35], v[132:135], v[172:175], v[32:35]
	v_mfma_f32_16x16x32_bf16 v[20:23], v[100:103], v[180:183], v[20:23]
	v_mfma_f32_16x16x32_bf16 v[16:19], v[132:135], v[180:183], v[16:19]
	v_mfma_f32_16x16x32_bf16 v[4:7], v[100:103], v[188:191], v[4:7]
	v_mfma_f32_16x16x32_bf16 v[0:3], v[132:135], v[188:191], v[0:3]
	v_mfma_f32_16x16x32_bf16 v[48:51], v[100:103], v[152:155], v[60:63]
	v_mfma_f32_16x16x32_bf16 v[52:55], v[132:135], v[152:155], v[56:59]
	v_mfma_f32_16x16x32_bf16 v[36:39], v[104:107], v[176:179], v[36:39]
	v_mfma_f32_16x16x32_bf16 v[32:35], v[144:147], v[176:179], v[32:35]
	v_mfma_f32_16x16x32_bf16 v[20:23], v[104:107], v[184:187], v[20:23]
	v_mfma_f32_16x16x32_bf16 v[16:19], v[144:147], v[184:187], v[16:19]
	v_mfma_f32_16x16x32_bf16 v[4:7], v[104:107], v[192:195], v[4:7]
	v_mfma_f32_16x16x32_bf16 v[0:3], v[144:147], v[192:195], v[0:3]
	v_mfma_f32_16x16x32_bf16 v[48:51], v[104:107], v[168:171], v[48:51]
	v_mfma_f32_16x16x32_bf16 v[52:55], v[144:147], v[168:171], v[52:55]
	s_barrier
	ds_read_b128 v[56:59], v124
	ds_read_b128 v[60:63], v124 offset:1024
	ds_read_b128 v[76:79], v124 offset:2048
	ds_read_b128 v[80:83], v124 offset:3072
	ds_read_b128 v[100:103], v125
	ds_read_b128 v[104:107], v125 offset:1024
	ds_read_b128 v[132:135], v125 offset:2048
	ds_read_b128 v[144:147], v125 offset:3072
	s_add_u32 s60, s60, 0x70000
	s_addc_u32 s61, s61, 0
	s_mov_b32 m0, s70
	ds_read_b128 v[152:155], v206 offset:32768
	ds_read_b128 v[168:171], v206 offset:33792
	ds_read_b128 v[172:175], v206 offset:34816
	ds_read_b128 v[176:179], v206 offset:35840
	ds_read_b128 v[180:183], v206 offset:36864
	ds_read_b128 v[184:187], v206 offset:37888
	ds_read_b128 v[188:191], v206 offset:38912
	ds_read_b128 v[192:195], v206 offset:39936
	global_load_lds_dwordx4 v199, s[60:61]
	s_mov_b32 m0, s71
	s_nop 0
	global_load_lds_dwordx4 v201, s[60:61]
	s_waitcnt vmcnt(8)
	s_waitcnt lgkmcnt(0)
	s_barrier
	v_mfma_f32_16x16x32_bf16 v[164:167], v[56:59], v[152:155], v[164:167]
	v_mfma_f32_16x16x32_bf16 v[160:163], v[76:79], v[152:155], v[160:163]
	v_mfma_f32_16x16x32_bf16 v[140:143], v[56:59], v[172:175], v[140:143]
	v_mfma_f32_16x16x32_bf16 v[136:139], v[76:79], v[172:175], v[136:139]
	v_mfma_f32_16x16x32_bf16 v[116:119], v[56:59], v[180:183], v[116:119]
	v_mfma_f32_16x16x32_bf16 v[112:115], v[76:79], v[180:183], v[112:115]
	v_mfma_f32_16x16x32_bf16 v[92:95], v[56:59], v[188:191], v[92:95]
	v_mfma_f32_16x16x32_bf16 v[88:91], v[76:79], v[188:191], v[88:91]
	v_mfma_f32_16x16x32_bf16 v[164:167], v[60:63], v[168:171], v[164:167]
	v_mfma_f32_16x16x32_bf16 v[160:163], v[80:83], v[168:171], v[160:163]
	v_mfma_f32_16x16x32_bf16 v[140:143], v[60:63], v[176:179], v[140:143]
	v_mfma_f32_16x16x32_bf16 v[136:139], v[80:83], v[176:179], v[136:139]
	v_mfma_f32_16x16x32_bf16 v[116:119], v[60:63], v[184:187], v[116:119]
	v_mfma_f32_16x16x32_bf16 v[112:115], v[80:83], v[184:187], v[112:115]
	v_mfma_f32_16x16x32_bf16 v[92:95], v[60:63], v[192:195], v[92:95]
	v_mfma_f32_16x16x32_bf16 v[88:91], v[80:83], v[192:195], v[88:91]
	v_mfma_f32_16x16x32_bf16 v[156:159], v[100:103], v[152:155], v[156:159]
	v_mfma_f32_16x16x32_bf16 v[148:151], v[132:135], v[152:155], v[148:151]
	v_mfma_f32_16x16x32_bf16 v[126:129], v[100:103], v[172:175], v[126:129]
	v_mfma_f32_16x16x32_bf16 v[120:123], v[132:135], v[172:175], v[120:123]
	v_mfma_f32_16x16x32_bf16 v[108:111], v[100:103], v[180:183], v[108:111]
	v_mfma_f32_16x16x32_bf16 v[96:99], v[132:135], v[180:183], v[96:99]
	v_mfma_f32_16x16x32_bf16 v[84:87], v[100:103], v[188:191], v[84:87]
	v_mfma_f32_16x16x32_bf16 v[72:75], v[132:135], v[188:191], v[72:75]
	v_mfma_f32_16x16x32_bf16 v[156:159], v[104:107], v[168:171], v[156:159]
	v_mfma_f32_16x16x32_bf16 v[148:151], v[144:147], v[168:171], v[148:151]
	v_mfma_f32_16x16x32_bf16 v[128:131], v[104:107], v[176:179], v[126:129]
	v_mfma_f32_16x16x32_bf16 v[120:123], v[144:147], v[176:179], v[120:123]
	v_mfma_f32_16x16x32_bf16 v[108:111], v[104:107], v[184:187], v[108:111]
	v_mfma_f32_16x16x32_bf16 v[96:99], v[144:147], v[184:187], v[96:99]
	v_mfma_f32_16x16x32_bf16 v[84:87], v[104:107], v[192:195], v[84:87]
	v_mfma_f32_16x16x32_bf16 v[72:75], v[144:147], v[192:195], v[72:75]
	s_barrier
	s_add_u32 s60, s58, 0x80
	s_mov_b32 m0, s21
	s_addc_u32 s61, s59, 0
	ds_read_b128 v[152:155], v206 offset:49152
	ds_read_b128 v[168:171], v206 offset:50176
	ds_read_b128 v[172:175], v206 offset:51200
	ds_read_b128 v[176:179], v206 offset:52224
	ds_read_b128 v[180:183], v206 offset:53248
	ds_read_b128 v[184:187], v206 offset:54272
	ds_read_b128 v[188:191], v206 offset:55296
	ds_read_b128 v[192:195], v206 offset:56320
	s_add_u32 s58, s58, 0x20080
	global_load_lds_dwordx4 v200, s[60:61]
	s_mov_b32 m0, s45
	s_addc_u32 s59, s59, 0
	global_load_lds_dwordx4 v202, s[60:61]
	s_mov_b32 m0, s47
	s_nop 0
	global_load_lds_dwordx4 v200, s[58:59]
	s_mov_b32 m0, s53
	s_nop 0
	global_load_lds_dwordx4 v202, s[58:59]
	s_mov_b32 m0, s72
	s_nop 0
	global_load_lds_dwordx4 v199, s[56:57]
	s_mov_b32 m0, s73
	s_nop 0
	global_load_lds_dwordx4 v201, s[56:57]
	s_waitcnt vmcnt(8)
	s_waitcnt lgkmcnt(0)
	s_barrier
	v_mfma_f32_16x16x32_bf16 v[68:71], v[56:59], v[152:155], v[68:71]
	v_mfma_f32_16x16x32_bf16 v[64:67], v[76:79], v[152:155], v[64:67]
	v_mfma_f32_16x16x32_bf16 v[44:47], v[56:59], v[172:175], v[44:47]
	v_mfma_f32_16x16x32_bf16 v[40:43], v[76:79], v[172:175], v[40:43]
	v_mfma_f32_16x16x32_bf16 v[28:31], v[56:59], v[180:183], v[28:31]
	v_mfma_f32_16x16x32_bf16 v[24:27], v[76:79], v[180:183], v[24:27]
	v_mfma_f32_16x16x32_bf16 v[12:15], v[56:59], v[188:191], v[12:15]
	v_mfma_f32_16x16x32_bf16 v[8:11], v[76:79], v[188:191], v[8:11]
	v_mfma_f32_16x16x32_bf16 v[68:71], v[60:63], v[168:171], v[68:71]
	v_mfma_f32_16x16x32_bf16 v[64:67], v[80:83], v[168:171], v[64:67]
	v_mfma_f32_16x16x32_bf16 v[44:47], v[60:63], v[176:179], v[44:47]
	v_mfma_f32_16x16x32_bf16 v[40:43], v[80:83], v[176:179], v[40:43]
	v_mfma_f32_16x16x32_bf16 v[28:31], v[60:63], v[184:187], v[28:31]
	v_mfma_f32_16x16x32_bf16 v[24:27], v[80:83], v[184:187], v[24:27]
	v_mfma_f32_16x16x32_bf16 v[12:15], v[60:63], v[192:195], v[12:15]
	v_mfma_f32_16x16x32_bf16 v[8:11], v[80:83], v[192:195], v[8:11]
	v_mfma_f32_16x16x32_bf16 v[48:51], v[100:103], v[152:155], v[48:51]
	v_mfma_f32_16x16x32_bf16 v[60:63], v[104:107], v[168:171], v[48:51]
	v_mfma_f32_16x16x32_bf16 v[48:51], v[132:135], v[152:155], v[52:55]
	v_mfma_f32_16x16x32_bf16 v[36:39], v[100:103], v[172:175], v[36:39]
	v_mfma_f32_16x16x32_bf16 v[32:35], v[132:135], v[172:175], v[32:35]
	v_mfma_f32_16x16x32_bf16 v[20:23], v[100:103], v[180:183], v[20:23]
	v_mfma_f32_16x16x32_bf16 v[16:19], v[132:135], v[180:183], v[16:19]
	v_mfma_f32_16x16x32_bf16 v[4:7], v[100:103], v[188:191], v[4:7]
	v_mfma_f32_16x16x32_bf16 v[0:3], v[132:135], v[188:191], v[0:3]
	v_mfma_f32_16x16x32_bf16 v[56:59], v[144:147], v[168:171], v[48:51]
	v_mfma_f32_16x16x32_bf16 v[36:39], v[104:107], v[176:179], v[36:39]
	v_mfma_f32_16x16x32_bf16 v[32:35], v[144:147], v[176:179], v[32:35]
	v_mfma_f32_16x16x32_bf16 v[20:23], v[104:107], v[184:187], v[20:23]
	v_mfma_f32_16x16x32_bf16 v[16:19], v[144:147], v[184:187], v[16:19]
	v_mfma_f32_16x16x32_bf16 v[4:7], v[104:107], v[192:195], v[4:7]
	v_mfma_f32_16x16x32_bf16 v[0:3], v[144:147], v[192:195], v[0:3]
	s_barrier
	s_add_i32 s86, s86, 2
	s_add_u32 s79, s79, 0x100
	s_addc_u32 s80, s80, 0
	s_cmp_gt_u32 s86, 5
	s_mov_b64 s[62:63], s[54:55]
	s_cbranch_scc0 .LBB0_1706
	s_and_b64 vcc, exec, s[42:43]
	s_cbranch_vccz .LBB0_1709
	s_barrier

.LBB0_1772:
	s_add_u32 s20, s42, 0x100
	s_addc_u32 s21, s43, 0
	s_waitcnt lgkmcnt(0)
	s_add_u32 s60, s6, 0x100
	s_addc_u32 s61, s7, 0
	s_barrier
	s_waitcnt lgkmcnt(0)
	v_mfma_f32_16x16x32_bf16 v[32:35], v[16:19], v[72:75], 0
	v_mfma_f32_16x16x32_bf16 v[36:39], v[24:27], v[72:75], 0
	v_mfma_f32_16x16x32_bf16 v[40:43], v[16:19], v[80:83], 0
	v_mfma_f32_16x16x32_bf16 v[44:47], v[24:27], v[80:83], 0
	v_mfma_f32_16x16x32_bf16 v[48:51], v[16:19], v[92:95], 0
	v_mfma_f32_16x16x32_bf16 v[52:55], v[24:27], v[92:95], 0
	v_mfma_f32_16x16x32_bf16 v[56:59], v[16:19], v[60:63], 0
	v_mfma_f32_16x16x32_bf16 v[64:67], v[24:27], v[60:63], 0
	v_mfma_f32_16x16x32_bf16 v[32:35], v[20:23], v[76:79], v[32:35]
	v_mfma_f32_16x16x32_bf16 v[36:39], v[28:31], v[76:79], v[36:39]
	v_mfma_f32_16x16x32_bf16 v[40:43], v[20:23], v[84:87], v[40:43]
	v_mfma_f32_16x16x32_bf16 v[44:47], v[28:31], v[84:87], v[44:47]
	v_mfma_f32_16x16x32_bf16 v[48:51], v[20:23], v[96:99], v[48:51]
	v_mfma_f32_16x16x32_bf16 v[52:55], v[28:31], v[96:99], v[52:55]
	v_mfma_f32_16x16x32_bf16 v[56:59], v[20:23], v[88:91], v[56:59]
	v_mfma_f32_16x16x32_bf16 v[64:67], v[28:31], v[88:91], v[64:67]
	v_mfma_f32_16x16x32_bf16 v[68:71], v[0:3], v[72:75], 0
	v_mfma_f32_16x16x32_bf16 v[72:75], v[8:11], v[72:75], 0
	v_mfma_f32_16x16x32_bf16 v[68:71], v[4:7], v[76:79], v[68:71]
	v_mfma_f32_16x16x32_bf16 v[72:75], v[12:15], v[76:79], v[72:75]
	v_mfma_f32_16x16x32_bf16 v[76:79], v[0:3], v[80:83], 0
	v_mfma_f32_16x16x32_bf16 v[80:83], v[8:11], v[80:83], 0
	v_mfma_f32_16x16x32_bf16 v[76:79], v[4:7], v[84:87], v[76:79]
	v_mfma_f32_16x16x32_bf16 v[80:83], v[12:15], v[84:87], v[80:83]
	v_mfma_f32_16x16x32_bf16 v[84:87], v[0:3], v[92:95], 0
	v_mfma_f32_16x16x32_bf16 v[92:95], v[8:11], v[92:95], 0
	v_mfma_f32_16x16x32_bf16 v[128:131], v[12:15], v[96:99], v[92:95]
	v_mfma_f32_16x16x32_bf16 v[92:95], v[0:3], v[60:63], 0
	v_mfma_f32_16x16x32_bf16 v[60:63], v[8:11], v[60:63], 0
	v_mfma_f32_16x16x32_bf16 v[84:87], v[4:7], v[96:99], v[84:87]
	v_mfma_f32_16x16x32_bf16 v[132:135], v[4:7], v[88:91], v[92:95]
	v_mfma_f32_16x16x32_bf16 v[136:139], v[12:15], v[88:91], v[60:63]
	s_barrier
	s_mov_b32 m0, s5
	ds_read_b128 v[108:111], v151 offset:16384
	ds_read_b128 v[112:115], v151 offset:17408
	ds_read_b128 v[100:103], v151 offset:18432
	ds_read_b128 v[104:107], v151 offset:19456
	ds_read_b128 v[92:95], v151 offset:20480
	ds_read_b128 v[96:99], v151 offset:21504
	ds_read_b128 v[60:63], v151 offset:22528
	ds_read_b128 v[88:91], v151 offset:23552
	global_load_lds_dwordx4 v145, s[60:61]
	s_mov_b32 m0, s70
	s_nop 0
	global_load_lds_dwordx4 v147, s[60:61]
	s_add_u32 s60, s6, 0x20100
	s_addc_u32 s61, s7, 0
	s_mov_b32 m0, s71
	s_and_b64 vcc, exec, s[58:59]
	global_load_lds_dwordx4 v145, s[60:61]
	s_mov_b32 m0, s72
	s_nop 0
	global_load_lds_dwordx4 v147, s[60:61]
	s_mov_b32 m0, s3
	s_mov_b64 s[60:61], -1
	global_load_lds_dwordx4 v144, s[20:21]
	s_mov_b32 m0, s73
	s_nop 0
	global_load_lds_dwordx4 v146, s[20:21]
	s_cbranch_vccz .LBB0_1774
	s_waitcnt vmcnt(8)
	s_mov_b64 s[60:61], 0

.LBB0_1776:
	s_ashr_i32 s51, s50, 31
	s_lshl_b64 s[20:21], s[50:51], 18
	s_add_u32 s58, s26, s20
	s_addc_u32 s59, s27, s21
	s_add_u32 s60, s42, 0x180
	s_addc_u32 s61, s43, 0
	s_waitcnt lgkmcnt(0)
	s_and_b64 s[20:21], s[52:53], exec
	s_cselect_b32 s20, s59, s7
	s_cselect_b32 s21, s58, s6
	s_add_u32 s62, s6, 0x180
	s_addc_u32 s63, s7, 0
	s_barrier
	s_waitcnt lgkmcnt(0)
	v_mfma_f32_16x16x32_bf16 v[116:119], v[16:19], v[108:111], 0
	v_mfma_f32_16x16x32_bf16 v[154:157], v[20:23], v[112:115], v[116:119]
	v_mfma_f32_16x16x32_bf16 v[116:119], v[24:27], v[108:111], 0
	v_mfma_f32_16x16x32_bf16 v[158:161], v[28:31], v[112:115], v[116:119]
	v_mfma_f32_16x16x32_bf16 v[116:119], v[16:19], v[100:103], 0
	v_mfma_f32_16x16x32_bf16 v[162:165], v[20:23], v[104:107], v[116:119]
	v_mfma_f32_16x16x32_bf16 v[116:119], v[24:27], v[100:103], 0
	v_mfma_f32_16x16x32_bf16 v[166:169], v[28:31], v[104:107], v[116:119]
	v_mfma_f32_16x16x32_bf16 v[116:119], v[16:19], v[92:95], 0
	v_mfma_f32_16x16x32_bf16 v[16:19], v[16:19], v[60:63], 0
	v_mfma_f32_16x16x32_bf16 v[170:173], v[20:23], v[96:99], v[116:119]
	v_mfma_f32_16x16x32_bf16 v[16:19], v[20:23], v[88:91], v[16:19]
	v_mfma_f32_16x16x32_bf16 v[20:23], v[24:27], v[60:63], 0
	v_mfma_f32_16x16x32_bf16 v[116:119], v[24:27], v[92:95], 0
	v_mfma_f32_16x16x32_bf16 v[20:23], v[28:31], v[88:91], v[20:23]
	v_mfma_f32_16x16x32_bf16 v[174:177], v[28:31], v[96:99], v[116:119]
	v_mfma_f32_16x16x32_bf16 v[24:27], v[0:3], v[108:111], 0
	v_mfma_f32_16x16x32_bf16 v[178:181], v[4:7], v[112:115], v[24:27]
	v_mfma_f32_16x16x32_bf16 v[24:27], v[8:11], v[108:111], 0
	v_mfma_f32_16x16x32_bf16 v[182:185], v[12:15], v[112:115], v[24:27]
	v_mfma_f32_16x16x32_bf16 v[24:27], v[0:3], v[100:103], 0
	v_mfma_f32_16x16x32_bf16 v[186:189], v[4:7], v[104:107], v[24:27]
	v_mfma_f32_16x16x32_bf16 v[24:27], v[8:11], v[100:103], 0
	v_mfma_f32_16x16x32_bf16 v[190:193], v[12:15], v[104:107], v[24:27]
	v_mfma_f32_16x16x32_bf16 v[24:27], v[0:3], v[92:95], 0
	v_mfma_f32_16x16x32_bf16 v[0:3], v[0:3], v[60:63], 0
	v_mfma_f32_16x16x32_bf16 v[194:197], v[4:7], v[96:99], v[24:27]
	v_mfma_f32_16x16x32_bf16 v[24:27], v[8:11], v[92:95], 0
	v_mfma_f32_16x16x32_bf16 v[0:3], v[4:7], v[88:91], v[0:3]
	v_mfma_f32_16x16x32_bf16 v[4:7], v[8:11], v[60:63], 0
	v_mfma_f32_16x16x32_bf16 v[198:201], v[12:15], v[96:99], v[24:27]
	v_mfma_f32_16x16x32_bf16 v[202:205], v[12:15], v[88:91], v[4:7]
	s_barrier
	v_add_u32_e32 v142, s88, v148
	v_add_u32_e32 v153, s89, v148
	s_nop 1
	ds_read_b128 v[4:7], v142
	ds_read_b128 v[8:11], v142 offset:1024
	ds_read_b128 v[206:209], v142 offset:2048
	ds_read_b128 v[210:213], v142 offset:3072
	ds_read_b128 v[214:217], v153
	ds_read_b128 v[218:221], v153 offset:1024
	ds_read_b128 v[222:225], v153 offset:2048
	ds_read_b128 v[226:229], v153 offset:3072
	s_add_u32 s64, s42, 0x70100
	s_addc_u32 s65, s43, 0
	s_mov_b32 m0, s74
	ds_read_b128 v[12:15], v151 offset:32768
	ds_read_b128 v[24:27], v151 offset:33792
	ds_read_b128 v[28:31], v151 offset:34816
	ds_read_b128 v[96:99], v151 offset:35840
	ds_read_b128 v[230:233], v151 offset:36864
	ds_read_b128 v[234:237], v151 offset:37888
	ds_read_b128 v[238:241], v151 offset:38912
	ds_read_b128 v[242:245], v151 offset:39936
	global_load_lds_dwordx4 v144, s[64:65]
	s_mov_b32 m0, s75
	s_nop 0
	global_load_lds_dwordx4 v146, s[64:65]
	s_waitcnt vmcnt(8)
	s_waitcnt lgkmcnt(0)
	s_barrier
	v_mfma_f32_16x16x32_bf16 v[32:35], v[4:7], v[12:15], v[32:35]
	v_mfma_f32_16x16x32_bf16 v[124:127], v[8:11], v[24:27], v[32:35]
	v_mfma_f32_16x16x32_bf16 v[32:35], v[206:209], v[12:15], v[36:39]
	v_mfma_f32_16x16x32_bf16 v[120:123], v[210:213], v[24:27], v[32:35]
	v_mfma_f32_16x16x32_bf16 v[32:35], v[4:7], v[28:31], v[40:43]
	v_mfma_f32_16x16x32_bf16 v[108:111], v[8:11], v[96:99], v[32:35]
	v_mfma_f32_16x16x32_bf16 v[32:35], v[206:209], v[28:31], v[44:47]
	v_mfma_f32_16x16x32_bf16 v[104:107], v[210:213], v[96:99], v[32:35]
	v_mfma_f32_16x16x32_bf16 v[32:35], v[4:7], v[230:233], v[48:51]
	v_mfma_f32_16x16x32_bf16 v[92:95], v[8:11], v[234:237], v[32:35]
	v_mfma_f32_16x16x32_bf16 v[32:35], v[206:209], v[230:233], v[52:55]
	v_mfma_f32_16x16x32_bf16 v[88:91], v[210:213], v[234:237], v[32:35]
	v_mfma_f32_16x16x32_bf16 v[32:35], v[4:7], v[238:241], v[56:59]
	v_mfma_f32_16x16x32_bf16 v[60:63], v[8:11], v[242:245], v[32:35]
	v_mfma_f32_16x16x32_bf16 v[32:35], v[206:209], v[238:241], v[64:67]
	v_mfma_f32_16x16x32_bf16 v[56:59], v[210:213], v[242:245], v[32:35]
	v_mfma_f32_16x16x32_bf16 v[32:35], v[214:217], v[12:15], v[68:71]
	v_mfma_f32_16x16x32_bf16 v[12:15], v[222:225], v[12:15], v[72:75]
	v_mfma_f32_16x16x32_bf16 v[112:115], v[226:229], v[24:27], v[12:15]
	v_mfma_f32_16x16x32_bf16 v[12:15], v[214:217], v[28:31], v[76:79]
	v_mfma_f32_16x16x32_bf16 v[100:103], v[218:221], v[96:99], v[12:15]
	v_mfma_f32_16x16x32_bf16 v[12:15], v[222:225], v[28:31], v[80:83]
	v_mfma_f32_16x16x32_bf16 v[96:99], v[226:229], v[96:99], v[12:15]
	v_mfma_f32_16x16x32_bf16 v[12:15], v[214:217], v[230:233], v[84:87]
	v_mfma_f32_16x16x32_bf16 v[84:87], v[218:221], v[234:237], v[12:15]
	v_mfma_f32_16x16x32_bf16 v[12:15], v[222:225], v[230:233], v[128:131]
	v_mfma_f32_16x16x32_bf16 v[80:83], v[226:229], v[234:237], v[12:15]
	v_mfma_f32_16x16x32_bf16 v[12:15], v[214:217], v[238:241], v[132:135]
	v_mfma_f32_16x16x32_bf16 v[52:55], v[218:221], v[242:245], v[12:15]
	v_mfma_f32_16x16x32_bf16 v[12:15], v[222:225], v[238:241], v[136:139]
	v_mfma_f32_16x16x32_bf16 v[116:119], v[218:221], v[24:27], v[32:35]
	v_mfma_f32_16x16x32_bf16 v[48:51], v[226:229], v[242:245], v[12:15]
	s_barrier
	s_add_i32 s49, s88, s68
	s_mov_b32 m0, s49
	s_add_i32 s51, s49, 0x2000
	ds_read_b128 v[32:35], v151 offset:49152
	ds_read_b128 v[36:39], v151 offset:50176
	ds_read_b128 v[128:131], v151 offset:51200
	ds_read_b128 v[132:135], v151 offset:52224
	ds_read_b128 v[136:139], v151 offset:53248
	ds_read_b128 v[230:233], v151 offset:54272
	ds_read_b128 v[234:237], v151 offset:55296
	ds_read_b128 v[238:241], v151 offset:56320
	global_load_lds_dwordx4 v145, s[62:63]
	s_mov_b32 m0, s51
	s_nop 0
	global_load_lds_dwordx4 v147, s[62:63]
	s_add_u32 s62, s6, 0x20180
	s_addc_u32 s63, s7, 0
	s_add_i32 s79, s89, s68
	s_mov_b32 m0, s79
	s_add_i32 s86, s79, 0x2000
	s_nop 0
	global_load_lds_dwordx4 v145, s[62:63]
	s_mov_b32 m0, s86
	s_nop 0
	global_load_lds_dwordx4 v147, s[62:63]
	s_mov_b32 m0, s76
	s_nop 0
	global_load_lds_dwordx4 v144, s[60:61]
	s_mov_b32 m0, s77
	s_nop 0
	global_load_lds_dwordx4 v146, s[60:61]
	s_waitcnt vmcnt(8)
	s_waitcnt lgkmcnt(0)
	s_barrier
	v_mfma_f32_16x16x32_bf16 v[12:15], v[4:7], v[32:35], v[154:157]
	v_mfma_f32_16x16x32_bf16 v[76:79], v[8:11], v[36:39], v[12:15]
	v_mfma_f32_16x16x32_bf16 v[12:15], v[206:209], v[32:35], v[158:161]
	v_mfma_f32_16x16x32_bf16 v[72:75], v[210:213], v[36:39], v[12:15]
	v_mfma_f32_16x16x32_bf16 v[12:15], v[4:7], v[128:131], v[162:165]
	v_mfma_f32_16x16x32_bf16 v[44:47], v[8:11], v[132:135], v[12:15]
	v_mfma_f32_16x16x32_bf16 v[12:15], v[206:209], v[128:131], v[166:169]
	v_mfma_f32_16x16x32_bf16 v[40:43], v[210:213], v[132:135], v[12:15]
	v_mfma_f32_16x16x32_bf16 v[12:15], v[4:7], v[136:139], v[170:173]
	v_mfma_f32_16x16x32_bf16 v[28:31], v[8:11], v[230:233], v[12:15]
	v_mfma_f32_16x16x32_bf16 v[12:15], v[206:209], v[136:139], v[174:177]
	v_mfma_f32_16x16x32_bf16 v[4:7], v[4:7], v[234:237], v[16:19]
	v_mfma_f32_16x16x32_bf16 v[24:27], v[210:213], v[230:233], v[12:15]
	v_mfma_f32_16x16x32_bf16 v[12:15], v[8:11], v[238:241], v[4:7]
	v_mfma_f32_16x16x32_bf16 v[4:7], v[206:209], v[234:237], v[20:23]
	v_mfma_f32_16x16x32_bf16 v[8:11], v[210:213], v[238:241], v[4:7]
	v_mfma_f32_16x16x32_bf16 v[4:7], v[214:217], v[32:35], v[178:181]
	v_mfma_f32_16x16x32_bf16 v[68:71], v[218:221], v[36:39], v[4:7]
	v_mfma_f32_16x16x32_bf16 v[4:7], v[222:225], v[32:35], v[182:185]
	v_mfma_f32_16x16x32_bf16 v[64:67], v[226:229], v[36:39], v[4:7]
	v_mfma_f32_16x16x32_bf16 v[4:7], v[214:217], v[128:131], v[186:189]
	v_mfma_f32_16x16x32_bf16 v[36:39], v[218:221], v[132:135], v[4:7]
	v_mfma_f32_16x16x32_bf16 v[4:7], v[222:225], v[128:131], v[190:193]
	v_mfma_f32_16x16x32_bf16 v[32:35], v[226:229], v[132:135], v[4:7]
	v_mfma_f32_16x16x32_bf16 v[4:7], v[214:217], v[136:139], v[194:197]
	v_mfma_f32_16x16x32_bf16 v[20:23], v[218:221], v[230:233], v[4:7]
	v_mfma_f32_16x16x32_bf16 v[4:7], v[222:225], v[136:139], v[198:201]
	v_mfma_f32_16x16x32_bf16 v[0:3], v[214:217], v[234:237], v[0:3]
	v_mfma_f32_16x16x32_bf16 v[16:19], v[226:229], v[230:233], v[4:7]
	v_mfma_f32_16x16x32_bf16 v[4:7], v[218:221], v[238:241], v[0:3]
	v_mfma_f32_16x16x32_bf16 v[0:3], v[222:225], v[234:237], v[202:205]
	v_mfma_f32_16x16x32_bf16 v[0:3], v[226:229], v[238:241], v[0:3]
	s_barrier
	s_mov_b32 s93, 0
	s_mov_b64 s[60:61], 0
.LBB0_1777:
	s_add_u32 s94, s42, s60
	s_addc_u32 s95, s43, s61
	s_add_u32 s62, s94, 0x200
	s_addc_u32 s63, s95, 0
	s_add_u32 s64, s6, s60
	s_addc_u32 s65, s7, s61
	s_add_u32 s64, s64, 0x200
	s_addc_u32 s65, s65, 0
	s_cmp_eq_u32 s93, 4
	s_cselect_b32 s66, s56, s62
	s_cselect_b32 s67, s57, s63
	s_cselect_b32 s64, s21, s64
	s_cselect_b32 s65, s20, s65
	s_add_u32 s62, s66, 0x80
	s_addc_u32 s63, s67, 0
	s_add_i32 s96, 0, 0x10000
	s_add_i32 s97, 0, 0x14000
	v_add_u32_e32 v154, s96, v148
	v_add_u32_e32 v170, s97, v148
	ds_read_b128 v[128:131], v154
	ds_read_b128 v[132:135], v154 offset:1024
	ds_read_b128 v[136:139], v154 offset:2048
	ds_read_b128 v[154:157], v154 offset:3072
	ds_read_b128 v[158:161], v170
	ds_read_b128 v[162:165], v170 offset:1024
	ds_read_b128 v[166:169], v170 offset:2048
	ds_read_b128 v[170:173], v170 offset:3072
	s_add_u32 s94, s94, 0x70180
	s_addc_u32 s95, s95, 0
	s_mov_b32 m0, s1
	ds_read_b128 v[174:177], v151
	ds_read_b128 v[178:181], v151 offset:1024
	ds_read_b128 v[182:185], v151 offset:2048
	ds_read_b128 v[186:189], v151 offset:3072
	ds_read_b128 v[190:193], v151 offset:4096
	ds_read_b128 v[194:197], v151 offset:5120
	ds_read_b128 v[198:201], v151 offset:6144
	ds_read_b128 v[202:205], v151 offset:7168
	global_load_lds_dwordx4 v144, s[94:95]
	s_mov_b32 m0, s12
	s_nop 0
	global_load_lds_dwordx4 v146, s[94:95]
	s_waitcnt vmcnt(8)
	s_waitcnt lgkmcnt(0)
	s_barrier
	v_mfma_f32_16x16x32_bf16 v[124:127], v[128:131], v[174:177], v[124:127]
	v_mfma_f32_16x16x32_bf16 v[120:123], v[136:139], v[174:177], v[120:123]
	v_mfma_f32_16x16x32_bf16 v[108:111], v[128:131], v[182:185], v[108:111]
	v_mfma_f32_16x16x32_bf16 v[104:107], v[136:139], v[182:185], v[104:107]
	v_mfma_f32_16x16x32_bf16 v[92:95], v[128:131], v[190:193], v[92:95]
	v_mfma_f32_16x16x32_bf16 v[88:91], v[136:139], v[190:193], v[88:91]
	v_mfma_f32_16x16x32_bf16 v[60:63], v[128:131], v[198:201], v[60:63]
	v_mfma_f32_16x16x32_bf16 v[56:59], v[136:139], v[198:201], v[56:59]
	v_mfma_f32_16x16x32_bf16 v[124:127], v[132:135], v[178:181], v[124:127]
	v_mfma_f32_16x16x32_bf16 v[120:123], v[154:157], v[178:181], v[120:123]
	v_mfma_f32_16x16x32_bf16 v[108:111], v[132:135], v[186:189], v[108:111]
	v_mfma_f32_16x16x32_bf16 v[104:107], v[154:157], v[186:189], v[104:107]
	v_mfma_f32_16x16x32_bf16 v[92:95], v[132:135], v[194:197], v[92:95]
	v_mfma_f32_16x16x32_bf16 v[88:91], v[154:157], v[194:197], v[88:91]
	v_mfma_f32_16x16x32_bf16 v[60:63], v[132:135], v[202:205], v[60:63]
	v_mfma_f32_16x16x32_bf16 v[56:59], v[154:157], v[202:205], v[56:59]
	v_mfma_f32_16x16x32_bf16 v[116:119], v[158:161], v[174:177], v[116:119]
	v_mfma_f32_16x16x32_bf16 v[112:115], v[166:169], v[174:177], v[112:115]
	v_mfma_f32_16x16x32_bf16 v[100:103], v[158:161], v[182:185], v[100:103]
	v_mfma_f32_16x16x32_bf16 v[96:99], v[166:169], v[182:185], v[96:99]
	v_mfma_f32_16x16x32_bf16 v[84:87], v[158:161], v[190:193], v[84:87]
	v_mfma_f32_16x16x32_bf16 v[80:83], v[166:169], v[190:193], v[80:83]
	v_mfma_f32_16x16x32_bf16 v[52:55], v[158:161], v[198:201], v[52:55]
	v_mfma_f32_16x16x32_bf16 v[48:51], v[166:169], v[198:201], v[48:51]
	v_mfma_f32_16x16x32_bf16 v[116:119], v[162:165], v[178:181], v[116:119]
	v_mfma_f32_16x16x32_bf16 v[112:115], v[170:173], v[178:181], v[112:115]
	v_mfma_f32_16x16x32_bf16 v[100:103], v[162:165], v[186:189], v[100:103]
	v_mfma_f32_16x16x32_bf16 v[96:99], v[170:173], v[186:189], v[96:99]
	v_mfma_f32_16x16x32_bf16 v[84:87], v[162:165], v[194:197], v[84:87]
	v_mfma_f32_16x16x32_bf16 v[80:83], v[170:173], v[194:197], v[80:83]
	v_mfma_f32_16x16x32_bf16 v[52:55], v[162:165], v[202:205], v[52:55]
	v_mfma_f32_16x16x32_bf16 v[48:51], v[170:173], v[202:205], v[48:51]
	s_barrier
	s_add_i32 s94, s96, s68
	s_mov_b32 m0, s94
	ds_read_b128 v[174:177], v151 offset:16384
	ds_read_b128 v[178:181], v151 offset:17408
	ds_read_b128 v[182:185], v151 offset:18432
	ds_read_b128 v[186:189], v151 offset:19456
	ds_read_b128 v[190:193], v151 offset:20480
	ds_read_b128 v[194:197], v151 offset:21504
	ds_read_b128 v[198:201], v151 offset:22528
	ds_read_b128 v[202:205], v151 offset:23552
	global_load_lds_dwordx4 v145, s[64:65]
	s_add_i32 m0, s94, 0x2000
	s_add_u32 s94, s64, 0x20000
	s_addc_u32 s95, s65, 0
	s_add_i32 s96, s97, s68
	s_nop 0
	global_load_lds_dwordx4 v147, s[64:65]
	s_mov_b32 m0, s96
	s_nop 0
	global_load_lds_dwordx4 v145, s[94:95]
	s_add_i32 m0, s96, 0x2000
	s_nop 0
	global_load_lds_dwordx4 v147, s[94:95]
	s_mov_b32 m0, s3
	s_nop 0
	global_load_lds_dwordx4 v144, s[66:67]
	s_mov_b32 m0, s73
	s_nop 0
	global_load_lds_dwordx4 v146, s[66:67]
	s_waitcnt vmcnt(8)
	s_waitcnt lgkmcnt(0)
	s_barrier
	v_mfma_f32_16x16x32_bf16 v[76:79], v[128:131], v[174:177], v[76:79]
	v_mfma_f32_16x16x32_bf16 v[72:75], v[136:139], v[174:177], v[72:75]
	v_mfma_f32_16x16x32_bf16 v[44:47], v[128:131], v[182:185], v[44:47]
	v_mfma_f32_16x16x32_bf16 v[40:43], v[136:139], v[182:185], v[40:43]
	v_mfma_f32_16x16x32_bf16 v[28:31], v[128:131], v[190:193], v[28:31]
	v_mfma_f32_16x16x32_bf16 v[24:27], v[136:139], v[190:193], v[24:27]
	v_mfma_f32_16x16x32_bf16 v[12:15], v[128:131], v[198:201], v[12:15]
	v_mfma_f32_16x16x32_bf16 v[8:11], v[136:139], v[198:201], v[8:11]
	v_mfma_f32_16x16x32_bf16 v[76:79], v[132:135], v[178:181], v[76:79]
	v_mfma_f32_16x16x32_bf16 v[72:75], v[154:157], v[178:181], v[72:75]
	v_mfma_f32_16x16x32_bf16 v[44:47], v[132:135], v[186:189], v[44:47]
	v_mfma_f32_16x16x32_bf16 v[40:43], v[154:157], v[186:189], v[40:43]
	v_mfma_f32_16x16x32_bf16 v[28:31], v[132:135], v[194:197], v[28:31]
	v_mfma_f32_16x16x32_bf16 v[24:27], v[154:157], v[194:197], v[24:27]
	v_mfma_f32_16x16x32_bf16 v[12:15], v[132:135], v[202:205], v[12:15]
	v_mfma_f32_16x16x32_bf16 v[8:11], v[154:157], v[202:205], v[8:11]
	v_mfma_f32_16x16x32_bf16 v[68:71], v[158:161], v[174:177], v[68:71]
	v_mfma_f32_16x16x32_bf16 v[64:67], v[166:169], v[174:177], v[64:67]
	v_mfma_f32_16x16x32_bf16 v[36:39], v[158:161], v[182:185], v[36:39]
	v_mfma_f32_16x16x32_bf16 v[32:35], v[166:169], v[182:185], v[32:35]
	v_mfma_f32_16x16x32_bf16 v[20:23], v[158:161], v[190:193], v[20:23]
	v_mfma_f32_16x16x32_bf16 v[16:19], v[166:169], v[190:193], v[16:19]
	v_mfma_f32_16x16x32_bf16 v[4:7], v[158:161], v[198:201], v[4:7]
	v_mfma_f32_16x16x32_bf16 v[0:3], v[166:169], v[198:201], v[0:3]
	v_mfma_f32_16x16x32_bf16 v[68:71], v[162:165], v[178:181], v[68:71]
	v_mfma_f32_16x16x32_bf16 v[64:67], v[170:173], v[178:181], v[64:67]
	v_mfma_f32_16x16x32_bf16 v[36:39], v[162:165], v[186:189], v[36:39]
	v_mfma_f32_16x16x32_bf16 v[32:35], v[170:173], v[186:189], v[32:35]
	v_mfma_f32_16x16x32_bf16 v[20:23], v[162:165], v[194:197], v[20:23]
	v_mfma_f32_16x16x32_bf16 v[16:19], v[170:173], v[194:197], v[16:19]
	v_mfma_f32_16x16x32_bf16 v[4:7], v[162:165], v[202:205], v[4:7]
	v_mfma_f32_16x16x32_bf16 v[0:3], v[170:173], v[202:205], v[0:3]
	s_barrier
	ds_read_b128 v[128:131], v142
	ds_read_b128 v[132:135], v142 offset:1024
	ds_read_b128 v[136:139], v142 offset:2048
	ds_read_b128 v[154:157], v142 offset:3072
	ds_read_b128 v[158:161], v153
	ds_read_b128 v[162:165], v153 offset:1024
	ds_read_b128 v[166:169], v153 offset:2048
	ds_read_b128 v[170:173], v153 offset:3072
	s_add_u32 s66, s66, 0x70000
	s_addc_u32 s67, s67, 0
	s_mov_b32 m0, s74
	ds_read_b128 v[174:177], v151 offset:32768
	ds_read_b128 v[178:181], v151 offset:33792
	ds_read_b128 v[182:185], v151 offset:34816
	ds_read_b128 v[186:189], v151 offset:35840
	ds_read_b128 v[190:193], v151 offset:36864
	ds_read_b128 v[194:197], v151 offset:37888
	ds_read_b128 v[198:201], v151 offset:38912
	ds_read_b128 v[202:205], v151 offset:39936
	global_load_lds_dwordx4 v144, s[66:67]
	s_mov_b32 m0, s75
	s_nop 0
	global_load_lds_dwordx4 v146, s[66:67]
	s_waitcnt vmcnt(8)
	s_waitcnt lgkmcnt(0)
	s_barrier
	v_mfma_f32_16x16x32_bf16 v[124:127], v[128:131], v[174:177], v[124:127]
	v_mfma_f32_16x16x32_bf16 v[120:123], v[136:139], v[174:177], v[120:123]
	v_mfma_f32_16x16x32_bf16 v[108:111], v[128:131], v[182:185], v[108:111]
	v_mfma_f32_16x16x32_bf16 v[104:107], v[136:139], v[182:185], v[104:107]
	v_mfma_f32_16x16x32_bf16 v[92:95], v[128:131], v[190:193], v[92:95]
	v_mfma_f32_16x16x32_bf16 v[88:91], v[136:139], v[190:193], v[88:91]
	v_mfma_f32_16x16x32_bf16 v[60:63], v[128:131], v[198:201], v[60:63]
	v_mfma_f32_16x16x32_bf16 v[56:59], v[136:139], v[198:201], v[56:59]
	v_mfma_f32_16x16x32_bf16 v[124:127], v[132:135], v[178:181], v[124:127]
	v_mfma_f32_16x16x32_bf16 v[120:123], v[154:157], v[178:181], v[120:123]
	v_mfma_f32_16x16x32_bf16 v[108:111], v[132:135], v[186:189], v[108:111]
	v_mfma_f32_16x16x32_bf16 v[104:107], v[154:157], v[186:189], v[104:107]
	v_mfma_f32_16x16x32_bf16 v[92:95], v[132:135], v[194:197], v[92:95]
	v_mfma_f32_16x16x32_bf16 v[88:91], v[154:157], v[194:197], v[88:91]
	v_mfma_f32_16x16x32_bf16 v[60:63], v[132:135], v[202:205], v[60:63]
	v_mfma_f32_16x16x32_bf16 v[56:59], v[154:157], v[202:205], v[56:59]
	v_mfma_f32_16x16x32_bf16 v[116:119], v[158:161], v[174:177], v[116:119]
	v_mfma_f32_16x16x32_bf16 v[112:115], v[166:169], v[174:177], v[112:115]
	v_mfma_f32_16x16x32_bf16 v[100:103], v[158:161], v[182:185], v[100:103]
	v_mfma_f32_16x16x32_bf16 v[96:99], v[166:169], v[182:185], v[96:99]
	v_mfma_f32_16x16x32_bf16 v[84:87], v[158:161], v[190:193], v[84:87]
	v_mfma_f32_16x16x32_bf16 v[80:83], v[166:169], v[190:193], v[80:83]
	v_mfma_f32_16x16x32_bf16 v[52:55], v[158:161], v[198:201], v[52:55]
	v_mfma_f32_16x16x32_bf16 v[48:51], v[166:169], v[198:201], v[48:51]
	v_mfma_f32_16x16x32_bf16 v[116:119], v[162:165], v[178:181], v[116:119]
	v_mfma_f32_16x16x32_bf16 v[112:115], v[170:173], v[178:181], v[112:115]
	v_mfma_f32_16x16x32_bf16 v[100:103], v[162:165], v[186:189], v[100:103]
	v_mfma_f32_16x16x32_bf16 v[96:99], v[170:173], v[186:189], v[96:99]
	v_mfma_f32_16x16x32_bf16 v[84:87], v[162:165], v[194:197], v[84:87]
	v_mfma_f32_16x16x32_bf16 v[80:83], v[170:173], v[194:197], v[80:83]
	v_mfma_f32_16x16x32_bf16 v[52:55], v[162:165], v[202:205], v[52:55]
	v_mfma_f32_16x16x32_bf16 v[48:51], v[170:173], v[202:205], v[48:51]
	s_barrier
	s_add_u32 s66, s64, 0x80
	s_mov_b32 m0, s49
	s_addc_u32 s67, s65, 0
	ds_read_b128 v[174:177], v151 offset:49152
	ds_read_b128 v[178:181], v151 offset:50176
	ds_read_b128 v[182:185], v151 offset:51200
	ds_read_b128 v[186:189], v151 offset:52224
	ds_read_b128 v[190:193], v151 offset:53248
	ds_read_b128 v[194:197], v151 offset:54272
	ds_read_b128 v[198:201], v151 offset:55296
	ds_read_b128 v[202:205], v151 offset:56320
	s_add_u32 s64, s64, 0x20080
	global_load_lds_dwordx4 v145, s[66:67]
	s_mov_b32 m0, s51
	s_addc_u32 s65, s65, 0
	global_load_lds_dwordx4 v147, s[66:67]
	s_mov_b32 m0, s79
	s_nop 0
	global_load_lds_dwordx4 v145, s[64:65]
	s_mov_b32 m0, s86
	s_nop 0
	global_load_lds_dwordx4 v147, s[64:65]
	s_mov_b32 m0, s76
	s_nop 0
	global_load_lds_dwordx4 v144, s[62:63]
	s_mov_b32 m0, s77
	s_nop 0
	global_load_lds_dwordx4 v146, s[62:63]
	s_waitcnt vmcnt(8)
	s_waitcnt lgkmcnt(0)
	s_barrier
	v_mfma_f32_16x16x32_bf16 v[76:79], v[128:131], v[174:177], v[76:79]
	v_mfma_f32_16x16x32_bf16 v[72:75], v[136:139], v[174:177], v[72:75]
	v_mfma_f32_16x16x32_bf16 v[44:47], v[128:131], v[182:185], v[44:47]
	v_mfma_f32_16x16x32_bf16 v[40:43], v[136:139], v[182:185], v[40:43]
	v_mfma_f32_16x16x32_bf16 v[28:31], v[128:131], v[190:193], v[28:31]
	v_mfma_f32_16x16x32_bf16 v[24:27], v[136:139], v[190:193], v[24:27]
	v_mfma_f32_16x16x32_bf16 v[12:15], v[128:131], v[198:201], v[12:15]
	v_mfma_f32_16x16x32_bf16 v[8:11], v[136:139], v[198:201], v[8:11]
	v_mfma_f32_16x16x32_bf16 v[76:79], v[132:135], v[178:181], v[76:79]
	v_mfma_f32_16x16x32_bf16 v[72:75], v[154:157], v[178:181], v[72:75]
	v_mfma_f32_16x16x32_bf16 v[44:47], v[132:135], v[186:189], v[44:47]
	v_mfma_f32_16x16x32_bf16 v[40:43], v[154:157], v[186:189], v[40:43]
	v_mfma_f32_16x16x32_bf16 v[28:31], v[132:135], v[194:197], v[28:31]
	v_mfma_f32_16x16x32_bf16 v[24:27], v[154:157], v[194:197], v[24:27]
	v_mfma_f32_16x16x32_bf16 v[12:15], v[132:135], v[202:205], v[12:15]
	v_mfma_f32_16x16x32_bf16 v[8:11], v[154:157], v[202:205], v[8:11]
	v_mfma_f32_16x16x32_bf16 v[68:71], v[158:161], v[174:177], v[68:71]
	v_mfma_f32_16x16x32_bf16 v[64:67], v[166:169], v[174:177], v[64:67]
	v_mfma_f32_16x16x32_bf16 v[36:39], v[158:161], v[182:185], v[36:39]
	v_mfma_f32_16x16x32_bf16 v[32:35], v[166:169], v[182:185], v[32:35]
	v_mfma_f32_16x16x32_bf16 v[20:23], v[158:161], v[190:193], v[20:23]
	v_mfma_f32_16x16x32_bf16 v[16:19], v[166:169], v[190:193], v[16:19]
	v_mfma_f32_16x16x32_bf16 v[4:7], v[158:161], v[198:201], v[4:7]
	v_mfma_f32_16x16x32_bf16 v[0:3], v[166:169], v[198:201], v[0:3]
	v_mfma_f32_16x16x32_bf16 v[68:71], v[162:165], v[178:181], v[68:71]
	v_mfma_f32_16x16x32_bf16 v[64:67], v[170:173], v[178:181], v[64:67]
	v_mfma_f32_16x16x32_bf16 v[36:39], v[162:165], v[186:189], v[36:39]
	v_mfma_f32_16x16x32_bf16 v[32:35], v[170:173], v[186:189], v[32:35]
	v_mfma_f32_16x16x32_bf16 v[20:23], v[162:165], v[194:197], v[20:23]
	v_mfma_f32_16x16x32_bf16 v[16:19], v[170:173], v[194:197], v[16:19]
	v_mfma_f32_16x16x32_bf16 v[4:7], v[162:165], v[202:205], v[4:7]
	v_mfma_f32_16x16x32_bf16 v[0:3], v[170:173], v[202:205], v[0:3]
	s_barrier
	s_add_i32 s93, s93, 2
	s_add_u32 s60, s60, 0x100
	s_addc_u32 s61, s61, 0
	s_cmp_gt_u32 s93, 5
	s_cbranch_scc0 .LBB0_1777
	s_and_b64 vcc, exec, s[46:47]
	s_cbranch_vccz .LBB0_1780
	s_barrier

.LBB0_1920:
	s_waitcnt lgkmcnt(0)
	s_barrier
	s_and_b64 vcc, exec, s[2:3]
	s_cbranch_vccnz .LBB0_1922
	s_add_u32 s4, s42, 0x100000
	s_mov_b32 m0, s68
	s_addc_u32 s5, s43, 0
	global_load_lds_dwordx4 v165, s[4:5]
	s_mov_b32 m0, s46
	s_nop 0
	global_load_lds_dwordx4 v166, s[4:5]
	s_add_u32 s4, s42, 0x80400
	s_addc_u32 s5, s43, 0
	s_mov_b32 m0, s53
	s_nop 0
	global_load_lds_dwordx4 v146, s[4:5]
	s_mov_b32 m0, s54
	s_nop 0
	global_load_lds_dwordx4 v144, s[4:5]

.LBB0_1924:
	v_lshlrev_b32_e32 v4, 1, v32
	v_and_b32_e32 v4, 32, v4
	v_and_b32_e32 v5, 0xc0, v33
	v_and_b32_e32 v6, 0x100, v35
	s_waitcnt lgkmcnt(0)
	s_barrier
	v_add3_u32 v4, v4, s55, v5
	v_add3_u32 v147, v4, v6, v34
	ds_read_b64_tr_b16 v[16:17], v147 offset:0
	ds_read_b64_tr_b16 v[18:19], v147 offset:0x800
	ds_read_b64_tr_b16 v[12:13], v147 offset:0x1000
	ds_read_b64_tr_b16 v[14:15], v147 offset:0x1800
	ds_read_b64_tr_b16 v[8:9], v147 offset:0x2000
	ds_read_b64_tr_b16 v[10:11], v147 offset:0x2800
	ds_read_b64_tr_b16 v[4:5], v147 offset:0x3000
	ds_read_b64_tr_b16 v[6:7], v147 offset:0x3800
	s_and_b64 vcc, exec, s[4:5]
	s_cbranch_vccnz .LBB0_1926
	s_add_u32 s20, s42, 0x100000
	s_mov_b32 m0, s68
	s_addc_u32 s21, s43, 0
	global_load_lds_dwordx4 v165, s[20:21]
	s_mov_b32 m0, s46
	s_nop 0
	global_load_lds_dwordx4 v166, s[20:21]
	s_add_u32 s20, s42, 0x80400
	s_addc_u32 s21, s43, 0
	s_mov_b32 m0, s53
	s_nop 0
	global_load_lds_dwordx4 v146, s[20:21]
	s_mov_b32 m0, s54
	s_nop 0
	global_load_lds_dwordx4 v144, s[20:21]

.LBB0_1928:
	s_waitcnt lgkmcnt(0)
	s_barrier
	s_and_b64 vcc, exec, s[2:3]
	s_cbranch_vccnz .LBB0_1930
	s_add_u32 s20, s42, 0x180000
	s_mov_b32 m0, s47
	s_addc_u32 s21, s43, 0
	global_load_lds_dwordx4 v165, s[20:21]
	s_mov_b32 m0, s48
	s_nop 0
	global_load_lds_dwordx4 v166, s[20:21]
	s_add_u32 s20, s42, 0x100400
	s_addc_u32 s21, s43, 0
	s_mov_b32 m0, s49
	s_nop 0
	global_load_lds_dwordx4 v146, s[20:21]
	s_mov_b32 m0, s50
	s_nop 0
	global_load_lds_dwordx4 v144, s[20:21]

.LBB0_1934:
	s_waitcnt lgkmcnt(0)
	s_barrier
	v_add_u32_e32 v148, 0x4000, v147
	ds_read_b64_tr_b16 v[108:109], v148 offset:0
	ds_read_b64_tr_b16 v[110:111], v148 offset:0x800
	ds_read_b64_tr_b16 v[104:105], v148 offset:0x1000
	ds_read_b64_tr_b16 v[106:107], v148 offset:0x1800
	ds_read_b64_tr_b16 v[100:101], v148 offset:0x2000
	ds_read_b64_tr_b16 v[102:103], v148 offset:0x2800
	ds_read_b64_tr_b16 v[96:97], v148 offset:0x3000
	ds_read_b64_tr_b16 v[98:99], v148 offset:0x3800
	s_and_b64 vcc, exec, s[4:5]
	s_cbranch_vccnz .LBB0_1936
	s_add_u32 s20, s42, 0x180000
	s_mov_b32 m0, s47
	s_addc_u32 s21, s43, 0
	global_load_lds_dwordx4 v165, s[20:21]
	s_mov_b32 m0, s48
	s_nop 0
	global_load_lds_dwordx4 v166, s[20:21]
	s_add_u32 s20, s42, 0x100400
	s_addc_u32 s21, s43, 0
	s_mov_b32 m0, s49
	s_nop 0
	global_load_lds_dwordx4 v146, s[20:21]
	s_mov_b32 m0, s50
	s_nop 0
	global_load_lds_dwordx4 v144, s[20:21]

.LBB0_2038:
	s_add_u32 s20, s56, 0x100
	s_addc_u32 s21, s57, 0
	s_waitcnt lgkmcnt(0)
	s_add_u32 s52, s54, 0x100
	s_addc_u32 s53, s55, 0
	s_barrier
	s_waitcnt lgkmcnt(0)
	v_mfma_f32_16x16x32_bf16 v[32:35], v[16:19], v[68:71], 0
	v_mfma_f32_16x16x32_bf16 v[36:39], v[24:27], v[68:71], 0
	v_mfma_f32_16x16x32_bf16 v[40:43], v[16:19], v[84:87], 0
	v_mfma_f32_16x16x32_bf16 v[44:47], v[24:27], v[84:87], 0
	v_mfma_f32_16x16x32_bf16 v[48:51], v[16:19], v[92:95], 0
	v_mfma_f32_16x16x32_bf16 v[52:55], v[24:27], v[92:95], 0
	v_mfma_f32_16x16x32_bf16 v[56:59], v[16:19], v[76:79], 0
	v_mfma_f32_16x16x32_bf16 v[60:63], v[24:27], v[76:79], 0
	v_mfma_f32_16x16x32_bf16 v[134:137], v[20:23], v[72:75], v[32:35]
	v_mfma_f32_16x16x32_bf16 v[36:39], v[28:31], v[72:75], v[36:39]
	v_mfma_f32_16x16x32_bf16 v[40:43], v[20:23], v[88:91], v[40:43]
	v_mfma_f32_16x16x32_bf16 v[44:47], v[28:31], v[88:91], v[44:47]
	v_mfma_f32_16x16x32_bf16 v[48:51], v[20:23], v[96:99], v[48:51]
	v_mfma_f32_16x16x32_bf16 v[52:55], v[28:31], v[96:99], v[52:55]
	v_mfma_f32_16x16x32_bf16 v[56:59], v[20:23], v[80:83], v[56:59]
	v_mfma_f32_16x16x32_bf16 v[60:63], v[28:31], v[80:83], v[60:63]
	v_mfma_f32_16x16x32_bf16 v[64:67], v[0:3], v[68:71], 0
	v_mfma_f32_16x16x32_bf16 v[68:71], v[8:11], v[68:71], 0
	v_mfma_f32_16x16x32_bf16 v[64:67], v[4:7], v[72:75], v[64:67]
	v_mfma_f32_16x16x32_bf16 v[68:71], v[12:15], v[72:75], v[68:71]
	v_mfma_f32_16x16x32_bf16 v[72:75], v[0:3], v[84:87], 0
	v_mfma_f32_16x16x32_bf16 v[84:87], v[8:11], v[84:87], 0
	v_mfma_f32_16x16x32_bf16 v[72:75], v[4:7], v[88:91], v[72:75]
	v_mfma_f32_16x16x32_bf16 v[84:87], v[12:15], v[88:91], v[84:87]
	v_mfma_f32_16x16x32_bf16 v[88:91], v[0:3], v[92:95], 0
	v_mfma_f32_16x16x32_bf16 v[92:95], v[8:11], v[92:95], 0
	v_mfma_f32_16x16x32_bf16 v[88:91], v[4:7], v[96:99], v[88:91]
	v_mfma_f32_16x16x32_bf16 v[96:99], v[12:15], v[96:99], v[92:95]
	v_mfma_f32_16x16x32_bf16 v[92:95], v[0:3], v[76:79], 0
	v_mfma_f32_16x16x32_bf16 v[76:79], v[8:11], v[76:79], 0
	v_mfma_f32_16x16x32_bf16 v[108:111], v[4:7], v[80:83], v[92:95]
	v_mfma_f32_16x16x32_bf16 v[120:123], v[12:15], v[80:83], v[76:79]
	s_barrier
	s_mov_b32 m0, s62
	ds_read_b128 v[116:119], v209 offset:16384
	ds_read_b128 v[124:127], v209 offset:17408
	ds_read_b128 v[104:107], v209 offset:18432
	ds_read_b128 v[112:115], v209 offset:19456
	ds_read_b128 v[92:95], v209 offset:20480
	ds_read_b128 v[100:103], v209 offset:21504
	ds_read_b128 v[76:79], v209 offset:22528
	ds_read_b128 v[80:83], v209 offset:23552
	global_load_lds_dwordx4 v203, s[52:53]
	s_mov_b32 m0, s63
	s_nop 0
	global_load_lds_dwordx4 v205, s[52:53]
	s_add_u32 s52, s54, 0x80100
	s_addc_u32 s53, s55, 0
	s_mov_b32 m0, s64
	s_and_b64 vcc, exec, s[50:51]
	global_load_lds_dwordx4 v203, s[52:53]
	s_mov_b32 m0, s65
	s_nop 0
	global_load_lds_dwordx4 v205, s[52:53]
	s_mov_b32 m0, s27
	s_mov_b64 s[52:53], -1
	global_load_lds_dwordx4 v202, s[20:21]
	s_mov_b32 m0, s66
	s_nop 0
	global_load_lds_dwordx4 v204, s[20:21]
	s_cbranch_vccz .LBB0_2040
	s_waitcnt vmcnt(8)
	s_mov_b64 s[52:53], 0

.LBB0_2042:
	s_ashr_i32 s45, s44, 31
	s_lshl_b64 s[20:21], s[44:45], 20
	s_add_u32 s50, s13, s20
	s_addc_u32 s51, s82, s21
	s_and_b64 s[20:21], s[48:49], exec
	s_cselect_b32 s5, s51, s57
	s_cselect_b32 s12, s50, s56
	s_ashr_i32 s47, s46, 31
	s_lshl_b64 s[20:21], s[46:47], 20
	s_add_u32 s52, s24, s20
	s_addc_u32 s53, s25, s21
	s_and_b64 s[20:21], s[48:49], exec
	s_cselect_b32 s20, s53, s55
	s_cselect_b32 s21, s52, s54
	s_add_u32 s58, s56, 0x180
	s_waitcnt lgkmcnt(0)
	s_addc_u32 s59, s57, 0
	s_add_u32 s60, s54, 0x180
	s_addc_u32 s61, s55, 0
	s_barrier
	s_waitcnt lgkmcnt(0)
	v_mfma_f32_16x16x32_bf16 v[128:131], v[16:19], v[116:119], 0
	v_mfma_f32_16x16x32_bf16 v[140:143], v[20:23], v[124:127], v[128:131]
	v_mfma_f32_16x16x32_bf16 v[128:131], v[24:27], v[116:119], 0
	v_mfma_f32_16x16x32_bf16 v[156:159], v[28:31], v[124:127], v[128:131]
	v_mfma_f32_16x16x32_bf16 v[128:131], v[16:19], v[104:107], 0
	v_mfma_f32_16x16x32_bf16 v[160:163], v[20:23], v[112:115], v[128:131]
	v_mfma_f32_16x16x32_bf16 v[128:131], v[24:27], v[104:107], 0
	v_mfma_f32_16x16x32_bf16 v[164:167], v[28:31], v[112:115], v[128:131]
	v_mfma_f32_16x16x32_bf16 v[128:131], v[16:19], v[92:95], 0
	v_mfma_f32_16x16x32_bf16 v[16:19], v[16:19], v[76:79], 0
	v_mfma_f32_16x16x32_bf16 v[168:171], v[20:23], v[100:103], v[128:131]
	v_mfma_f32_16x16x32_bf16 v[16:19], v[20:23], v[80:83], v[16:19]
	v_mfma_f32_16x16x32_bf16 v[20:23], v[24:27], v[76:79], 0
	v_mfma_f32_16x16x32_bf16 v[128:131], v[24:27], v[92:95], 0
	v_mfma_f32_16x16x32_bf16 v[20:23], v[28:31], v[80:83], v[20:23]
	v_mfma_f32_16x16x32_bf16 v[172:175], v[28:31], v[100:103], v[128:131]
	v_mfma_f32_16x16x32_bf16 v[24:27], v[0:3], v[116:119], 0
	v_mfma_f32_16x16x32_bf16 v[176:179], v[4:7], v[124:127], v[24:27]
	v_mfma_f32_16x16x32_bf16 v[24:27], v[8:11], v[116:119], 0
	v_mfma_f32_16x16x32_bf16 v[180:183], v[12:15], v[124:127], v[24:27]
	v_mfma_f32_16x16x32_bf16 v[24:27], v[0:3], v[104:107], 0
	v_mfma_f32_16x16x32_bf16 v[186:189], v[4:7], v[112:115], v[24:27]
	v_mfma_f32_16x16x32_bf16 v[24:27], v[8:11], v[104:107], 0
	v_mfma_f32_16x16x32_bf16 v[190:193], v[12:15], v[112:115], v[24:27]
	v_mfma_f32_16x16x32_bf16 v[24:27], v[0:3], v[92:95], 0
	v_mfma_f32_16x16x32_bf16 v[0:3], v[0:3], v[76:79], 0
	v_mfma_f32_16x16x32_bf16 v[194:197], v[4:7], v[100:103], v[24:27]
	v_mfma_f32_16x16x32_bf16 v[24:27], v[8:11], v[92:95], 0
	v_mfma_f32_16x16x32_bf16 v[0:3], v[4:7], v[80:83], v[0:3]
	v_mfma_f32_16x16x32_bf16 v[4:7], v[8:11], v[76:79], 0
	v_mfma_f32_16x16x32_bf16 v[198:201], v[12:15], v[100:103], v[24:27]
	v_mfma_f32_16x16x32_bf16 v[212:215], v[12:15], v[80:83], v[4:7]
	s_barrier
	v_add_u32_e32 v132, s75, v206
	v_add_u32_e32 v133, s76, v206
	s_nop 1
	ds_read_b128 v[4:7], v132
	ds_read_b128 v[8:11], v132 offset:1024
	ds_read_b128 v[216:219], v132 offset:2048
	ds_read_b128 v[220:223], v132 offset:3072
	ds_read_b128 v[224:227], v133
	ds_read_b128 v[228:231], v133 offset:1024
	ds_read_b128 v[232:235], v133 offset:2048
	ds_read_b128 v[236:239], v133 offset:3072
	s_add_u32 s88, s56, 0x80100
	s_addc_u32 s89, s57, 0
	s_mov_b32 m0, s67
	ds_read_b128 v[12:15], v209 offset:32768
	ds_read_b128 v[24:27], v209 offset:33792
	ds_read_b128 v[28:31], v209 offset:34816
	ds_read_b128 v[92:95], v209 offset:35840
	ds_read_b128 v[240:243], v209 offset:36864
	ds_read_b128 v[244:247], v209 offset:37888
	ds_read_b128 v[248:251], v209 offset:38912
	ds_read_b128 v[32:35], v209 offset:39936
	global_load_lds_dwordx4 v202, s[88:89]
	s_mov_b32 m0, s68
	s_nop 0
	global_load_lds_dwordx4 v204, s[88:89]
	s_waitcnt vmcnt(8)
	s_waitcnt lgkmcnt(0)
	s_barrier
	v_mfma_f32_16x16x32_bf16 v[36:39], v[216:219], v[12:15], v[36:39]
	v_mfma_f32_16x16x32_bf16 v[148:151], v[220:223], v[24:27], v[36:39]
	v_mfma_f32_16x16x32_bf16 v[36:39], v[4:7], v[28:31], v[40:43]
	v_mfma_f32_16x16x32_bf16 v[128:131], v[8:11], v[92:95], v[36:39]
	v_mfma_f32_16x16x32_bf16 v[36:39], v[216:219], v[28:31], v[44:47]
	v_mfma_f32_16x16x32_bf16 v[124:127], v[220:223], v[92:95], v[36:39]
	v_mfma_f32_16x16x32_bf16 v[36:39], v[4:7], v[240:243], v[48:51]
	v_mfma_f32_16x16x32_bf16 v[104:107], v[8:11], v[244:247], v[36:39]
	v_mfma_f32_16x16x32_bf16 v[36:39], v[216:219], v[240:243], v[52:55]
	v_mfma_f32_16x16x32_bf16 v[100:103], v[220:223], v[244:247], v[36:39]
	v_mfma_f32_16x16x32_bf16 v[36:39], v[4:7], v[248:251], v[56:59]
	v_mfma_f32_16x16x32_bf16 v[76:79], v[4:7], v[12:15], v[134:137]
	v_mfma_f32_16x16x32_bf16 v[80:83], v[8:11], v[32:35], v[36:39]
	v_mfma_f32_16x16x32_bf16 v[36:39], v[216:219], v[248:251], v[60:63]
	v_mfma_f32_16x16x32_bf16 v[152:155], v[8:11], v[24:27], v[76:79]
	v_mfma_f32_16x16x32_bf16 v[76:79], v[220:223], v[32:35], v[36:39]
	v_mfma_f32_16x16x32_bf16 v[36:39], v[224:227], v[12:15], v[64:67]
	v_mfma_f32_16x16x32_bf16 v[12:15], v[232:235], v[12:15], v[68:71]
	v_mfma_f32_16x16x32_bf16 v[136:139], v[236:239], v[24:27], v[12:15]
	v_mfma_f32_16x16x32_bf16 v[12:15], v[224:227], v[28:31], v[72:75]
	v_mfma_f32_16x16x32_bf16 v[116:119], v[228:231], v[92:95], v[12:15]
	v_mfma_f32_16x16x32_bf16 v[12:15], v[232:235], v[28:31], v[84:87]
	v_mfma_f32_16x16x32_bf16 v[112:115], v[236:239], v[92:95], v[12:15]
	v_mfma_f32_16x16x32_bf16 v[12:15], v[224:227], v[240:243], v[88:91]
	v_mfma_f32_16x16x32_bf16 v[92:95], v[228:231], v[244:247], v[12:15]
	v_mfma_f32_16x16x32_bf16 v[12:15], v[232:235], v[240:243], v[96:99]
	v_mfma_f32_16x16x32_bf16 v[88:91], v[236:239], v[244:247], v[12:15]
	v_mfma_f32_16x16x32_bf16 v[12:15], v[224:227], v[248:251], v[108:111]
	v_mfma_f32_16x16x32_bf16 v[68:71], v[228:231], v[32:35], v[12:15]
	v_mfma_f32_16x16x32_bf16 v[12:15], v[232:235], v[248:251], v[120:123]
	v_mfma_f32_16x16x32_bf16 v[144:147], v[228:231], v[24:27], v[36:39]
	v_mfma_f32_16x16x32_bf16 v[64:67], v[236:239], v[32:35], v[12:15]
	s_barrier
	s_add_i32 s45, s75, s26
	s_mov_b32 m0, s45
	s_add_i32 s47, s45, 0x2000
	ds_read_b128 v[32:35], v209 offset:49152
	ds_read_b128 v[36:39], v209 offset:50176
	ds_read_b128 v[72:75], v209 offset:51200
	ds_read_b128 v[84:87], v209 offset:52224
	ds_read_b128 v[96:99], v209 offset:53248
	ds_read_b128 v[108:111], v209 offset:54272
	ds_read_b128 v[120:123], v209 offset:55296
	ds_read_b128 v[240:243], v209 offset:56320
	global_load_lds_dwordx4 v203, s[60:61]
	s_mov_b32 m0, s47
	s_nop 0
	global_load_lds_dwordx4 v205, s[60:61]
	s_add_u32 s60, s54, 0x80180
	s_addc_u32 s61, s55, 0
	s_add_i32 s79, s76, s26
	s_mov_b32 m0, s79
	s_add_i32 s80, s79, 0x2000
	s_nop 0
	global_load_lds_dwordx4 v203, s[60:61]
	s_mov_b32 m0, s80
	s_nop 0
	global_load_lds_dwordx4 v205, s[60:61]
	s_mov_b32 m0, s69
	s_nop 0
	global_load_lds_dwordx4 v202, s[58:59]
	s_mov_b32 m0, s70
	s_nop 0
	global_load_lds_dwordx4 v204, s[58:59]
	s_waitcnt vmcnt(8)
	s_waitcnt lgkmcnt(0)
	s_barrier
	v_mfma_f32_16x16x32_bf16 v[12:15], v[4:7], v[32:35], v[140:143]
	v_mfma_f32_16x16x32_bf16 v[60:63], v[8:11], v[36:39], v[12:15]
	v_mfma_f32_16x16x32_bf16 v[12:15], v[216:219], v[32:35], v[156:159]
	v_mfma_f32_16x16x32_bf16 v[56:59], v[220:223], v[36:39], v[12:15]
	v_mfma_f32_16x16x32_bf16 v[12:15], v[4:7], v[72:75], v[160:163]
	v_mfma_f32_16x16x32_bf16 v[44:47], v[8:11], v[84:87], v[12:15]
	v_mfma_f32_16x16x32_bf16 v[12:15], v[216:219], v[72:75], v[164:167]
	v_mfma_f32_16x16x32_bf16 v[40:43], v[220:223], v[84:87], v[12:15]
	v_mfma_f32_16x16x32_bf16 v[12:15], v[4:7], v[96:99], v[168:171]
	v_mfma_f32_16x16x32_bf16 v[28:31], v[8:11], v[108:111], v[12:15]
	v_mfma_f32_16x16x32_bf16 v[12:15], v[216:219], v[96:99], v[172:175]
	v_mfma_f32_16x16x32_bf16 v[4:7], v[4:7], v[120:123], v[16:19]
	v_mfma_f32_16x16x32_bf16 v[24:27], v[220:223], v[108:111], v[12:15]
	v_mfma_f32_16x16x32_bf16 v[12:15], v[8:11], v[240:243], v[4:7]
	v_mfma_f32_16x16x32_bf16 v[4:7], v[216:219], v[120:123], v[20:23]
	v_mfma_f32_16x16x32_bf16 v[8:11], v[220:223], v[240:243], v[4:7]
	v_mfma_f32_16x16x32_bf16 v[4:7], v[224:227], v[32:35], v[176:179]
	v_mfma_f32_16x16x32_bf16 v[52:55], v[228:231], v[36:39], v[4:7]
	v_mfma_f32_16x16x32_bf16 v[4:7], v[232:235], v[32:35], v[180:183]
	v_mfma_f32_16x16x32_bf16 v[48:51], v[236:239], v[36:39], v[4:7]
	v_mfma_f32_16x16x32_bf16 v[4:7], v[224:227], v[72:75], v[186:189]
	v_mfma_f32_16x16x32_bf16 v[36:39], v[228:231], v[84:87], v[4:7]
	v_mfma_f32_16x16x32_bf16 v[4:7], v[232:235], v[72:75], v[190:193]
	v_mfma_f32_16x16x32_bf16 v[32:35], v[236:239], v[84:87], v[4:7]
	v_mfma_f32_16x16x32_bf16 v[4:7], v[224:227], v[96:99], v[194:197]
	v_mfma_f32_16x16x32_bf16 v[20:23], v[228:231], v[108:111], v[4:7]
	v_mfma_f32_16x16x32_bf16 v[4:7], v[232:235], v[96:99], v[198:201]
	v_mfma_f32_16x16x32_bf16 v[0:3], v[224:227], v[120:123], v[0:3]
	v_mfma_f32_16x16x32_bf16 v[16:19], v[236:239], v[108:111], v[4:7]
	v_mfma_f32_16x16x32_bf16 v[4:7], v[228:231], v[240:243], v[0:3]
	v_mfma_f32_16x16x32_bf16 v[0:3], v[232:235], v[120:123], v[212:215]
	v_mfma_f32_16x16x32_bf16 v[0:3], v[236:239], v[240:243], v[0:3]
	s_barrier
	s_add_u32 s83, s56, 0x200
	s_addc_u32 s86, s57, 0
	s_add_u32 s88, s54, 0x200
	s_addc_u32 s89, s55, 0
	s_add_u32 s54, s56, 0x80180
	s_addc_u32 s55, s57, 0
	s_mov_b32 s90, 0
.LBB0_2043:
	s_cmp_eq_u32 s90, 28
	s_cselect_b32 s60, s12, s83
	s_cselect_b32 s61, s5, s86
	s_cselect_b32 s58, s21, s88
	s_cselect_b32 s59, s20, s89
	s_add_u32 s56, s60, 0x80
	s_addc_u32 s57, s61, 0
	s_add_i32 s91, 0, 0x10000
	s_add_i32 s94, 0, 0x14000
	v_add_u32_e32 v108, s91, v206
	v_add_u32_e32 v134, s94, v206
	ds_read_b128 v[72:75], v108
	ds_read_b128 v[84:87], v108 offset:1024
	ds_read_b128 v[96:99], v108 offset:2048
	ds_read_b128 v[108:111], v108 offset:3072
	ds_read_b128 v[120:123], v134
	ds_read_b128 v[140:143], v134 offset:1024
	ds_read_b128 v[156:159], v134 offset:2048
	ds_read_b128 v[160:163], v134 offset:3072
	s_mov_b32 m0, s1
	ds_read_b128 v[164:167], v209
	ds_read_b128 v[168:171], v209 offset:1024
	ds_read_b128 v[172:175], v209 offset:2048
	ds_read_b128 v[176:179], v209 offset:3072
	ds_read_b128 v[180:183], v209 offset:4096
	ds_read_b128 v[186:189], v209 offset:5120
	ds_read_b128 v[190:193], v209 offset:6144
	ds_read_b128 v[194:197], v209 offset:7168
	global_load_lds_dwordx4 v202, s[54:55]
	s_mov_b32 m0, s3
	s_nop 0
	global_load_lds_dwordx4 v204, s[54:55]
	s_waitcnt vmcnt(8)
	s_waitcnt lgkmcnt(0)
	s_barrier
	v_mfma_f32_16x16x32_bf16 v[152:155], v[72:75], v[164:167], v[152:155]
	v_mfma_f32_16x16x32_bf16 v[148:151], v[96:99], v[164:167], v[148:151]
	v_mfma_f32_16x16x32_bf16 v[128:131], v[72:75], v[172:175], v[128:131]
	v_mfma_f32_16x16x32_bf16 v[124:127], v[96:99], v[172:175], v[124:127]
	v_mfma_f32_16x16x32_bf16 v[104:107], v[72:75], v[180:183], v[104:107]
	v_mfma_f32_16x16x32_bf16 v[100:103], v[96:99], v[180:183], v[100:103]
	v_mfma_f32_16x16x32_bf16 v[80:83], v[72:75], v[190:193], v[80:83]
	v_mfma_f32_16x16x32_bf16 v[76:79], v[96:99], v[190:193], v[76:79]
	v_mfma_f32_16x16x32_bf16 v[152:155], v[84:87], v[168:171], v[152:155]
	v_mfma_f32_16x16x32_bf16 v[148:151], v[108:111], v[168:171], v[148:151]
	v_mfma_f32_16x16x32_bf16 v[128:131], v[84:87], v[176:179], v[128:131]
	v_mfma_f32_16x16x32_bf16 v[124:127], v[108:111], v[176:179], v[124:127]
	v_mfma_f32_16x16x32_bf16 v[104:107], v[84:87], v[186:189], v[104:107]
	v_mfma_f32_16x16x32_bf16 v[100:103], v[108:111], v[186:189], v[100:103]
	v_mfma_f32_16x16x32_bf16 v[80:83], v[84:87], v[194:197], v[80:83]
	v_mfma_f32_16x16x32_bf16 v[76:79], v[108:111], v[194:197], v[76:79]
	v_mfma_f32_16x16x32_bf16 v[144:147], v[120:123], v[164:167], v[144:147]
	v_mfma_f32_16x16x32_bf16 v[134:137], v[156:159], v[164:167], v[136:139]
	v_mfma_f32_16x16x32_bf16 v[116:119], v[120:123], v[172:175], v[116:119]
	v_mfma_f32_16x16x32_bf16 v[112:115], v[156:159], v[172:175], v[112:115]
	v_mfma_f32_16x16x32_bf16 v[92:95], v[120:123], v[180:183], v[92:95]
	v_mfma_f32_16x16x32_bf16 v[88:91], v[156:159], v[180:183], v[88:91]
	v_mfma_f32_16x16x32_bf16 v[68:71], v[120:123], v[190:193], v[68:71]
	v_mfma_f32_16x16x32_bf16 v[64:67], v[156:159], v[190:193], v[64:67]
	v_mfma_f32_16x16x32_bf16 v[144:147], v[140:143], v[168:171], v[144:147]
	v_mfma_f32_16x16x32_bf16 v[134:137], v[160:163], v[168:171], v[134:137]
	v_mfma_f32_16x16x32_bf16 v[116:119], v[140:143], v[176:179], v[116:119]
	v_mfma_f32_16x16x32_bf16 v[112:115], v[160:163], v[176:179], v[112:115]
	v_mfma_f32_16x16x32_bf16 v[92:95], v[140:143], v[186:189], v[92:95]
	v_mfma_f32_16x16x32_bf16 v[88:91], v[160:163], v[186:189], v[88:91]
	v_mfma_f32_16x16x32_bf16 v[68:71], v[140:143], v[194:197], v[68:71]
	v_mfma_f32_16x16x32_bf16 v[64:67], v[160:163], v[194:197], v[64:67]
	s_barrier
	s_add_i32 s91, s91, s26
	s_mov_b32 m0, s91
	ds_read_b128 v[164:167], v209 offset:16384
	ds_read_b128 v[168:171], v209 offset:17408
	ds_read_b128 v[172:175], v209 offset:18432
	ds_read_b128 v[176:179], v209 offset:19456
	ds_read_b128 v[180:183], v209 offset:20480
	ds_read_b128 v[186:189], v209 offset:21504
	ds_read_b128 v[190:193], v209 offset:22528
	ds_read_b128 v[194:197], v209 offset:23552
	global_load_lds_dwordx4 v203, s[58:59]
	s_add_i32 m0, s91, 0x2000
	s_add_u32 s92, s58, 0x80000
	s_addc_u32 s93, s59, 0
	s_add_i32 s91, s94, s26
	s_nop 0
	global_load_lds_dwordx4 v205, s[58:59]
	s_mov_b32 m0, s91
	s_nop 0
	global_load_lds_dwordx4 v203, s[92:93]
	s_add_i32 m0, s91, 0x2000
	s_nop 0
	global_load_lds_dwordx4 v205, s[92:93]
	s_mov_b32 m0, s27
	s_nop 0
	global_load_lds_dwordx4 v202, s[60:61]
	s_mov_b32 m0, s66
	s_nop 0
	global_load_lds_dwordx4 v204, s[60:61]
	s_waitcnt vmcnt(8)
	s_waitcnt lgkmcnt(0)
	s_barrier
	v_mfma_f32_16x16x32_bf16 v[60:63], v[72:75], v[164:167], v[60:63]
	v_mfma_f32_16x16x32_bf16 v[56:59], v[96:99], v[164:167], v[56:59]
	v_mfma_f32_16x16x32_bf16 v[44:47], v[72:75], v[172:175], v[44:47]
	v_mfma_f32_16x16x32_bf16 v[40:43], v[96:99], v[172:175], v[40:43]
	v_mfma_f32_16x16x32_bf16 v[28:31], v[72:75], v[180:183], v[28:31]
	v_mfma_f32_16x16x32_bf16 v[24:27], v[96:99], v[180:183], v[24:27]
	v_mfma_f32_16x16x32_bf16 v[12:15], v[72:75], v[190:193], v[12:15]
	v_mfma_f32_16x16x32_bf16 v[8:11], v[96:99], v[190:193], v[8:11]
	v_mfma_f32_16x16x32_bf16 v[60:63], v[84:87], v[168:171], v[60:63]
	v_mfma_f32_16x16x32_bf16 v[56:59], v[108:111], v[168:171], v[56:59]
	v_mfma_f32_16x16x32_bf16 v[44:47], v[84:87], v[176:179], v[44:47]
	v_mfma_f32_16x16x32_bf16 v[40:43], v[108:111], v[176:179], v[40:43]
	v_mfma_f32_16x16x32_bf16 v[28:31], v[84:87], v[186:189], v[28:31]
	v_mfma_f32_16x16x32_bf16 v[24:27], v[108:111], v[186:189], v[24:27]
	v_mfma_f32_16x16x32_bf16 v[12:15], v[84:87], v[194:197], v[12:15]
	v_mfma_f32_16x16x32_bf16 v[8:11], v[108:111], v[194:197], v[8:11]
	v_mfma_f32_16x16x32_bf16 v[52:55], v[120:123], v[164:167], v[52:55]
	v_mfma_f32_16x16x32_bf16 v[48:51], v[156:159], v[164:167], v[48:51]
	v_mfma_f32_16x16x32_bf16 v[36:39], v[120:123], v[172:175], v[36:39]
	v_mfma_f32_16x16x32_bf16 v[32:35], v[156:159], v[172:175], v[32:35]
	v_mfma_f32_16x16x32_bf16 v[20:23], v[120:123], v[180:183], v[20:23]
	v_mfma_f32_16x16x32_bf16 v[16:19], v[156:159], v[180:183], v[16:19]
	v_mfma_f32_16x16x32_bf16 v[4:7], v[120:123], v[190:193], v[4:7]
	v_mfma_f32_16x16x32_bf16 v[0:3], v[156:159], v[190:193], v[0:3]
	v_mfma_f32_16x16x32_bf16 v[52:55], v[140:143], v[168:171], v[52:55]
	v_mfma_f32_16x16x32_bf16 v[48:51], v[160:163], v[168:171], v[48:51]
	v_mfma_f32_16x16x32_bf16 v[36:39], v[140:143], v[176:179], v[36:39]
	v_mfma_f32_16x16x32_bf16 v[32:35], v[160:163], v[176:179], v[32:35]
	v_mfma_f32_16x16x32_bf16 v[20:23], v[140:143], v[186:189], v[20:23]
	v_mfma_f32_16x16x32_bf16 v[16:19], v[160:163], v[186:189], v[16:19]
	v_mfma_f32_16x16x32_bf16 v[4:7], v[140:143], v[194:197], v[4:7]
	v_mfma_f32_16x16x32_bf16 v[0:3], v[160:163], v[194:197], v[0:3]
	s_barrier
	ds_read_b128 v[72:75], v132
	ds_read_b128 v[84:87], v132 offset:1024
	ds_read_b128 v[96:99], v132 offset:2048
	ds_read_b128 v[108:111], v132 offset:3072
	ds_read_b128 v[120:123], v133
	ds_read_b128 v[140:143], v133 offset:1024
	ds_read_b128 v[156:159], v133 offset:2048
	ds_read_b128 v[160:163], v133 offset:3072
	s_add_u32 s60, s60, 0x80000
	s_addc_u32 s61, s61, 0
	s_mov_b32 m0, s67
	ds_read_b128 v[164:167], v209 offset:32768
	ds_read_b128 v[168:171], v209 offset:33792
	ds_read_b128 v[172:175], v209 offset:34816
	ds_read_b128 v[176:179], v209 offset:35840
	ds_read_b128 v[180:183], v209 offset:36864
	ds_read_b128 v[186:189], v209 offset:37888
	ds_read_b128 v[190:193], v209 offset:38912
	ds_read_b128 v[194:197], v209 offset:39936
	global_load_lds_dwordx4 v202, s[60:61]
	s_mov_b32 m0, s68
	s_nop 0
	global_load_lds_dwordx4 v204, s[60:61]
	s_waitcnt vmcnt(8)
	s_waitcnt lgkmcnt(0)
	s_barrier
	v_mfma_f32_16x16x32_bf16 v[152:155], v[72:75], v[164:167], v[152:155]
	v_mfma_f32_16x16x32_bf16 v[148:151], v[96:99], v[164:167], v[148:151]
	v_mfma_f32_16x16x32_bf16 v[128:131], v[72:75], v[172:175], v[128:131]
	v_mfma_f32_16x16x32_bf16 v[124:127], v[96:99], v[172:175], v[124:127]
	v_mfma_f32_16x16x32_bf16 v[104:107], v[72:75], v[180:183], v[104:107]
	v_mfma_f32_16x16x32_bf16 v[100:103], v[96:99], v[180:183], v[100:103]
	v_mfma_f32_16x16x32_bf16 v[80:83], v[72:75], v[190:193], v[80:83]
	v_mfma_f32_16x16x32_bf16 v[76:79], v[96:99], v[190:193], v[76:79]
	v_mfma_f32_16x16x32_bf16 v[152:155], v[84:87], v[168:171], v[152:155]
	v_mfma_f32_16x16x32_bf16 v[148:151], v[108:111], v[168:171], v[148:151]
	v_mfma_f32_16x16x32_bf16 v[128:131], v[84:87], v[176:179], v[128:131]
	v_mfma_f32_16x16x32_bf16 v[124:127], v[108:111], v[176:179], v[124:127]
	v_mfma_f32_16x16x32_bf16 v[104:107], v[84:87], v[186:189], v[104:107]
	v_mfma_f32_16x16x32_bf16 v[100:103], v[108:111], v[186:189], v[100:103]
	v_mfma_f32_16x16x32_bf16 v[80:83], v[84:87], v[194:197], v[80:83]
	v_mfma_f32_16x16x32_bf16 v[76:79], v[108:111], v[194:197], v[76:79]
	v_mfma_f32_16x16x32_bf16 v[144:147], v[120:123], v[164:167], v[144:147]
	v_mfma_f32_16x16x32_bf16 v[134:137], v[156:159], v[164:167], v[134:137]
	v_mfma_f32_16x16x32_bf16 v[116:119], v[120:123], v[172:175], v[116:119]
	v_mfma_f32_16x16x32_bf16 v[112:115], v[156:159], v[172:175], v[112:115]
	v_mfma_f32_16x16x32_bf16 v[92:95], v[120:123], v[180:183], v[92:95]
	v_mfma_f32_16x16x32_bf16 v[88:91], v[156:159], v[180:183], v[88:91]
	v_mfma_f32_16x16x32_bf16 v[68:71], v[120:123], v[190:193], v[68:71]
	v_mfma_f32_16x16x32_bf16 v[64:67], v[156:159], v[190:193], v[64:67]
	v_mfma_f32_16x16x32_bf16 v[144:147], v[140:143], v[168:171], v[144:147]
	v_mfma_f32_16x16x32_bf16 v[136:139], v[160:163], v[168:171], v[134:137]
	v_mfma_f32_16x16x32_bf16 v[116:119], v[140:143], v[176:179], v[116:119]
	v_mfma_f32_16x16x32_bf16 v[112:115], v[160:163], v[176:179], v[112:115]
	v_mfma_f32_16x16x32_bf16 v[92:95], v[140:143], v[186:189], v[92:95]
	v_mfma_f32_16x16x32_bf16 v[88:91], v[160:163], v[186:189], v[88:91]
	v_mfma_f32_16x16x32_bf16 v[68:71], v[140:143], v[194:197], v[68:71]
	v_mfma_f32_16x16x32_bf16 v[64:67], v[160:163], v[194:197], v[64:67]
	s_barrier
	s_add_u32 s60, s58, 0x80
	s_mov_b32 m0, s45
	s_addc_u32 s61, s59, 0
	ds_read_b128 v[164:167], v209 offset:49152
	ds_read_b128 v[168:171], v209 offset:50176
	ds_read_b128 v[172:175], v209 offset:51200
	ds_read_b128 v[176:179], v209 offset:52224
	ds_read_b128 v[180:183], v209 offset:53248
	ds_read_b128 v[186:189], v209 offset:54272
	ds_read_b128 v[190:193], v209 offset:55296
	ds_read_b128 v[194:197], v209 offset:56320
	s_add_u32 s58, s58, 0x80080
	global_load_lds_dwordx4 v203, s[60:61]
	s_mov_b32 m0, s47
	s_addc_u32 s59, s59, 0
	global_load_lds_dwordx4 v205, s[60:61]
	s_mov_b32 m0, s79
	s_nop 0
	global_load_lds_dwordx4 v203, s[58:59]
	s_mov_b32 m0, s80
	s_nop 0
	global_load_lds_dwordx4 v205, s[58:59]
	s_mov_b32 m0, s69
	s_nop 0
	global_load_lds_dwordx4 v202, s[56:57]
	s_mov_b32 m0, s70
	s_nop 0
	global_load_lds_dwordx4 v204, s[56:57]
	s_waitcnt vmcnt(8)
	s_waitcnt lgkmcnt(0)
	s_barrier
	v_mfma_f32_16x16x32_bf16 v[60:63], v[72:75], v[164:167], v[60:63]
	v_mfma_f32_16x16x32_bf16 v[56:59], v[96:99], v[164:167], v[56:59]
	v_mfma_f32_16x16x32_bf16 v[44:47], v[72:75], v[172:175], v[44:47]
	v_mfma_f32_16x16x32_bf16 v[40:43], v[96:99], v[172:175], v[40:43]
	v_mfma_f32_16x16x32_bf16 v[28:31], v[72:75], v[180:183], v[28:31]
	v_mfma_f32_16x16x32_bf16 v[24:27], v[96:99], v[180:183], v[24:27]
	v_mfma_f32_16x16x32_bf16 v[12:15], v[72:75], v[190:193], v[12:15]
	v_mfma_f32_16x16x32_bf16 v[8:11], v[96:99], v[190:193], v[8:11]
	v_mfma_f32_16x16x32_bf16 v[60:63], v[84:87], v[168:171], v[60:63]
	v_mfma_f32_16x16x32_bf16 v[56:59], v[108:111], v[168:171], v[56:59]
	v_mfma_f32_16x16x32_bf16 v[44:47], v[84:87], v[176:179], v[44:47]
	v_mfma_f32_16x16x32_bf16 v[40:43], v[108:111], v[176:179], v[40:43]
	v_mfma_f32_16x16x32_bf16 v[28:31], v[84:87], v[186:189], v[28:31]
	v_mfma_f32_16x16x32_bf16 v[24:27], v[108:111], v[186:189], v[24:27]
	v_mfma_f32_16x16x32_bf16 v[12:15], v[84:87], v[194:197], v[12:15]
	v_mfma_f32_16x16x32_bf16 v[8:11], v[108:111], v[194:197], v[8:11]
	v_mfma_f32_16x16x32_bf16 v[52:55], v[120:123], v[164:167], v[52:55]
	v_mfma_f32_16x16x32_bf16 v[48:51], v[156:159], v[164:167], v[48:51]
	v_mfma_f32_16x16x32_bf16 v[36:39], v[120:123], v[172:175], v[36:39]
	v_mfma_f32_16x16x32_bf16 v[32:35], v[156:159], v[172:175], v[32:35]
	v_mfma_f32_16x16x32_bf16 v[20:23], v[120:123], v[180:183], v[20:23]
	v_mfma_f32_16x16x32_bf16 v[16:19], v[156:159], v[180:183], v[16:19]
	v_mfma_f32_16x16x32_bf16 v[4:7], v[120:123], v[190:193], v[4:7]
	v_mfma_f32_16x16x32_bf16 v[0:3], v[156:159], v[190:193], v[0:3]
	v_mfma_f32_16x16x32_bf16 v[52:55], v[140:143], v[168:171], v[52:55]
	v_mfma_f32_16x16x32_bf16 v[48:51], v[160:163], v[168:171], v[48:51]
	v_mfma_f32_16x16x32_bf16 v[36:39], v[140:143], v[176:179], v[36:39]
	v_mfma_f32_16x16x32_bf16 v[32:35], v[160:163], v[176:179], v[32:35]
	v_mfma_f32_16x16x32_bf16 v[20:23], v[140:143], v[186:189], v[20:23]
	v_mfma_f32_16x16x32_bf16 v[16:19], v[160:163], v[186:189], v[16:19]
	v_mfma_f32_16x16x32_bf16 v[4:7], v[140:143], v[194:197], v[4:7]
	v_mfma_f32_16x16x32_bf16 v[0:3], v[160:163], v[194:197], v[0:3]
	s_barrier
	s_add_i32 s90, s90, 2
	s_add_u32 s83, s83, 0x100
	s_addc_u32 s86, s86, 0
	s_add_u32 s88, s88, 0x100
	s_addc_u32 s89, s89, 0
	s_add_u32 s54, s54, 0x100
	s_addc_u32 s55, s55, 0
	s_cmp_gt_u32 s90, 29
	s_cbranch_scc0 .LBB0_2043
	s_and_b64 vcc, exec, s[42:43]
	s_cbranch_vccz .LBB0_2046
	s_barrier

.LBB0_2148:
	s_add_u32 s20, s56, 0x100
	s_addc_u32 s21, s57, 0
	s_waitcnt lgkmcnt(0)
	s_add_u32 s48, s54, 0x100
	s_addc_u32 s49, s55, 0
	s_barrier
	s_waitcnt lgkmcnt(0)
	v_mfma_f32_16x16x32_bf16 v[32:35], v[16:19], v[72:75], 0
	v_mfma_f32_16x16x32_bf16 v[36:39], v[24:27], v[72:75], 0
	v_mfma_f32_16x16x32_bf16 v[40:43], v[16:19], v[84:87], 0
	v_mfma_f32_16x16x32_bf16 v[44:47], v[24:27], v[84:87], 0
	v_mfma_f32_16x16x32_bf16 v[48:51], v[16:19], v[88:91], 0
	v_mfma_f32_16x16x32_bf16 v[52:55], v[24:27], v[88:91], 0
	v_mfma_f32_16x16x32_bf16 v[56:59], v[16:19], v[68:71], 0
	v_mfma_f32_16x16x32_bf16 v[60:63], v[24:27], v[68:71], 0
	v_mfma_f32_16x16x32_bf16 v[32:35], v[20:23], v[76:79], v[32:35]
	v_mfma_f32_16x16x32_bf16 v[36:39], v[28:31], v[76:79], v[36:39]
	v_mfma_f32_16x16x32_bf16 v[40:43], v[20:23], v[92:95], v[40:43]
	v_mfma_f32_16x16x32_bf16 v[44:47], v[28:31], v[92:95], v[44:47]
	v_mfma_f32_16x16x32_bf16 v[48:51], v[20:23], v[96:99], v[48:51]
	v_mfma_f32_16x16x32_bf16 v[52:55], v[28:31], v[96:99], v[52:55]
	v_mfma_f32_16x16x32_bf16 v[56:59], v[20:23], v[80:83], v[56:59]
	v_mfma_f32_16x16x32_bf16 v[60:63], v[28:31], v[80:83], v[60:63]
	v_mfma_f32_16x16x32_bf16 v[64:67], v[0:3], v[72:75], 0
	v_mfma_f32_16x16x32_bf16 v[72:75], v[8:11], v[72:75], 0
	v_mfma_f32_16x16x32_bf16 v[64:67], v[4:7], v[76:79], v[64:67]
	v_mfma_f32_16x16x32_bf16 v[72:75], v[12:15], v[76:79], v[72:75]
	v_mfma_f32_16x16x32_bf16 v[76:79], v[0:3], v[84:87], 0
	v_mfma_f32_16x16x32_bf16 v[84:87], v[8:11], v[84:87], 0
	v_mfma_f32_16x16x32_bf16 v[76:79], v[4:7], v[92:95], v[76:79]
	v_mfma_f32_16x16x32_bf16 v[84:87], v[12:15], v[92:95], v[84:87]
	v_mfma_f32_16x16x32_bf16 v[92:95], v[0:3], v[88:91], 0
	v_mfma_f32_16x16x32_bf16 v[88:91], v[8:11], v[88:91], 0
	v_mfma_f32_16x16x32_bf16 v[128:131], v[12:15], v[96:99], v[88:91]
	v_mfma_f32_16x16x32_bf16 v[88:91], v[0:3], v[68:71], 0
	v_mfma_f32_16x16x32_bf16 v[68:71], v[8:11], v[68:71], 0
	v_mfma_f32_16x16x32_bf16 v[92:95], v[4:7], v[96:99], v[92:95]
	v_mfma_f32_16x16x32_bf16 v[132:135], v[4:7], v[80:83], v[88:91]
	v_mfma_f32_16x16x32_bf16 v[136:139], v[12:15], v[80:83], v[68:71]
	s_barrier
	s_mov_b32 m0, s51
	ds_read_b128 v[108:111], v150 offset:16384
	ds_read_b128 v[112:115], v150 offset:17408
	ds_read_b128 v[100:103], v150 offset:18432
	ds_read_b128 v[104:107], v150 offset:19456
	ds_read_b128 v[88:91], v150 offset:20480
	ds_read_b128 v[96:99], v150 offset:21504
	ds_read_b128 v[68:71], v150 offset:22528
	ds_read_b128 v[80:83], v150 offset:23552
	global_load_lds_dwordx4 v144, s[48:49]
	s_mov_b32 m0, s53
	s_nop 0
	global_load_lds_dwordx4 v146, s[48:49]
	s_add_u32 s48, s54, 0x80100
	s_addc_u32 s49, s55, 0
	s_mov_b32 m0, s65
	s_and_b64 vcc, exec, s[46:47]
	global_load_lds_dwordx4 v144, s[48:49]
	s_mov_b32 m0, s66
	s_nop 0
	global_load_lds_dwordx4 v146, s[48:49]
	s_mov_b32 m0, s27
	s_mov_b64 s[48:49], -1
	global_load_lds_dwordx4 v143, s[20:21]
	s_mov_b32 m0, s67
	s_nop 0
	global_load_lds_dwordx4 v145, s[20:21]
	s_cbranch_vccz .LBB0_2150
	s_waitcnt vmcnt(8)
	s_mov_b64 s[48:49], 0

.LBB0_2152:
	s_ashr_i32 s7, s6, 31
	s_lshl_b64 s[20:21], s[6:7], 20
	s_add_u32 s46, s14, s20
	s_addc_u32 s47, s15, s21
	s_ashr_i32 s43, s42, 31
	s_lshl_b64 s[20:21], s[42:43], 20
	s_add_u32 s48, s24, s20
	s_addc_u32 s49, s25, s21
	s_add_u32 s58, s56, 0x180
	s_addc_u32 s59, s57, 0
	s_waitcnt lgkmcnt(0)
	s_and_b64 s[20:21], s[44:45], exec
	s_cselect_b32 s20, s49, s55
	s_cselect_b32 s21, s48, s54
	s_cselect_b32 s43, s47, s57
	s_cselect_b32 s79, s46, s56
	s_add_u32 s60, s54, 0x180
	s_addc_u32 s61, s55, 0
	s_barrier
	s_waitcnt lgkmcnt(0)
	v_mfma_f32_16x16x32_bf16 v[116:119], v[16:19], v[108:111], 0
	v_mfma_f32_16x16x32_bf16 v[154:157], v[20:23], v[112:115], v[116:119]
	v_mfma_f32_16x16x32_bf16 v[116:119], v[24:27], v[108:111], 0
	v_mfma_f32_16x16x32_bf16 v[158:161], v[28:31], v[112:115], v[116:119]
	v_mfma_f32_16x16x32_bf16 v[116:119], v[16:19], v[100:103], 0
	v_mfma_f32_16x16x32_bf16 v[162:165], v[20:23], v[104:107], v[116:119]
	v_mfma_f32_16x16x32_bf16 v[116:119], v[24:27], v[100:103], 0
	v_mfma_f32_16x16x32_bf16 v[166:169], v[28:31], v[104:107], v[116:119]
	v_mfma_f32_16x16x32_bf16 v[116:119], v[16:19], v[88:91], 0
	v_mfma_f32_16x16x32_bf16 v[16:19], v[16:19], v[68:71], 0
	v_mfma_f32_16x16x32_bf16 v[170:173], v[20:23], v[96:99], v[116:119]
	v_mfma_f32_16x16x32_bf16 v[116:119], v[24:27], v[88:91], 0
	v_mfma_f32_16x16x32_bf16 v[20:23], v[20:23], v[80:83], v[16:19]
	v_mfma_f32_16x16x32_bf16 v[16:19], v[24:27], v[68:71], 0
	v_mfma_f32_16x16x32_bf16 v[174:177], v[28:31], v[96:99], v[116:119]
	v_mfma_f32_16x16x32_bf16 v[28:31], v[28:31], v[80:83], v[16:19]
	v_mfma_f32_16x16x32_bf16 v[16:19], v[0:3], v[108:111], 0
	v_mfma_f32_16x16x32_bf16 v[178:181], v[4:7], v[112:115], v[16:19]
	v_mfma_f32_16x16x32_bf16 v[16:19], v[8:11], v[108:111], 0
	v_mfma_f32_16x16x32_bf16 v[182:185], v[12:15], v[112:115], v[16:19]
	v_mfma_f32_16x16x32_bf16 v[16:19], v[0:3], v[100:103], 0
	v_mfma_f32_16x16x32_bf16 v[186:189], v[4:7], v[104:107], v[16:19]
	v_mfma_f32_16x16x32_bf16 v[16:19], v[8:11], v[100:103], 0
	v_mfma_f32_16x16x32_bf16 v[190:193], v[12:15], v[104:107], v[16:19]
	v_mfma_f32_16x16x32_bf16 v[16:19], v[0:3], v[88:91], 0
	v_mfma_f32_16x16x32_bf16 v[0:3], v[0:3], v[68:71], 0
	v_mfma_f32_16x16x32_bf16 v[194:197], v[4:7], v[96:99], v[16:19]
	v_mfma_f32_16x16x32_bf16 v[16:19], v[8:11], v[88:91], 0
	v_mfma_f32_16x16x32_bf16 v[4:7], v[4:7], v[80:83], v[0:3]
	v_mfma_f32_16x16x32_bf16 v[0:3], v[8:11], v[68:71], 0
	v_mfma_f32_16x16x32_bf16 v[198:201], v[12:15], v[96:99], v[16:19]
	v_mfma_f32_16x16x32_bf16 v[202:205], v[12:15], v[80:83], v[0:3]
	s_barrier
	v_add_u32_e32 v152, s76, v147
	v_add_u32_e32 v153, s77, v147
	s_nop 1
	ds_read_b128 v[0:3], v152
	ds_read_b128 v[8:11], v152 offset:1024
	ds_read_b128 v[12:15], v152 offset:2048
	ds_read_b128 v[206:209], v152 offset:3072
	ds_read_b128 v[210:213], v153
	ds_read_b128 v[214:217], v153 offset:1024
	ds_read_b128 v[218:221], v153 offset:2048
	ds_read_b128 v[222:225], v153 offset:3072
	s_add_u32 s62, s56, 0x80100
	s_addc_u32 s63, s57, 0
	s_mov_b32 m0, s68
	ds_read_b128 v[16:19], v150 offset:32768
	ds_read_b128 v[24:27], v150 offset:33792
	ds_read_b128 v[100:103], v150 offset:34816
	ds_read_b128 v[226:229], v150 offset:35840
	ds_read_b128 v[230:233], v150 offset:36864
	ds_read_b128 v[234:237], v150 offset:37888
	ds_read_b128 v[238:241], v150 offset:38912
	ds_read_b128 v[242:245], v150 offset:39936
	global_load_lds_dwordx4 v143, s[62:63]
	s_mov_b32 m0, s69
	s_nop 0
	global_load_lds_dwordx4 v145, s[62:63]
	s_waitcnt vmcnt(8)
	s_waitcnt lgkmcnt(0)
	s_barrier
	v_mfma_f32_16x16x32_bf16 v[32:35], v[0:3], v[16:19], v[32:35]
	v_mfma_f32_16x16x32_bf16 v[120:123], v[8:11], v[24:27], v[32:35]
	v_mfma_f32_16x16x32_bf16 v[32:35], v[12:15], v[16:19], v[36:39]
	v_mfma_f32_16x16x32_bf16 v[112:115], v[206:209], v[24:27], v[32:35]
	v_mfma_f32_16x16x32_bf16 v[32:35], v[0:3], v[100:103], v[40:43]
	v_mfma_f32_16x16x32_bf16 v[104:107], v[8:11], v[226:229], v[32:35]
	v_mfma_f32_16x16x32_bf16 v[32:35], v[12:15], v[100:103], v[44:47]
	v_mfma_f32_16x16x32_bf16 v[96:99], v[206:209], v[226:229], v[32:35]
	v_mfma_f32_16x16x32_bf16 v[32:35], v[0:3], v[230:233], v[48:51]
	v_mfma_f32_16x16x32_bf16 v[88:91], v[8:11], v[234:237], v[32:35]
	v_mfma_f32_16x16x32_bf16 v[32:35], v[12:15], v[230:233], v[52:55]
	v_mfma_f32_16x16x32_bf16 v[80:83], v[206:209], v[234:237], v[32:35]
	v_mfma_f32_16x16x32_bf16 v[32:35], v[0:3], v[238:241], v[56:59]
	v_mfma_f32_16x16x32_bf16 v[68:71], v[8:11], v[242:245], v[32:35]
	v_mfma_f32_16x16x32_bf16 v[32:35], v[12:15], v[238:241], v[60:63]
	v_mfma_f32_16x16x32_bf16 v[52:55], v[206:209], v[242:245], v[32:35]
	v_mfma_f32_16x16x32_bf16 v[32:35], v[210:213], v[16:19], v[64:67]
	v_mfma_f32_16x16x32_bf16 v[16:19], v[218:221], v[16:19], v[72:75]
	v_mfma_f32_16x16x32_bf16 v[116:119], v[222:225], v[24:27], v[16:19]
	v_mfma_f32_16x16x32_bf16 v[16:19], v[210:213], v[100:103], v[76:79]
	v_mfma_f32_16x16x32_bf16 v[108:111], v[214:217], v[226:229], v[16:19]
	v_mfma_f32_16x16x32_bf16 v[16:19], v[218:221], v[100:103], v[84:87]
	v_mfma_f32_16x16x32_bf16 v[100:103], v[222:225], v[226:229], v[16:19]
	v_mfma_f32_16x16x32_bf16 v[16:19], v[210:213], v[230:233], v[92:95]
	v_mfma_f32_16x16x32_bf16 v[92:95], v[214:217], v[234:237], v[16:19]
	v_mfma_f32_16x16x32_bf16 v[16:19], v[218:221], v[230:233], v[128:131]
	v_mfma_f32_16x16x32_bf16 v[84:87], v[222:225], v[234:237], v[16:19]
	v_mfma_f32_16x16x32_bf16 v[16:19], v[210:213], v[238:241], v[132:135]
	v_mfma_f32_16x16x32_bf16 v[76:79], v[214:217], v[242:245], v[16:19]
	v_mfma_f32_16x16x32_bf16 v[16:19], v[218:221], v[238:241], v[136:139]
	v_mfma_f32_16x16x32_bf16 v[124:127], v[214:217], v[24:27], v[32:35]
	v_mfma_f32_16x16x32_bf16 v[60:63], v[222:225], v[242:245], v[16:19]
	s_barrier
	s_add_i32 s80, s76, s26
	s_mov_b32 m0, s80
	s_add_i32 s86, s80, 0x2000
	ds_read_b128 v[36:39], v150 offset:49152
	ds_read_b128 v[44:47], v150 offset:50176
	ds_read_b128 v[128:131], v150 offset:51200
	ds_read_b128 v[132:135], v150 offset:52224
	ds_read_b128 v[136:139], v150 offset:53248
	ds_read_b128 v[226:229], v150 offset:54272
	ds_read_b128 v[230:233], v150 offset:55296
	ds_read_b128 v[234:237], v150 offset:56320
	global_load_lds_dwordx4 v144, s[60:61]
	s_mov_b32 m0, s86
	s_nop 0
	global_load_lds_dwordx4 v146, s[60:61]
	s_add_u32 s60, s54, 0x80180
	s_addc_u32 s61, s55, 0
	s_add_i32 s89, s77, s26
	s_mov_b32 m0, s89
	s_add_i32 s90, s89, 0x2000
	s_nop 0
	global_load_lds_dwordx4 v144, s[60:61]
	s_mov_b32 m0, s90
	s_nop 0
	global_load_lds_dwordx4 v146, s[60:61]
	s_mov_b32 m0, s70
	s_nop 0
	global_load_lds_dwordx4 v143, s[58:59]
	s_mov_b32 m0, s71
	s_nop 0
	global_load_lds_dwordx4 v145, s[58:59]
	s_waitcnt vmcnt(8)
	s_waitcnt lgkmcnt(0)
	s_barrier
	v_mfma_f32_16x16x32_bf16 v[16:19], v[0:3], v[36:39], v[154:157]
	v_mfma_f32_16x16x32_bf16 v[64:67], v[8:11], v[44:47], v[16:19]
	v_mfma_f32_16x16x32_bf16 v[16:19], v[12:15], v[36:39], v[158:161]
	v_mfma_f32_16x16x32_bf16 v[48:51], v[206:209], v[44:47], v[16:19]
	v_mfma_f32_16x16x32_bf16 v[16:19], v[0:3], v[128:131], v[162:165]
	v_mfma_f32_16x16x32_bf16 v[40:43], v[8:11], v[132:135], v[16:19]
	v_mfma_f32_16x16x32_bf16 v[16:19], v[12:15], v[128:131], v[166:169]
	v_mfma_f32_16x16x32_bf16 v[32:35], v[206:209], v[132:135], v[16:19]
	v_mfma_f32_16x16x32_bf16 v[16:19], v[0:3], v[136:139], v[170:173]
	v_mfma_f32_16x16x32_bf16 v[0:3], v[0:3], v[230:233], v[20:23]
	v_mfma_f32_16x16x32_bf16 v[24:27], v[8:11], v[226:229], v[16:19]
	v_mfma_f32_16x16x32_bf16 v[16:19], v[12:15], v[136:139], v[174:177]
	v_mfma_f32_16x16x32_bf16 v[8:11], v[8:11], v[234:237], v[0:3]
	v_mfma_f32_16x16x32_bf16 v[0:3], v[12:15], v[230:233], v[28:31]
	v_mfma_f32_16x16x32_bf16 v[16:19], v[206:209], v[226:229], v[16:19]
	v_mfma_f32_16x16x32_bf16 v[0:3], v[206:209], v[234:237], v[0:3]
	v_mfma_f32_16x16x32_bf16 v[12:15], v[210:213], v[36:39], v[178:181]
	v_mfma_f32_16x16x32_bf16 v[72:75], v[214:217], v[44:47], v[12:15]
	v_mfma_f32_16x16x32_bf16 v[12:15], v[218:221], v[36:39], v[182:185]
	v_mfma_f32_16x16x32_bf16 v[56:59], v[222:225], v[44:47], v[12:15]
	v_mfma_f32_16x16x32_bf16 v[12:15], v[210:213], v[128:131], v[186:189]
	v_mfma_f32_16x16x32_bf16 v[44:47], v[214:217], v[132:135], v[12:15]
	v_mfma_f32_16x16x32_bf16 v[12:15], v[218:221], v[128:131], v[190:193]
	v_mfma_f32_16x16x32_bf16 v[36:39], v[222:225], v[132:135], v[12:15]
	v_mfma_f32_16x16x32_bf16 v[12:15], v[210:213], v[136:139], v[194:197]
	v_mfma_f32_16x16x32_bf16 v[28:31], v[214:217], v[226:229], v[12:15]
	v_mfma_f32_16x16x32_bf16 v[12:15], v[218:221], v[136:139], v[198:201]
	v_mfma_f32_16x16x32_bf16 v[4:7], v[210:213], v[230:233], v[4:7]
	v_mfma_f32_16x16x32_bf16 v[20:23], v[222:225], v[226:229], v[12:15]
	v_mfma_f32_16x16x32_bf16 v[12:15], v[214:217], v[234:237], v[4:7]
	v_mfma_f32_16x16x32_bf16 v[4:7], v[218:221], v[230:233], v[202:205]
	v_mfma_f32_16x16x32_bf16 v[4:7], v[222:225], v[234:237], v[4:7]
	s_barrier
	s_add_u32 s62, s56, 0x100
	s_addc_u32 s63, s57, 0
	s_add_u32 s91, s54, 0x200
	s_addc_u32 s92, s55, 0
	s_mov_b32 s93, 0
.LBB0_2153:
	s_add_u32 s54, s62, 0x100
	s_addc_u32 s55, s63, 0
	s_cmp_eq_u32 s93, 28
	s_cselect_b32 s60, s79, s54
	s_cselect_b32 s61, s43, s55
	s_cselect_b32 s58, s21, s91
	s_cselect_b32 s59, s20, s92
	s_add_u32 s56, s60, 0x80
	s_addc_u32 s57, s61, 0
	s_add_i32 s94, 0, 0x10000
	s_add_i32 s95, 0, 0x14000
	v_add_u32_e32 v154, s94, v147
	v_add_u32_e32 v170, s95, v147
	ds_read_b128 v[128:131], v154
	ds_read_b128 v[132:135], v154 offset:1024
	ds_read_b128 v[136:139], v154 offset:2048
	ds_read_b128 v[154:157], v154 offset:3072
	ds_read_b128 v[158:161], v170
	ds_read_b128 v[162:165], v170 offset:1024
	ds_read_b128 v[166:169], v170 offset:2048
	ds_read_b128 v[170:173], v170 offset:3072
	s_add_u32 s62, s62, 0x80080
	s_addc_u32 s63, s63, 0
	s_mov_b32 m0, s1
	ds_read_b128 v[174:177], v150
	ds_read_b128 v[178:181], v150 offset:1024
	ds_read_b128 v[182:185], v150 offset:2048
	ds_read_b128 v[186:189], v150 offset:3072
	ds_read_b128 v[190:193], v150 offset:4096
	ds_read_b128 v[194:197], v150 offset:5120
	ds_read_b128 v[198:201], v150 offset:6144
	ds_read_b128 v[202:205], v150 offset:7168
	global_load_lds_dwordx4 v143, s[62:63]
	s_mov_b32 m0, s12
	s_nop 0
	global_load_lds_dwordx4 v145, s[62:63]
	s_waitcnt vmcnt(8)
	s_waitcnt lgkmcnt(0)
	s_barrier
	v_mfma_f32_16x16x32_bf16 v[120:123], v[128:131], v[174:177], v[120:123]
	v_mfma_f32_16x16x32_bf16 v[112:115], v[136:139], v[174:177], v[112:115]
	v_mfma_f32_16x16x32_bf16 v[104:107], v[128:131], v[182:185], v[104:107]
	v_mfma_f32_16x16x32_bf16 v[96:99], v[136:139], v[182:185], v[96:99]
	v_mfma_f32_16x16x32_bf16 v[88:91], v[128:131], v[190:193], v[88:91]
	v_mfma_f32_16x16x32_bf16 v[80:83], v[136:139], v[190:193], v[80:83]
	v_mfma_f32_16x16x32_bf16 v[68:71], v[128:131], v[198:201], v[68:71]
	v_mfma_f32_16x16x32_bf16 v[52:55], v[136:139], v[198:201], v[52:55]
	v_mfma_f32_16x16x32_bf16 v[120:123], v[132:135], v[178:181], v[120:123]
	v_mfma_f32_16x16x32_bf16 v[112:115], v[154:157], v[178:181], v[112:115]
	v_mfma_f32_16x16x32_bf16 v[104:107], v[132:135], v[186:189], v[104:107]
	v_mfma_f32_16x16x32_bf16 v[96:99], v[154:157], v[186:189], v[96:99]
	v_mfma_f32_16x16x32_bf16 v[88:91], v[132:135], v[194:197], v[88:91]
	v_mfma_f32_16x16x32_bf16 v[80:83], v[154:157], v[194:197], v[80:83]
	v_mfma_f32_16x16x32_bf16 v[68:71], v[132:135], v[202:205], v[68:71]
	v_mfma_f32_16x16x32_bf16 v[52:55], v[154:157], v[202:205], v[52:55]
	v_mfma_f32_16x16x32_bf16 v[124:127], v[158:161], v[174:177], v[124:127]
	v_mfma_f32_16x16x32_bf16 v[116:119], v[166:169], v[174:177], v[116:119]
	v_mfma_f32_16x16x32_bf16 v[108:111], v[158:161], v[182:185], v[108:111]
	v_mfma_f32_16x16x32_bf16 v[100:103], v[166:169], v[182:185], v[100:103]
	v_mfma_f32_16x16x32_bf16 v[92:95], v[158:161], v[190:193], v[92:95]
	v_mfma_f32_16x16x32_bf16 v[84:87], v[166:169], v[190:193], v[84:87]
	v_mfma_f32_16x16x32_bf16 v[76:79], v[158:161], v[198:201], v[76:79]
	v_mfma_f32_16x16x32_bf16 v[60:63], v[166:169], v[198:201], v[60:63]
	v_mfma_f32_16x16x32_bf16 v[124:127], v[162:165], v[178:181], v[124:127]
	v_mfma_f32_16x16x32_bf16 v[116:119], v[170:173], v[178:181], v[116:119]
	v_mfma_f32_16x16x32_bf16 v[108:111], v[162:165], v[186:189], v[108:111]
	v_mfma_f32_16x16x32_bf16 v[100:103], v[170:173], v[186:189], v[100:103]
	v_mfma_f32_16x16x32_bf16 v[92:95], v[162:165], v[194:197], v[92:95]
	v_mfma_f32_16x16x32_bf16 v[84:87], v[170:173], v[194:197], v[84:87]
	v_mfma_f32_16x16x32_bf16 v[76:79], v[162:165], v[202:205], v[76:79]
	v_mfma_f32_16x16x32_bf16 v[60:63], v[170:173], v[202:205], v[60:63]
	s_barrier
	s_add_i32 s62, s94, s26
	s_mov_b32 m0, s62
	ds_read_b128 v[174:177], v150 offset:16384
	ds_read_b128 v[178:181], v150 offset:17408
	ds_read_b128 v[182:185], v150 offset:18432
	ds_read_b128 v[186:189], v150 offset:19456
	ds_read_b128 v[190:193], v150 offset:20480
	ds_read_b128 v[194:197], v150 offset:21504
	ds_read_b128 v[198:201], v150 offset:22528
	ds_read_b128 v[202:205], v150 offset:23552
	global_load_lds_dwordx4 v144, s[58:59]
	s_add_i32 m0, s62, 0x2000
	s_add_u32 s62, s58, 0x80000
	s_addc_u32 s63, s59, 0
	s_add_i32 s94, s95, s26
	s_nop 0
	global_load_lds_dwordx4 v146, s[58:59]
	s_mov_b32 m0, s94
	s_nop 0
	global_load_lds_dwordx4 v144, s[62:63]
	s_add_i32 m0, s94, 0x2000
	s_nop 0
	global_load_lds_dwordx4 v146, s[62:63]
	s_mov_b32 m0, s27
	s_nop 0
	global_load_lds_dwordx4 v143, s[60:61]
	s_mov_b32 m0, s67
	s_nop 0
	global_load_lds_dwordx4 v145, s[60:61]
	s_waitcnt vmcnt(8)
	s_waitcnt lgkmcnt(0)
	s_barrier
	v_mfma_f32_16x16x32_bf16 v[64:67], v[128:131], v[174:177], v[64:67]
	v_mfma_f32_16x16x32_bf16 v[48:51], v[136:139], v[174:177], v[48:51]
	v_mfma_f32_16x16x32_bf16 v[40:43], v[128:131], v[182:185], v[40:43]
	v_mfma_f32_16x16x32_bf16 v[32:35], v[136:139], v[182:185], v[32:35]
	v_mfma_f32_16x16x32_bf16 v[24:27], v[128:131], v[190:193], v[24:27]
	v_mfma_f32_16x16x32_bf16 v[16:19], v[136:139], v[190:193], v[16:19]
	v_mfma_f32_16x16x32_bf16 v[8:11], v[128:131], v[198:201], v[8:11]
	v_mfma_f32_16x16x32_bf16 v[0:3], v[136:139], v[198:201], v[0:3]
	v_mfma_f32_16x16x32_bf16 v[64:67], v[132:135], v[178:181], v[64:67]
	v_mfma_f32_16x16x32_bf16 v[48:51], v[154:157], v[178:181], v[48:51]
	v_mfma_f32_16x16x32_bf16 v[40:43], v[132:135], v[186:189], v[40:43]
	v_mfma_f32_16x16x32_bf16 v[32:35], v[154:157], v[186:189], v[32:35]
	v_mfma_f32_16x16x32_bf16 v[24:27], v[132:135], v[194:197], v[24:27]
	v_mfma_f32_16x16x32_bf16 v[16:19], v[154:157], v[194:197], v[16:19]
	v_mfma_f32_16x16x32_bf16 v[8:11], v[132:135], v[202:205], v[8:11]
	v_mfma_f32_16x16x32_bf16 v[0:3], v[154:157], v[202:205], v[0:3]
	v_mfma_f32_16x16x32_bf16 v[72:75], v[158:161], v[174:177], v[72:75]
	v_mfma_f32_16x16x32_bf16 v[56:59], v[166:169], v[174:177], v[56:59]
	v_mfma_f32_16x16x32_bf16 v[44:47], v[158:161], v[182:185], v[44:47]
	v_mfma_f32_16x16x32_bf16 v[36:39], v[166:169], v[182:185], v[36:39]
	v_mfma_f32_16x16x32_bf16 v[28:31], v[158:161], v[190:193], v[28:31]
	v_mfma_f32_16x16x32_bf16 v[20:23], v[166:169], v[190:193], v[20:23]
	v_mfma_f32_16x16x32_bf16 v[12:15], v[158:161], v[198:201], v[12:15]
	v_mfma_f32_16x16x32_bf16 v[4:7], v[166:169], v[198:201], v[4:7]
	v_mfma_f32_16x16x32_bf16 v[72:75], v[162:165], v[178:181], v[72:75]
	v_mfma_f32_16x16x32_bf16 v[56:59], v[170:173], v[178:181], v[56:59]
	v_mfma_f32_16x16x32_bf16 v[44:47], v[162:165], v[186:189], v[44:47]
	v_mfma_f32_16x16x32_bf16 v[36:39], v[170:173], v[186:189], v[36:39]
	v_mfma_f32_16x16x32_bf16 v[28:31], v[162:165], v[194:197], v[28:31]
	v_mfma_f32_16x16x32_bf16 v[20:23], v[170:173], v[194:197], v[20:23]
	v_mfma_f32_16x16x32_bf16 v[12:15], v[162:165], v[202:205], v[12:15]
	v_mfma_f32_16x16x32_bf16 v[4:7], v[170:173], v[202:205], v[4:7]
	s_barrier
	ds_read_b128 v[128:131], v152
	ds_read_b128 v[132:135], v152 offset:1024
	ds_read_b128 v[136:139], v152 offset:2048
	ds_read_b128 v[154:157], v152 offset:3072
	ds_read_b128 v[158:161], v153
	ds_read_b128 v[162:165], v153 offset:1024
	ds_read_b128 v[166:169], v153 offset:2048
	ds_read_b128 v[170:173], v153 offset:3072
	s_add_u32 s60, s60, 0x80000
	s_addc_u32 s61, s61, 0
	s_mov_b32 m0, s68
	ds_read_b128 v[174:177], v150 offset:32768
	ds_read_b128 v[178:181], v150 offset:33792
	ds_read_b128 v[182:185], v150 offset:34816
	ds_read_b128 v[186:189], v150 offset:35840
	ds_read_b128 v[190:193], v150 offset:36864
	ds_read_b128 v[194:197], v150 offset:37888
	ds_read_b128 v[198:201], v150 offset:38912
	ds_read_b128 v[202:205], v150 offset:39936
	global_load_lds_dwordx4 v143, s[60:61]
	s_mov_b32 m0, s69
	s_nop 0
	global_load_lds_dwordx4 v145, s[60:61]
	s_waitcnt vmcnt(8)
	s_waitcnt lgkmcnt(0)
	s_barrier
	v_mfma_f32_16x16x32_bf16 v[120:123], v[128:131], v[174:177], v[120:123]
	v_mfma_f32_16x16x32_bf16 v[112:115], v[136:139], v[174:177], v[112:115]
	v_mfma_f32_16x16x32_bf16 v[104:107], v[128:131], v[182:185], v[104:107]
	v_mfma_f32_16x16x32_bf16 v[96:99], v[136:139], v[182:185], v[96:99]
	v_mfma_f32_16x16x32_bf16 v[88:91], v[128:131], v[190:193], v[88:91]
	v_mfma_f32_16x16x32_bf16 v[80:83], v[136:139], v[190:193], v[80:83]
	v_mfma_f32_16x16x32_bf16 v[68:71], v[128:131], v[198:201], v[68:71]
	v_mfma_f32_16x16x32_bf16 v[52:55], v[136:139], v[198:201], v[52:55]
	v_mfma_f32_16x16x32_bf16 v[120:123], v[132:135], v[178:181], v[120:123]
	v_mfma_f32_16x16x32_bf16 v[112:115], v[154:157], v[178:181], v[112:115]
	v_mfma_f32_16x16x32_bf16 v[104:107], v[132:135], v[186:189], v[104:107]
	v_mfma_f32_16x16x32_bf16 v[96:99], v[154:157], v[186:189], v[96:99]
	v_mfma_f32_16x16x32_bf16 v[88:91], v[132:135], v[194:197], v[88:91]
	v_mfma_f32_16x16x32_bf16 v[80:83], v[154:157], v[194:197], v[80:83]
	v_mfma_f32_16x16x32_bf16 v[68:71], v[132:135], v[202:205], v[68:71]
	v_mfma_f32_16x16x32_bf16 v[52:55], v[154:157], v[202:205], v[52:55]
	v_mfma_f32_16x16x32_bf16 v[124:127], v[158:161], v[174:177], v[124:127]
	v_mfma_f32_16x16x32_bf16 v[116:119], v[166:169], v[174:177], v[116:119]
	v_mfma_f32_16x16x32_bf16 v[108:111], v[158:161], v[182:185], v[108:111]
	v_mfma_f32_16x16x32_bf16 v[100:103], v[166:169], v[182:185], v[100:103]
	v_mfma_f32_16x16x32_bf16 v[92:95], v[158:161], v[190:193], v[92:95]
	v_mfma_f32_16x16x32_bf16 v[84:87], v[166:169], v[190:193], v[84:87]
	v_mfma_f32_16x16x32_bf16 v[76:79], v[158:161], v[198:201], v[76:79]
	v_mfma_f32_16x16x32_bf16 v[60:63], v[166:169], v[198:201], v[60:63]
	v_mfma_f32_16x16x32_bf16 v[124:127], v[162:165], v[178:181], v[124:127]
	v_mfma_f32_16x16x32_bf16 v[116:119], v[170:173], v[178:181], v[116:119]
	v_mfma_f32_16x16x32_bf16 v[108:111], v[162:165], v[186:189], v[108:111]
	v_mfma_f32_16x16x32_bf16 v[100:103], v[170:173], v[186:189], v[100:103]
	v_mfma_f32_16x16x32_bf16 v[92:95], v[162:165], v[194:197], v[92:95]
	v_mfma_f32_16x16x32_bf16 v[84:87], v[170:173], v[194:197], v[84:87]
	v_mfma_f32_16x16x32_bf16 v[76:79], v[162:165], v[202:205], v[76:79]
	v_mfma_f32_16x16x32_bf16 v[60:63], v[170:173], v[202:205], v[60:63]
	s_barrier
	s_add_u32 s60, s58, 0x80
	s_mov_b32 m0, s80
	s_addc_u32 s61, s59, 0
	ds_read_b128 v[174:177], v150 offset:49152
	ds_read_b128 v[178:181], v150 offset:50176
	ds_read_b128 v[182:185], v150 offset:51200
	ds_read_b128 v[186:189], v150 offset:52224
	ds_read_b128 v[190:193], v150 offset:53248
	ds_read_b128 v[194:197], v150 offset:54272
	ds_read_b128 v[198:201], v150 offset:55296
	ds_read_b128 v[202:205], v150 offset:56320
	s_add_u32 s58, s58, 0x80080
	global_load_lds_dwordx4 v144, s[60:61]
	s_mov_b32 m0, s86
	s_addc_u32 s59, s59, 0
	global_load_lds_dwordx4 v146, s[60:61]
	s_mov_b32 m0, s89
	s_nop 0
	global_load_lds_dwordx4 v144, s[58:59]
	s_mov_b32 m0, s90
	s_nop 0
	global_load_lds_dwordx4 v146, s[58:59]
	s_mov_b32 m0, s70
	s_nop 0
	global_load_lds_dwordx4 v143, s[56:57]
	s_mov_b32 m0, s71
	s_nop 0
	global_load_lds_dwordx4 v145, s[56:57]
	s_waitcnt vmcnt(8)
	s_waitcnt lgkmcnt(0)
	s_barrier
	v_mfma_f32_16x16x32_bf16 v[64:67], v[128:131], v[174:177], v[64:67]
	v_mfma_f32_16x16x32_bf16 v[48:51], v[136:139], v[174:177], v[48:51]
	v_mfma_f32_16x16x32_bf16 v[40:43], v[128:131], v[182:185], v[40:43]
	v_mfma_f32_16x16x32_bf16 v[32:35], v[136:139], v[182:185], v[32:35]
	v_mfma_f32_16x16x32_bf16 v[24:27], v[128:131], v[190:193], v[24:27]
	v_mfma_f32_16x16x32_bf16 v[16:19], v[136:139], v[190:193], v[16:19]
	v_mfma_f32_16x16x32_bf16 v[8:11], v[128:131], v[198:201], v[8:11]
	v_mfma_f32_16x16x32_bf16 v[0:3], v[136:139], v[198:201], v[0:3]
	v_mfma_f32_16x16x32_bf16 v[64:67], v[132:135], v[178:181], v[64:67]
	v_mfma_f32_16x16x32_bf16 v[48:51], v[154:157], v[178:181], v[48:51]
	v_mfma_f32_16x16x32_bf16 v[40:43], v[132:135], v[186:189], v[40:43]
	v_mfma_f32_16x16x32_bf16 v[32:35], v[154:157], v[186:189], v[32:35]
	v_mfma_f32_16x16x32_bf16 v[24:27], v[132:135], v[194:197], v[24:27]
	v_mfma_f32_16x16x32_bf16 v[16:19], v[154:157], v[194:197], v[16:19]
	v_mfma_f32_16x16x32_bf16 v[8:11], v[132:135], v[202:205], v[8:11]
	v_mfma_f32_16x16x32_bf16 v[0:3], v[154:157], v[202:205], v[0:3]
	v_mfma_f32_16x16x32_bf16 v[72:75], v[158:161], v[174:177], v[72:75]
	v_mfma_f32_16x16x32_bf16 v[56:59], v[166:169], v[174:177], v[56:59]
	v_mfma_f32_16x16x32_bf16 v[44:47], v[158:161], v[182:185], v[44:47]
	v_mfma_f32_16x16x32_bf16 v[36:39], v[166:169], v[182:185], v[36:39]
	v_mfma_f32_16x16x32_bf16 v[28:31], v[158:161], v[190:193], v[28:31]
	v_mfma_f32_16x16x32_bf16 v[20:23], v[166:169], v[190:193], v[20:23]
	v_mfma_f32_16x16x32_bf16 v[12:15], v[158:161], v[198:201], v[12:15]
	v_mfma_f32_16x16x32_bf16 v[4:7], v[166:169], v[198:201], v[4:7]
	v_mfma_f32_16x16x32_bf16 v[72:75], v[162:165], v[178:181], v[72:75]
	v_mfma_f32_16x16x32_bf16 v[56:59], v[170:173], v[178:181], v[56:59]
	v_mfma_f32_16x16x32_bf16 v[44:47], v[162:165], v[186:189], v[44:47]
	v_mfma_f32_16x16x32_bf16 v[36:39], v[170:173], v[186:189], v[36:39]
	v_mfma_f32_16x16x32_bf16 v[28:31], v[162:165], v[194:197], v[28:31]
	v_mfma_f32_16x16x32_bf16 v[20:23], v[170:173], v[194:197], v[20:23]
	v_mfma_f32_16x16x32_bf16 v[12:15], v[162:165], v[202:205], v[12:15]
	v_mfma_f32_16x16x32_bf16 v[4:7], v[170:173], v[202:205], v[4:7]
	s_barrier
	s_add_i32 s93, s93, 2
	s_add_u32 s91, s91, 0x100
	s_addc_u32 s92, s92, 0
	s_cmp_gt_u32 s93, 29
	s_mov_b64 s[62:63], s[54:55]
	s_cbranch_scc0 .LBB0_2153
	s_and_b64 vcc, exec, s[4:5]
	s_cbranch_vccz .LBB0_2156
	s_barrier

.LBB0_2246:
	s_add_u32 s20, s50, 0x100
	s_addc_u32 s21, s51, 0
	s_waitcnt lgkmcnt(0)
	s_add_u32 s54, s4, 0x100
	s_addc_u32 s55, s5, 0
	s_barrier
	s_waitcnt lgkmcnt(0)
	v_mfma_f32_16x16x32_bf16 v[32:35], v[16:19], v[68:71], 0
	v_mfma_f32_16x16x32_bf16 v[36:39], v[24:27], v[68:71], 0
	v_mfma_f32_16x16x32_bf16 v[40:43], v[16:19], v[84:87], 0
	v_mfma_f32_16x16x32_bf16 v[44:47], v[24:27], v[84:87], 0
	v_mfma_f32_16x16x32_bf16 v[48:51], v[16:19], v[92:95], 0
	v_mfma_f32_16x16x32_bf16 v[52:55], v[24:27], v[92:95], 0
	v_mfma_f32_16x16x32_bf16 v[56:59], v[16:19], v[76:79], 0
	v_mfma_f32_16x16x32_bf16 v[60:63], v[24:27], v[76:79], 0
	v_mfma_f32_16x16x32_bf16 v[134:137], v[20:23], v[72:75], v[32:35]
	v_mfma_f32_16x16x32_bf16 v[36:39], v[28:31], v[72:75], v[36:39]
	v_mfma_f32_16x16x32_bf16 v[40:43], v[20:23], v[88:91], v[40:43]
	v_mfma_f32_16x16x32_bf16 v[44:47], v[28:31], v[88:91], v[44:47]
	v_mfma_f32_16x16x32_bf16 v[48:51], v[20:23], v[96:99], v[48:51]
	v_mfma_f32_16x16x32_bf16 v[52:55], v[28:31], v[96:99], v[52:55]
	v_mfma_f32_16x16x32_bf16 v[56:59], v[20:23], v[80:83], v[56:59]
	v_mfma_f32_16x16x32_bf16 v[60:63], v[28:31], v[80:83], v[60:63]
	v_mfma_f32_16x16x32_bf16 v[64:67], v[0:3], v[68:71], 0
	v_mfma_f32_16x16x32_bf16 v[68:71], v[8:11], v[68:71], 0
	v_mfma_f32_16x16x32_bf16 v[64:67], v[4:7], v[72:75], v[64:67]
	v_mfma_f32_16x16x32_bf16 v[68:71], v[12:15], v[72:75], v[68:71]
	v_mfma_f32_16x16x32_bf16 v[72:75], v[0:3], v[84:87], 0
	v_mfma_f32_16x16x32_bf16 v[84:87], v[8:11], v[84:87], 0
	v_mfma_f32_16x16x32_bf16 v[72:75], v[4:7], v[88:91], v[72:75]
	v_mfma_f32_16x16x32_bf16 v[84:87], v[12:15], v[88:91], v[84:87]
	v_mfma_f32_16x16x32_bf16 v[88:91], v[0:3], v[92:95], 0
	v_mfma_f32_16x16x32_bf16 v[92:95], v[8:11], v[92:95], 0
	v_mfma_f32_16x16x32_bf16 v[88:91], v[4:7], v[96:99], v[88:91]
	v_mfma_f32_16x16x32_bf16 v[96:99], v[12:15], v[96:99], v[92:95]
	v_mfma_f32_16x16x32_bf16 v[92:95], v[0:3], v[76:79], 0
	v_mfma_f32_16x16x32_bf16 v[76:79], v[8:11], v[76:79], 0
	v_mfma_f32_16x16x32_bf16 v[108:111], v[4:7], v[80:83], v[92:95]
	v_mfma_f32_16x16x32_bf16 v[120:123], v[12:15], v[80:83], v[76:79]
	s_barrier
	s_mov_b32 m0, s56
	ds_read_b128 v[116:119], v209 offset:16384
	ds_read_b128 v[124:127], v209 offset:17408
	ds_read_b128 v[104:107], v209 offset:18432
	ds_read_b128 v[112:115], v209 offset:19456
	ds_read_b128 v[92:95], v209 offset:20480
	ds_read_b128 v[100:103], v209 offset:21504
	ds_read_b128 v[76:79], v209 offset:22528
	ds_read_b128 v[80:83], v209 offset:23552
	global_load_lds_dwordx4 v203, s[54:55]
	s_mov_b32 m0, s57
	s_nop 0
	global_load_lds_dwordx4 v205, s[54:55]
	s_add_u32 s54, s4, 0x160100
	s_addc_u32 s55, s5, 0
	s_mov_b32 m0, s58
	s_and_b64 vcc, exec, s[52:53]
	global_load_lds_dwordx4 v203, s[54:55]
	s_mov_b32 m0, s59
	s_nop 0
	global_load_lds_dwordx4 v205, s[54:55]
	s_mov_b32 m0, s27
	s_mov_b64 s[54:55], -1
	global_load_lds_dwordx4 v202, s[20:21]
	s_mov_b32 m0, s60
	s_nop 0
	global_load_lds_dwordx4 v204, s[20:21]
	s_cbranch_vccz .LBB0_2248
	s_waitcnt vmcnt(8)
	s_mov_b64 s[54:55], 0

.LBB0_2250:
	s_add_u32 s52, s50, 0x180
	s_waitcnt lgkmcnt(0)
	s_addc_u32 s53, s51, 0
	s_add_u32 s54, s4, 0x180
	s_addc_u32 s55, s5, 0
	s_barrier
	s_waitcnt lgkmcnt(0)
	v_mfma_f32_16x16x32_bf16 v[128:131], v[16:19], v[116:119], 0
	v_mfma_f32_16x16x32_bf16 v[140:143], v[20:23], v[124:127], v[128:131]
	v_mfma_f32_16x16x32_bf16 v[128:131], v[24:27], v[116:119], 0
	v_mfma_f32_16x16x32_bf16 v[156:159], v[28:31], v[124:127], v[128:131]
	v_mfma_f32_16x16x32_bf16 v[128:131], v[16:19], v[104:107], 0
	v_mfma_f32_16x16x32_bf16 v[160:163], v[20:23], v[112:115], v[128:131]
	v_mfma_f32_16x16x32_bf16 v[128:131], v[24:27], v[104:107], 0
	v_mfma_f32_16x16x32_bf16 v[164:167], v[28:31], v[112:115], v[128:131]
	v_mfma_f32_16x16x32_bf16 v[128:131], v[16:19], v[92:95], 0
	v_mfma_f32_16x16x32_bf16 v[16:19], v[16:19], v[76:79], 0
	v_mfma_f32_16x16x32_bf16 v[168:171], v[20:23], v[100:103], v[128:131]
	v_mfma_f32_16x16x32_bf16 v[16:19], v[20:23], v[80:83], v[16:19]
	v_mfma_f32_16x16x32_bf16 v[20:23], v[24:27], v[76:79], 0
	v_mfma_f32_16x16x32_bf16 v[128:131], v[24:27], v[92:95], 0
	v_mfma_f32_16x16x32_bf16 v[20:23], v[28:31], v[80:83], v[20:23]
	v_mfma_f32_16x16x32_bf16 v[172:175], v[28:31], v[100:103], v[128:131]
	v_mfma_f32_16x16x32_bf16 v[24:27], v[0:3], v[116:119], 0
	v_mfma_f32_16x16x32_bf16 v[176:179], v[4:7], v[124:127], v[24:27]
	v_mfma_f32_16x16x32_bf16 v[24:27], v[8:11], v[116:119], 0
	v_mfma_f32_16x16x32_bf16 v[180:183], v[12:15], v[124:127], v[24:27]
	v_mfma_f32_16x16x32_bf16 v[24:27], v[0:3], v[104:107], 0
	v_mfma_f32_16x16x32_bf16 v[186:189], v[4:7], v[112:115], v[24:27]
	v_mfma_f32_16x16x32_bf16 v[24:27], v[8:11], v[104:107], 0
	v_mfma_f32_16x16x32_bf16 v[190:193], v[12:15], v[112:115], v[24:27]
	v_mfma_f32_16x16x32_bf16 v[24:27], v[0:3], v[92:95], 0
	v_mfma_f32_16x16x32_bf16 v[0:3], v[0:3], v[76:79], 0
	v_mfma_f32_16x16x32_bf16 v[194:197], v[4:7], v[100:103], v[24:27]
	v_mfma_f32_16x16x32_bf16 v[24:27], v[8:11], v[92:95], 0
	v_mfma_f32_16x16x32_bf16 v[0:3], v[4:7], v[80:83], v[0:3]
	v_mfma_f32_16x16x32_bf16 v[4:7], v[8:11], v[76:79], 0
	v_mfma_f32_16x16x32_bf16 v[198:201], v[12:15], v[100:103], v[24:27]
	v_mfma_f32_16x16x32_bf16 v[212:215], v[12:15], v[80:83], v[4:7]
	s_barrier
	v_add_u32_e32 v132, s69, v206
	v_add_u32_e32 v133, s70, v206
	s_nop 1
	ds_read_b128 v[4:7], v132
	ds_read_b128 v[8:11], v132 offset:1024
	ds_read_b128 v[216:219], v132 offset:2048
	ds_read_b128 v[220:223], v132 offset:3072
	ds_read_b128 v[224:227], v133
	ds_read_b128 v[228:231], v133 offset:1024
	ds_read_b128 v[232:235], v133 offset:2048
	ds_read_b128 v[236:239], v133 offset:3072
	s_add_u32 s20, s50, 0x160100
	s_addc_u32 s21, s51, 0
	s_mov_b32 m0, s61
	ds_read_b128 v[12:15], v209 offset:32768
	ds_read_b128 v[24:27], v209 offset:33792
	ds_read_b128 v[28:31], v209 offset:34816
	ds_read_b128 v[92:95], v209 offset:35840
	ds_read_b128 v[240:243], v209 offset:36864
	ds_read_b128 v[244:247], v209 offset:37888
	ds_read_b128 v[248:251], v209 offset:38912
	ds_read_b128 v[32:35], v209 offset:39936
	global_load_lds_dwordx4 v202, s[20:21]
	s_mov_b32 m0, s62
	s_nop 0
	global_load_lds_dwordx4 v204, s[20:21]
	s_waitcnt vmcnt(8)
	s_waitcnt lgkmcnt(0)
	s_barrier
	v_mfma_f32_16x16x32_bf16 v[36:39], v[216:219], v[12:15], v[36:39]
	v_mfma_f32_16x16x32_bf16 v[148:151], v[220:223], v[24:27], v[36:39]
	v_mfma_f32_16x16x32_bf16 v[36:39], v[4:7], v[28:31], v[40:43]
	v_mfma_f32_16x16x32_bf16 v[128:131], v[8:11], v[92:95], v[36:39]
	v_mfma_f32_16x16x32_bf16 v[36:39], v[216:219], v[28:31], v[44:47]
	v_mfma_f32_16x16x32_bf16 v[124:127], v[220:223], v[92:95], v[36:39]
	v_mfma_f32_16x16x32_bf16 v[36:39], v[4:7], v[240:243], v[48:51]
	v_mfma_f32_16x16x32_bf16 v[104:107], v[8:11], v[244:247], v[36:39]
	v_mfma_f32_16x16x32_bf16 v[36:39], v[216:219], v[240:243], v[52:55]
	v_mfma_f32_16x16x32_bf16 v[100:103], v[220:223], v[244:247], v[36:39]
	v_mfma_f32_16x16x32_bf16 v[36:39], v[4:7], v[248:251], v[56:59]
	v_mfma_f32_16x16x32_bf16 v[76:79], v[4:7], v[12:15], v[134:137]
	v_mfma_f32_16x16x32_bf16 v[80:83], v[8:11], v[32:35], v[36:39]
	v_mfma_f32_16x16x32_bf16 v[36:39], v[216:219], v[248:251], v[60:63]
	v_mfma_f32_16x16x32_bf16 v[152:155], v[8:11], v[24:27], v[76:79]
	v_mfma_f32_16x16x32_bf16 v[76:79], v[220:223], v[32:35], v[36:39]
	v_mfma_f32_16x16x32_bf16 v[36:39], v[224:227], v[12:15], v[64:67]
	v_mfma_f32_16x16x32_bf16 v[12:15], v[232:235], v[12:15], v[68:71]
	v_mfma_f32_16x16x32_bf16 v[136:139], v[236:239], v[24:27], v[12:15]
	v_mfma_f32_16x16x32_bf16 v[12:15], v[224:227], v[28:31], v[72:75]
	v_mfma_f32_16x16x32_bf16 v[116:119], v[228:231], v[92:95], v[12:15]
	v_mfma_f32_16x16x32_bf16 v[12:15], v[232:235], v[28:31], v[84:87]
	v_mfma_f32_16x16x32_bf16 v[112:115], v[236:239], v[92:95], v[12:15]
	v_mfma_f32_16x16x32_bf16 v[12:15], v[224:227], v[240:243], v[88:91]
	v_mfma_f32_16x16x32_bf16 v[92:95], v[228:231], v[244:247], v[12:15]
	v_mfma_f32_16x16x32_bf16 v[12:15], v[232:235], v[240:243], v[96:99]
	v_mfma_f32_16x16x32_bf16 v[88:91], v[236:239], v[244:247], v[12:15]
	v_mfma_f32_16x16x32_bf16 v[12:15], v[224:227], v[248:251], v[108:111]
	v_mfma_f32_16x16x32_bf16 v[68:71], v[228:231], v[32:35], v[12:15]
	v_mfma_f32_16x16x32_bf16 v[12:15], v[232:235], v[248:251], v[120:123]
	v_mfma_f32_16x16x32_bf16 v[144:147], v[228:231], v[24:27], v[36:39]
	v_mfma_f32_16x16x32_bf16 v[64:67], v[236:239], v[32:35], v[12:15]
	s_barrier
	s_add_i32 s20, s69, s26
	s_mov_b32 m0, s20
	s_add_i32 s21, s20, 0x2000
	ds_read_b128 v[32:35], v209 offset:49152
	ds_read_b128 v[36:39], v209 offset:50176
	ds_read_b128 v[72:75], v209 offset:51200
	ds_read_b128 v[84:87], v209 offset:52224
	ds_read_b128 v[96:99], v209 offset:53248
	ds_read_b128 v[108:111], v209 offset:54272
	ds_read_b128 v[120:123], v209 offset:55296
	ds_read_b128 v[240:243], v209 offset:56320
	global_load_lds_dwordx4 v203, s[54:55]
	s_mov_b32 m0, s21
	s_nop 0
	global_load_lds_dwordx4 v205, s[54:55]
	s_add_u32 s54, s4, 0x160180
	s_addc_u32 s55, s5, 0
	s_add_i32 s75, s70, s26
	s_mov_b32 m0, s75
	s_add_i32 s76, s75, 0x2000
	s_nop 0
	global_load_lds_dwordx4 v203, s[54:55]
	s_mov_b32 m0, s76
	s_nop 0
	global_load_lds_dwordx4 v205, s[54:55]
	s_mov_b32 m0, s63
	s_nop 0
	global_load_lds_dwordx4 v202, s[52:53]
	s_mov_b32 m0, s64
	s_nop 0
	global_load_lds_dwordx4 v204, s[52:53]
	s_waitcnt vmcnt(8)
	s_waitcnt lgkmcnt(0)
	s_barrier
	v_mfma_f32_16x16x32_bf16 v[12:15], v[4:7], v[32:35], v[140:143]
	v_mfma_f32_16x16x32_bf16 v[60:63], v[8:11], v[36:39], v[12:15]
	v_mfma_f32_16x16x32_bf16 v[12:15], v[216:219], v[32:35], v[156:159]
	v_mfma_f32_16x16x32_bf16 v[56:59], v[220:223], v[36:39], v[12:15]
	v_mfma_f32_16x16x32_bf16 v[12:15], v[4:7], v[72:75], v[160:163]
	v_mfma_f32_16x16x32_bf16 v[44:47], v[8:11], v[84:87], v[12:15]
	v_mfma_f32_16x16x32_bf16 v[12:15], v[216:219], v[72:75], v[164:167]
	v_mfma_f32_16x16x32_bf16 v[40:43], v[220:223], v[84:87], v[12:15]
	v_mfma_f32_16x16x32_bf16 v[12:15], v[4:7], v[96:99], v[168:171]
	v_mfma_f32_16x16x32_bf16 v[28:31], v[8:11], v[108:111], v[12:15]
	v_mfma_f32_16x16x32_bf16 v[12:15], v[216:219], v[96:99], v[172:175]
	v_mfma_f32_16x16x32_bf16 v[4:7], v[4:7], v[120:123], v[16:19]
	v_mfma_f32_16x16x32_bf16 v[24:27], v[220:223], v[108:111], v[12:15]
	v_mfma_f32_16x16x32_bf16 v[12:15], v[8:11], v[240:243], v[4:7]
	v_mfma_f32_16x16x32_bf16 v[4:7], v[216:219], v[120:123], v[20:23]
	v_mfma_f32_16x16x32_bf16 v[8:11], v[220:223], v[240:243], v[4:7]
	v_mfma_f32_16x16x32_bf16 v[4:7], v[224:227], v[32:35], v[176:179]
	v_mfma_f32_16x16x32_bf16 v[52:55], v[228:231], v[36:39], v[4:7]
	v_mfma_f32_16x16x32_bf16 v[4:7], v[232:235], v[32:35], v[180:183]
	v_mfma_f32_16x16x32_bf16 v[48:51], v[236:239], v[36:39], v[4:7]
	v_mfma_f32_16x16x32_bf16 v[4:7], v[224:227], v[72:75], v[186:189]
	v_mfma_f32_16x16x32_bf16 v[36:39], v[228:231], v[84:87], v[4:7]
	v_mfma_f32_16x16x32_bf16 v[4:7], v[232:235], v[72:75], v[190:193]
	v_mfma_f32_16x16x32_bf16 v[32:35], v[236:239], v[84:87], v[4:7]
	v_mfma_f32_16x16x32_bf16 v[4:7], v[224:227], v[96:99], v[194:197]
	v_mfma_f32_16x16x32_bf16 v[20:23], v[228:231], v[108:111], v[4:7]
	v_mfma_f32_16x16x32_bf16 v[4:7], v[232:235], v[96:99], v[198:201]
	v_mfma_f32_16x16x32_bf16 v[0:3], v[224:227], v[120:123], v[0:3]
	v_mfma_f32_16x16x32_bf16 v[16:19], v[236:239], v[108:111], v[4:7]
	v_mfma_f32_16x16x32_bf16 v[4:7], v[228:231], v[240:243], v[0:3]
	v_mfma_f32_16x16x32_bf16 v[0:3], v[232:235], v[120:123], v[212:215]
	v_mfma_f32_16x16x32_bf16 v[0:3], v[236:239], v[240:243], v[0:3]
	s_barrier
	s_add_u32 s77, s50, 0x200
	s_addc_u32 s78, s51, 0
	s_add_u32 s79, s4, 0x200
	s_addc_u32 s80, s5, 0
	s_add_u32 s4, s50, 0x160180
	s_addc_u32 s5, s51, 0
	s_mov_b32 s83, 0
.LBB0_2251:
	s_cmpk_eq_i32 s83, 0x54
	s_cselect_b32 s54, s46, s77
	s_cselect_b32 s55, s47, s78
	s_cselect_b32 s52, s48, s79
	s_cselect_b32 s53, s49, s80
	s_add_u32 s50, s54, 0x80
	s_addc_u32 s51, s55, 0
	s_add_i32 s86, 0, 0x10000
	s_add_i32 s90, 0, 0x14000
	v_add_u32_e32 v108, s86, v206
	v_add_u32_e32 v134, s90, v206
	ds_read_b128 v[72:75], v108
	ds_read_b128 v[84:87], v108 offset:1024
	ds_read_b128 v[96:99], v108 offset:2048
	ds_read_b128 v[108:111], v108 offset:3072
	ds_read_b128 v[120:123], v134
	ds_read_b128 v[140:143], v134 offset:1024
	ds_read_b128 v[156:159], v134 offset:2048
	ds_read_b128 v[160:163], v134 offset:3072
	s_mov_b32 m0, s1
	ds_read_b128 v[164:167], v209
	ds_read_b128 v[168:171], v209 offset:1024
	ds_read_b128 v[172:175], v209 offset:2048
	ds_read_b128 v[176:179], v209 offset:3072
	ds_read_b128 v[180:183], v209 offset:4096
	ds_read_b128 v[186:189], v209 offset:5120
	ds_read_b128 v[190:193], v209 offset:6144
	ds_read_b128 v[194:197], v209 offset:7168
	global_load_lds_dwordx4 v202, s[4:5]
	s_mov_b32 m0, s12
	s_nop 0
	global_load_lds_dwordx4 v204, s[4:5]
	s_waitcnt vmcnt(8)
	s_waitcnt lgkmcnt(0)
	s_barrier
	v_mfma_f32_16x16x32_bf16 v[152:155], v[72:75], v[164:167], v[152:155]
	v_mfma_f32_16x16x32_bf16 v[148:151], v[96:99], v[164:167], v[148:151]
	v_mfma_f32_16x16x32_bf16 v[128:131], v[72:75], v[172:175], v[128:131]
	v_mfma_f32_16x16x32_bf16 v[124:127], v[96:99], v[172:175], v[124:127]
	v_mfma_f32_16x16x32_bf16 v[104:107], v[72:75], v[180:183], v[104:107]
	v_mfma_f32_16x16x32_bf16 v[100:103], v[96:99], v[180:183], v[100:103]
	v_mfma_f32_16x16x32_bf16 v[80:83], v[72:75], v[190:193], v[80:83]
	v_mfma_f32_16x16x32_bf16 v[76:79], v[96:99], v[190:193], v[76:79]
	v_mfma_f32_16x16x32_bf16 v[152:155], v[84:87], v[168:171], v[152:155]
	v_mfma_f32_16x16x32_bf16 v[148:151], v[108:111], v[168:171], v[148:151]
	v_mfma_f32_16x16x32_bf16 v[128:131], v[84:87], v[176:179], v[128:131]
	v_mfma_f32_16x16x32_bf16 v[124:127], v[108:111], v[176:179], v[124:127]
	v_mfma_f32_16x16x32_bf16 v[104:107], v[84:87], v[186:189], v[104:107]
	v_mfma_f32_16x16x32_bf16 v[100:103], v[108:111], v[186:189], v[100:103]
	v_mfma_f32_16x16x32_bf16 v[80:83], v[84:87], v[194:197], v[80:83]
	v_mfma_f32_16x16x32_bf16 v[76:79], v[108:111], v[194:197], v[76:79]
	v_mfma_f32_16x16x32_bf16 v[144:147], v[120:123], v[164:167], v[144:147]
	v_mfma_f32_16x16x32_bf16 v[134:137], v[156:159], v[164:167], v[136:139]
	v_mfma_f32_16x16x32_bf16 v[116:119], v[120:123], v[172:175], v[116:119]
	v_mfma_f32_16x16x32_bf16 v[112:115], v[156:159], v[172:175], v[112:115]
	v_mfma_f32_16x16x32_bf16 v[92:95], v[120:123], v[180:183], v[92:95]
	v_mfma_f32_16x16x32_bf16 v[88:91], v[156:159], v[180:183], v[88:91]
	v_mfma_f32_16x16x32_bf16 v[68:71], v[120:123], v[190:193], v[68:71]
	v_mfma_f32_16x16x32_bf16 v[64:67], v[156:159], v[190:193], v[64:67]
	v_mfma_f32_16x16x32_bf16 v[144:147], v[140:143], v[168:171], v[144:147]
	v_mfma_f32_16x16x32_bf16 v[134:137], v[160:163], v[168:171], v[134:137]
	v_mfma_f32_16x16x32_bf16 v[116:119], v[140:143], v[176:179], v[116:119]
	v_mfma_f32_16x16x32_bf16 v[112:115], v[160:163], v[176:179], v[112:115]
	v_mfma_f32_16x16x32_bf16 v[92:95], v[140:143], v[186:189], v[92:95]
	v_mfma_f32_16x16x32_bf16 v[88:91], v[160:163], v[186:189], v[88:91]
	v_mfma_f32_16x16x32_bf16 v[68:71], v[140:143], v[194:197], v[68:71]
	v_mfma_f32_16x16x32_bf16 v[64:67], v[160:163], v[194:197], v[64:67]
	s_barrier
	s_add_i32 s86, s86, s26
	s_mov_b32 m0, s86
	ds_read_b128 v[164:167], v209 offset:16384
	ds_read_b128 v[168:171], v209 offset:17408
	ds_read_b128 v[172:175], v209 offset:18432
	ds_read_b128 v[176:179], v209 offset:19456
	ds_read_b128 v[180:183], v209 offset:20480
	ds_read_b128 v[186:189], v209 offset:21504
	ds_read_b128 v[190:193], v209 offset:22528
	ds_read_b128 v[194:197], v209 offset:23552
	global_load_lds_dwordx4 v203, s[52:53]
	s_add_i32 m0, s86, 0x2000
	s_add_u32 s88, s52, 0x160000
	s_addc_u32 s89, s53, 0
	s_add_i32 s86, s90, s26
	s_nop 0
	global_load_lds_dwordx4 v205, s[52:53]
	s_mov_b32 m0, s86
	s_nop 0
	global_load_lds_dwordx4 v203, s[88:89]
	s_add_i32 m0, s86, 0x2000
	s_nop 0
	global_load_lds_dwordx4 v205, s[88:89]
	s_mov_b32 m0, s27
	s_nop 0
	global_load_lds_dwordx4 v202, s[54:55]
	s_mov_b32 m0, s60
	s_nop 0
	global_load_lds_dwordx4 v204, s[54:55]
	s_waitcnt vmcnt(8)
	s_waitcnt lgkmcnt(0)
	s_barrier
	v_mfma_f32_16x16x32_bf16 v[60:63], v[72:75], v[164:167], v[60:63]
	v_mfma_f32_16x16x32_bf16 v[56:59], v[96:99], v[164:167], v[56:59]
	v_mfma_f32_16x16x32_bf16 v[44:47], v[72:75], v[172:175], v[44:47]
	v_mfma_f32_16x16x32_bf16 v[40:43], v[96:99], v[172:175], v[40:43]
	v_mfma_f32_16x16x32_bf16 v[28:31], v[72:75], v[180:183], v[28:31]
	v_mfma_f32_16x16x32_bf16 v[24:27], v[96:99], v[180:183], v[24:27]
	v_mfma_f32_16x16x32_bf16 v[12:15], v[72:75], v[190:193], v[12:15]
	v_mfma_f32_16x16x32_bf16 v[8:11], v[96:99], v[190:193], v[8:11]
	v_mfma_f32_16x16x32_bf16 v[60:63], v[84:87], v[168:171], v[60:63]
	v_mfma_f32_16x16x32_bf16 v[56:59], v[108:111], v[168:171], v[56:59]
	v_mfma_f32_16x16x32_bf16 v[44:47], v[84:87], v[176:179], v[44:47]
	v_mfma_f32_16x16x32_bf16 v[40:43], v[108:111], v[176:179], v[40:43]
	v_mfma_f32_16x16x32_bf16 v[28:31], v[84:87], v[186:189], v[28:31]
	v_mfma_f32_16x16x32_bf16 v[24:27], v[108:111], v[186:189], v[24:27]
	v_mfma_f32_16x16x32_bf16 v[12:15], v[84:87], v[194:197], v[12:15]
	v_mfma_f32_16x16x32_bf16 v[8:11], v[108:111], v[194:197], v[8:11]
	v_mfma_f32_16x16x32_bf16 v[52:55], v[120:123], v[164:167], v[52:55]
	v_mfma_f32_16x16x32_bf16 v[48:51], v[156:159], v[164:167], v[48:51]
	v_mfma_f32_16x16x32_bf16 v[36:39], v[120:123], v[172:175], v[36:39]
	v_mfma_f32_16x16x32_bf16 v[32:35], v[156:159], v[172:175], v[32:35]
	v_mfma_f32_16x16x32_bf16 v[20:23], v[120:123], v[180:183], v[20:23]
	v_mfma_f32_16x16x32_bf16 v[16:19], v[156:159], v[180:183], v[16:19]
	v_mfma_f32_16x16x32_bf16 v[4:7], v[120:123], v[190:193], v[4:7]
	v_mfma_f32_16x16x32_bf16 v[0:3], v[156:159], v[190:193], v[0:3]
	v_mfma_f32_16x16x32_bf16 v[52:55], v[140:143], v[168:171], v[52:55]
	v_mfma_f32_16x16x32_bf16 v[48:51], v[160:163], v[168:171], v[48:51]
	v_mfma_f32_16x16x32_bf16 v[36:39], v[140:143], v[176:179], v[36:39]
	v_mfma_f32_16x16x32_bf16 v[32:35], v[160:163], v[176:179], v[32:35]
	v_mfma_f32_16x16x32_bf16 v[20:23], v[140:143], v[186:189], v[20:23]
	v_mfma_f32_16x16x32_bf16 v[16:19], v[160:163], v[186:189], v[16:19]
	v_mfma_f32_16x16x32_bf16 v[4:7], v[140:143], v[194:197], v[4:7]
	v_mfma_f32_16x16x32_bf16 v[0:3], v[160:163], v[194:197], v[0:3]
	s_barrier
	ds_read_b128 v[72:75], v132
	ds_read_b128 v[84:87], v132 offset:1024
	ds_read_b128 v[96:99], v132 offset:2048
	ds_read_b128 v[108:111], v132 offset:3072
	ds_read_b128 v[120:123], v133
	ds_read_b128 v[140:143], v133 offset:1024
	ds_read_b128 v[156:159], v133 offset:2048
	ds_read_b128 v[160:163], v133 offset:3072
	s_add_u32 s54, s54, 0x160000
	s_addc_u32 s55, s55, 0
	s_mov_b32 m0, s61
	ds_read_b128 v[164:167], v209 offset:32768
	ds_read_b128 v[168:171], v209 offset:33792
	ds_read_b128 v[172:175], v209 offset:34816
	ds_read_b128 v[176:179], v209 offset:35840
	ds_read_b128 v[180:183], v209 offset:36864
	ds_read_b128 v[186:189], v209 offset:37888
	ds_read_b128 v[190:193], v209 offset:38912
	ds_read_b128 v[194:197], v209 offset:39936
	global_load_lds_dwordx4 v202, s[54:55]
	s_mov_b32 m0, s62
	s_nop 0
	global_load_lds_dwordx4 v204, s[54:55]
	s_waitcnt vmcnt(8)
	s_waitcnt lgkmcnt(0)
	s_barrier
	v_mfma_f32_16x16x32_bf16 v[152:155], v[72:75], v[164:167], v[152:155]
	v_mfma_f32_16x16x32_bf16 v[148:151], v[96:99], v[164:167], v[148:151]
	v_mfma_f32_16x16x32_bf16 v[128:131], v[72:75], v[172:175], v[128:131]
	v_mfma_f32_16x16x32_bf16 v[124:127], v[96:99], v[172:175], v[124:127]
	v_mfma_f32_16x16x32_bf16 v[104:107], v[72:75], v[180:183], v[104:107]
	v_mfma_f32_16x16x32_bf16 v[100:103], v[96:99], v[180:183], v[100:103]
	v_mfma_f32_16x16x32_bf16 v[80:83], v[72:75], v[190:193], v[80:83]
	v_mfma_f32_16x16x32_bf16 v[76:79], v[96:99], v[190:193], v[76:79]
	v_mfma_f32_16x16x32_bf16 v[152:155], v[84:87], v[168:171], v[152:155]
	v_mfma_f32_16x16x32_bf16 v[148:151], v[108:111], v[168:171], v[148:151]
	v_mfma_f32_16x16x32_bf16 v[128:131], v[84:87], v[176:179], v[128:131]
	v_mfma_f32_16x16x32_bf16 v[124:127], v[108:111], v[176:179], v[124:127]
	v_mfma_f32_16x16x32_bf16 v[104:107], v[84:87], v[186:189], v[104:107]
	v_mfma_f32_16x16x32_bf16 v[100:103], v[108:111], v[186:189], v[100:103]
	v_mfma_f32_16x16x32_bf16 v[80:83], v[84:87], v[194:197], v[80:83]
	v_mfma_f32_16x16x32_bf16 v[76:79], v[108:111], v[194:197], v[76:79]
	v_mfma_f32_16x16x32_bf16 v[144:147], v[120:123], v[164:167], v[144:147]
	v_mfma_f32_16x16x32_bf16 v[134:137], v[156:159], v[164:167], v[134:137]
	v_mfma_f32_16x16x32_bf16 v[116:119], v[120:123], v[172:175], v[116:119]
	v_mfma_f32_16x16x32_bf16 v[112:115], v[156:159], v[172:175], v[112:115]
	v_mfma_f32_16x16x32_bf16 v[92:95], v[120:123], v[180:183], v[92:95]
	v_mfma_f32_16x16x32_bf16 v[88:91], v[156:159], v[180:183], v[88:91]
	v_mfma_f32_16x16x32_bf16 v[68:71], v[120:123], v[190:193], v[68:71]
	v_mfma_f32_16x16x32_bf16 v[64:67], v[156:159], v[190:193], v[64:67]
	v_mfma_f32_16x16x32_bf16 v[144:147], v[140:143], v[168:171], v[144:147]
	v_mfma_f32_16x16x32_bf16 v[136:139], v[160:163], v[168:171], v[134:137]
	v_mfma_f32_16x16x32_bf16 v[116:119], v[140:143], v[176:179], v[116:119]
	v_mfma_f32_16x16x32_bf16 v[112:115], v[160:163], v[176:179], v[112:115]
	v_mfma_f32_16x16x32_bf16 v[92:95], v[140:143], v[186:189], v[92:95]
	v_mfma_f32_16x16x32_bf16 v[88:91], v[160:163], v[186:189], v[88:91]
	v_mfma_f32_16x16x32_bf16 v[68:71], v[140:143], v[194:197], v[68:71]
	v_mfma_f32_16x16x32_bf16 v[64:67], v[160:163], v[194:197], v[64:67]
	s_barrier
	s_add_u32 s54, s52, 0x80
	s_mov_b32 m0, s20
	s_addc_u32 s55, s53, 0
	ds_read_b128 v[164:167], v209 offset:49152
	ds_read_b128 v[168:171], v209 offset:50176
	ds_read_b128 v[172:175], v209 offset:51200
	ds_read_b128 v[176:179], v209 offset:52224
	ds_read_b128 v[180:183], v209 offset:53248
	ds_read_b128 v[186:189], v209 offset:54272
	ds_read_b128 v[190:193], v209 offset:55296
	ds_read_b128 v[194:197], v209 offset:56320
	s_add_u32 s52, s52, 0x160080
	global_load_lds_dwordx4 v203, s[54:55]
	s_mov_b32 m0, s21
	s_addc_u32 s53, s53, 0
	global_load_lds_dwordx4 v205, s[54:55]
	s_mov_b32 m0, s75
	s_nop 0
	global_load_lds_dwordx4 v203, s[52:53]
	s_mov_b32 m0, s76
	s_nop 0
	global_load_lds_dwordx4 v205, s[52:53]
	s_mov_b32 m0, s63
	s_nop 0
	global_load_lds_dwordx4 v202, s[50:51]
	s_mov_b32 m0, s64
	s_nop 0
	global_load_lds_dwordx4 v204, s[50:51]
	s_waitcnt vmcnt(8)
	s_waitcnt lgkmcnt(0)
	s_barrier
	v_mfma_f32_16x16x32_bf16 v[60:63], v[72:75], v[164:167], v[60:63]
	v_mfma_f32_16x16x32_bf16 v[56:59], v[96:99], v[164:167], v[56:59]
	v_mfma_f32_16x16x32_bf16 v[44:47], v[72:75], v[172:175], v[44:47]
	v_mfma_f32_16x16x32_bf16 v[40:43], v[96:99], v[172:175], v[40:43]
	v_mfma_f32_16x16x32_bf16 v[28:31], v[72:75], v[180:183], v[28:31]
	v_mfma_f32_16x16x32_bf16 v[24:27], v[96:99], v[180:183], v[24:27]
	v_mfma_f32_16x16x32_bf16 v[12:15], v[72:75], v[190:193], v[12:15]
	v_mfma_f32_16x16x32_bf16 v[8:11], v[96:99], v[190:193], v[8:11]
	v_mfma_f32_16x16x32_bf16 v[60:63], v[84:87], v[168:171], v[60:63]
	v_mfma_f32_16x16x32_bf16 v[56:59], v[108:111], v[168:171], v[56:59]
	v_mfma_f32_16x16x32_bf16 v[44:47], v[84:87], v[176:179], v[44:47]
	v_mfma_f32_16x16x32_bf16 v[40:43], v[108:111], v[176:179], v[40:43]
	v_mfma_f32_16x16x32_bf16 v[28:31], v[84:87], v[186:189], v[28:31]
	v_mfma_f32_16x16x32_bf16 v[24:27], v[108:111], v[186:189], v[24:27]
	v_mfma_f32_16x16x32_bf16 v[12:15], v[84:87], v[194:197], v[12:15]
	v_mfma_f32_16x16x32_bf16 v[8:11], v[108:111], v[194:197], v[8:11]
	v_mfma_f32_16x16x32_bf16 v[52:55], v[120:123], v[164:167], v[52:55]
	v_mfma_f32_16x16x32_bf16 v[48:51], v[156:159], v[164:167], v[48:51]
	v_mfma_f32_16x16x32_bf16 v[36:39], v[120:123], v[172:175], v[36:39]
	v_mfma_f32_16x16x32_bf16 v[32:35], v[156:159], v[172:175], v[32:35]
	v_mfma_f32_16x16x32_bf16 v[20:23], v[120:123], v[180:183], v[20:23]
	v_mfma_f32_16x16x32_bf16 v[16:19], v[156:159], v[180:183], v[16:19]
	v_mfma_f32_16x16x32_bf16 v[4:7], v[120:123], v[190:193], v[4:7]
	v_mfma_f32_16x16x32_bf16 v[0:3], v[156:159], v[190:193], v[0:3]
	v_mfma_f32_16x16x32_bf16 v[52:55], v[140:143], v[168:171], v[52:55]
	v_mfma_f32_16x16x32_bf16 v[48:51], v[160:163], v[168:171], v[48:51]
	v_mfma_f32_16x16x32_bf16 v[36:39], v[140:143], v[176:179], v[36:39]
	v_mfma_f32_16x16x32_bf16 v[32:35], v[160:163], v[176:179], v[32:35]
	v_mfma_f32_16x16x32_bf16 v[20:23], v[140:143], v[186:189], v[20:23]
	v_mfma_f32_16x16x32_bf16 v[16:19], v[160:163], v[186:189], v[16:19]
	v_mfma_f32_16x16x32_bf16 v[4:7], v[140:143], v[194:197], v[4:7]
	v_mfma_f32_16x16x32_bf16 v[0:3], v[160:163], v[194:197], v[0:3]
	s_barrier
	s_add_i32 s83, s83, 2
	s_add_u32 s77, s77, 0x100
	s_addc_u32 s78, s78, 0
	s_add_u32 s79, s79, 0x100
	s_addc_u32 s80, s80, 0
	s_add_u32 s4, s4, 0x100
	s_addc_u32 s5, s5, 0
	s_cmpk_gt_u32 s83, 0x55
	s_cbranch_scc0 .LBB0_2251
	s_and_b64 vcc, exec, s[44:45]
	s_cbranch_vccz .LBB0_2254
	s_barrier

.LBB0_2360:
	s_add_u32 s20, s56, 0x100
	s_addc_u32 s21, s57, 0
	s_waitcnt lgkmcnt(0)
	s_add_u32 s48, s54, 0x100
	s_addc_u32 s49, s55, 0
	s_barrier
	s_waitcnt lgkmcnt(0)
	v_mfma_f32_16x16x32_bf16 v[32:35], v[16:19], v[68:71], 0
	v_mfma_f32_16x16x32_bf16 v[36:39], v[24:27], v[68:71], 0
	v_mfma_f32_16x16x32_bf16 v[40:43], v[16:19], v[84:87], 0
	v_mfma_f32_16x16x32_bf16 v[44:47], v[24:27], v[84:87], 0
	v_mfma_f32_16x16x32_bf16 v[48:51], v[16:19], v[88:91], 0
	v_mfma_f32_16x16x32_bf16 v[52:55], v[24:27], v[88:91], 0
	v_mfma_f32_16x16x32_bf16 v[56:59], v[16:19], v[72:75], 0
	v_mfma_f32_16x16x32_bf16 v[60:63], v[24:27], v[72:75], 0
	v_mfma_f32_16x16x32_bf16 v[116:119], v[20:23], v[80:83], v[32:35]
	v_mfma_f32_16x16x32_bf16 v[36:39], v[28:31], v[80:83], v[36:39]
	v_mfma_f32_16x16x32_bf16 v[40:43], v[20:23], v[96:99], v[40:43]
	v_mfma_f32_16x16x32_bf16 v[44:47], v[28:31], v[96:99], v[44:47]
	v_mfma_f32_16x16x32_bf16 v[48:51], v[20:23], v[92:95], v[48:51]
	v_mfma_f32_16x16x32_bf16 v[52:55], v[28:31], v[92:95], v[52:55]
	v_mfma_f32_16x16x32_bf16 v[56:59], v[20:23], v[76:79], v[56:59]
	v_mfma_f32_16x16x32_bf16 v[60:63], v[28:31], v[76:79], v[60:63]
	v_mfma_f32_16x16x32_bf16 v[64:67], v[0:3], v[68:71], 0
	v_mfma_f32_16x16x32_bf16 v[68:71], v[8:11], v[68:71], 0
	v_mfma_f32_16x16x32_bf16 v[64:67], v[4:7], v[80:83], v[64:67]
	v_mfma_f32_16x16x32_bf16 v[68:71], v[12:15], v[80:83], v[68:71]
	v_mfma_f32_16x16x32_bf16 v[80:83], v[0:3], v[84:87], 0
	v_mfma_f32_16x16x32_bf16 v[84:87], v[8:11], v[84:87], 0
	v_mfma_f32_16x16x32_bf16 v[80:83], v[4:7], v[96:99], v[80:83]
	v_mfma_f32_16x16x32_bf16 v[84:87], v[12:15], v[96:99], v[84:87]
	v_mfma_f32_16x16x32_bf16 v[96:99], v[0:3], v[88:91], 0
	v_mfma_f32_16x16x32_bf16 v[88:91], v[8:11], v[88:91], 0
	v_mfma_f32_16x16x32_bf16 v[132:135], v[12:15], v[92:95], v[88:91]
	v_mfma_f32_16x16x32_bf16 v[88:91], v[0:3], v[72:75], 0
	v_mfma_f32_16x16x32_bf16 v[72:75], v[8:11], v[72:75], 0
	v_mfma_f32_16x16x32_bf16 v[128:131], v[4:7], v[92:95], v[96:99]
	v_mfma_f32_16x16x32_bf16 v[136:139], v[4:7], v[76:79], v[88:91]
	v_mfma_f32_16x16x32_bf16 v[140:143], v[12:15], v[76:79], v[72:75]
	s_barrier
	s_mov_b32 m0, s65
	ds_read_b128 v[104:107], v162 offset:16384
	ds_read_b128 v[108:111], v162 offset:17408
	ds_read_b128 v[96:99], v162 offset:18432
	ds_read_b128 v[100:103], v162 offset:19456
	ds_read_b128 v[88:91], v162 offset:20480
	ds_read_b128 v[92:95], v162 offset:21504
	ds_read_b128 v[72:75], v162 offset:22528
	ds_read_b128 v[76:79], v162 offset:23552
	global_load_lds_dwordx4 v156, s[48:49]
	s_mov_b32 m0, s66
	s_nop 0
	global_load_lds_dwordx4 v158, s[48:49]
	s_add_u32 s48, s54, 0x80100
	s_addc_u32 s49, s55, 0
	s_mov_b32 m0, s67
	s_and_b64 vcc, exec, s[46:47]
	global_load_lds_dwordx4 v156, s[48:49]
	s_mov_b32 m0, s68
	s_nop 0
	global_load_lds_dwordx4 v158, s[48:49]
	s_mov_b32 m0, s27
	s_mov_b64 s[48:49], -1
	global_load_lds_dwordx4 v153, s[20:21]
	s_mov_b32 m0, s69
	s_nop 0
	global_load_lds_dwordx4 v157, s[20:21]
	s_cbranch_vccz .LBB0_2362
	s_waitcnt vmcnt(8)
	s_mov_b64 s[48:49], 0

.LBB0_2364:
	s_ashr_i32 s7, s6, 31
	s_lshl_b64 s[20:21], s[6:7], 20
	s_add_u32 s46, s14, s20
	s_addc_u32 s47, s15, s21
	s_ashr_i32 s43, s42, 31
	s_lshl_b64 s[20:21], s[42:43], 20
	s_add_u32 s48, s24, s20
	s_addc_u32 s49, s25, s21
	s_add_u32 s58, s56, 0x180
	s_addc_u32 s59, s57, 0
	s_waitcnt lgkmcnt(0)
	s_and_b64 s[20:21], s[44:45], exec
	s_cselect_b32 s20, s49, s55
	s_cselect_b32 s21, s48, s54
	s_cselect_b32 s43, s47, s57
	s_cselect_b32 s51, s46, s56
	s_add_u32 s60, s54, 0x180
	s_addc_u32 s61, s55, 0
	s_barrier
	s_waitcnt lgkmcnt(0)
	v_mfma_f32_16x16x32_bf16 v[112:115], v[16:19], v[104:107], 0
	v_mfma_f32_16x16x32_bf16 v[166:169], v[20:23], v[108:111], v[112:115]
	v_mfma_f32_16x16x32_bf16 v[112:115], v[24:27], v[104:107], 0
	v_mfma_f32_16x16x32_bf16 v[170:173], v[28:31], v[108:111], v[112:115]
	v_mfma_f32_16x16x32_bf16 v[112:115], v[16:19], v[96:99], 0
	v_mfma_f32_16x16x32_bf16 v[174:177], v[20:23], v[100:103], v[112:115]
	v_mfma_f32_16x16x32_bf16 v[112:115], v[24:27], v[96:99], 0
	v_mfma_f32_16x16x32_bf16 v[178:181], v[28:31], v[100:103], v[112:115]
	v_mfma_f32_16x16x32_bf16 v[112:115], v[16:19], v[88:91], 0
	v_mfma_f32_16x16x32_bf16 v[16:19], v[16:19], v[72:75], 0
	v_mfma_f32_16x16x32_bf16 v[182:185], v[20:23], v[92:95], v[112:115]
	v_mfma_f32_16x16x32_bf16 v[16:19], v[20:23], v[76:79], v[16:19]
	v_mfma_f32_16x16x32_bf16 v[20:23], v[24:27], v[72:75], 0
	v_mfma_f32_16x16x32_bf16 v[112:115], v[24:27], v[88:91], 0
	v_mfma_f32_16x16x32_bf16 v[20:23], v[28:31], v[76:79], v[20:23]
	v_mfma_f32_16x16x32_bf16 v[186:189], v[28:31], v[92:95], v[112:115]
	v_mfma_f32_16x16x32_bf16 v[24:27], v[0:3], v[104:107], 0
	v_mfma_f32_16x16x32_bf16 v[190:193], v[4:7], v[108:111], v[24:27]
	v_mfma_f32_16x16x32_bf16 v[24:27], v[8:11], v[104:107], 0
	v_mfma_f32_16x16x32_bf16 v[194:197], v[12:15], v[108:111], v[24:27]
	v_mfma_f32_16x16x32_bf16 v[24:27], v[0:3], v[96:99], 0
	v_mfma_f32_16x16x32_bf16 v[198:201], v[4:7], v[100:103], v[24:27]
	v_mfma_f32_16x16x32_bf16 v[24:27], v[8:11], v[96:99], 0
	v_mfma_f32_16x16x32_bf16 v[202:205], v[12:15], v[100:103], v[24:27]
	v_mfma_f32_16x16x32_bf16 v[24:27], v[0:3], v[88:91], 0
	v_mfma_f32_16x16x32_bf16 v[0:3], v[0:3], v[72:75], 0
	v_mfma_f32_16x16x32_bf16 v[206:209], v[4:7], v[92:95], v[24:27]
	v_mfma_f32_16x16x32_bf16 v[24:27], v[8:11], v[88:91], 0
	v_mfma_f32_16x16x32_bf16 v[0:3], v[4:7], v[76:79], v[0:3]
	v_mfma_f32_16x16x32_bf16 v[4:7], v[8:11], v[72:75], 0
	v_mfma_f32_16x16x32_bf16 v[210:213], v[12:15], v[92:95], v[24:27]
	v_mfma_f32_16x16x32_bf16 v[214:217], v[12:15], v[76:79], v[4:7]
	s_barrier
	v_add_u32_e32 v144, s78, v159
	v_add_u32_e32 v148, s83, v159
	s_nop 1
	ds_read_b128 v[4:7], v144
	ds_read_b128 v[8:11], v144 offset:1024
	ds_read_b128 v[218:221], v144 offset:2048
	ds_read_b128 v[222:225], v144 offset:3072
	ds_read_b128 v[226:229], v148
	ds_read_b128 v[230:233], v148 offset:1024
	ds_read_b128 v[234:237], v148 offset:2048
	ds_read_b128 v[238:241], v148 offset:3072
	s_add_u32 s62, s56, 0x80100
	s_addc_u32 s63, s57, 0
	s_mov_b32 m0, s70
	ds_read_b128 v[12:15], v162 offset:32768
	ds_read_b128 v[24:27], v162 offset:33792
	ds_read_b128 v[28:31], v162 offset:34816
	ds_read_b128 v[96:99], v162 offset:35840
	ds_read_b128 v[242:245], v162 offset:36864
	ds_read_b128 v[246:249], v162 offset:37888
	ds_read_b128 v[250:253], v162 offset:38912
	ds_read_b128 v[32:35], v162 offset:39936
	global_load_lds_dwordx4 v153, s[62:63]
	s_mov_b32 m0, s71
	s_nop 0
	global_load_lds_dwordx4 v157, s[62:63]
	s_waitcnt vmcnt(8)
	s_waitcnt lgkmcnt(0)
	s_barrier
	v_mfma_f32_16x16x32_bf16 v[36:39], v[218:221], v[12:15], v[36:39]
	v_mfma_f32_16x16x32_bf16 v[120:123], v[222:225], v[24:27], v[36:39]
	v_mfma_f32_16x16x32_bf16 v[36:39], v[4:7], v[28:31], v[40:43]
	v_mfma_f32_16x16x32_bf16 v[108:111], v[8:11], v[96:99], v[36:39]
	v_mfma_f32_16x16x32_bf16 v[36:39], v[218:221], v[28:31], v[44:47]
	v_mfma_f32_16x16x32_bf16 v[104:107], v[222:225], v[96:99], v[36:39]
	v_mfma_f32_16x16x32_bf16 v[36:39], v[4:7], v[242:245], v[48:51]
	v_mfma_f32_16x16x32_bf16 v[92:95], v[8:11], v[246:249], v[36:39]
	v_mfma_f32_16x16x32_bf16 v[36:39], v[218:221], v[242:245], v[52:55]
	v_mfma_f32_16x16x32_bf16 v[88:91], v[222:225], v[246:249], v[36:39]
	v_mfma_f32_16x16x32_bf16 v[36:39], v[4:7], v[250:253], v[56:59]
	v_mfma_f32_16x16x32_bf16 v[72:75], v[4:7], v[12:15], v[116:119]
	v_mfma_f32_16x16x32_bf16 v[76:79], v[8:11], v[32:35], v[36:39]
	v_mfma_f32_16x16x32_bf16 v[36:39], v[218:221], v[250:253], v[60:63]
	v_mfma_f32_16x16x32_bf16 v[124:127], v[8:11], v[24:27], v[72:75]
	v_mfma_f32_16x16x32_bf16 v[72:75], v[222:225], v[32:35], v[36:39]
	v_mfma_f32_16x16x32_bf16 v[36:39], v[226:229], v[12:15], v[64:67]
	v_mfma_f32_16x16x32_bf16 v[12:15], v[234:237], v[12:15], v[68:71]
	v_mfma_f32_16x16x32_bf16 v[112:115], v[238:241], v[24:27], v[12:15]
	v_mfma_f32_16x16x32_bf16 v[12:15], v[226:229], v[28:31], v[80:83]
	v_mfma_f32_16x16x32_bf16 v[100:103], v[230:233], v[96:99], v[12:15]
	v_mfma_f32_16x16x32_bf16 v[12:15], v[234:237], v[28:31], v[84:87]
	v_mfma_f32_16x16x32_bf16 v[96:99], v[238:241], v[96:99], v[12:15]
	v_mfma_f32_16x16x32_bf16 v[12:15], v[226:229], v[242:245], v[128:131]
	v_mfma_f32_16x16x32_bf16 v[84:87], v[230:233], v[246:249], v[12:15]
	v_mfma_f32_16x16x32_bf16 v[12:15], v[234:237], v[242:245], v[132:135]
	v_mfma_f32_16x16x32_bf16 v[80:83], v[238:241], v[246:249], v[12:15]
	v_mfma_f32_16x16x32_bf16 v[12:15], v[226:229], v[250:253], v[136:139]
	v_mfma_f32_16x16x32_bf16 v[68:71], v[230:233], v[32:35], v[12:15]
	v_mfma_f32_16x16x32_bf16 v[12:15], v[234:237], v[250:253], v[140:143]
	v_mfma_f32_16x16x32_bf16 v[116:119], v[230:233], v[24:27], v[36:39]
	v_mfma_f32_16x16x32_bf16 v[60:63], v[238:241], v[32:35], v[12:15]
	s_barrier
	s_add_i32 s53, s78, s26
	s_mov_b32 m0, s53
	s_add_i32 s79, s53, 0x2000
	ds_read_b128 v[32:35], v162 offset:49152
	ds_read_b128 v[36:39], v162 offset:50176
	ds_read_b128 v[128:131], v162 offset:51200
	ds_read_b128 v[132:135], v162 offset:52224
	ds_read_b128 v[136:139], v162 offset:53248
	ds_read_b128 v[140:143], v162 offset:54272
	ds_read_b128 v[242:245], v162 offset:55296
	ds_read_b128 v[246:249], v162 offset:56320
	global_load_lds_dwordx4 v156, s[60:61]
	s_mov_b32 m0, s79
	s_nop 0
	global_load_lds_dwordx4 v158, s[60:61]
	s_add_u32 s60, s54, 0x80180
	s_addc_u32 s61, s55, 0
	s_add_i32 s80, s83, s26
	s_mov_b32 m0, s80
	s_add_i32 s86, s80, 0x2000
	s_nop 0
	global_load_lds_dwordx4 v156, s[60:61]
	s_mov_b32 m0, s86
	s_nop 0
	global_load_lds_dwordx4 v158, s[60:61]
	s_mov_b32 m0, s72
	s_nop 0
	global_load_lds_dwordx4 v153, s[58:59]
	s_mov_b32 m0, s73
	s_nop 0
	global_load_lds_dwordx4 v157, s[58:59]
	s_waitcnt vmcnt(8)
	s_waitcnt lgkmcnt(0)
	s_barrier
	v_mfma_f32_16x16x32_bf16 v[12:15], v[4:7], v[32:35], v[166:169]
	v_mfma_f32_16x16x32_bf16 v[64:67], v[8:11], v[36:39], v[12:15]
	v_mfma_f32_16x16x32_bf16 v[12:15], v[218:221], v[32:35], v[170:173]
	v_mfma_f32_16x16x32_bf16 v[56:59], v[222:225], v[36:39], v[12:15]
	v_mfma_f32_16x16x32_bf16 v[12:15], v[4:7], v[128:131], v[174:177]
	v_mfma_f32_16x16x32_bf16 v[44:47], v[8:11], v[132:135], v[12:15]
	v_mfma_f32_16x16x32_bf16 v[12:15], v[218:221], v[128:131], v[178:181]
	v_mfma_f32_16x16x32_bf16 v[40:43], v[222:225], v[132:135], v[12:15]
	v_mfma_f32_16x16x32_bf16 v[12:15], v[4:7], v[136:139], v[182:185]
	v_mfma_f32_16x16x32_bf16 v[28:31], v[8:11], v[140:143], v[12:15]
	v_mfma_f32_16x16x32_bf16 v[12:15], v[218:221], v[136:139], v[186:189]
	v_mfma_f32_16x16x32_bf16 v[4:7], v[4:7], v[242:245], v[16:19]
	v_mfma_f32_16x16x32_bf16 v[24:27], v[222:225], v[140:143], v[12:15]
	v_mfma_f32_16x16x32_bf16 v[12:15], v[8:11], v[246:249], v[4:7]
	v_mfma_f32_16x16x32_bf16 v[4:7], v[218:221], v[242:245], v[20:23]
	v_mfma_f32_16x16x32_bf16 v[8:11], v[222:225], v[246:249], v[4:7]
	v_mfma_f32_16x16x32_bf16 v[4:7], v[226:229], v[32:35], v[190:193]
	v_mfma_f32_16x16x32_bf16 v[52:55], v[230:233], v[36:39], v[4:7]
	v_mfma_f32_16x16x32_bf16 v[4:7], v[234:237], v[32:35], v[194:197]
	v_mfma_f32_16x16x32_bf16 v[48:51], v[238:241], v[36:39], v[4:7]
	v_mfma_f32_16x16x32_bf16 v[4:7], v[226:229], v[128:131], v[198:201]
	v_mfma_f32_16x16x32_bf16 v[36:39], v[230:233], v[132:135], v[4:7]
	v_mfma_f32_16x16x32_bf16 v[4:7], v[234:237], v[128:131], v[202:205]
	v_mfma_f32_16x16x32_bf16 v[32:35], v[238:241], v[132:135], v[4:7]
	v_mfma_f32_16x16x32_bf16 v[4:7], v[226:229], v[136:139], v[206:209]
	v_mfma_f32_16x16x32_bf16 v[20:23], v[230:233], v[140:143], v[4:7]
	v_mfma_f32_16x16x32_bf16 v[4:7], v[234:237], v[136:139], v[210:213]
	v_mfma_f32_16x16x32_bf16 v[0:3], v[226:229], v[242:245], v[0:3]
	v_mfma_f32_16x16x32_bf16 v[16:19], v[238:241], v[140:143], v[4:7]
	v_mfma_f32_16x16x32_bf16 v[4:7], v[230:233], v[246:249], v[0:3]
	v_mfma_f32_16x16x32_bf16 v[0:3], v[234:237], v[242:245], v[214:217]
	v_mfma_f32_16x16x32_bf16 v[0:3], v[238:241], v[246:249], v[0:3]
	s_barrier
	s_add_u32 s62, s56, 0x100
	s_addc_u32 s63, s57, 0
	s_add_u32 s91, s54, 0x200
	s_addc_u32 s92, s55, 0
	s_mov_b32 s93, 0
.LBB0_2365:
	s_add_u32 s54, s62, 0x100
	s_addc_u32 s55, s63, 0
	s_cmp_eq_u32 s93, 28
	s_cselect_b32 s60, s51, s54
	s_cselect_b32 s61, s43, s55
	s_cselect_b32 s58, s21, s91
	s_cselect_b32 s59, s20, s92
	s_add_u32 s56, s60, 0x80
	s_addc_u32 s57, s61, 0
	s_add_i32 s94, 0, 0x10000
	s_add_i32 s95, 0, 0x14000
	v_add_u32_e32 v140, s94, v159
	v_add_u32_e32 v149, s95, v159
	ds_read_b128 v[128:131], v140
	ds_read_b128 v[132:135], v140 offset:1024
	ds_read_b128 v[136:139], v140 offset:2048
	ds_read_b128 v[140:143], v140 offset:3072
	ds_read_b128 v[166:169], v149
	ds_read_b128 v[170:173], v149 offset:1024
	ds_read_b128 v[174:177], v149 offset:2048
	ds_read_b128 v[178:181], v149 offset:3072
	s_add_u32 s62, s62, 0x80080
	s_addc_u32 s63, s63, 0
	s_mov_b32 m0, s1
	ds_read_b128 v[182:185], v162
	ds_read_b128 v[186:189], v162 offset:1024
	ds_read_b128 v[190:193], v162 offset:2048
	ds_read_b128 v[194:197], v162 offset:3072
	ds_read_b128 v[198:201], v162 offset:4096
	ds_read_b128 v[202:205], v162 offset:5120
	ds_read_b128 v[206:209], v162 offset:6144
	ds_read_b128 v[210:213], v162 offset:7168
	global_load_lds_dwordx4 v153, s[62:63]
	s_mov_b32 m0, s12
	s_nop 0
	global_load_lds_dwordx4 v157, s[62:63]
	s_waitcnt vmcnt(8)
	s_waitcnt lgkmcnt(0)
	s_barrier
	v_mfma_f32_16x16x32_bf16 v[124:127], v[128:131], v[182:185], v[124:127]
	v_mfma_f32_16x16x32_bf16 v[120:123], v[136:139], v[182:185], v[120:123]
	v_mfma_f32_16x16x32_bf16 v[108:111], v[128:131], v[190:193], v[108:111]
	v_mfma_f32_16x16x32_bf16 v[104:107], v[136:139], v[190:193], v[104:107]
	v_mfma_f32_16x16x32_bf16 v[92:95], v[128:131], v[198:201], v[92:95]
	v_mfma_f32_16x16x32_bf16 v[88:91], v[136:139], v[198:201], v[88:91]
	v_mfma_f32_16x16x32_bf16 v[76:79], v[128:131], v[206:209], v[76:79]
	v_mfma_f32_16x16x32_bf16 v[72:75], v[136:139], v[206:209], v[72:75]
	v_mfma_f32_16x16x32_bf16 v[124:127], v[132:135], v[186:189], v[124:127]
	v_mfma_f32_16x16x32_bf16 v[120:123], v[140:143], v[186:189], v[120:123]
	v_mfma_f32_16x16x32_bf16 v[108:111], v[132:135], v[194:197], v[108:111]
	v_mfma_f32_16x16x32_bf16 v[104:107], v[140:143], v[194:197], v[104:107]
	v_mfma_f32_16x16x32_bf16 v[92:95], v[132:135], v[202:205], v[92:95]
	v_mfma_f32_16x16x32_bf16 v[88:91], v[140:143], v[202:205], v[88:91]
	v_mfma_f32_16x16x32_bf16 v[76:79], v[132:135], v[210:213], v[76:79]
	v_mfma_f32_16x16x32_bf16 v[72:75], v[140:143], v[210:213], v[72:75]
	v_mfma_f32_16x16x32_bf16 v[116:119], v[166:169], v[182:185], v[116:119]
	v_mfma_f32_16x16x32_bf16 v[112:115], v[174:177], v[182:185], v[112:115]
	v_mfma_f32_16x16x32_bf16 v[100:103], v[166:169], v[190:193], v[100:103]
	v_mfma_f32_16x16x32_bf16 v[96:99], v[174:177], v[190:193], v[96:99]
	v_mfma_f32_16x16x32_bf16 v[84:87], v[166:169], v[198:201], v[84:87]
	v_mfma_f32_16x16x32_bf16 v[80:83], v[174:177], v[198:201], v[80:83]
	v_mfma_f32_16x16x32_bf16 v[68:71], v[166:169], v[206:209], v[68:71]
	v_mfma_f32_16x16x32_bf16 v[60:63], v[174:177], v[206:209], v[60:63]
	v_mfma_f32_16x16x32_bf16 v[116:119], v[170:173], v[186:189], v[116:119]
	v_mfma_f32_16x16x32_bf16 v[112:115], v[178:181], v[186:189], v[112:115]
	v_mfma_f32_16x16x32_bf16 v[100:103], v[170:173], v[194:197], v[100:103]
	v_mfma_f32_16x16x32_bf16 v[96:99], v[178:181], v[194:197], v[96:99]
	v_mfma_f32_16x16x32_bf16 v[84:87], v[170:173], v[202:205], v[84:87]
	v_mfma_f32_16x16x32_bf16 v[80:83], v[178:181], v[202:205], v[80:83]
	v_mfma_f32_16x16x32_bf16 v[68:71], v[170:173], v[210:213], v[68:71]
	v_mfma_f32_16x16x32_bf16 v[60:63], v[178:181], v[210:213], v[60:63]
	s_barrier
	s_add_i32 s62, s94, s26
	s_mov_b32 m0, s62
	ds_read_b128 v[182:185], v162 offset:16384
	ds_read_b128 v[186:189], v162 offset:17408
	ds_read_b128 v[190:193], v162 offset:18432
	ds_read_b128 v[194:197], v162 offset:19456
	ds_read_b128 v[198:201], v162 offset:20480
	ds_read_b128 v[202:205], v162 offset:21504
	ds_read_b128 v[206:209], v162 offset:22528
	ds_read_b128 v[210:213], v162 offset:23552
	global_load_lds_dwordx4 v156, s[58:59]
	s_add_i32 m0, s62, 0x2000
	s_add_u32 s62, s58, 0x80000
	s_addc_u32 s63, s59, 0
	s_add_i32 s94, s95, s26
	s_nop 0
	global_load_lds_dwordx4 v158, s[58:59]
	s_mov_b32 m0, s94
	s_nop 0
	global_load_lds_dwordx4 v156, s[62:63]
	s_add_i32 m0, s94, 0x2000
	s_nop 0
	global_load_lds_dwordx4 v158, s[62:63]
	s_mov_b32 m0, s27
	s_nop 0
	global_load_lds_dwordx4 v153, s[60:61]
	s_mov_b32 m0, s69
	s_nop 0
	global_load_lds_dwordx4 v157, s[60:61]
	s_waitcnt vmcnt(8)
	s_waitcnt lgkmcnt(0)
	s_barrier
	v_mfma_f32_16x16x32_bf16 v[64:67], v[128:131], v[182:185], v[64:67]
	v_mfma_f32_16x16x32_bf16 v[56:59], v[136:139], v[182:185], v[56:59]
	v_mfma_f32_16x16x32_bf16 v[44:47], v[128:131], v[190:193], v[44:47]
	v_mfma_f32_16x16x32_bf16 v[40:43], v[136:139], v[190:193], v[40:43]
	v_mfma_f32_16x16x32_bf16 v[28:31], v[128:131], v[198:201], v[28:31]
	v_mfma_f32_16x16x32_bf16 v[24:27], v[136:139], v[198:201], v[24:27]
	v_mfma_f32_16x16x32_bf16 v[12:15], v[128:131], v[206:209], v[12:15]
	v_mfma_f32_16x16x32_bf16 v[8:11], v[136:139], v[206:209], v[8:11]
	v_mfma_f32_16x16x32_bf16 v[64:67], v[132:135], v[186:189], v[64:67]
	v_mfma_f32_16x16x32_bf16 v[56:59], v[140:143], v[186:189], v[56:59]
	v_mfma_f32_16x16x32_bf16 v[44:47], v[132:135], v[194:197], v[44:47]
	v_mfma_f32_16x16x32_bf16 v[40:43], v[140:143], v[194:197], v[40:43]
	v_mfma_f32_16x16x32_bf16 v[28:31], v[132:135], v[202:205], v[28:31]
	v_mfma_f32_16x16x32_bf16 v[24:27], v[140:143], v[202:205], v[24:27]
	v_mfma_f32_16x16x32_bf16 v[12:15], v[132:135], v[210:213], v[12:15]
	v_mfma_f32_16x16x32_bf16 v[8:11], v[140:143], v[210:213], v[8:11]
	v_mfma_f32_16x16x32_bf16 v[52:55], v[166:169], v[182:185], v[52:55]
	v_mfma_f32_16x16x32_bf16 v[48:51], v[174:177], v[182:185], v[48:51]
	v_mfma_f32_16x16x32_bf16 v[36:39], v[166:169], v[190:193], v[36:39]
	v_mfma_f32_16x16x32_bf16 v[32:35], v[174:177], v[190:193], v[32:35]
	v_mfma_f32_16x16x32_bf16 v[20:23], v[166:169], v[198:201], v[20:23]
	v_mfma_f32_16x16x32_bf16 v[16:19], v[174:177], v[198:201], v[16:19]
	v_mfma_f32_16x16x32_bf16 v[4:7], v[166:169], v[206:209], v[4:7]
	v_mfma_f32_16x16x32_bf16 v[0:3], v[174:177], v[206:209], v[0:3]
	v_mfma_f32_16x16x32_bf16 v[52:55], v[170:173], v[186:189], v[52:55]
	v_mfma_f32_16x16x32_bf16 v[48:51], v[178:181], v[186:189], v[48:51]
	v_mfma_f32_16x16x32_bf16 v[36:39], v[170:173], v[194:197], v[36:39]
	v_mfma_f32_16x16x32_bf16 v[32:35], v[178:181], v[194:197], v[32:35]
	v_mfma_f32_16x16x32_bf16 v[20:23], v[170:173], v[202:205], v[20:23]
	v_mfma_f32_16x16x32_bf16 v[16:19], v[178:181], v[202:205], v[16:19]
	v_mfma_f32_16x16x32_bf16 v[4:7], v[170:173], v[210:213], v[4:7]
	v_mfma_f32_16x16x32_bf16 v[0:3], v[178:181], v[210:213], v[0:3]
	s_barrier
	ds_read_b128 v[128:131], v144
	ds_read_b128 v[132:135], v144 offset:1024
	ds_read_b128 v[136:139], v144 offset:2048
	ds_read_b128 v[140:143], v144 offset:3072
	ds_read_b128 v[166:169], v148
	ds_read_b128 v[170:173], v148 offset:1024
	ds_read_b128 v[174:177], v148 offset:2048
	ds_read_b128 v[178:181], v148 offset:3072
	s_add_u32 s60, s60, 0x80000
	s_addc_u32 s61, s61, 0
	s_mov_b32 m0, s70
	ds_read_b128 v[182:185], v162 offset:32768
	ds_read_b128 v[186:189], v162 offset:33792
	ds_read_b128 v[190:193], v162 offset:34816
	ds_read_b128 v[194:197], v162 offset:35840
	ds_read_b128 v[198:201], v162 offset:36864
	ds_read_b128 v[202:205], v162 offset:37888
	ds_read_b128 v[206:209], v162 offset:38912
	ds_read_b128 v[210:213], v162 offset:39936
	global_load_lds_dwordx4 v153, s[60:61]
	s_mov_b32 m0, s71
	s_nop 0
	global_load_lds_dwordx4 v157, s[60:61]
	s_waitcnt vmcnt(8)
	s_waitcnt lgkmcnt(0)
	s_barrier
	v_mfma_f32_16x16x32_bf16 v[124:127], v[128:131], v[182:185], v[124:127]
	v_mfma_f32_16x16x32_bf16 v[120:123], v[136:139], v[182:185], v[120:123]
	v_mfma_f32_16x16x32_bf16 v[108:111], v[128:131], v[190:193], v[108:111]
	v_mfma_f32_16x16x32_bf16 v[104:107], v[136:139], v[190:193], v[104:107]
	v_mfma_f32_16x16x32_bf16 v[92:95], v[128:131], v[198:201], v[92:95]
	v_mfma_f32_16x16x32_bf16 v[88:91], v[136:139], v[198:201], v[88:91]
	v_mfma_f32_16x16x32_bf16 v[76:79], v[128:131], v[206:209], v[76:79]
	v_mfma_f32_16x16x32_bf16 v[72:75], v[136:139], v[206:209], v[72:75]
	v_mfma_f32_16x16x32_bf16 v[124:127], v[132:135], v[186:189], v[124:127]
	v_mfma_f32_16x16x32_bf16 v[120:123], v[140:143], v[186:189], v[120:123]
	v_mfma_f32_16x16x32_bf16 v[108:111], v[132:135], v[194:197], v[108:111]
	v_mfma_f32_16x16x32_bf16 v[104:107], v[140:143], v[194:197], v[104:107]
	v_mfma_f32_16x16x32_bf16 v[92:95], v[132:135], v[202:205], v[92:95]
	v_mfma_f32_16x16x32_bf16 v[88:91], v[140:143], v[202:205], v[88:91]
	v_mfma_f32_16x16x32_bf16 v[76:79], v[132:135], v[210:213], v[76:79]
	v_mfma_f32_16x16x32_bf16 v[72:75], v[140:143], v[210:213], v[72:75]
	v_mfma_f32_16x16x32_bf16 v[116:119], v[166:169], v[182:185], v[116:119]
	v_mfma_f32_16x16x32_bf16 v[112:115], v[174:177], v[182:185], v[112:115]
	v_mfma_f32_16x16x32_bf16 v[100:103], v[166:169], v[190:193], v[100:103]
	v_mfma_f32_16x16x32_bf16 v[96:99], v[174:177], v[190:193], v[96:99]
	v_mfma_f32_16x16x32_bf16 v[84:87], v[166:169], v[198:201], v[84:87]
	v_mfma_f32_16x16x32_bf16 v[80:83], v[174:177], v[198:201], v[80:83]
	v_mfma_f32_16x16x32_bf16 v[68:71], v[166:169], v[206:209], v[68:71]
	v_mfma_f32_16x16x32_bf16 v[60:63], v[174:177], v[206:209], v[60:63]
	v_mfma_f32_16x16x32_bf16 v[116:119], v[170:173], v[186:189], v[116:119]
	v_mfma_f32_16x16x32_bf16 v[112:115], v[178:181], v[186:189], v[112:115]
	v_mfma_f32_16x16x32_bf16 v[100:103], v[170:173], v[194:197], v[100:103]
	v_mfma_f32_16x16x32_bf16 v[96:99], v[178:181], v[194:197], v[96:99]
	v_mfma_f32_16x16x32_bf16 v[84:87], v[170:173], v[202:205], v[84:87]
	v_mfma_f32_16x16x32_bf16 v[80:83], v[178:181], v[202:205], v[80:83]
	v_mfma_f32_16x16x32_bf16 v[68:71], v[170:173], v[210:213], v[68:71]
	v_mfma_f32_16x16x32_bf16 v[60:63], v[178:181], v[210:213], v[60:63]
	s_barrier
	s_add_u32 s60, s58, 0x80
	s_mov_b32 m0, s53
	s_addc_u32 s61, s59, 0
	ds_read_b128 v[182:185], v162 offset:49152
	ds_read_b128 v[186:189], v162 offset:50176
	ds_read_b128 v[190:193], v162 offset:51200
	ds_read_b128 v[194:197], v162 offset:52224
	ds_read_b128 v[198:201], v162 offset:53248
	ds_read_b128 v[202:205], v162 offset:54272
	ds_read_b128 v[206:209], v162 offset:55296
	ds_read_b128 v[210:213], v162 offset:56320
	s_add_u32 s58, s58, 0x80080
	global_load_lds_dwordx4 v156, s[60:61]
	s_mov_b32 m0, s79
	s_addc_u32 s59, s59, 0
	global_load_lds_dwordx4 v158, s[60:61]
	s_mov_b32 m0, s80
	s_nop 0
	global_load_lds_dwordx4 v156, s[58:59]
	s_mov_b32 m0, s86
	s_nop 0
	global_load_lds_dwordx4 v158, s[58:59]
	s_mov_b32 m0, s72
	s_nop 0
	global_load_lds_dwordx4 v153, s[56:57]
	s_mov_b32 m0, s73
	s_nop 0
	global_load_lds_dwordx4 v157, s[56:57]
	s_waitcnt vmcnt(8)
	s_waitcnt lgkmcnt(0)
	s_barrier
	v_mfma_f32_16x16x32_bf16 v[64:67], v[128:131], v[182:185], v[64:67]
	v_mfma_f32_16x16x32_bf16 v[56:59], v[136:139], v[182:185], v[56:59]
	v_mfma_f32_16x16x32_bf16 v[44:47], v[128:131], v[190:193], v[44:47]
	v_mfma_f32_16x16x32_bf16 v[40:43], v[136:139], v[190:193], v[40:43]
	v_mfma_f32_16x16x32_bf16 v[28:31], v[128:131], v[198:201], v[28:31]
	v_mfma_f32_16x16x32_bf16 v[24:27], v[136:139], v[198:201], v[24:27]
	v_mfma_f32_16x16x32_bf16 v[12:15], v[128:131], v[206:209], v[12:15]
	v_mfma_f32_16x16x32_bf16 v[8:11], v[136:139], v[206:209], v[8:11]
	v_mfma_f32_16x16x32_bf16 v[64:67], v[132:135], v[186:189], v[64:67]
	v_mfma_f32_16x16x32_bf16 v[56:59], v[140:143], v[186:189], v[56:59]
	v_mfma_f32_16x16x32_bf16 v[44:47], v[132:135], v[194:197], v[44:47]
	v_mfma_f32_16x16x32_bf16 v[40:43], v[140:143], v[194:197], v[40:43]
	v_mfma_f32_16x16x32_bf16 v[28:31], v[132:135], v[202:205], v[28:31]
	v_mfma_f32_16x16x32_bf16 v[24:27], v[140:143], v[202:205], v[24:27]
	v_mfma_f32_16x16x32_bf16 v[12:15], v[132:135], v[210:213], v[12:15]
	v_mfma_f32_16x16x32_bf16 v[8:11], v[140:143], v[210:213], v[8:11]
	v_mfma_f32_16x16x32_bf16 v[52:55], v[166:169], v[182:185], v[52:55]
	v_mfma_f32_16x16x32_bf16 v[48:51], v[174:177], v[182:185], v[48:51]
	v_mfma_f32_16x16x32_bf16 v[36:39], v[166:169], v[190:193], v[36:39]
	v_mfma_f32_16x16x32_bf16 v[32:35], v[174:177], v[190:193], v[32:35]
	v_mfma_f32_16x16x32_bf16 v[20:23], v[166:169], v[198:201], v[20:23]
	v_mfma_f32_16x16x32_bf16 v[16:19], v[174:177], v[198:201], v[16:19]
	v_mfma_f32_16x16x32_bf16 v[4:7], v[166:169], v[206:209], v[4:7]
	v_mfma_f32_16x16x32_bf16 v[0:3], v[174:177], v[206:209], v[0:3]
	v_mfma_f32_16x16x32_bf16 v[52:55], v[170:173], v[186:189], v[52:55]
	v_mfma_f32_16x16x32_bf16 v[48:51], v[178:181], v[186:189], v[48:51]
	v_mfma_f32_16x16x32_bf16 v[36:39], v[170:173], v[194:197], v[36:39]
	v_mfma_f32_16x16x32_bf16 v[32:35], v[178:181], v[194:197], v[32:35]
	v_mfma_f32_16x16x32_bf16 v[20:23], v[170:173], v[202:205], v[20:23]
	v_mfma_f32_16x16x32_bf16 v[16:19], v[178:181], v[202:205], v[16:19]
	v_mfma_f32_16x16x32_bf16 v[4:7], v[170:173], v[210:213], v[4:7]
	v_mfma_f32_16x16x32_bf16 v[0:3], v[178:181], v[210:213], v[0:3]
	s_barrier
	s_add_i32 s93, s93, 2
	s_add_u32 s91, s91, 0x100
	s_addc_u32 s92, s92, 0
	s_cmp_gt_u32 s93, 29
	s_mov_b64 s[62:63], s[54:55]
	s_cbranch_scc0 .LBB0_2365
	s_and_b64 vcc, exec, s[4:5]
	s_cbranch_vccz .LBB0_2368
	s_barrier

.LBB0_2480:
	s_ashr_i32 s47, s46, 31
	s_lshl_b64 s[20:21], s[46:47], 18
	s_add_u32 s50, s24, s20
	s_addc_u32 s51, s25, s21
	s_add_u32 s60, s56, 0x180
	s_addc_u32 s61, s57, 0
	s_waitcnt lgkmcnt(0)
	s_and_b64 s[20:21], s[58:59], exec
	s_cselect_b32 s5, s51, s55
	s_cselect_b32 s12, s50, s54
	s_add_u32 s58, s54, 0x180
	s_addc_u32 s59, s55, 0
	s_barrier
	s_waitcnt lgkmcnt(0)
	v_mfma_f32_16x16x32_bf16 v[128:131], v[16:19], v[120:123], 0
	v_mfma_f32_16x16x32_bf16 v[132:135], v[20:23], v[124:127], v[128:131]
	v_mfma_f32_16x16x32_bf16 v[128:131], v[24:27], v[120:123], 0
	v_mfma_f32_16x16x32_bf16 v[144:147], v[28:31], v[124:127], v[128:131]
	v_mfma_f32_16x16x32_bf16 v[128:131], v[16:19], v[112:115], 0
	v_mfma_f32_16x16x32_bf16 v[152:155], v[20:23], v[116:119], v[128:131]
	v_mfma_f32_16x16x32_bf16 v[128:131], v[24:27], v[112:115], 0
	v_mfma_f32_16x16x32_bf16 v[168:171], v[28:31], v[116:119], v[128:131]
	v_mfma_f32_16x16x32_bf16 v[128:131], v[16:19], v[96:99], 0
	v_mfma_f32_16x16x32_bf16 v[16:19], v[16:19], v[88:91], 0
	v_mfma_f32_16x16x32_bf16 v[172:175], v[20:23], v[108:111], v[128:131]
	v_mfma_f32_16x16x32_bf16 v[16:19], v[20:23], v[92:95], v[16:19]
	v_mfma_f32_16x16x32_bf16 v[20:23], v[24:27], v[88:91], 0
	v_mfma_f32_16x16x32_bf16 v[128:131], v[24:27], v[96:99], 0
	v_mfma_f32_16x16x32_bf16 v[20:23], v[28:31], v[92:95], v[20:23]
	v_mfma_f32_16x16x32_bf16 v[176:179], v[28:31], v[108:111], v[128:131]
	v_mfma_f32_16x16x32_bf16 v[24:27], v[0:3], v[120:123], 0
	v_mfma_f32_16x16x32_bf16 v[180:183], v[4:7], v[124:127], v[24:27]
	v_mfma_f32_16x16x32_bf16 v[24:27], v[8:11], v[120:123], 0
	v_mfma_f32_16x16x32_bf16 v[188:191], v[12:15], v[124:127], v[24:27]
	v_mfma_f32_16x16x32_bf16 v[24:27], v[0:3], v[112:115], 0
	v_mfma_f32_16x16x32_bf16 v[192:195], v[4:7], v[116:119], v[24:27]
	v_mfma_f32_16x16x32_bf16 v[24:27], v[8:11], v[112:115], 0
	v_mfma_f32_16x16x32_bf16 v[208:211], v[12:15], v[116:119], v[24:27]
	v_mfma_f32_16x16x32_bf16 v[24:27], v[0:3], v[96:99], 0
	v_mfma_f32_16x16x32_bf16 v[0:3], v[0:3], v[88:91], 0
	v_mfma_f32_16x16x32_bf16 v[212:215], v[4:7], v[108:111], v[24:27]
	v_mfma_f32_16x16x32_bf16 v[24:27], v[8:11], v[96:99], 0
	v_mfma_f32_16x16x32_bf16 v[0:3], v[4:7], v[92:95], v[0:3]
	v_mfma_f32_16x16x32_bf16 v[4:7], v[8:11], v[88:91], 0
	v_mfma_f32_16x16x32_bf16 v[216:219], v[12:15], v[108:111], v[24:27]
	v_mfma_f32_16x16x32_bf16 v[220:223], v[12:15], v[92:95], v[4:7]
	s_barrier
	v_add_u32_e32 v124, s78, v203
	v_add_u32_e32 v125, s83, v203
	s_nop 1
	ds_read_b128 v[4:7], v124
	ds_read_b128 v[8:11], v124 offset:1024
	ds_read_b128 v[224:227], v124 offset:2048
	ds_read_b128 v[228:231], v124 offset:3072
	ds_read_b128 v[232:235], v125
	ds_read_b128 v[236:239], v125 offset:1024
	ds_read_b128 v[240:243], v125 offset:2048
	ds_read_b128 v[244:247], v125 offset:3072
	s_add_u32 s20, s56, 0x70100
	s_addc_u32 s21, s57, 0
	s_mov_b32 m0, s70
	ds_read_b128 v[12:15], v206 offset:32768
	ds_read_b128 v[24:27], v206 offset:33792
	ds_read_b128 v[28:31], v206 offset:34816
	ds_read_b128 v[96:99], v206 offset:35840
	ds_read_b128 v[248:251], v206 offset:36864
	ds_read_b128 v[184:187], v206 offset:37888
	ds_read_b128 v[32:35], v206 offset:38912
	ds_read_b128 v[36:39], v206 offset:39936
	global_load_lds_dwordx4 v199, s[20:21]
	s_mov_b32 m0, s71
	s_nop 0
	global_load_lds_dwordx4 v201, s[20:21]
	s_waitcnt vmcnt(8)
	s_waitcnt lgkmcnt(0)
	s_barrier
	v_mfma_f32_16x16x32_bf16 v[88:91], v[4:7], v[12:15], v[136:139]
	v_mfma_f32_16x16x32_bf16 v[40:43], v[4:7], v[28:31], v[40:43]
	v_mfma_f32_16x16x32_bf16 v[164:167], v[8:11], v[24:27], v[88:91]
	v_mfma_f32_16x16x32_bf16 v[88:91], v[224:227], v[12:15], v[140:143]
	v_mfma_f32_16x16x32_bf16 v[140:143], v[8:11], v[96:99], v[40:43]
	v_mfma_f32_16x16x32_bf16 v[40:43], v[224:227], v[28:31], v[44:47]
	v_mfma_f32_16x16x32_bf16 v[136:139], v[228:231], v[96:99], v[40:43]
	v_mfma_f32_16x16x32_bf16 v[40:43], v[4:7], v[248:251], v[48:51]
	v_mfma_f32_16x16x32_bf16 v[116:119], v[8:11], v[184:187], v[40:43]
	v_mfma_f32_16x16x32_bf16 v[40:43], v[224:227], v[248:251], v[52:55]
	v_mfma_f32_16x16x32_bf16 v[112:115], v[228:231], v[184:187], v[40:43]
	v_mfma_f32_16x16x32_bf16 v[40:43], v[4:7], v[32:35], v[56:59]
	v_mfma_f32_16x16x32_bf16 v[92:95], v[8:11], v[36:39], v[40:43]
	v_mfma_f32_16x16x32_bf16 v[40:43], v[224:227], v[32:35], v[60:63]
	v_mfma_f32_16x16x32_bf16 v[160:163], v[228:231], v[24:27], v[88:91]
	v_mfma_f32_16x16x32_bf16 v[88:91], v[228:231], v[36:39], v[40:43]
	v_mfma_f32_16x16x32_bf16 v[40:43], v[232:235], v[12:15], v[64:67]
	v_mfma_f32_16x16x32_bf16 v[12:15], v[240:243], v[12:15], v[68:71]
	v_mfma_f32_16x16x32_bf16 v[148:151], v[244:247], v[24:27], v[12:15]
	v_mfma_f32_16x16x32_bf16 v[12:15], v[232:235], v[28:31], v[72:75]
	v_mfma_f32_16x16x32_bf16 v[128:131], v[236:239], v[96:99], v[12:15]
	v_mfma_f32_16x16x32_bf16 v[12:15], v[240:243], v[28:31], v[76:79]
	v_mfma_f32_16x16x32_bf16 v[120:123], v[244:247], v[96:99], v[12:15]
	v_mfma_f32_16x16x32_bf16 v[12:15], v[232:235], v[248:251], v[80:83]
	v_mfma_f32_16x16x32_bf16 v[108:111], v[236:239], v[184:187], v[12:15]
	v_mfma_f32_16x16x32_bf16 v[12:15], v[240:243], v[248:251], v[84:87]
	v_mfma_f32_16x16x32_bf16 v[96:99], v[244:247], v[184:187], v[12:15]
	v_mfma_f32_16x16x32_bf16 v[12:15], v[232:235], v[32:35], v[100:103]
	v_mfma_f32_16x16x32_bf16 v[84:87], v[236:239], v[36:39], v[12:15]
	v_mfma_f32_16x16x32_bf16 v[12:15], v[240:243], v[32:35], v[104:107]
	v_mfma_f32_16x16x32_bf16 v[156:159], v[236:239], v[24:27], v[40:43]
	v_mfma_f32_16x16x32_bf16 v[72:75], v[244:247], v[36:39], v[12:15]
	s_barrier
	s_add_i32 s20, s78, s26
	s_mov_b32 m0, s20
	s_add_i32 s21, s20, 0x2000
	ds_read_b128 v[32:35], v206 offset:49152
	ds_read_b128 v[36:39], v206 offset:50176
	ds_read_b128 v[48:51], v206 offset:51200
	ds_read_b128 v[52:55], v206 offset:52224
	ds_read_b128 v[76:79], v206 offset:53248
	ds_read_b128 v[80:83], v206 offset:54272
	ds_read_b128 v[100:103], v206 offset:55296
	ds_read_b128 v[104:107], v206 offset:56320
	global_load_lds_dwordx4 v200, s[58:59]
	s_mov_b32 m0, s21
	s_nop 0
	global_load_lds_dwordx4 v202, s[58:59]
	s_add_u32 s58, s54, 0x20180
	s_addc_u32 s59, s55, 0
	s_add_i32 s45, s83, s26
	s_mov_b32 m0, s45
	s_add_i32 s47, s45, 0x2000
	s_nop 0
	global_load_lds_dwordx4 v200, s[58:59]
	s_mov_b32 m0, s47
	s_nop 0
	global_load_lds_dwordx4 v202, s[58:59]
	s_mov_b32 m0, s72
	s_nop 0
	global_load_lds_dwordx4 v199, s[60:61]
	s_mov_b32 m0, s73
	s_nop 0
	global_load_lds_dwordx4 v201, s[60:61]
	s_waitcnt vmcnt(8)
	s_waitcnt lgkmcnt(0)
	s_barrier
	v_mfma_f32_16x16x32_bf16 v[12:15], v[4:7], v[32:35], v[132:135]
	v_mfma_f32_16x16x32_bf16 v[68:71], v[8:11], v[36:39], v[12:15]
	v_mfma_f32_16x16x32_bf16 v[12:15], v[224:227], v[32:35], v[144:147]
	v_mfma_f32_16x16x32_bf16 v[64:67], v[228:231], v[36:39], v[12:15]
	v_mfma_f32_16x16x32_bf16 v[12:15], v[4:7], v[48:51], v[152:155]
	v_mfma_f32_16x16x32_bf16 v[44:47], v[8:11], v[52:55], v[12:15]
	v_mfma_f32_16x16x32_bf16 v[12:15], v[224:227], v[48:51], v[168:171]
	v_mfma_f32_16x16x32_bf16 v[40:43], v[228:231], v[52:55], v[12:15]
	v_mfma_f32_16x16x32_bf16 v[12:15], v[4:7], v[76:79], v[172:175]
	v_mfma_f32_16x16x32_bf16 v[28:31], v[8:11], v[80:83], v[12:15]
	v_mfma_f32_16x16x32_bf16 v[12:15], v[224:227], v[76:79], v[176:179]
	v_mfma_f32_16x16x32_bf16 v[4:7], v[4:7], v[100:103], v[16:19]
	v_mfma_f32_16x16x32_bf16 v[24:27], v[228:231], v[80:83], v[12:15]
	v_mfma_f32_16x16x32_bf16 v[12:15], v[8:11], v[104:107], v[4:7]
	v_mfma_f32_16x16x32_bf16 v[4:7], v[224:227], v[100:103], v[20:23]
	v_mfma_f32_16x16x32_bf16 v[8:11], v[228:231], v[104:107], v[4:7]
	v_mfma_f32_16x16x32_bf16 v[4:7], v[232:235], v[32:35], v[180:183]
	v_mfma_f32_16x16x32_bf16 v[60:63], v[236:239], v[36:39], v[4:7]
	v_mfma_f32_16x16x32_bf16 v[4:7], v[240:243], v[32:35], v[188:191]
	v_mfma_f32_16x16x32_bf16 v[56:59], v[244:247], v[36:39], v[4:7]
	v_mfma_f32_16x16x32_bf16 v[4:7], v[232:235], v[48:51], v[192:195]
	v_mfma_f32_16x16x32_bf16 v[36:39], v[236:239], v[52:55], v[4:7]
	v_mfma_f32_16x16x32_bf16 v[4:7], v[240:243], v[48:51], v[208:211]
	v_mfma_f32_16x16x32_bf16 v[32:35], v[244:247], v[52:55], v[4:7]
	v_mfma_f32_16x16x32_bf16 v[4:7], v[232:235], v[76:79], v[212:215]
	v_mfma_f32_16x16x32_bf16 v[20:23], v[236:239], v[80:83], v[4:7]
	v_mfma_f32_16x16x32_bf16 v[4:7], v[240:243], v[76:79], v[216:219]
	v_mfma_f32_16x16x32_bf16 v[0:3], v[232:235], v[100:103], v[0:3]
	v_mfma_f32_16x16x32_bf16 v[16:19], v[244:247], v[80:83], v[4:7]
	v_mfma_f32_16x16x32_bf16 v[4:7], v[236:239], v[104:107], v[0:3]
	v_mfma_f32_16x16x32_bf16 v[0:3], v[240:243], v[100:103], v[220:223]
	v_mfma_f32_16x16x32_bf16 v[0:3], v[244:247], v[104:107], v[0:3]
	s_barrier
	s_add_u32 s62, s56, 0x100
	s_addc_u32 s63, s57, 0
	s_add_u32 s53, s54, 0x200
	s_addc_u32 s79, s55, 0
	s_mov_b32 s80, 0
.LBB0_2481:
	s_add_u32 s54, s62, 0x100
	s_addc_u32 s55, s63, 0
	s_cmp_eq_u32 s80, 4
	s_cselect_b32 s60, s48, s54
	s_cselect_b32 s61, s49, s55
	s_cselect_b32 s58, s12, s53
	s_cselect_b32 s59, s5, s79
	s_add_u32 s56, s60, 0x80
	s_addc_u32 s57, s61, 0
	s_add_i32 s90, 0, 0x10000
	s_add_i32 s91, 0, 0x14000
	v_add_u32_e32 v80, s90, v203
	v_add_u32_e32 v126, s91, v203
	ds_read_b128 v[48:51], v80
	ds_read_b128 v[52:55], v80 offset:1024
	ds_read_b128 v[76:79], v80 offset:2048
	ds_read_b128 v[80:83], v80 offset:3072
	ds_read_b128 v[100:103], v126
	ds_read_b128 v[104:107], v126 offset:1024
	ds_read_b128 v[132:135], v126 offset:2048
	ds_read_b128 v[144:147], v126 offset:3072
	s_add_u32 s62, s62, 0x70080
	s_addc_u32 s63, s63, 0
	s_mov_b32 m0, s0
	ds_read_b128 v[152:155], v206
	ds_read_b128 v[168:171], v206 offset:1024
	ds_read_b128 v[172:175], v206 offset:2048
	ds_read_b128 v[176:179], v206 offset:3072
	ds_read_b128 v[180:183], v206 offset:4096
	ds_read_b128 v[184:187], v206 offset:5120
	ds_read_b128 v[188:191], v206 offset:6144
	ds_read_b128 v[192:195], v206 offset:7168
	global_load_lds_dwordx4 v199, s[62:63]
	s_mov_b32 m0, s1
	s_nop 0
	global_load_lds_dwordx4 v201, s[62:63]
	s_waitcnt vmcnt(8)
	s_waitcnt lgkmcnt(0)
	s_barrier
	v_mfma_f32_16x16x32_bf16 v[164:167], v[48:51], v[152:155], v[164:167]
	v_mfma_f32_16x16x32_bf16 v[160:163], v[76:79], v[152:155], v[160:163]
	v_mfma_f32_16x16x32_bf16 v[140:143], v[48:51], v[172:175], v[140:143]
	v_mfma_f32_16x16x32_bf16 v[136:139], v[76:79], v[172:175], v[136:139]
	v_mfma_f32_16x16x32_bf16 v[116:119], v[48:51], v[180:183], v[116:119]
	v_mfma_f32_16x16x32_bf16 v[112:115], v[76:79], v[180:183], v[112:115]
	v_mfma_f32_16x16x32_bf16 v[92:95], v[48:51], v[188:191], v[92:95]
	v_mfma_f32_16x16x32_bf16 v[88:91], v[76:79], v[188:191], v[88:91]
	v_mfma_f32_16x16x32_bf16 v[164:167], v[52:55], v[168:171], v[164:167]
	v_mfma_f32_16x16x32_bf16 v[160:163], v[80:83], v[168:171], v[160:163]
	v_mfma_f32_16x16x32_bf16 v[140:143], v[52:55], v[176:179], v[140:143]
	v_mfma_f32_16x16x32_bf16 v[136:139], v[80:83], v[176:179], v[136:139]
	v_mfma_f32_16x16x32_bf16 v[116:119], v[52:55], v[184:187], v[116:119]
	v_mfma_f32_16x16x32_bf16 v[112:115], v[80:83], v[184:187], v[112:115]
	v_mfma_f32_16x16x32_bf16 v[92:95], v[52:55], v[192:195], v[92:95]
	v_mfma_f32_16x16x32_bf16 v[88:91], v[80:83], v[192:195], v[88:91]
	v_mfma_f32_16x16x32_bf16 v[156:159], v[100:103], v[152:155], v[156:159]
	v_mfma_f32_16x16x32_bf16 v[148:151], v[132:135], v[152:155], v[148:151]
	v_mfma_f32_16x16x32_bf16 v[126:129], v[100:103], v[172:175], v[128:131]
	v_mfma_f32_16x16x32_bf16 v[120:123], v[132:135], v[172:175], v[120:123]
	v_mfma_f32_16x16x32_bf16 v[108:111], v[100:103], v[180:183], v[108:111]
	v_mfma_f32_16x16x32_bf16 v[96:99], v[132:135], v[180:183], v[96:99]
	v_mfma_f32_16x16x32_bf16 v[84:87], v[100:103], v[188:191], v[84:87]
	v_mfma_f32_16x16x32_bf16 v[72:75], v[132:135], v[188:191], v[72:75]
	v_mfma_f32_16x16x32_bf16 v[156:159], v[104:107], v[168:171], v[156:159]
	v_mfma_f32_16x16x32_bf16 v[148:151], v[144:147], v[168:171], v[148:151]
	v_mfma_f32_16x16x32_bf16 v[126:129], v[104:107], v[176:179], v[126:129]
	v_mfma_f32_16x16x32_bf16 v[120:123], v[144:147], v[176:179], v[120:123]
	v_mfma_f32_16x16x32_bf16 v[108:111], v[104:107], v[184:187], v[108:111]
	v_mfma_f32_16x16x32_bf16 v[96:99], v[144:147], v[184:187], v[96:99]
	v_mfma_f32_16x16x32_bf16 v[84:87], v[104:107], v[192:195], v[84:87]
	v_mfma_f32_16x16x32_bf16 v[72:75], v[144:147], v[192:195], v[72:75]
	s_barrier
	s_add_i32 s62, s90, s26
	s_mov_b32 m0, s62
	ds_read_b128 v[152:155], v206 offset:16384
	ds_read_b128 v[168:171], v206 offset:17408
	ds_read_b128 v[172:175], v206 offset:18432
	ds_read_b128 v[176:179], v206 offset:19456
	ds_read_b128 v[180:183], v206 offset:20480
	ds_read_b128 v[184:187], v206 offset:21504
	ds_read_b128 v[188:191], v206 offset:22528
	ds_read_b128 v[192:195], v206 offset:23552
	global_load_lds_dwordx4 v200, s[58:59]
	s_add_i32 m0, s62, 0x2000
	s_add_u32 s62, s58, 0x20000
	s_addc_u32 s63, s59, 0
	s_add_i32 s90, s91, s26
	s_nop 0
	global_load_lds_dwordx4 v202, s[58:59]
	s_mov_b32 m0, s90
	s_nop 0
	global_load_lds_dwordx4 v200, s[62:63]
	s_add_i32 m0, s90, 0x2000
	s_nop 0
	global_load_lds_dwordx4 v202, s[62:63]
	s_mov_b32 m0, s27
	s_nop 0
	global_load_lds_dwordx4 v199, s[60:61]
	s_mov_b32 m0, s69
	s_nop 0
	global_load_lds_dwordx4 v201, s[60:61]
	s_waitcnt vmcnt(8)
	s_waitcnt lgkmcnt(0)
	s_barrier
	v_mfma_f32_16x16x32_bf16 v[68:71], v[48:51], v[152:155], v[68:71]
	v_mfma_f32_16x16x32_bf16 v[64:67], v[76:79], v[152:155], v[64:67]
	v_mfma_f32_16x16x32_bf16 v[44:47], v[48:51], v[172:175], v[44:47]
	v_mfma_f32_16x16x32_bf16 v[40:43], v[76:79], v[172:175], v[40:43]
	v_mfma_f32_16x16x32_bf16 v[28:31], v[48:51], v[180:183], v[28:31]
	v_mfma_f32_16x16x32_bf16 v[24:27], v[76:79], v[180:183], v[24:27]
	v_mfma_f32_16x16x32_bf16 v[12:15], v[48:51], v[188:191], v[12:15]
	v_mfma_f32_16x16x32_bf16 v[8:11], v[76:79], v[188:191], v[8:11]
	v_mfma_f32_16x16x32_bf16 v[68:71], v[52:55], v[168:171], v[68:71]
	v_mfma_f32_16x16x32_bf16 v[64:67], v[80:83], v[168:171], v[64:67]
	v_mfma_f32_16x16x32_bf16 v[44:47], v[52:55], v[176:179], v[44:47]
	v_mfma_f32_16x16x32_bf16 v[40:43], v[80:83], v[176:179], v[40:43]
	v_mfma_f32_16x16x32_bf16 v[28:31], v[52:55], v[184:187], v[28:31]
	v_mfma_f32_16x16x32_bf16 v[24:27], v[80:83], v[184:187], v[24:27]
	v_mfma_f32_16x16x32_bf16 v[12:15], v[52:55], v[192:195], v[12:15]
	v_mfma_f32_16x16x32_bf16 v[8:11], v[80:83], v[192:195], v[8:11]
	v_mfma_f32_16x16x32_bf16 v[36:39], v[100:103], v[172:175], v[36:39]
	v_mfma_f32_16x16x32_bf16 v[32:35], v[132:135], v[172:175], v[32:35]
	v_mfma_f32_16x16x32_bf16 v[20:23], v[100:103], v[180:183], v[20:23]
	v_mfma_f32_16x16x32_bf16 v[16:19], v[132:135], v[180:183], v[16:19]
	v_mfma_f32_16x16x32_bf16 v[4:7], v[100:103], v[188:191], v[4:7]
	v_mfma_f32_16x16x32_bf16 v[0:3], v[132:135], v[188:191], v[0:3]
	v_mfma_f32_16x16x32_bf16 v[48:51], v[100:103], v[152:155], v[60:63]
	v_mfma_f32_16x16x32_bf16 v[52:55], v[132:135], v[152:155], v[56:59]
	v_mfma_f32_16x16x32_bf16 v[36:39], v[104:107], v[176:179], v[36:39]
	v_mfma_f32_16x16x32_bf16 v[32:35], v[144:147], v[176:179], v[32:35]
	v_mfma_f32_16x16x32_bf16 v[20:23], v[104:107], v[184:187], v[20:23]
	v_mfma_f32_16x16x32_bf16 v[16:19], v[144:147], v[184:187], v[16:19]
	v_mfma_f32_16x16x32_bf16 v[4:7], v[104:107], v[192:195], v[4:7]
	v_mfma_f32_16x16x32_bf16 v[0:3], v[144:147], v[192:195], v[0:3]
	v_mfma_f32_16x16x32_bf16 v[48:51], v[104:107], v[168:171], v[48:51]
	v_mfma_f32_16x16x32_bf16 v[52:55], v[144:147], v[168:171], v[52:55]
	s_barrier
	ds_read_b128 v[56:59], v124
	ds_read_b128 v[60:63], v124 offset:1024
	ds_read_b128 v[76:79], v124 offset:2048
	ds_read_b128 v[80:83], v124 offset:3072
	ds_read_b128 v[100:103], v125
	ds_read_b128 v[104:107], v125 offset:1024
	ds_read_b128 v[132:135], v125 offset:2048
	ds_read_b128 v[144:147], v125 offset:3072
	s_add_u32 s60, s60, 0x70000
	s_addc_u32 s61, s61, 0
	s_mov_b32 m0, s70
	ds_read_b128 v[152:155], v206 offset:32768
	ds_read_b128 v[168:171], v206 offset:33792
	ds_read_b128 v[172:175], v206 offset:34816
	ds_read_b128 v[176:179], v206 offset:35840
	ds_read_b128 v[180:183], v206 offset:36864
	ds_read_b128 v[184:187], v206 offset:37888
	ds_read_b128 v[188:191], v206 offset:38912
	ds_read_b128 v[192:195], v206 offset:39936
	global_load_lds_dwordx4 v199, s[60:61]
	s_mov_b32 m0, s71
	s_nop 0
	global_load_lds_dwordx4 v201, s[60:61]
	s_waitcnt vmcnt(8)
	s_waitcnt lgkmcnt(0)
	s_barrier
	v_mfma_f32_16x16x32_bf16 v[164:167], v[56:59], v[152:155], v[164:167]
	v_mfma_f32_16x16x32_bf16 v[160:163], v[76:79], v[152:155], v[160:163]
	v_mfma_f32_16x16x32_bf16 v[140:143], v[56:59], v[172:175], v[140:143]
	v_mfma_f32_16x16x32_bf16 v[136:139], v[76:79], v[172:175], v[136:139]
	v_mfma_f32_16x16x32_bf16 v[116:119], v[56:59], v[180:183], v[116:119]
	v_mfma_f32_16x16x32_bf16 v[112:115], v[76:79], v[180:183], v[112:115]
	v_mfma_f32_16x16x32_bf16 v[92:95], v[56:59], v[188:191], v[92:95]
	v_mfma_f32_16x16x32_bf16 v[88:91], v[76:79], v[188:191], v[88:91]
	v_mfma_f32_16x16x32_bf16 v[164:167], v[60:63], v[168:171], v[164:167]
	v_mfma_f32_16x16x32_bf16 v[160:163], v[80:83], v[168:171], v[160:163]
	v_mfma_f32_16x16x32_bf16 v[140:143], v[60:63], v[176:179], v[140:143]
	v_mfma_f32_16x16x32_bf16 v[136:139], v[80:83], v[176:179], v[136:139]
	v_mfma_f32_16x16x32_bf16 v[116:119], v[60:63], v[184:187], v[116:119]
	v_mfma_f32_16x16x32_bf16 v[112:115], v[80:83], v[184:187], v[112:115]
	v_mfma_f32_16x16x32_bf16 v[92:95], v[60:63], v[192:195], v[92:95]
	v_mfma_f32_16x16x32_bf16 v[88:91], v[80:83], v[192:195], v[88:91]
	v_mfma_f32_16x16x32_bf16 v[156:159], v[100:103], v[152:155], v[156:159]
	v_mfma_f32_16x16x32_bf16 v[148:151], v[132:135], v[152:155], v[148:151]
	v_mfma_f32_16x16x32_bf16 v[126:129], v[100:103], v[172:175], v[126:129]
	v_mfma_f32_16x16x32_bf16 v[120:123], v[132:135], v[172:175], v[120:123]
	v_mfma_f32_16x16x32_bf16 v[108:111], v[100:103], v[180:183], v[108:111]
	v_mfma_f32_16x16x32_bf16 v[96:99], v[132:135], v[180:183], v[96:99]
	v_mfma_f32_16x16x32_bf16 v[84:87], v[100:103], v[188:191], v[84:87]
	v_mfma_f32_16x16x32_bf16 v[72:75], v[132:135], v[188:191], v[72:75]
	v_mfma_f32_16x16x32_bf16 v[156:159], v[104:107], v[168:171], v[156:159]
	v_mfma_f32_16x16x32_bf16 v[148:151], v[144:147], v[168:171], v[148:151]
	v_mfma_f32_16x16x32_bf16 v[128:131], v[104:107], v[176:179], v[126:129]
	v_mfma_f32_16x16x32_bf16 v[120:123], v[144:147], v[176:179], v[120:123]
	v_mfma_f32_16x16x32_bf16 v[108:111], v[104:107], v[184:187], v[108:111]
	v_mfma_f32_16x16x32_bf16 v[96:99], v[144:147], v[184:187], v[96:99]
	v_mfma_f32_16x16x32_bf16 v[84:87], v[104:107], v[192:195], v[84:87]
	v_mfma_f32_16x16x32_bf16 v[72:75], v[144:147], v[192:195], v[72:75]
	s_barrier
	s_add_u32 s60, s58, 0x80
	s_mov_b32 m0, s20
	s_addc_u32 s61, s59, 0
	ds_read_b128 v[152:155], v206 offset:49152
	ds_read_b128 v[168:171], v206 offset:50176
	ds_read_b128 v[172:175], v206 offset:51200
	ds_read_b128 v[176:179], v206 offset:52224
	ds_read_b128 v[180:183], v206 offset:53248
	ds_read_b128 v[184:187], v206 offset:54272
	ds_read_b128 v[188:191], v206 offset:55296
	ds_read_b128 v[192:195], v206 offset:56320
	s_add_u32 s58, s58, 0x20080
	global_load_lds_dwordx4 v200, s[60:61]
	s_mov_b32 m0, s21
	s_addc_u32 s59, s59, 0
	global_load_lds_dwordx4 v202, s[60:61]
	s_mov_b32 m0, s45
	s_nop 0
	global_load_lds_dwordx4 v200, s[58:59]
	s_mov_b32 m0, s47
	s_nop 0
	global_load_lds_dwordx4 v202, s[58:59]
	s_mov_b32 m0, s72
	s_nop 0
	global_load_lds_dwordx4 v199, s[56:57]
	s_mov_b32 m0, s73
	s_nop 0
	global_load_lds_dwordx4 v201, s[56:57]
	s_waitcnt vmcnt(8)
	s_waitcnt lgkmcnt(0)
	s_barrier
	v_mfma_f32_16x16x32_bf16 v[68:71], v[56:59], v[152:155], v[68:71]
	v_mfma_f32_16x16x32_bf16 v[64:67], v[76:79], v[152:155], v[64:67]
	v_mfma_f32_16x16x32_bf16 v[44:47], v[56:59], v[172:175], v[44:47]
	v_mfma_f32_16x16x32_bf16 v[40:43], v[76:79], v[172:175], v[40:43]
	v_mfma_f32_16x16x32_bf16 v[28:31], v[56:59], v[180:183], v[28:31]
	v_mfma_f32_16x16x32_bf16 v[24:27], v[76:79], v[180:183], v[24:27]
	v_mfma_f32_16x16x32_bf16 v[12:15], v[56:59], v[188:191], v[12:15]
	v_mfma_f32_16x16x32_bf16 v[8:11], v[76:79], v[188:191], v[8:11]
	v_mfma_f32_16x16x32_bf16 v[68:71], v[60:63], v[168:171], v[68:71]
	v_mfma_f32_16x16x32_bf16 v[64:67], v[80:83], v[168:171], v[64:67]
	v_mfma_f32_16x16x32_bf16 v[44:47], v[60:63], v[176:179], v[44:47]
	v_mfma_f32_16x16x32_bf16 v[40:43], v[80:83], v[176:179], v[40:43]
	v_mfma_f32_16x16x32_bf16 v[28:31], v[60:63], v[184:187], v[28:31]
	v_mfma_f32_16x16x32_bf16 v[24:27], v[80:83], v[184:187], v[24:27]
	v_mfma_f32_16x16x32_bf16 v[12:15], v[60:63], v[192:195], v[12:15]
	v_mfma_f32_16x16x32_bf16 v[8:11], v[80:83], v[192:195], v[8:11]
	v_mfma_f32_16x16x32_bf16 v[48:51], v[100:103], v[152:155], v[48:51]
	v_mfma_f32_16x16x32_bf16 v[60:63], v[104:107], v[168:171], v[48:51]
	v_mfma_f32_16x16x32_bf16 v[48:51], v[132:135], v[152:155], v[52:55]
	v_mfma_f32_16x16x32_bf16 v[36:39], v[100:103], v[172:175], v[36:39]
	v_mfma_f32_16x16x32_bf16 v[32:35], v[132:135], v[172:175], v[32:35]
	v_mfma_f32_16x16x32_bf16 v[20:23], v[100:103], v[180:183], v[20:23]
	v_mfma_f32_16x16x32_bf16 v[16:19], v[132:135], v[180:183], v[16:19]
	v_mfma_f32_16x16x32_bf16 v[4:7], v[100:103], v[188:191], v[4:7]
	v_mfma_f32_16x16x32_bf16 v[0:3], v[132:135], v[188:191], v[0:3]
	v_mfma_f32_16x16x32_bf16 v[56:59], v[144:147], v[168:171], v[48:51]
	v_mfma_f32_16x16x32_bf16 v[36:39], v[104:107], v[176:179], v[36:39]
	v_mfma_f32_16x16x32_bf16 v[32:35], v[144:147], v[176:179], v[32:35]
	v_mfma_f32_16x16x32_bf16 v[20:23], v[104:107], v[184:187], v[20:23]
	v_mfma_f32_16x16x32_bf16 v[16:19], v[144:147], v[184:187], v[16:19]
	v_mfma_f32_16x16x32_bf16 v[4:7], v[104:107], v[192:195], v[4:7]
	v_mfma_f32_16x16x32_bf16 v[0:3], v[144:147], v[192:195], v[0:3]
	s_barrier
	s_add_i32 s80, s80, 2
	s_add_u32 s53, s53, 0x100
	s_addc_u32 s79, s79, 0
	s_cmp_gt_u32 s80, 5
	s_mov_b64 s[62:63], s[54:55]
	s_cbranch_scc0 .LBB0_2481
	s_and_b64 vcc, exec, s[42:43]
	s_cbranch_vccz .LBB0_2484
	s_barrier

.LBB0_2656:
	s_waitcnt lgkmcnt(0)
	s_barrier
	s_and_b64 vcc, exec, s[2:3]
	s_cbranch_vccnz .LBB0_2658
	s_add_u32 s0, s8, 0x100000
	s_mov_b32 m0, s64
	s_addc_u32 s1, s9, 0
	global_load_lds_dwordx4 v165, s[0:1]
	s_mov_b32 m0, s36
	s_nop 0
	global_load_lds_dwordx4 v166, s[0:1]
	s_add_u32 s0, s8, 0x80400
	s_addc_u32 s1, s9, 0
	s_mov_b32 m0, s43
	s_nop 0
	global_load_lds_dwordx4 v146, s[0:1]
	s_mov_b32 m0, s44
	s_nop 0
	global_load_lds_dwordx4 v144, s[0:1]

.LBB0_2660:
	v_lshlrev_b32_e32 v4, 1, v32
	v_and_b32_e32 v4, 32, v4
	v_and_b32_e32 v5, 0xc0, v33
	v_and_b32_e32 v6, 0x100, v35
	s_waitcnt lgkmcnt(0)
	s_barrier
	v_add3_u32 v4, v4, s45, v5
	v_add3_u32 v147, v4, v6, v34
	ds_read_b64_tr_b16 v[16:17], v147 offset:0
	ds_read_b64_tr_b16 v[18:19], v147 offset:0x800
	ds_read_b64_tr_b16 v[12:13], v147 offset:0x1000
	ds_read_b64_tr_b16 v[14:15], v147 offset:0x1800
	ds_read_b64_tr_b16 v[8:9], v147 offset:0x2000
	ds_read_b64_tr_b16 v[10:11], v147 offset:0x2800
	ds_read_b64_tr_b16 v[4:5], v147 offset:0x3000
	ds_read_b64_tr_b16 v[6:7], v147 offset:0x3800
	s_and_b64 vcc, exec, s[4:5]
	s_cbranch_vccnz .LBB0_2662
	s_add_u32 s0, s8, 0x100000
	s_mov_b32 m0, s64
	s_addc_u32 s1, s9, 0
	global_load_lds_dwordx4 v165, s[0:1]
	s_mov_b32 m0, s36
	s_nop 0
	global_load_lds_dwordx4 v166, s[0:1]
	s_add_u32 s0, s8, 0x80400
	s_addc_u32 s1, s9, 0
	s_mov_b32 m0, s43
	s_nop 0
	global_load_lds_dwordx4 v146, s[0:1]
	s_mov_b32 m0, s44
	s_nop 0
	global_load_lds_dwordx4 v144, s[0:1]

.LBB0_2774:
	s_add_u32 s20, s54, 0x100
	s_addc_u32 s21, s55, 0
	s_waitcnt lgkmcnt(0)
	s_add_u32 s50, s52, 0x100
	s_addc_u32 s51, s53, 0
	s_barrier
	s_waitcnt lgkmcnt(0)
	v_mfma_f32_16x16x32_bf16 v[32:35], v[16:19], v[68:71], 0
	v_mfma_f32_16x16x32_bf16 v[36:39], v[24:27], v[68:71], 0
	v_mfma_f32_16x16x32_bf16 v[40:43], v[16:19], v[84:87], 0
	v_mfma_f32_16x16x32_bf16 v[44:47], v[24:27], v[84:87], 0
	v_mfma_f32_16x16x32_bf16 v[48:51], v[16:19], v[92:95], 0
	v_mfma_f32_16x16x32_bf16 v[52:55], v[24:27], v[92:95], 0
	v_mfma_f32_16x16x32_bf16 v[56:59], v[16:19], v[76:79], 0
	v_mfma_f32_16x16x32_bf16 v[60:63], v[24:27], v[76:79], 0
	v_mfma_f32_16x16x32_bf16 v[138:141], v[20:23], v[72:75], v[32:35]
	v_mfma_f32_16x16x32_bf16 v[36:39], v[28:31], v[72:75], v[36:39]
	v_mfma_f32_16x16x32_bf16 v[40:43], v[20:23], v[88:91], v[40:43]
	v_mfma_f32_16x16x32_bf16 v[44:47], v[28:31], v[88:91], v[44:47]
	v_mfma_f32_16x16x32_bf16 v[48:51], v[20:23], v[96:99], v[48:51]
	v_mfma_f32_16x16x32_bf16 v[52:55], v[28:31], v[96:99], v[52:55]
	v_mfma_f32_16x16x32_bf16 v[56:59], v[20:23], v[80:83], v[56:59]
	v_mfma_f32_16x16x32_bf16 v[60:63], v[28:31], v[80:83], v[60:63]
	v_mfma_f32_16x16x32_bf16 v[64:67], v[0:3], v[68:71], 0
	v_mfma_f32_16x16x32_bf16 v[68:71], v[8:11], v[68:71], 0
	v_mfma_f32_16x16x32_bf16 v[64:67], v[4:7], v[72:75], v[64:67]
	v_mfma_f32_16x16x32_bf16 v[68:71], v[12:15], v[72:75], v[68:71]
	v_mfma_f32_16x16x32_bf16 v[72:75], v[0:3], v[84:87], 0
	v_mfma_f32_16x16x32_bf16 v[84:87], v[8:11], v[84:87], 0
	v_mfma_f32_16x16x32_bf16 v[72:75], v[4:7], v[88:91], v[72:75]
	v_mfma_f32_16x16x32_bf16 v[84:87], v[12:15], v[88:91], v[84:87]
	v_mfma_f32_16x16x32_bf16 v[88:91], v[0:3], v[92:95], 0
	v_mfma_f32_16x16x32_bf16 v[92:95], v[8:11], v[92:95], 0
	v_mfma_f32_16x16x32_bf16 v[88:91], v[4:7], v[96:99], v[88:91]
	v_mfma_f32_16x16x32_bf16 v[92:95], v[12:15], v[96:99], v[92:95]
	v_mfma_f32_16x16x32_bf16 v[96:99], v[0:3], v[76:79], 0
	v_mfma_f32_16x16x32_bf16 v[76:79], v[8:11], v[76:79], 0
	v_mfma_f32_16x16x32_bf16 v[108:111], v[4:7], v[80:83], v[96:99]
	v_mfma_f32_16x16x32_bf16 v[112:115], v[12:15], v[80:83], v[76:79]
	s_barrier
	s_mov_b32 m0, s60
	ds_read_b128 v[120:123], v209 offset:16384
	ds_read_b128 v[124:127], v209 offset:17408
	ds_read_b128 v[104:107], v209 offset:18432
	ds_read_b128 v[116:119], v209 offset:19456
	ds_read_b128 v[96:99], v209 offset:20480
	ds_read_b128 v[100:103], v209 offset:21504
	ds_read_b128 v[76:79], v209 offset:22528
	ds_read_b128 v[80:83], v209 offset:23552
	global_load_lds_dwordx4 v203, s[50:51]
	s_mov_b32 m0, s61
	s_nop 0
	global_load_lds_dwordx4 v205, s[50:51]
	s_add_u32 s50, s52, 0x80100
	s_addc_u32 s51, s53, 0
	s_mov_b32 m0, s62
	s_and_b64 vcc, exec, s[48:49]
	global_load_lds_dwordx4 v203, s[50:51]
	s_mov_b32 m0, s63
	s_nop 0
	global_load_lds_dwordx4 v205, s[50:51]
	s_mov_b32 m0, s27
	s_mov_b64 s[50:51], -1
	global_load_lds_dwordx4 v202, s[20:21]
	s_mov_b32 m0, s64
	s_nop 0
	global_load_lds_dwordx4 v204, s[20:21]
	s_cbranch_vccz .LBB0_2776
	s_waitcnt vmcnt(8)
	s_mov_b64 s[50:51], 0

.LBB0_2778:
	s_ashr_i32 s43, s42, 31
	s_lshl_b64 s[20:21], s[42:43], 20
	s_add_u32 s48, s13, s20
	s_addc_u32 s49, s82, s21
	s_and_b64 s[20:21], s[46:47], exec
	s_cselect_b32 s3, s49, s55
	s_cselect_b32 s5, s48, s54
	s_ashr_i32 s45, s44, 31
	s_lshl_b64 s[20:21], s[44:45], 20
	s_add_u32 s50, s24, s20
	s_addc_u32 s51, s25, s21
	s_and_b64 s[20:21], s[46:47], exec
	s_cselect_b32 s12, s51, s53
	s_cselect_b32 s20, s50, s52
	s_add_u32 s56, s54, 0x180
	s_waitcnt lgkmcnt(0)
	s_addc_u32 s57, s55, 0
	s_add_u32 s58, s52, 0x180
	s_addc_u32 s59, s53, 0
	s_barrier
	s_waitcnt lgkmcnt(0)
	v_mfma_f32_16x16x32_bf16 v[128:131], v[16:19], v[120:123], 0
	v_mfma_f32_16x16x32_bf16 v[134:137], v[20:23], v[124:127], v[128:131]
	v_mfma_f32_16x16x32_bf16 v[128:131], v[24:27], v[120:123], 0
	v_mfma_f32_16x16x32_bf16 v[156:159], v[28:31], v[124:127], v[128:131]
	v_mfma_f32_16x16x32_bf16 v[128:131], v[16:19], v[104:107], 0
	v_mfma_f32_16x16x32_bf16 v[160:163], v[20:23], v[116:119], v[128:131]
	v_mfma_f32_16x16x32_bf16 v[128:131], v[24:27], v[104:107], 0
	v_mfma_f32_16x16x32_bf16 v[164:167], v[28:31], v[116:119], v[128:131]
	v_mfma_f32_16x16x32_bf16 v[128:131], v[16:19], v[96:99], 0
	v_mfma_f32_16x16x32_bf16 v[16:19], v[16:19], v[76:79], 0
	v_mfma_f32_16x16x32_bf16 v[168:171], v[20:23], v[100:103], v[128:131]
	v_mfma_f32_16x16x32_bf16 v[16:19], v[20:23], v[80:83], v[16:19]
	v_mfma_f32_16x16x32_bf16 v[20:23], v[24:27], v[76:79], 0
	v_mfma_f32_16x16x32_bf16 v[128:131], v[24:27], v[96:99], 0
	v_mfma_f32_16x16x32_bf16 v[20:23], v[28:31], v[80:83], v[20:23]
	v_mfma_f32_16x16x32_bf16 v[172:175], v[28:31], v[100:103], v[128:131]
	v_mfma_f32_16x16x32_bf16 v[24:27], v[0:3], v[120:123], 0
	v_mfma_f32_16x16x32_bf16 v[176:179], v[4:7], v[124:127], v[24:27]
	v_mfma_f32_16x16x32_bf16 v[24:27], v[8:11], v[120:123], 0
	v_mfma_f32_16x16x32_bf16 v[180:183], v[12:15], v[124:127], v[24:27]
	v_mfma_f32_16x16x32_bf16 v[24:27], v[0:3], v[104:107], 0
	v_mfma_f32_16x16x32_bf16 v[186:189], v[4:7], v[116:119], v[24:27]
	v_mfma_f32_16x16x32_bf16 v[24:27], v[8:11], v[104:107], 0
	v_mfma_f32_16x16x32_bf16 v[190:193], v[12:15], v[116:119], v[24:27]
	v_mfma_f32_16x16x32_bf16 v[24:27], v[0:3], v[96:99], 0
	v_mfma_f32_16x16x32_bf16 v[0:3], v[0:3], v[76:79], 0
	v_mfma_f32_16x16x32_bf16 v[194:197], v[4:7], v[100:103], v[24:27]
	v_mfma_f32_16x16x32_bf16 v[24:27], v[8:11], v[96:99], 0
	v_mfma_f32_16x16x32_bf16 v[0:3], v[4:7], v[80:83], v[0:3]
	v_mfma_f32_16x16x32_bf16 v[4:7], v[8:11], v[76:79], 0
	v_mfma_f32_16x16x32_bf16 v[198:201], v[12:15], v[100:103], v[24:27]
	v_mfma_f32_16x16x32_bf16 v[212:215], v[12:15], v[80:83], v[4:7]
	s_barrier
	v_add_u32_e32 v132, s74, v206
	v_add_u32_e32 v133, s75, v206
	s_nop 1
	ds_read_b128 v[4:7], v132
	ds_read_b128 v[8:11], v132 offset:1024
	ds_read_b128 v[216:219], v132 offset:2048
	ds_read_b128 v[220:223], v132 offset:3072
	ds_read_b128 v[224:227], v133
	ds_read_b128 v[228:231], v133 offset:1024
	ds_read_b128 v[232:235], v133 offset:2048
	ds_read_b128 v[236:239], v133 offset:3072
	s_add_u32 s78, s54, 0x80100
	s_addc_u32 s79, s55, 0
	s_mov_b32 m0, s65
	ds_read_b128 v[12:15], v209 offset:32768
	ds_read_b128 v[24:27], v209 offset:33792
	ds_read_b128 v[28:31], v209 offset:34816
	ds_read_b128 v[96:99], v209 offset:35840
	ds_read_b128 v[240:243], v209 offset:36864
	ds_read_b128 v[244:247], v209 offset:37888
	ds_read_b128 v[248:251], v209 offset:38912
	ds_read_b128 v[32:35], v209 offset:39936
	global_load_lds_dwordx4 v202, s[78:79]
	s_mov_b32 m0, s66
	s_nop 0
	global_load_lds_dwordx4 v204, s[78:79]
	s_waitcnt vmcnt(8)
	s_waitcnt lgkmcnt(0)
	s_barrier
	v_mfma_f32_16x16x32_bf16 v[36:39], v[216:219], v[12:15], v[36:39]
	v_mfma_f32_16x16x32_bf16 v[148:151], v[220:223], v[24:27], v[36:39]
	v_mfma_f32_16x16x32_bf16 v[36:39], v[4:7], v[28:31], v[40:43]
	v_mfma_f32_16x16x32_bf16 v[128:131], v[8:11], v[96:99], v[36:39]
	v_mfma_f32_16x16x32_bf16 v[36:39], v[216:219], v[28:31], v[44:47]
	v_mfma_f32_16x16x32_bf16 v[124:127], v[220:223], v[96:99], v[36:39]
	v_mfma_f32_16x16x32_bf16 v[36:39], v[4:7], v[240:243], v[48:51]
	v_mfma_f32_16x16x32_bf16 v[104:107], v[8:11], v[244:247], v[36:39]
	v_mfma_f32_16x16x32_bf16 v[36:39], v[216:219], v[240:243], v[52:55]
	v_mfma_f32_16x16x32_bf16 v[100:103], v[220:223], v[244:247], v[36:39]
	v_mfma_f32_16x16x32_bf16 v[36:39], v[4:7], v[248:251], v[56:59]
	v_mfma_f32_16x16x32_bf16 v[76:79], v[4:7], v[12:15], v[138:141]
	v_mfma_f32_16x16x32_bf16 v[80:83], v[8:11], v[32:35], v[36:39]
	v_mfma_f32_16x16x32_bf16 v[36:39], v[216:219], v[248:251], v[60:63]
	v_mfma_f32_16x16x32_bf16 v[152:155], v[8:11], v[24:27], v[76:79]
	v_mfma_f32_16x16x32_bf16 v[76:79], v[220:223], v[32:35], v[36:39]
	v_mfma_f32_16x16x32_bf16 v[36:39], v[224:227], v[12:15], v[64:67]
	v_mfma_f32_16x16x32_bf16 v[12:15], v[232:235], v[12:15], v[68:71]
	v_mfma_f32_16x16x32_bf16 v[140:143], v[236:239], v[24:27], v[12:15]
	v_mfma_f32_16x16x32_bf16 v[12:15], v[224:227], v[28:31], v[72:75]
	v_mfma_f32_16x16x32_bf16 v[120:123], v[228:231], v[96:99], v[12:15]
	v_mfma_f32_16x16x32_bf16 v[12:15], v[232:235], v[28:31], v[84:87]
	v_mfma_f32_16x16x32_bf16 v[116:119], v[236:239], v[96:99], v[12:15]
	v_mfma_f32_16x16x32_bf16 v[12:15], v[224:227], v[240:243], v[88:91]
	v_mfma_f32_16x16x32_bf16 v[96:99], v[228:231], v[244:247], v[12:15]
	v_mfma_f32_16x16x32_bf16 v[12:15], v[232:235], v[240:243], v[92:95]
	v_mfma_f32_16x16x32_bf16 v[92:95], v[236:239], v[244:247], v[12:15]
	v_mfma_f32_16x16x32_bf16 v[12:15], v[224:227], v[248:251], v[108:111]
	v_mfma_f32_16x16x32_bf16 v[72:75], v[228:231], v[32:35], v[12:15]
	v_mfma_f32_16x16x32_bf16 v[12:15], v[232:235], v[248:251], v[112:115]
	v_mfma_f32_16x16x32_bf16 v[144:147], v[228:231], v[24:27], v[36:39]
	v_mfma_f32_16x16x32_bf16 v[68:71], v[236:239], v[32:35], v[12:15]
	s_barrier
	s_add_i32 s21, s74, s26
	s_mov_b32 m0, s21
	s_add_i32 s43, s21, 0x2000
	ds_read_b128 v[32:35], v209 offset:49152
	ds_read_b128 v[36:39], v209 offset:50176
	ds_read_b128 v[60:63], v209 offset:51200
	ds_read_b128 v[84:87], v209 offset:52224
	ds_read_b128 v[88:91], v209 offset:53248
	ds_read_b128 v[108:111], v209 offset:54272
	ds_read_b128 v[112:115], v209 offset:55296
	ds_read_b128 v[240:243], v209 offset:56320
	global_load_lds_dwordx4 v203, s[58:59]
	s_mov_b32 m0, s43
	s_nop 0
	global_load_lds_dwordx4 v205, s[58:59]
	s_add_u32 s58, s52, 0x80180
	s_addc_u32 s59, s53, 0
	s_add_i32 s45, s75, s26
	s_mov_b32 m0, s45
	s_add_i32 s78, s45, 0x2000
	s_nop 0
	global_load_lds_dwordx4 v203, s[58:59]
	s_mov_b32 m0, s78
	s_nop 0
	global_load_lds_dwordx4 v205, s[58:59]
	s_mov_b32 m0, s67
	s_nop 0
	global_load_lds_dwordx4 v202, s[56:57]
	s_mov_b32 m0, s68
	s_nop 0
	global_load_lds_dwordx4 v204, s[56:57]
	s_waitcnt vmcnt(8)
	s_waitcnt lgkmcnt(0)
	s_barrier
	v_mfma_f32_16x16x32_bf16 v[12:15], v[4:7], v[32:35], v[134:137]
	v_mfma_f32_16x16x32_bf16 v[64:67], v[8:11], v[36:39], v[12:15]
	v_mfma_f32_16x16x32_bf16 v[12:15], v[216:219], v[32:35], v[156:159]
	v_mfma_f32_16x16x32_bf16 v[56:59], v[220:223], v[36:39], v[12:15]
	v_mfma_f32_16x16x32_bf16 v[12:15], v[4:7], v[60:63], v[160:163]
	v_mfma_f32_16x16x32_bf16 v[44:47], v[8:11], v[84:87], v[12:15]
	v_mfma_f32_16x16x32_bf16 v[12:15], v[216:219], v[60:63], v[164:167]
	v_mfma_f32_16x16x32_bf16 v[40:43], v[220:223], v[84:87], v[12:15]
	v_mfma_f32_16x16x32_bf16 v[12:15], v[4:7], v[88:91], v[168:171]
	v_mfma_f32_16x16x32_bf16 v[28:31], v[8:11], v[108:111], v[12:15]
	v_mfma_f32_16x16x32_bf16 v[12:15], v[216:219], v[88:91], v[172:175]
	v_mfma_f32_16x16x32_bf16 v[4:7], v[4:7], v[112:115], v[16:19]
	v_mfma_f32_16x16x32_bf16 v[24:27], v[220:223], v[108:111], v[12:15]
	v_mfma_f32_16x16x32_bf16 v[12:15], v[8:11], v[240:243], v[4:7]
	v_mfma_f32_16x16x32_bf16 v[4:7], v[216:219], v[112:115], v[20:23]
	v_mfma_f32_16x16x32_bf16 v[8:11], v[220:223], v[240:243], v[4:7]
	v_mfma_f32_16x16x32_bf16 v[4:7], v[224:227], v[32:35], v[176:179]
	v_mfma_f32_16x16x32_bf16 v[52:55], v[228:231], v[36:39], v[4:7]
	v_mfma_f32_16x16x32_bf16 v[4:7], v[232:235], v[32:35], v[180:183]
	v_mfma_f32_16x16x32_bf16 v[48:51], v[236:239], v[36:39], v[4:7]
	v_mfma_f32_16x16x32_bf16 v[4:7], v[224:227], v[60:63], v[186:189]
	v_mfma_f32_16x16x32_bf16 v[36:39], v[228:231], v[84:87], v[4:7]
	v_mfma_f32_16x16x32_bf16 v[4:7], v[232:235], v[60:63], v[190:193]
	v_mfma_f32_16x16x32_bf16 v[32:35], v[236:239], v[84:87], v[4:7]
	v_mfma_f32_16x16x32_bf16 v[4:7], v[224:227], v[88:91], v[194:197]
	v_mfma_f32_16x16x32_bf16 v[20:23], v[228:231], v[108:111], v[4:7]
	v_mfma_f32_16x16x32_bf16 v[4:7], v[232:235], v[88:91], v[198:201]
	v_mfma_f32_16x16x32_bf16 v[0:3], v[224:227], v[112:115], v[0:3]
	v_mfma_f32_16x16x32_bf16 v[16:19], v[236:239], v[108:111], v[4:7]
	v_mfma_f32_16x16x32_bf16 v[4:7], v[228:231], v[240:243], v[0:3]
	v_mfma_f32_16x16x32_bf16 v[0:3], v[232:235], v[112:115], v[212:215]
	v_mfma_f32_16x16x32_bf16 v[0:3], v[236:239], v[240:243], v[0:3]
	s_barrier
	s_add_u32 s79, s54, 0x200
	s_addc_u32 s80, s55, 0
	s_add_u32 s81, s52, 0x200
	s_addc_u32 s83, s53, 0
	s_add_u32 s52, s54, 0x80180
	s_addc_u32 s53, s55, 0
	s_mov_b32 s84, 0
.LBB0_2779:
	s_cmp_eq_u32 s84, 28
	s_cselect_b32 s58, s5, s79
	s_cselect_b32 s59, s3, s80
	s_cselect_b32 s56, s20, s81
	s_cselect_b32 s57, s12, s83
	s_add_u32 s54, s58, 0x80
	s_addc_u32 s55, s59, 0
	s_add_i32 s85, 0, 0x10000
	s_add_i32 s88, 0, 0x14000
	v_add_u32_e32 v108, s85, v206
	v_add_u32_e32 v138, s88, v206
	ds_read_b128 v[60:63], v108
	ds_read_b128 v[84:87], v108 offset:1024
	ds_read_b128 v[88:91], v108 offset:2048
	ds_read_b128 v[108:111], v108 offset:3072
	ds_read_b128 v[112:115], v138
	ds_read_b128 v[134:137], v138 offset:1024
	ds_read_b128 v[156:159], v138 offset:2048
	ds_read_b128 v[160:163], v138 offset:3072
	s_mov_b32 m0, s0
	ds_read_b128 v[164:167], v209
	ds_read_b128 v[168:171], v209 offset:1024
	ds_read_b128 v[172:175], v209 offset:2048
	ds_read_b128 v[176:179], v209 offset:3072
	ds_read_b128 v[180:183], v209 offset:4096
	ds_read_b128 v[186:189], v209 offset:5120
	ds_read_b128 v[190:193], v209 offset:6144
	ds_read_b128 v[194:197], v209 offset:7168
	global_load_lds_dwordx4 v202, s[52:53]
	s_mov_b32 m0, s1
	s_nop 0
	global_load_lds_dwordx4 v204, s[52:53]
	s_waitcnt vmcnt(8)
	s_waitcnt lgkmcnt(0)
	s_barrier
	v_mfma_f32_16x16x32_bf16 v[152:155], v[60:63], v[164:167], v[152:155]
	v_mfma_f32_16x16x32_bf16 v[148:151], v[88:91], v[164:167], v[148:151]
	v_mfma_f32_16x16x32_bf16 v[128:131], v[60:63], v[172:175], v[128:131]
	v_mfma_f32_16x16x32_bf16 v[124:127], v[88:91], v[172:175], v[124:127]
	v_mfma_f32_16x16x32_bf16 v[104:107], v[60:63], v[180:183], v[104:107]
	v_mfma_f32_16x16x32_bf16 v[100:103], v[88:91], v[180:183], v[100:103]
	v_mfma_f32_16x16x32_bf16 v[80:83], v[60:63], v[190:193], v[80:83]
	v_mfma_f32_16x16x32_bf16 v[76:79], v[88:91], v[190:193], v[76:79]
	v_mfma_f32_16x16x32_bf16 v[152:155], v[84:87], v[168:171], v[152:155]
	v_mfma_f32_16x16x32_bf16 v[148:151], v[108:111], v[168:171], v[148:151]
	v_mfma_f32_16x16x32_bf16 v[128:131], v[84:87], v[176:179], v[128:131]
	v_mfma_f32_16x16x32_bf16 v[124:127], v[108:111], v[176:179], v[124:127]
	v_mfma_f32_16x16x32_bf16 v[104:107], v[84:87], v[186:189], v[104:107]
	v_mfma_f32_16x16x32_bf16 v[100:103], v[108:111], v[186:189], v[100:103]
	v_mfma_f32_16x16x32_bf16 v[80:83], v[84:87], v[194:197], v[80:83]
	v_mfma_f32_16x16x32_bf16 v[76:79], v[108:111], v[194:197], v[76:79]
	v_mfma_f32_16x16x32_bf16 v[144:147], v[112:115], v[164:167], v[144:147]
	v_mfma_f32_16x16x32_bf16 v[138:141], v[156:159], v[164:167], v[140:143]
	v_mfma_f32_16x16x32_bf16 v[120:123], v[112:115], v[172:175], v[120:123]
	v_mfma_f32_16x16x32_bf16 v[116:119], v[156:159], v[172:175], v[116:119]
	v_mfma_f32_16x16x32_bf16 v[96:99], v[112:115], v[180:183], v[96:99]
	v_mfma_f32_16x16x32_bf16 v[92:95], v[156:159], v[180:183], v[92:95]
	v_mfma_f32_16x16x32_bf16 v[72:75], v[112:115], v[190:193], v[72:75]
	v_mfma_f32_16x16x32_bf16 v[68:71], v[156:159], v[190:193], v[68:71]
	v_mfma_f32_16x16x32_bf16 v[144:147], v[134:137], v[168:171], v[144:147]
	v_mfma_f32_16x16x32_bf16 v[138:141], v[160:163], v[168:171], v[138:141]
	v_mfma_f32_16x16x32_bf16 v[120:123], v[134:137], v[176:179], v[120:123]
	v_mfma_f32_16x16x32_bf16 v[116:119], v[160:163], v[176:179], v[116:119]
	v_mfma_f32_16x16x32_bf16 v[96:99], v[134:137], v[186:189], v[96:99]
	v_mfma_f32_16x16x32_bf16 v[92:95], v[160:163], v[186:189], v[92:95]
	v_mfma_f32_16x16x32_bf16 v[72:75], v[134:137], v[194:197], v[72:75]
	v_mfma_f32_16x16x32_bf16 v[68:71], v[160:163], v[194:197], v[68:71]
	s_barrier
	s_add_i32 s85, s85, s26
	s_mov_b32 m0, s85
	ds_read_b128 v[164:167], v209 offset:16384
	ds_read_b128 v[168:171], v209 offset:17408
	ds_read_b128 v[172:175], v209 offset:18432
	ds_read_b128 v[176:179], v209 offset:19456
	ds_read_b128 v[180:183], v209 offset:20480
	ds_read_b128 v[186:189], v209 offset:21504
	ds_read_b128 v[190:193], v209 offset:22528
	ds_read_b128 v[194:197], v209 offset:23552
	global_load_lds_dwordx4 v203, s[56:57]
	s_add_i32 m0, s85, 0x2000
	s_add_u32 s86, s56, 0x80000
	s_addc_u32 s87, s57, 0
	s_add_i32 s85, s88, s26
	s_nop 0
	global_load_lds_dwordx4 v205, s[56:57]
	s_mov_b32 m0, s85
	s_nop 0
	global_load_lds_dwordx4 v203, s[86:87]
	s_add_i32 m0, s85, 0x2000
	s_nop 0
	global_load_lds_dwordx4 v205, s[86:87]
	s_mov_b32 m0, s27
	s_nop 0
	global_load_lds_dwordx4 v202, s[58:59]
	s_mov_b32 m0, s64
	s_nop 0
	global_load_lds_dwordx4 v204, s[58:59]
	s_waitcnt vmcnt(8)
	s_waitcnt lgkmcnt(0)
	s_barrier
	v_mfma_f32_16x16x32_bf16 v[64:67], v[60:63], v[164:167], v[64:67]
	v_mfma_f32_16x16x32_bf16 v[56:59], v[88:91], v[164:167], v[56:59]
	v_mfma_f32_16x16x32_bf16 v[44:47], v[60:63], v[172:175], v[44:47]
	v_mfma_f32_16x16x32_bf16 v[40:43], v[88:91], v[172:175], v[40:43]
	v_mfma_f32_16x16x32_bf16 v[28:31], v[60:63], v[180:183], v[28:31]
	v_mfma_f32_16x16x32_bf16 v[24:27], v[88:91], v[180:183], v[24:27]
	v_mfma_f32_16x16x32_bf16 v[12:15], v[60:63], v[190:193], v[12:15]
	v_mfma_f32_16x16x32_bf16 v[8:11], v[88:91], v[190:193], v[8:11]
	v_mfma_f32_16x16x32_bf16 v[64:67], v[84:87], v[168:171], v[64:67]
	v_mfma_f32_16x16x32_bf16 v[56:59], v[108:111], v[168:171], v[56:59]
	v_mfma_f32_16x16x32_bf16 v[44:47], v[84:87], v[176:179], v[44:47]
	v_mfma_f32_16x16x32_bf16 v[40:43], v[108:111], v[176:179], v[40:43]
	v_mfma_f32_16x16x32_bf16 v[28:31], v[84:87], v[186:189], v[28:31]
	v_mfma_f32_16x16x32_bf16 v[24:27], v[108:111], v[186:189], v[24:27]
	v_mfma_f32_16x16x32_bf16 v[12:15], v[84:87], v[194:197], v[12:15]
	v_mfma_f32_16x16x32_bf16 v[8:11], v[108:111], v[194:197], v[8:11]
	v_mfma_f32_16x16x32_bf16 v[52:55], v[112:115], v[164:167], v[52:55]
	v_mfma_f32_16x16x32_bf16 v[48:51], v[156:159], v[164:167], v[48:51]
	v_mfma_f32_16x16x32_bf16 v[36:39], v[112:115], v[172:175], v[36:39]
	v_mfma_f32_16x16x32_bf16 v[32:35], v[156:159], v[172:175], v[32:35]
	v_mfma_f32_16x16x32_bf16 v[20:23], v[112:115], v[180:183], v[20:23]
	v_mfma_f32_16x16x32_bf16 v[16:19], v[156:159], v[180:183], v[16:19]
	v_mfma_f32_16x16x32_bf16 v[4:7], v[112:115], v[190:193], v[4:7]
	v_mfma_f32_16x16x32_bf16 v[0:3], v[156:159], v[190:193], v[0:3]
	v_mfma_f32_16x16x32_bf16 v[52:55], v[134:137], v[168:171], v[52:55]
	v_mfma_f32_16x16x32_bf16 v[48:51], v[160:163], v[168:171], v[48:51]
	v_mfma_f32_16x16x32_bf16 v[36:39], v[134:137], v[176:179], v[36:39]
	v_mfma_f32_16x16x32_bf16 v[32:35], v[160:163], v[176:179], v[32:35]
	v_mfma_f32_16x16x32_bf16 v[20:23], v[134:137], v[186:189], v[20:23]
	v_mfma_f32_16x16x32_bf16 v[16:19], v[160:163], v[186:189], v[16:19]
	v_mfma_f32_16x16x32_bf16 v[4:7], v[134:137], v[194:197], v[4:7]
	v_mfma_f32_16x16x32_bf16 v[0:3], v[160:163], v[194:197], v[0:3]
	s_barrier
	ds_read_b128 v[60:63], v132
	ds_read_b128 v[84:87], v132 offset:1024
	ds_read_b128 v[88:91], v132 offset:2048
	ds_read_b128 v[108:111], v132 offset:3072
	ds_read_b128 v[112:115], v133
	ds_read_b128 v[134:137], v133 offset:1024
	ds_read_b128 v[156:159], v133 offset:2048
	ds_read_b128 v[160:163], v133 offset:3072
	s_add_u32 s58, s58, 0x80000
	s_addc_u32 s59, s59, 0
	s_mov_b32 m0, s65
	ds_read_b128 v[164:167], v209 offset:32768
	ds_read_b128 v[168:171], v209 offset:33792
	ds_read_b128 v[172:175], v209 offset:34816
	ds_read_b128 v[176:179], v209 offset:35840
	ds_read_b128 v[180:183], v209 offset:36864
	ds_read_b128 v[186:189], v209 offset:37888
	ds_read_b128 v[190:193], v209 offset:38912
	ds_read_b128 v[194:197], v209 offset:39936
	global_load_lds_dwordx4 v202, s[58:59]
	s_mov_b32 m0, s66
	s_nop 0
	global_load_lds_dwordx4 v204, s[58:59]
	s_waitcnt vmcnt(8)
	s_waitcnt lgkmcnt(0)
	s_barrier
	v_mfma_f32_16x16x32_bf16 v[152:155], v[60:63], v[164:167], v[152:155]
	v_mfma_f32_16x16x32_bf16 v[148:151], v[88:91], v[164:167], v[148:151]
	v_mfma_f32_16x16x32_bf16 v[128:131], v[60:63], v[172:175], v[128:131]
	v_mfma_f32_16x16x32_bf16 v[124:127], v[88:91], v[172:175], v[124:127]
	v_mfma_f32_16x16x32_bf16 v[104:107], v[60:63], v[180:183], v[104:107]
	v_mfma_f32_16x16x32_bf16 v[100:103], v[88:91], v[180:183], v[100:103]
	v_mfma_f32_16x16x32_bf16 v[80:83], v[60:63], v[190:193], v[80:83]
	v_mfma_f32_16x16x32_bf16 v[76:79], v[88:91], v[190:193], v[76:79]
	v_mfma_f32_16x16x32_bf16 v[152:155], v[84:87], v[168:171], v[152:155]
	v_mfma_f32_16x16x32_bf16 v[148:151], v[108:111], v[168:171], v[148:151]
	v_mfma_f32_16x16x32_bf16 v[128:131], v[84:87], v[176:179], v[128:131]
	v_mfma_f32_16x16x32_bf16 v[124:127], v[108:111], v[176:179], v[124:127]
	v_mfma_f32_16x16x32_bf16 v[104:107], v[84:87], v[186:189], v[104:107]
	v_mfma_f32_16x16x32_bf16 v[100:103], v[108:111], v[186:189], v[100:103]
	v_mfma_f32_16x16x32_bf16 v[80:83], v[84:87], v[194:197], v[80:83]
	v_mfma_f32_16x16x32_bf16 v[76:79], v[108:111], v[194:197], v[76:79]
	v_mfma_f32_16x16x32_bf16 v[142:145], v[112:115], v[164:167], v[144:147]
	v_mfma_f32_16x16x32_bf16 v[138:141], v[156:159], v[164:167], v[138:141]
	v_mfma_f32_16x16x32_bf16 v[120:123], v[112:115], v[172:175], v[120:123]
	v_mfma_f32_16x16x32_bf16 v[116:119], v[156:159], v[172:175], v[116:119]
	v_mfma_f32_16x16x32_bf16 v[96:99], v[112:115], v[180:183], v[96:99]
	v_mfma_f32_16x16x32_bf16 v[92:95], v[156:159], v[180:183], v[92:95]
	v_mfma_f32_16x16x32_bf16 v[72:75], v[112:115], v[190:193], v[72:75]
	v_mfma_f32_16x16x32_bf16 v[68:71], v[156:159], v[190:193], v[68:71]
	v_mfma_f32_16x16x32_bf16 v[144:147], v[134:137], v[168:171], v[142:145]
	v_mfma_f32_16x16x32_bf16 v[140:143], v[160:163], v[168:171], v[138:141]
	v_mfma_f32_16x16x32_bf16 v[120:123], v[134:137], v[176:179], v[120:123]
	v_mfma_f32_16x16x32_bf16 v[116:119], v[160:163], v[176:179], v[116:119]
	v_mfma_f32_16x16x32_bf16 v[96:99], v[134:137], v[186:189], v[96:99]
	v_mfma_f32_16x16x32_bf16 v[92:95], v[160:163], v[186:189], v[92:95]
	v_mfma_f32_16x16x32_bf16 v[72:75], v[134:137], v[194:197], v[72:75]
	v_mfma_f32_16x16x32_bf16 v[68:71], v[160:163], v[194:197], v[68:71]
	s_barrier
	s_add_u32 s58, s56, 0x80
	s_mov_b32 m0, s21
	s_addc_u32 s59, s57, 0
	ds_read_b128 v[164:167], v209 offset:49152
	ds_read_b128 v[168:171], v209 offset:50176
	ds_read_b128 v[172:175], v209 offset:51200
	ds_read_b128 v[176:179], v209 offset:52224
	ds_read_b128 v[180:183], v209 offset:53248
	ds_read_b128 v[186:189], v209 offset:54272
	ds_read_b128 v[190:193], v209 offset:55296
	ds_read_b128 v[194:197], v209 offset:56320
	s_add_u32 s56, s56, 0x80080
	global_load_lds_dwordx4 v203, s[58:59]
	s_mov_b32 m0, s43
	s_addc_u32 s57, s57, 0
	global_load_lds_dwordx4 v205, s[58:59]
	s_mov_b32 m0, s45
	s_nop 0
	global_load_lds_dwordx4 v203, s[56:57]
	s_mov_b32 m0, s78
	s_nop 0
	global_load_lds_dwordx4 v205, s[56:57]
	s_mov_b32 m0, s67
	s_nop 0
	global_load_lds_dwordx4 v202, s[54:55]
	s_mov_b32 m0, s68
	s_nop 0
	global_load_lds_dwordx4 v204, s[54:55]
	s_waitcnt vmcnt(8)
	s_waitcnt lgkmcnt(0)
	s_barrier
	v_mfma_f32_16x16x32_bf16 v[64:67], v[60:63], v[164:167], v[64:67]
	v_mfma_f32_16x16x32_bf16 v[56:59], v[88:91], v[164:167], v[56:59]
	v_mfma_f32_16x16x32_bf16 v[44:47], v[60:63], v[172:175], v[44:47]
	v_mfma_f32_16x16x32_bf16 v[40:43], v[88:91], v[172:175], v[40:43]
	v_mfma_f32_16x16x32_bf16 v[28:31], v[60:63], v[180:183], v[28:31]
	v_mfma_f32_16x16x32_bf16 v[24:27], v[88:91], v[180:183], v[24:27]
	v_mfma_f32_16x16x32_bf16 v[12:15], v[60:63], v[190:193], v[12:15]
	v_mfma_f32_16x16x32_bf16 v[8:11], v[88:91], v[190:193], v[8:11]
	v_mfma_f32_16x16x32_bf16 v[64:67], v[84:87], v[168:171], v[64:67]
	v_mfma_f32_16x16x32_bf16 v[56:59], v[108:111], v[168:171], v[56:59]
	v_mfma_f32_16x16x32_bf16 v[44:47], v[84:87], v[176:179], v[44:47]
	v_mfma_f32_16x16x32_bf16 v[40:43], v[108:111], v[176:179], v[40:43]
	v_mfma_f32_16x16x32_bf16 v[28:31], v[84:87], v[186:189], v[28:31]
	v_mfma_f32_16x16x32_bf16 v[24:27], v[108:111], v[186:189], v[24:27]
	v_mfma_f32_16x16x32_bf16 v[12:15], v[84:87], v[194:197], v[12:15]
	v_mfma_f32_16x16x32_bf16 v[8:11], v[108:111], v[194:197], v[8:11]
	v_mfma_f32_16x16x32_bf16 v[52:55], v[112:115], v[164:167], v[52:55]
	v_mfma_f32_16x16x32_bf16 v[48:51], v[156:159], v[164:167], v[48:51]
	v_mfma_f32_16x16x32_bf16 v[36:39], v[112:115], v[172:175], v[36:39]
	v_mfma_f32_16x16x32_bf16 v[32:35], v[156:159], v[172:175], v[32:35]
	v_mfma_f32_16x16x32_bf16 v[20:23], v[112:115], v[180:183], v[20:23]
	v_mfma_f32_16x16x32_bf16 v[16:19], v[156:159], v[180:183], v[16:19]
	v_mfma_f32_16x16x32_bf16 v[4:7], v[112:115], v[190:193], v[4:7]
	v_mfma_f32_16x16x32_bf16 v[0:3], v[156:159], v[190:193], v[0:3]
	v_mfma_f32_16x16x32_bf16 v[52:55], v[134:137], v[168:171], v[52:55]
	v_mfma_f32_16x16x32_bf16 v[48:51], v[160:163], v[168:171], v[48:51]
	v_mfma_f32_16x16x32_bf16 v[36:39], v[134:137], v[176:179], v[36:39]
	v_mfma_f32_16x16x32_bf16 v[32:35], v[160:163], v[176:179], v[32:35]
	v_mfma_f32_16x16x32_bf16 v[20:23], v[134:137], v[186:189], v[20:23]
	v_mfma_f32_16x16x32_bf16 v[16:19], v[160:163], v[186:189], v[16:19]
	v_mfma_f32_16x16x32_bf16 v[4:7], v[134:137], v[194:197], v[4:7]
	v_mfma_f32_16x16x32_bf16 v[0:3], v[160:163], v[194:197], v[0:3]
	s_barrier
	s_add_i32 s84, s84, 2
	s_add_u32 s79, s79, 0x100
	s_addc_u32 s80, s80, 0
	s_add_u32 s81, s81, 0x100
	s_addc_u32 s83, s83, 0
	s_add_u32 s52, s52, 0x100
	s_addc_u32 s53, s53, 0
	s_cmp_gt_u32 s84, 29
	s_cbranch_scc0 .LBB0_2779
	s_and_b64 vcc, exec, s[34:35]
	s_cbranch_vccz .LBB0_2782
	s_barrier

.LBB0_2884:
	s_add_u32 s20, s46, 0x100
	s_addc_u32 s21, s47, 0
	s_waitcnt lgkmcnt(0)
	s_add_u32 s38, s44, 0x100
	s_addc_u32 s39, s45, 0
	s_barrier
	s_waitcnt lgkmcnt(0)
	v_mfma_f32_16x16x32_bf16 v[32:35], v[16:19], v[72:75], 0
	v_mfma_f32_16x16x32_bf16 v[36:39], v[24:27], v[72:75], 0
	v_mfma_f32_16x16x32_bf16 v[40:43], v[16:19], v[84:87], 0
	v_mfma_f32_16x16x32_bf16 v[44:47], v[24:27], v[84:87], 0
	v_mfma_f32_16x16x32_bf16 v[48:51], v[16:19], v[88:91], 0
	v_mfma_f32_16x16x32_bf16 v[52:55], v[24:27], v[88:91], 0
	v_mfma_f32_16x16x32_bf16 v[56:59], v[16:19], v[68:71], 0
	v_mfma_f32_16x16x32_bf16 v[60:63], v[24:27], v[68:71], 0
	v_mfma_f32_16x16x32_bf16 v[32:35], v[20:23], v[76:79], v[32:35]
	v_mfma_f32_16x16x32_bf16 v[36:39], v[28:31], v[76:79], v[36:39]
	v_mfma_f32_16x16x32_bf16 v[40:43], v[20:23], v[92:95], v[40:43]
	v_mfma_f32_16x16x32_bf16 v[44:47], v[28:31], v[92:95], v[44:47]
	v_mfma_f32_16x16x32_bf16 v[48:51], v[20:23], v[96:99], v[48:51]
	v_mfma_f32_16x16x32_bf16 v[52:55], v[28:31], v[96:99], v[52:55]
	v_mfma_f32_16x16x32_bf16 v[56:59], v[20:23], v[80:83], v[56:59]
	v_mfma_f32_16x16x32_bf16 v[60:63], v[28:31], v[80:83], v[60:63]
	v_mfma_f32_16x16x32_bf16 v[64:67], v[0:3], v[72:75], 0
	v_mfma_f32_16x16x32_bf16 v[72:75], v[8:11], v[72:75], 0
	v_mfma_f32_16x16x32_bf16 v[64:67], v[4:7], v[76:79], v[64:67]
	v_mfma_f32_16x16x32_bf16 v[72:75], v[12:15], v[76:79], v[72:75]
	v_mfma_f32_16x16x32_bf16 v[76:79], v[0:3], v[84:87], 0
	v_mfma_f32_16x16x32_bf16 v[84:87], v[8:11], v[84:87], 0
	v_mfma_f32_16x16x32_bf16 v[76:79], v[4:7], v[92:95], v[76:79]
	v_mfma_f32_16x16x32_bf16 v[84:87], v[12:15], v[92:95], v[84:87]
	v_mfma_f32_16x16x32_bf16 v[92:95], v[0:3], v[88:91], 0
	v_mfma_f32_16x16x32_bf16 v[88:91], v[8:11], v[88:91], 0
	v_mfma_f32_16x16x32_bf16 v[128:131], v[12:15], v[96:99], v[88:91]
	v_mfma_f32_16x16x32_bf16 v[88:91], v[0:3], v[68:71], 0
	v_mfma_f32_16x16x32_bf16 v[68:71], v[8:11], v[68:71], 0
	v_mfma_f32_16x16x32_bf16 v[92:95], v[4:7], v[96:99], v[92:95]
	v_mfma_f32_16x16x32_bf16 v[132:135], v[4:7], v[80:83], v[88:91]
	v_mfma_f32_16x16x32_bf16 v[136:139], v[12:15], v[80:83], v[68:71]
	s_barrier
	s_mov_b32 m0, s41
	ds_read_b128 v[108:111], v150 offset:16384
	ds_read_b128 v[112:115], v150 offset:17408
	ds_read_b128 v[100:103], v150 offset:18432
	ds_read_b128 v[104:107], v150 offset:19456
	ds_read_b128 v[88:91], v150 offset:20480
	ds_read_b128 v[96:99], v150 offset:21504
	ds_read_b128 v[68:71], v150 offset:22528
	ds_read_b128 v[80:83], v150 offset:23552
	global_load_lds_dwordx4 v144, s[38:39]
	s_mov_b32 m0, s43
	s_nop 0
	global_load_lds_dwordx4 v146, s[38:39]
	s_add_u32 s38, s44, 0x80100
	s_addc_u32 s39, s45, 0
	s_mov_b32 m0, s54
	s_and_b64 vcc, exec, s[36:37]
	global_load_lds_dwordx4 v144, s[38:39]
	s_mov_b32 m0, s55
	s_nop 0
	global_load_lds_dwordx4 v146, s[38:39]
	s_mov_b32 m0, s26
	s_mov_b64 s[38:39], -1
	global_load_lds_dwordx4 v143, s[20:21]
	s_mov_b32 m0, s56
	s_nop 0
	global_load_lds_dwordx4 v145, s[20:21]
	s_cbranch_vccz .LBB0_2886
	s_waitcnt vmcnt(8)
	s_mov_b64 s[38:39], 0

.LBB0_2888:
	s_ashr_i32 s7, s6, 31
	s_lshl_b64 s[20:21], s[6:7], 20
	s_add_u32 s36, s14, s20
	s_addc_u32 s37, s15, s21
	s_ashr_i32 s9, s8, 31
	s_lshl_b64 s[20:21], s[8:9], 20
	s_add_u32 s38, s17, s20
	s_addc_u32 s39, s24, s21
	s_add_u32 s48, s46, 0x180
	s_addc_u32 s49, s47, 0
	s_waitcnt lgkmcnt(0)
	s_and_b64 s[20:21], s[34:35], exec
	s_cselect_b32 s9, s39, s45
	s_cselect_b32 s12, s38, s44
	s_cselect_b32 s20, s37, s47
	s_cselect_b32 s21, s36, s46
	s_add_u32 s50, s44, 0x180
	s_addc_u32 s51, s45, 0
	s_barrier
	s_waitcnt lgkmcnt(0)
	v_mfma_f32_16x16x32_bf16 v[116:119], v[16:19], v[108:111], 0
	v_mfma_f32_16x16x32_bf16 v[154:157], v[20:23], v[112:115], v[116:119]
	v_mfma_f32_16x16x32_bf16 v[116:119], v[24:27], v[108:111], 0
	v_mfma_f32_16x16x32_bf16 v[158:161], v[28:31], v[112:115], v[116:119]
	v_mfma_f32_16x16x32_bf16 v[116:119], v[16:19], v[100:103], 0
	v_mfma_f32_16x16x32_bf16 v[162:165], v[20:23], v[104:107], v[116:119]
	v_mfma_f32_16x16x32_bf16 v[116:119], v[24:27], v[100:103], 0
	v_mfma_f32_16x16x32_bf16 v[166:169], v[28:31], v[104:107], v[116:119]
	v_mfma_f32_16x16x32_bf16 v[116:119], v[16:19], v[88:91], 0
	v_mfma_f32_16x16x32_bf16 v[16:19], v[16:19], v[68:71], 0
	v_mfma_f32_16x16x32_bf16 v[170:173], v[20:23], v[96:99], v[116:119]
	v_mfma_f32_16x16x32_bf16 v[116:119], v[24:27], v[88:91], 0
	v_mfma_f32_16x16x32_bf16 v[20:23], v[20:23], v[80:83], v[16:19]
	v_mfma_f32_16x16x32_bf16 v[16:19], v[24:27], v[68:71], 0
	v_mfma_f32_16x16x32_bf16 v[174:177], v[28:31], v[96:99], v[116:119]
	v_mfma_f32_16x16x32_bf16 v[28:31], v[28:31], v[80:83], v[16:19]
	v_mfma_f32_16x16x32_bf16 v[16:19], v[0:3], v[108:111], 0
	v_mfma_f32_16x16x32_bf16 v[178:181], v[4:7], v[112:115], v[16:19]
	v_mfma_f32_16x16x32_bf16 v[16:19], v[8:11], v[108:111], 0
	v_mfma_f32_16x16x32_bf16 v[182:185], v[12:15], v[112:115], v[16:19]
	v_mfma_f32_16x16x32_bf16 v[16:19], v[0:3], v[100:103], 0
	v_mfma_f32_16x16x32_bf16 v[186:189], v[4:7], v[104:107], v[16:19]
	v_mfma_f32_16x16x32_bf16 v[16:19], v[8:11], v[100:103], 0
	v_mfma_f32_16x16x32_bf16 v[190:193], v[12:15], v[104:107], v[16:19]
	v_mfma_f32_16x16x32_bf16 v[16:19], v[0:3], v[88:91], 0
	v_mfma_f32_16x16x32_bf16 v[0:3], v[0:3], v[68:71], 0
	v_mfma_f32_16x16x32_bf16 v[194:197], v[4:7], v[96:99], v[16:19]
	v_mfma_f32_16x16x32_bf16 v[16:19], v[8:11], v[88:91], 0
	v_mfma_f32_16x16x32_bf16 v[4:7], v[4:7], v[80:83], v[0:3]
	v_mfma_f32_16x16x32_bf16 v[0:3], v[8:11], v[68:71], 0
	v_mfma_f32_16x16x32_bf16 v[198:201], v[12:15], v[96:99], v[16:19]
	v_mfma_f32_16x16x32_bf16 v[202:205], v[12:15], v[80:83], v[0:3]
	s_barrier
	v_add_u32_e32 v152, s66, v147
	v_add_u32_e32 v153, s67, v147
	s_nop 1
	ds_read_b128 v[0:3], v152
	ds_read_b128 v[8:11], v152 offset:1024
	ds_read_b128 v[12:15], v152 offset:2048
	ds_read_b128 v[206:209], v152 offset:3072
	ds_read_b128 v[210:213], v153
	ds_read_b128 v[214:217], v153 offset:1024
	ds_read_b128 v[218:221], v153 offset:2048
	ds_read_b128 v[222:225], v153 offset:3072
	s_add_u32 s52, s46, 0x80100
	s_addc_u32 s53, s47, 0
	s_mov_b32 m0, s57
	ds_read_b128 v[16:19], v150 offset:32768
	ds_read_b128 v[24:27], v150 offset:33792
	ds_read_b128 v[100:103], v150 offset:34816
	ds_read_b128 v[226:229], v150 offset:35840
	ds_read_b128 v[230:233], v150 offset:36864
	ds_read_b128 v[234:237], v150 offset:37888
	ds_read_b128 v[238:241], v150 offset:38912
	ds_read_b128 v[242:245], v150 offset:39936
	global_load_lds_dwordx4 v143, s[52:53]
	s_mov_b32 m0, s58
	s_nop 0
	global_load_lds_dwordx4 v145, s[52:53]
	s_waitcnt vmcnt(8)
	s_waitcnt lgkmcnt(0)
	s_barrier
	v_mfma_f32_16x16x32_bf16 v[32:35], v[0:3], v[16:19], v[32:35]
	v_mfma_f32_16x16x32_bf16 v[120:123], v[8:11], v[24:27], v[32:35]
	v_mfma_f32_16x16x32_bf16 v[32:35], v[12:15], v[16:19], v[36:39]
	v_mfma_f32_16x16x32_bf16 v[112:115], v[206:209], v[24:27], v[32:35]
	v_mfma_f32_16x16x32_bf16 v[32:35], v[0:3], v[100:103], v[40:43]
	v_mfma_f32_16x16x32_bf16 v[104:107], v[8:11], v[226:229], v[32:35]
	v_mfma_f32_16x16x32_bf16 v[32:35], v[12:15], v[100:103], v[44:47]
	v_mfma_f32_16x16x32_bf16 v[96:99], v[206:209], v[226:229], v[32:35]
	v_mfma_f32_16x16x32_bf16 v[32:35], v[0:3], v[230:233], v[48:51]
	v_mfma_f32_16x16x32_bf16 v[88:91], v[8:11], v[234:237], v[32:35]
	v_mfma_f32_16x16x32_bf16 v[32:35], v[12:15], v[230:233], v[52:55]
	v_mfma_f32_16x16x32_bf16 v[80:83], v[206:209], v[234:237], v[32:35]
	v_mfma_f32_16x16x32_bf16 v[32:35], v[0:3], v[238:241], v[56:59]
	v_mfma_f32_16x16x32_bf16 v[68:71], v[8:11], v[242:245], v[32:35]
	v_mfma_f32_16x16x32_bf16 v[32:35], v[12:15], v[238:241], v[60:63]
	v_mfma_f32_16x16x32_bf16 v[52:55], v[206:209], v[242:245], v[32:35]
	v_mfma_f32_16x16x32_bf16 v[32:35], v[210:213], v[16:19], v[64:67]
	v_mfma_f32_16x16x32_bf16 v[16:19], v[218:221], v[16:19], v[72:75]
	v_mfma_f32_16x16x32_bf16 v[116:119], v[222:225], v[24:27], v[16:19]
	v_mfma_f32_16x16x32_bf16 v[16:19], v[210:213], v[100:103], v[76:79]
	v_mfma_f32_16x16x32_bf16 v[108:111], v[214:217], v[226:229], v[16:19]
	v_mfma_f32_16x16x32_bf16 v[16:19], v[218:221], v[100:103], v[84:87]
	v_mfma_f32_16x16x32_bf16 v[100:103], v[222:225], v[226:229], v[16:19]
	v_mfma_f32_16x16x32_bf16 v[16:19], v[210:213], v[230:233], v[92:95]
	v_mfma_f32_16x16x32_bf16 v[92:95], v[214:217], v[234:237], v[16:19]
	v_mfma_f32_16x16x32_bf16 v[16:19], v[218:221], v[230:233], v[128:131]
	v_mfma_f32_16x16x32_bf16 v[84:87], v[222:225], v[234:237], v[16:19]
	v_mfma_f32_16x16x32_bf16 v[16:19], v[210:213], v[238:241], v[132:135]
	v_mfma_f32_16x16x32_bf16 v[76:79], v[214:217], v[242:245], v[16:19]
	v_mfma_f32_16x16x32_bf16 v[16:19], v[218:221], v[238:241], v[136:139]
	v_mfma_f32_16x16x32_bf16 v[124:127], v[214:217], v[24:27], v[32:35]
	v_mfma_f32_16x16x32_bf16 v[60:63], v[222:225], v[242:245], v[16:19]
	s_barrier
	s_add_i32 s71, s66, s25
	s_mov_b32 m0, s71
	s_add_i32 s72, s71, 0x2000
	ds_read_b128 v[36:39], v150 offset:49152
	ds_read_b128 v[44:47], v150 offset:50176
	ds_read_b128 v[128:131], v150 offset:51200
	ds_read_b128 v[132:135], v150 offset:52224
	ds_read_b128 v[136:139], v150 offset:53248
	ds_read_b128 v[226:229], v150 offset:54272
	ds_read_b128 v[230:233], v150 offset:55296
	ds_read_b128 v[234:237], v150 offset:56320
	global_load_lds_dwordx4 v144, s[50:51]
	s_mov_b32 m0, s72
	s_nop 0
	global_load_lds_dwordx4 v146, s[50:51]
	s_add_u32 s50, s44, 0x80180
	s_addc_u32 s51, s45, 0
	s_add_i32 s73, s67, s25
	s_mov_b32 m0, s73
	s_add_i32 s74, s73, 0x2000
	s_nop 0
	global_load_lds_dwordx4 v144, s[50:51]
	s_mov_b32 m0, s74
	s_nop 0
	global_load_lds_dwordx4 v146, s[50:51]
	s_mov_b32 m0, s59
	s_nop 0
	global_load_lds_dwordx4 v143, s[48:49]
	s_mov_b32 m0, s60
	s_nop 0
	global_load_lds_dwordx4 v145, s[48:49]
	s_waitcnt vmcnt(8)
	s_waitcnt lgkmcnt(0)
	s_barrier
	v_mfma_f32_16x16x32_bf16 v[16:19], v[0:3], v[36:39], v[154:157]
	v_mfma_f32_16x16x32_bf16 v[64:67], v[8:11], v[44:47], v[16:19]
	v_mfma_f32_16x16x32_bf16 v[16:19], v[12:15], v[36:39], v[158:161]
	v_mfma_f32_16x16x32_bf16 v[48:51], v[206:209], v[44:47], v[16:19]
	v_mfma_f32_16x16x32_bf16 v[16:19], v[0:3], v[128:131], v[162:165]
	v_mfma_f32_16x16x32_bf16 v[40:43], v[8:11], v[132:135], v[16:19]
	v_mfma_f32_16x16x32_bf16 v[16:19], v[12:15], v[128:131], v[166:169]
	v_mfma_f32_16x16x32_bf16 v[32:35], v[206:209], v[132:135], v[16:19]
	v_mfma_f32_16x16x32_bf16 v[16:19], v[0:3], v[136:139], v[170:173]
	v_mfma_f32_16x16x32_bf16 v[0:3], v[0:3], v[230:233], v[20:23]
	v_mfma_f32_16x16x32_bf16 v[24:27], v[8:11], v[226:229], v[16:19]
	v_mfma_f32_16x16x32_bf16 v[16:19], v[12:15], v[136:139], v[174:177]
	v_mfma_f32_16x16x32_bf16 v[8:11], v[8:11], v[234:237], v[0:3]
	v_mfma_f32_16x16x32_bf16 v[0:3], v[12:15], v[230:233], v[28:31]
	v_mfma_f32_16x16x32_bf16 v[16:19], v[206:209], v[226:229], v[16:19]
	v_mfma_f32_16x16x32_bf16 v[0:3], v[206:209], v[234:237], v[0:3]
	v_mfma_f32_16x16x32_bf16 v[12:15], v[210:213], v[36:39], v[178:181]
	v_mfma_f32_16x16x32_bf16 v[72:75], v[214:217], v[44:47], v[12:15]
	v_mfma_f32_16x16x32_bf16 v[12:15], v[218:221], v[36:39], v[182:185]
	v_mfma_f32_16x16x32_bf16 v[56:59], v[222:225], v[44:47], v[12:15]
	v_mfma_f32_16x16x32_bf16 v[12:15], v[210:213], v[128:131], v[186:189]
	v_mfma_f32_16x16x32_bf16 v[44:47], v[214:217], v[132:135], v[12:15]
	v_mfma_f32_16x16x32_bf16 v[12:15], v[218:221], v[128:131], v[190:193]
	v_mfma_f32_16x16x32_bf16 v[36:39], v[222:225], v[132:135], v[12:15]
	v_mfma_f32_16x16x32_bf16 v[12:15], v[210:213], v[136:139], v[194:197]
	v_mfma_f32_16x16x32_bf16 v[28:31], v[214:217], v[226:229], v[12:15]
	v_mfma_f32_16x16x32_bf16 v[12:15], v[218:221], v[136:139], v[198:201]
	v_mfma_f32_16x16x32_bf16 v[4:7], v[210:213], v[230:233], v[4:7]
	v_mfma_f32_16x16x32_bf16 v[20:23], v[222:225], v[226:229], v[12:15]
	v_mfma_f32_16x16x32_bf16 v[12:15], v[214:217], v[234:237], v[4:7]
	v_mfma_f32_16x16x32_bf16 v[4:7], v[218:221], v[230:233], v[202:205]
	v_mfma_f32_16x16x32_bf16 v[4:7], v[222:225], v[234:237], v[4:7]
	s_barrier
	s_add_u32 s52, s46, 0x100
	s_addc_u32 s53, s47, 0
	s_add_u32 s75, s44, 0x200
	s_addc_u32 s76, s45, 0
	s_mov_b32 s77, 0
.LBB0_2889:
	s_add_u32 s44, s52, 0x100
	s_addc_u32 s45, s53, 0
	s_cmp_eq_u32 s77, 28
	s_cselect_b32 s50, s21, s44
	s_cselect_b32 s51, s20, s45
	s_cselect_b32 s48, s12, s75
	s_cselect_b32 s49, s9, s76
	s_add_u32 s46, s50, 0x80
	s_addc_u32 s47, s51, 0
	s_add_i32 s78, 0, 0x10000
	s_add_i32 s79, 0, 0x14000
	v_add_u32_e32 v154, s78, v147
	v_add_u32_e32 v170, s79, v147
	ds_read_b128 v[128:131], v154
	ds_read_b128 v[132:135], v154 offset:1024
	ds_read_b128 v[136:139], v154 offset:2048
	ds_read_b128 v[154:157], v154 offset:3072
	ds_read_b128 v[158:161], v170
	ds_read_b128 v[162:165], v170 offset:1024
	ds_read_b128 v[166:169], v170 offset:2048
	ds_read_b128 v[170:173], v170 offset:3072
	s_add_u32 s52, s52, 0x80080
	s_addc_u32 s53, s53, 0
	s_mov_b32 m0, s0
	ds_read_b128 v[174:177], v150
	ds_read_b128 v[178:181], v150 offset:1024
	ds_read_b128 v[182:185], v150 offset:2048
	ds_read_b128 v[186:189], v150 offset:3072
	ds_read_b128 v[190:193], v150 offset:4096
	ds_read_b128 v[194:197], v150 offset:5120
	ds_read_b128 v[198:201], v150 offset:6144
	ds_read_b128 v[202:205], v150 offset:7168
	global_load_lds_dwordx4 v143, s[52:53]
	s_mov_b32 m0, s1
	s_nop 0
	global_load_lds_dwordx4 v145, s[52:53]
	s_waitcnt vmcnt(8)
	s_waitcnt lgkmcnt(0)
	s_barrier
	v_mfma_f32_16x16x32_bf16 v[120:123], v[128:131], v[174:177], v[120:123]
	v_mfma_f32_16x16x32_bf16 v[112:115], v[136:139], v[174:177], v[112:115]
	v_mfma_f32_16x16x32_bf16 v[104:107], v[128:131], v[182:185], v[104:107]
	v_mfma_f32_16x16x32_bf16 v[96:99], v[136:139], v[182:185], v[96:99]
	v_mfma_f32_16x16x32_bf16 v[88:91], v[128:131], v[190:193], v[88:91]
	v_mfma_f32_16x16x32_bf16 v[80:83], v[136:139], v[190:193], v[80:83]
	v_mfma_f32_16x16x32_bf16 v[68:71], v[128:131], v[198:201], v[68:71]
	v_mfma_f32_16x16x32_bf16 v[52:55], v[136:139], v[198:201], v[52:55]
	v_mfma_f32_16x16x32_bf16 v[120:123], v[132:135], v[178:181], v[120:123]
	v_mfma_f32_16x16x32_bf16 v[112:115], v[154:157], v[178:181], v[112:115]
	v_mfma_f32_16x16x32_bf16 v[104:107], v[132:135], v[186:189], v[104:107]
	v_mfma_f32_16x16x32_bf16 v[96:99], v[154:157], v[186:189], v[96:99]
	v_mfma_f32_16x16x32_bf16 v[88:91], v[132:135], v[194:197], v[88:91]
	v_mfma_f32_16x16x32_bf16 v[80:83], v[154:157], v[194:197], v[80:83]
	v_mfma_f32_16x16x32_bf16 v[68:71], v[132:135], v[202:205], v[68:71]
	v_mfma_f32_16x16x32_bf16 v[52:55], v[154:157], v[202:205], v[52:55]
	v_mfma_f32_16x16x32_bf16 v[124:127], v[158:161], v[174:177], v[124:127]
	v_mfma_f32_16x16x32_bf16 v[116:119], v[166:169], v[174:177], v[116:119]
	v_mfma_f32_16x16x32_bf16 v[108:111], v[158:161], v[182:185], v[108:111]
	v_mfma_f32_16x16x32_bf16 v[100:103], v[166:169], v[182:185], v[100:103]
	v_mfma_f32_16x16x32_bf16 v[92:95], v[158:161], v[190:193], v[92:95]
	v_mfma_f32_16x16x32_bf16 v[84:87], v[166:169], v[190:193], v[84:87]
	v_mfma_f32_16x16x32_bf16 v[76:79], v[158:161], v[198:201], v[76:79]
	v_mfma_f32_16x16x32_bf16 v[60:63], v[166:169], v[198:201], v[60:63]
	v_mfma_f32_16x16x32_bf16 v[124:127], v[162:165], v[178:181], v[124:127]
	v_mfma_f32_16x16x32_bf16 v[116:119], v[170:173], v[178:181], v[116:119]
	v_mfma_f32_16x16x32_bf16 v[108:111], v[162:165], v[186:189], v[108:111]
	v_mfma_f32_16x16x32_bf16 v[100:103], v[170:173], v[186:189], v[100:103]
	v_mfma_f32_16x16x32_bf16 v[92:95], v[162:165], v[194:197], v[92:95]
	v_mfma_f32_16x16x32_bf16 v[84:87], v[170:173], v[194:197], v[84:87]
	v_mfma_f32_16x16x32_bf16 v[76:79], v[162:165], v[202:205], v[76:79]
	v_mfma_f32_16x16x32_bf16 v[60:63], v[170:173], v[202:205], v[60:63]
	s_barrier
	s_add_i32 s52, s78, s25
	s_mov_b32 m0, s52
	ds_read_b128 v[174:177], v150 offset:16384
	ds_read_b128 v[178:181], v150 offset:17408
	ds_read_b128 v[182:185], v150 offset:18432
	ds_read_b128 v[186:189], v150 offset:19456
	ds_read_b128 v[190:193], v150 offset:20480
	ds_read_b128 v[194:197], v150 offset:21504
	ds_read_b128 v[198:201], v150 offset:22528
	ds_read_b128 v[202:205], v150 offset:23552
	global_load_lds_dwordx4 v144, s[48:49]
	s_add_i32 m0, s52, 0x2000
	s_add_u32 s52, s48, 0x80000
	s_addc_u32 s53, s49, 0
	s_add_i32 s78, s79, s25
	s_nop 0
	global_load_lds_dwordx4 v146, s[48:49]
	s_mov_b32 m0, s78
	s_nop 0
	global_load_lds_dwordx4 v144, s[52:53]
	s_add_i32 m0, s78, 0x2000
	s_nop 0
	global_load_lds_dwordx4 v146, s[52:53]
	s_mov_b32 m0, s26
	s_nop 0
	global_load_lds_dwordx4 v143, s[50:51]
	s_mov_b32 m0, s56
	s_nop 0
	global_load_lds_dwordx4 v145, s[50:51]
	s_waitcnt vmcnt(8)
	s_waitcnt lgkmcnt(0)
	s_barrier
	v_mfma_f32_16x16x32_bf16 v[64:67], v[128:131], v[174:177], v[64:67]
	v_mfma_f32_16x16x32_bf16 v[48:51], v[136:139], v[174:177], v[48:51]
	v_mfma_f32_16x16x32_bf16 v[40:43], v[128:131], v[182:185], v[40:43]
	v_mfma_f32_16x16x32_bf16 v[32:35], v[136:139], v[182:185], v[32:35]
	v_mfma_f32_16x16x32_bf16 v[24:27], v[128:131], v[190:193], v[24:27]
	v_mfma_f32_16x16x32_bf16 v[16:19], v[136:139], v[190:193], v[16:19]
	v_mfma_f32_16x16x32_bf16 v[8:11], v[128:131], v[198:201], v[8:11]
	v_mfma_f32_16x16x32_bf16 v[0:3], v[136:139], v[198:201], v[0:3]
	v_mfma_f32_16x16x32_bf16 v[64:67], v[132:135], v[178:181], v[64:67]
	v_mfma_f32_16x16x32_bf16 v[48:51], v[154:157], v[178:181], v[48:51]
	v_mfma_f32_16x16x32_bf16 v[40:43], v[132:135], v[186:189], v[40:43]
	v_mfma_f32_16x16x32_bf16 v[32:35], v[154:157], v[186:189], v[32:35]
	v_mfma_f32_16x16x32_bf16 v[24:27], v[132:135], v[194:197], v[24:27]
	v_mfma_f32_16x16x32_bf16 v[16:19], v[154:157], v[194:197], v[16:19]
	v_mfma_f32_16x16x32_bf16 v[8:11], v[132:135], v[202:205], v[8:11]
	v_mfma_f32_16x16x32_bf16 v[0:3], v[154:157], v[202:205], v[0:3]
	v_mfma_f32_16x16x32_bf16 v[72:75], v[158:161], v[174:177], v[72:75]
	v_mfma_f32_16x16x32_bf16 v[56:59], v[166:169], v[174:177], v[56:59]
	v_mfma_f32_16x16x32_bf16 v[44:47], v[158:161], v[182:185], v[44:47]
	v_mfma_f32_16x16x32_bf16 v[36:39], v[166:169], v[182:185], v[36:39]
	v_mfma_f32_16x16x32_bf16 v[28:31], v[158:161], v[190:193], v[28:31]
	v_mfma_f32_16x16x32_bf16 v[20:23], v[166:169], v[190:193], v[20:23]
	v_mfma_f32_16x16x32_bf16 v[12:15], v[158:161], v[198:201], v[12:15]
	v_mfma_f32_16x16x32_bf16 v[4:7], v[166:169], v[198:201], v[4:7]
	v_mfma_f32_16x16x32_bf16 v[72:75], v[162:165], v[178:181], v[72:75]
	v_mfma_f32_16x16x32_bf16 v[56:59], v[170:173], v[178:181], v[56:59]
	v_mfma_f32_16x16x32_bf16 v[44:47], v[162:165], v[186:189], v[44:47]
	v_mfma_f32_16x16x32_bf16 v[36:39], v[170:173], v[186:189], v[36:39]
	v_mfma_f32_16x16x32_bf16 v[28:31], v[162:165], v[194:197], v[28:31]
	v_mfma_f32_16x16x32_bf16 v[20:23], v[170:173], v[194:197], v[20:23]
	v_mfma_f32_16x16x32_bf16 v[12:15], v[162:165], v[202:205], v[12:15]
	v_mfma_f32_16x16x32_bf16 v[4:7], v[170:173], v[202:205], v[4:7]
	s_barrier
	ds_read_b128 v[128:131], v152
	ds_read_b128 v[132:135], v152 offset:1024
	ds_read_b128 v[136:139], v152 offset:2048
	ds_read_b128 v[154:157], v152 offset:3072
	ds_read_b128 v[158:161], v153
	ds_read_b128 v[162:165], v153 offset:1024
	ds_read_b128 v[166:169], v153 offset:2048
	ds_read_b128 v[170:173], v153 offset:3072
	s_add_u32 s50, s50, 0x80000
	s_addc_u32 s51, s51, 0
	s_mov_b32 m0, s57
	ds_read_b128 v[174:177], v150 offset:32768
	ds_read_b128 v[178:181], v150 offset:33792
	ds_read_b128 v[182:185], v150 offset:34816
	ds_read_b128 v[186:189], v150 offset:35840
	ds_read_b128 v[190:193], v150 offset:36864
	ds_read_b128 v[194:197], v150 offset:37888
	ds_read_b128 v[198:201], v150 offset:38912
	ds_read_b128 v[202:205], v150 offset:39936
	global_load_lds_dwordx4 v143, s[50:51]
	s_mov_b32 m0, s58
	s_nop 0
	global_load_lds_dwordx4 v145, s[50:51]
	s_waitcnt vmcnt(8)
	s_waitcnt lgkmcnt(0)
	s_barrier
	v_mfma_f32_16x16x32_bf16 v[120:123], v[128:131], v[174:177], v[120:123]
	v_mfma_f32_16x16x32_bf16 v[112:115], v[136:139], v[174:177], v[112:115]
	v_mfma_f32_16x16x32_bf16 v[104:107], v[128:131], v[182:185], v[104:107]
	v_mfma_f32_16x16x32_bf16 v[96:99], v[136:139], v[182:185], v[96:99]
	v_mfma_f32_16x16x32_bf16 v[88:91], v[128:131], v[190:193], v[88:91]
	v_mfma_f32_16x16x32_bf16 v[80:83], v[136:139], v[190:193], v[80:83]
	v_mfma_f32_16x16x32_bf16 v[68:71], v[128:131], v[198:201], v[68:71]
	v_mfma_f32_16x16x32_bf16 v[52:55], v[136:139], v[198:201], v[52:55]
	v_mfma_f32_16x16x32_bf16 v[120:123], v[132:135], v[178:181], v[120:123]
	v_mfma_f32_16x16x32_bf16 v[112:115], v[154:157], v[178:181], v[112:115]
	v_mfma_f32_16x16x32_bf16 v[104:107], v[132:135], v[186:189], v[104:107]
	v_mfma_f32_16x16x32_bf16 v[96:99], v[154:157], v[186:189], v[96:99]
	v_mfma_f32_16x16x32_bf16 v[88:91], v[132:135], v[194:197], v[88:91]
	v_mfma_f32_16x16x32_bf16 v[80:83], v[154:157], v[194:197], v[80:83]
	v_mfma_f32_16x16x32_bf16 v[68:71], v[132:135], v[202:205], v[68:71]
	v_mfma_f32_16x16x32_bf16 v[52:55], v[154:157], v[202:205], v[52:55]
	v_mfma_f32_16x16x32_bf16 v[124:127], v[158:161], v[174:177], v[124:127]
	v_mfma_f32_16x16x32_bf16 v[116:119], v[166:169], v[174:177], v[116:119]
	v_mfma_f32_16x16x32_bf16 v[108:111], v[158:161], v[182:185], v[108:111]
	v_mfma_f32_16x16x32_bf16 v[100:103], v[166:169], v[182:185], v[100:103]
	v_mfma_f32_16x16x32_bf16 v[92:95], v[158:161], v[190:193], v[92:95]
	v_mfma_f32_16x16x32_bf16 v[84:87], v[166:169], v[190:193], v[84:87]
	v_mfma_f32_16x16x32_bf16 v[76:79], v[158:161], v[198:201], v[76:79]
	v_mfma_f32_16x16x32_bf16 v[60:63], v[166:169], v[198:201], v[60:63]
	v_mfma_f32_16x16x32_bf16 v[124:127], v[162:165], v[178:181], v[124:127]
	v_mfma_f32_16x16x32_bf16 v[116:119], v[170:173], v[178:181], v[116:119]
	v_mfma_f32_16x16x32_bf16 v[108:111], v[162:165], v[186:189], v[108:111]
	v_mfma_f32_16x16x32_bf16 v[100:103], v[170:173], v[186:189], v[100:103]
	v_mfma_f32_16x16x32_bf16 v[92:95], v[162:165], v[194:197], v[92:95]
	v_mfma_f32_16x16x32_bf16 v[84:87], v[170:173], v[194:197], v[84:87]
	v_mfma_f32_16x16x32_bf16 v[76:79], v[162:165], v[202:205], v[76:79]
	v_mfma_f32_16x16x32_bf16 v[60:63], v[170:173], v[202:205], v[60:63]
	s_barrier
	s_add_u32 s50, s48, 0x80
	s_mov_b32 m0, s71
	s_addc_u32 s51, s49, 0
	ds_read_b128 v[174:177], v150 offset:49152
	ds_read_b128 v[178:181], v150 offset:50176
	ds_read_b128 v[182:185], v150 offset:51200
	ds_read_b128 v[186:189], v150 offset:52224
	ds_read_b128 v[190:193], v150 offset:53248
	ds_read_b128 v[194:197], v150 offset:54272
	ds_read_b128 v[198:201], v150 offset:55296
	ds_read_b128 v[202:205], v150 offset:56320
	s_add_u32 s48, s48, 0x80080
	global_load_lds_dwordx4 v144, s[50:51]
	s_mov_b32 m0, s72
	s_addc_u32 s49, s49, 0
	global_load_lds_dwordx4 v146, s[50:51]
	s_mov_b32 m0, s73
	s_nop 0
	global_load_lds_dwordx4 v144, s[48:49]
	s_mov_b32 m0, s74
	s_nop 0
	global_load_lds_dwordx4 v146, s[48:49]
	s_mov_b32 m0, s59
	s_nop 0
	global_load_lds_dwordx4 v143, s[46:47]
	s_mov_b32 m0, s60
	s_nop 0
	global_load_lds_dwordx4 v145, s[46:47]
	s_waitcnt vmcnt(8)
	s_waitcnt lgkmcnt(0)
	s_barrier
	v_mfma_f32_16x16x32_bf16 v[64:67], v[128:131], v[174:177], v[64:67]
	v_mfma_f32_16x16x32_bf16 v[48:51], v[136:139], v[174:177], v[48:51]
	v_mfma_f32_16x16x32_bf16 v[40:43], v[128:131], v[182:185], v[40:43]
	v_mfma_f32_16x16x32_bf16 v[32:35], v[136:139], v[182:185], v[32:35]
	v_mfma_f32_16x16x32_bf16 v[24:27], v[128:131], v[190:193], v[24:27]
	v_mfma_f32_16x16x32_bf16 v[16:19], v[136:139], v[190:193], v[16:19]
	v_mfma_f32_16x16x32_bf16 v[8:11], v[128:131], v[198:201], v[8:11]
	v_mfma_f32_16x16x32_bf16 v[0:3], v[136:139], v[198:201], v[0:3]
	v_mfma_f32_16x16x32_bf16 v[64:67], v[132:135], v[178:181], v[64:67]
	v_mfma_f32_16x16x32_bf16 v[48:51], v[154:157], v[178:181], v[48:51]
	v_mfma_f32_16x16x32_bf16 v[40:43], v[132:135], v[186:189], v[40:43]
	v_mfma_f32_16x16x32_bf16 v[32:35], v[154:157], v[186:189], v[32:35]
	v_mfma_f32_16x16x32_bf16 v[24:27], v[132:135], v[194:197], v[24:27]
	v_mfma_f32_16x16x32_bf16 v[16:19], v[154:157], v[194:197], v[16:19]
	v_mfma_f32_16x16x32_bf16 v[8:11], v[132:135], v[202:205], v[8:11]
	v_mfma_f32_16x16x32_bf16 v[0:3], v[154:157], v[202:205], v[0:3]
	v_mfma_f32_16x16x32_bf16 v[72:75], v[158:161], v[174:177], v[72:75]
	v_mfma_f32_16x16x32_bf16 v[56:59], v[166:169], v[174:177], v[56:59]
	v_mfma_f32_16x16x32_bf16 v[44:47], v[158:161], v[182:185], v[44:47]
	v_mfma_f32_16x16x32_bf16 v[36:39], v[166:169], v[182:185], v[36:39]
	v_mfma_f32_16x16x32_bf16 v[28:31], v[158:161], v[190:193], v[28:31]
	v_mfma_f32_16x16x32_bf16 v[20:23], v[166:169], v[190:193], v[20:23]
	v_mfma_f32_16x16x32_bf16 v[12:15], v[158:161], v[198:201], v[12:15]
	v_mfma_f32_16x16x32_bf16 v[4:7], v[166:169], v[198:201], v[4:7]
	v_mfma_f32_16x16x32_bf16 v[72:75], v[162:165], v[178:181], v[72:75]
	v_mfma_f32_16x16x32_bf16 v[56:59], v[170:173], v[178:181], v[56:59]
	v_mfma_f32_16x16x32_bf16 v[44:47], v[162:165], v[186:189], v[44:47]
	v_mfma_f32_16x16x32_bf16 v[36:39], v[170:173], v[186:189], v[36:39]
	v_mfma_f32_16x16x32_bf16 v[28:31], v[162:165], v[194:197], v[28:31]
	v_mfma_f32_16x16x32_bf16 v[20:23], v[170:173], v[194:197], v[20:23]
	v_mfma_f32_16x16x32_bf16 v[12:15], v[162:165], v[202:205], v[12:15]
	v_mfma_f32_16x16x32_bf16 v[4:7], v[170:173], v[202:205], v[4:7]
	s_barrier
	s_add_i32 s77, s77, 2
	s_add_u32 s75, s75, 0x100
	s_addc_u32 s76, s76, 0
	s_cmp_gt_u32 s77, 29
	s_mov_b64 s[52:53], s[44:45]
	s_cbranch_scc0 .LBB0_2889
	s_and_b64 vcc, exec, s[4:5]
	s_cbranch_vccz .LBB0_2892
	s_barrier

.LBB0_2982:
	s_add_u32 s20, s48, 0x100
	s_addc_u32 s21, s49, 0
	s_waitcnt lgkmcnt(0)
	s_add_u32 s52, s4, 0x100
	s_addc_u32 s53, s5, 0
	s_barrier
	s_waitcnt lgkmcnt(0)
	v_mfma_f32_16x16x32_bf16 v[32:35], v[16:19], v[68:71], 0
	v_mfma_f32_16x16x32_bf16 v[36:39], v[24:27], v[68:71], 0
	v_mfma_f32_16x16x32_bf16 v[40:43], v[16:19], v[84:87], 0
	v_mfma_f32_16x16x32_bf16 v[44:47], v[24:27], v[84:87], 0
	v_mfma_f32_16x16x32_bf16 v[48:51], v[16:19], v[92:95], 0
	v_mfma_f32_16x16x32_bf16 v[52:55], v[24:27], v[92:95], 0
	v_mfma_f32_16x16x32_bf16 v[56:59], v[16:19], v[76:79], 0
	v_mfma_f32_16x16x32_bf16 v[60:63], v[24:27], v[76:79], 0
	v_mfma_f32_16x16x32_bf16 v[138:141], v[20:23], v[72:75], v[32:35]
	v_mfma_f32_16x16x32_bf16 v[36:39], v[28:31], v[72:75], v[36:39]
	v_mfma_f32_16x16x32_bf16 v[40:43], v[20:23], v[88:91], v[40:43]
	v_mfma_f32_16x16x32_bf16 v[44:47], v[28:31], v[88:91], v[44:47]
	v_mfma_f32_16x16x32_bf16 v[48:51], v[20:23], v[96:99], v[48:51]
	v_mfma_f32_16x16x32_bf16 v[52:55], v[28:31], v[96:99], v[52:55]
	v_mfma_f32_16x16x32_bf16 v[56:59], v[20:23], v[80:83], v[56:59]
	v_mfma_f32_16x16x32_bf16 v[60:63], v[28:31], v[80:83], v[60:63]
	v_mfma_f32_16x16x32_bf16 v[64:67], v[0:3], v[68:71], 0
	v_mfma_f32_16x16x32_bf16 v[68:71], v[8:11], v[68:71], 0
	v_mfma_f32_16x16x32_bf16 v[64:67], v[4:7], v[72:75], v[64:67]
	v_mfma_f32_16x16x32_bf16 v[68:71], v[12:15], v[72:75], v[68:71]
	v_mfma_f32_16x16x32_bf16 v[72:75], v[0:3], v[84:87], 0
	v_mfma_f32_16x16x32_bf16 v[84:87], v[8:11], v[84:87], 0
	v_mfma_f32_16x16x32_bf16 v[72:75], v[4:7], v[88:91], v[72:75]
	v_mfma_f32_16x16x32_bf16 v[84:87], v[12:15], v[88:91], v[84:87]
	v_mfma_f32_16x16x32_bf16 v[88:91], v[0:3], v[92:95], 0
	v_mfma_f32_16x16x32_bf16 v[92:95], v[8:11], v[92:95], 0
	v_mfma_f32_16x16x32_bf16 v[88:91], v[4:7], v[96:99], v[88:91]
	v_mfma_f32_16x16x32_bf16 v[92:95], v[12:15], v[96:99], v[92:95]
	v_mfma_f32_16x16x32_bf16 v[96:99], v[0:3], v[76:79], 0
	v_mfma_f32_16x16x32_bf16 v[76:79], v[8:11], v[76:79], 0
	v_mfma_f32_16x16x32_bf16 v[108:111], v[4:7], v[80:83], v[96:99]
	v_mfma_f32_16x16x32_bf16 v[112:115], v[12:15], v[80:83], v[76:79]
	s_barrier
	s_mov_b32 m0, s27
	ds_read_b128 v[120:123], v209 offset:16384
	ds_read_b128 v[124:127], v209 offset:17408
	ds_read_b128 v[104:107], v209 offset:18432
	ds_read_b128 v[116:119], v209 offset:19456
	ds_read_b128 v[96:99], v209 offset:20480
	ds_read_b128 v[100:103], v209 offset:21504
	ds_read_b128 v[76:79], v209 offset:22528
	ds_read_b128 v[80:83], v209 offset:23552
	global_load_lds_dwordx4 v203, s[52:53]
	s_mov_b32 m0, s54
	s_nop 0
	global_load_lds_dwordx4 v205, s[52:53]
	s_add_u32 s52, s4, 0x160100
	s_addc_u32 s53, s5, 0
	s_mov_b32 m0, s55
	s_and_b64 vcc, exec, s[50:51]
	global_load_lds_dwordx4 v203, s[52:53]
	s_mov_b32 m0, s56
	s_nop 0
	global_load_lds_dwordx4 v205, s[52:53]
	s_mov_b32 m0, s26
	s_mov_b64 s[52:53], -1
	global_load_lds_dwordx4 v202, s[20:21]
	s_mov_b32 m0, s57
	s_nop 0
	global_load_lds_dwordx4 v204, s[20:21]
	s_cbranch_vccz .LBB0_2984
	s_waitcnt vmcnt(8)
	s_mov_b64 s[52:53], 0

.LBB0_2986:
	s_add_u32 s50, s48, 0x180
	s_waitcnt lgkmcnt(0)
	s_addc_u32 s51, s49, 0
	s_add_u32 s52, s4, 0x180
	s_addc_u32 s53, s5, 0
	s_barrier
	s_waitcnt lgkmcnt(0)
	v_mfma_f32_16x16x32_bf16 v[128:131], v[16:19], v[120:123], 0
	v_mfma_f32_16x16x32_bf16 v[134:137], v[20:23], v[124:127], v[128:131]
	v_mfma_f32_16x16x32_bf16 v[128:131], v[24:27], v[120:123], 0
	v_mfma_f32_16x16x32_bf16 v[156:159], v[28:31], v[124:127], v[128:131]
	v_mfma_f32_16x16x32_bf16 v[128:131], v[16:19], v[104:107], 0
	v_mfma_f32_16x16x32_bf16 v[160:163], v[20:23], v[116:119], v[128:131]
	v_mfma_f32_16x16x32_bf16 v[128:131], v[24:27], v[104:107], 0
	v_mfma_f32_16x16x32_bf16 v[164:167], v[28:31], v[116:119], v[128:131]
	v_mfma_f32_16x16x32_bf16 v[128:131], v[16:19], v[96:99], 0
	v_mfma_f32_16x16x32_bf16 v[16:19], v[16:19], v[76:79], 0
	v_mfma_f32_16x16x32_bf16 v[168:171], v[20:23], v[100:103], v[128:131]
	v_mfma_f32_16x16x32_bf16 v[16:19], v[20:23], v[80:83], v[16:19]
	v_mfma_f32_16x16x32_bf16 v[20:23], v[24:27], v[76:79], 0
	v_mfma_f32_16x16x32_bf16 v[128:131], v[24:27], v[96:99], 0
	v_mfma_f32_16x16x32_bf16 v[20:23], v[28:31], v[80:83], v[20:23]
	v_mfma_f32_16x16x32_bf16 v[172:175], v[28:31], v[100:103], v[128:131]
	v_mfma_f32_16x16x32_bf16 v[24:27], v[0:3], v[120:123], 0
	v_mfma_f32_16x16x32_bf16 v[176:179], v[4:7], v[124:127], v[24:27]
	v_mfma_f32_16x16x32_bf16 v[24:27], v[8:11], v[120:123], 0
	v_mfma_f32_16x16x32_bf16 v[180:183], v[12:15], v[124:127], v[24:27]
	v_mfma_f32_16x16x32_bf16 v[24:27], v[0:3], v[104:107], 0
	v_mfma_f32_16x16x32_bf16 v[186:189], v[4:7], v[116:119], v[24:27]
	v_mfma_f32_16x16x32_bf16 v[24:27], v[8:11], v[104:107], 0
	v_mfma_f32_16x16x32_bf16 v[190:193], v[12:15], v[116:119], v[24:27]
	v_mfma_f32_16x16x32_bf16 v[24:27], v[0:3], v[96:99], 0
	v_mfma_f32_16x16x32_bf16 v[0:3], v[0:3], v[76:79], 0
	v_mfma_f32_16x16x32_bf16 v[194:197], v[4:7], v[100:103], v[24:27]
	v_mfma_f32_16x16x32_bf16 v[24:27], v[8:11], v[96:99], 0
	v_mfma_f32_16x16x32_bf16 v[0:3], v[4:7], v[80:83], v[0:3]
	v_mfma_f32_16x16x32_bf16 v[4:7], v[8:11], v[76:79], 0
	v_mfma_f32_16x16x32_bf16 v[198:201], v[12:15], v[100:103], v[24:27]
	v_mfma_f32_16x16x32_bf16 v[212:215], v[12:15], v[80:83], v[4:7]
	s_barrier
	v_add_u32_e32 v132, s67, v206
	v_add_u32_e32 v133, s68, v206
	s_nop 1
	ds_read_b128 v[4:7], v132
	ds_read_b128 v[8:11], v132 offset:1024
	ds_read_b128 v[216:219], v132 offset:2048
	ds_read_b128 v[220:223], v132 offset:3072
	ds_read_b128 v[224:227], v133
	ds_read_b128 v[228:231], v133 offset:1024
	ds_read_b128 v[232:235], v133 offset:2048
	ds_read_b128 v[236:239], v133 offset:3072
	s_add_u32 s20, s48, 0x160100
	s_addc_u32 s21, s49, 0
	s_mov_b32 m0, s58
	ds_read_b128 v[12:15], v209 offset:32768
	ds_read_b128 v[24:27], v209 offset:33792
	ds_read_b128 v[28:31], v209 offset:34816
	ds_read_b128 v[96:99], v209 offset:35840
	ds_read_b128 v[240:243], v209 offset:36864
	ds_read_b128 v[244:247], v209 offset:37888
	ds_read_b128 v[248:251], v209 offset:38912
	ds_read_b128 v[32:35], v209 offset:39936
	global_load_lds_dwordx4 v202, s[20:21]
	s_mov_b32 m0, s59
	s_nop 0
	global_load_lds_dwordx4 v204, s[20:21]
	s_waitcnt vmcnt(8)
	s_waitcnt lgkmcnt(0)
	s_barrier
	v_mfma_f32_16x16x32_bf16 v[36:39], v[216:219], v[12:15], v[36:39]
	v_mfma_f32_16x16x32_bf16 v[148:151], v[220:223], v[24:27], v[36:39]
	v_mfma_f32_16x16x32_bf16 v[36:39], v[4:7], v[28:31], v[40:43]
	v_mfma_f32_16x16x32_bf16 v[128:131], v[8:11], v[96:99], v[36:39]
	v_mfma_f32_16x16x32_bf16 v[36:39], v[216:219], v[28:31], v[44:47]
	v_mfma_f32_16x16x32_bf16 v[124:127], v[220:223], v[96:99], v[36:39]
	v_mfma_f32_16x16x32_bf16 v[36:39], v[4:7], v[240:243], v[48:51]
	v_mfma_f32_16x16x32_bf16 v[104:107], v[8:11], v[244:247], v[36:39]
	v_mfma_f32_16x16x32_bf16 v[36:39], v[216:219], v[240:243], v[52:55]
	v_mfma_f32_16x16x32_bf16 v[100:103], v[220:223], v[244:247], v[36:39]
	v_mfma_f32_16x16x32_bf16 v[36:39], v[4:7], v[248:251], v[56:59]
	v_mfma_f32_16x16x32_bf16 v[76:79], v[4:7], v[12:15], v[138:141]
	v_mfma_f32_16x16x32_bf16 v[80:83], v[8:11], v[32:35], v[36:39]
	v_mfma_f32_16x16x32_bf16 v[36:39], v[216:219], v[248:251], v[60:63]
	v_mfma_f32_16x16x32_bf16 v[152:155], v[8:11], v[24:27], v[76:79]
	v_mfma_f32_16x16x32_bf16 v[76:79], v[220:223], v[32:35], v[36:39]
	v_mfma_f32_16x16x32_bf16 v[36:39], v[224:227], v[12:15], v[64:67]
	v_mfma_f32_16x16x32_bf16 v[12:15], v[232:235], v[12:15], v[68:71]
	v_mfma_f32_16x16x32_bf16 v[140:143], v[236:239], v[24:27], v[12:15]
	v_mfma_f32_16x16x32_bf16 v[12:15], v[224:227], v[28:31], v[72:75]
	v_mfma_f32_16x16x32_bf16 v[120:123], v[228:231], v[96:99], v[12:15]
	v_mfma_f32_16x16x32_bf16 v[12:15], v[232:235], v[28:31], v[84:87]
	v_mfma_f32_16x16x32_bf16 v[116:119], v[236:239], v[96:99], v[12:15]
	v_mfma_f32_16x16x32_bf16 v[12:15], v[224:227], v[240:243], v[88:91]
	v_mfma_f32_16x16x32_bf16 v[96:99], v[228:231], v[244:247], v[12:15]
	v_mfma_f32_16x16x32_bf16 v[12:15], v[232:235], v[240:243], v[92:95]
	v_mfma_f32_16x16x32_bf16 v[92:95], v[236:239], v[244:247], v[12:15]
	v_mfma_f32_16x16x32_bf16 v[12:15], v[224:227], v[248:251], v[108:111]
	v_mfma_f32_16x16x32_bf16 v[72:75], v[228:231], v[32:35], v[12:15]
	v_mfma_f32_16x16x32_bf16 v[12:15], v[232:235], v[248:251], v[112:115]
	v_mfma_f32_16x16x32_bf16 v[144:147], v[228:231], v[24:27], v[36:39]
	v_mfma_f32_16x16x32_bf16 v[68:71], v[236:239], v[32:35], v[12:15]
	s_barrier
	s_add_i32 s12, s67, s25
	s_mov_b32 m0, s12
	s_add_i32 s20, s12, 0x2000
	ds_read_b128 v[32:35], v209 offset:49152
	ds_read_b128 v[36:39], v209 offset:50176
	ds_read_b128 v[60:63], v209 offset:51200
	ds_read_b128 v[84:87], v209 offset:52224
	ds_read_b128 v[88:91], v209 offset:53248
	ds_read_b128 v[108:111], v209 offset:54272
	ds_read_b128 v[112:115], v209 offset:55296
	ds_read_b128 v[240:243], v209 offset:56320
	global_load_lds_dwordx4 v203, s[52:53]
	s_mov_b32 m0, s20
	s_nop 0
	global_load_lds_dwordx4 v205, s[52:53]
	s_add_u32 s52, s4, 0x160180
	s_addc_u32 s53, s5, 0
	s_add_i32 s21, s68, s25
	s_mov_b32 m0, s21
	s_add_i32 s72, s21, 0x2000
	s_nop 0
	global_load_lds_dwordx4 v203, s[52:53]
	s_mov_b32 m0, s72
	s_nop 0
	global_load_lds_dwordx4 v205, s[52:53]
	s_mov_b32 m0, s60
	s_nop 0
	global_load_lds_dwordx4 v202, s[50:51]
	s_mov_b32 m0, s61
	s_nop 0
	global_load_lds_dwordx4 v204, s[50:51]
	s_waitcnt vmcnt(8)
	s_waitcnt lgkmcnt(0)
	s_barrier
	v_mfma_f32_16x16x32_bf16 v[12:15], v[4:7], v[32:35], v[134:137]
	v_mfma_f32_16x16x32_bf16 v[64:67], v[8:11], v[36:39], v[12:15]
	v_mfma_f32_16x16x32_bf16 v[12:15], v[216:219], v[32:35], v[156:159]
	v_mfma_f32_16x16x32_bf16 v[56:59], v[220:223], v[36:39], v[12:15]
	v_mfma_f32_16x16x32_bf16 v[12:15], v[4:7], v[60:63], v[160:163]
	v_mfma_f32_16x16x32_bf16 v[44:47], v[8:11], v[84:87], v[12:15]
	v_mfma_f32_16x16x32_bf16 v[12:15], v[216:219], v[60:63], v[164:167]
	v_mfma_f32_16x16x32_bf16 v[40:43], v[220:223], v[84:87], v[12:15]
	v_mfma_f32_16x16x32_bf16 v[12:15], v[4:7], v[88:91], v[168:171]
	v_mfma_f32_16x16x32_bf16 v[28:31], v[8:11], v[108:111], v[12:15]
	v_mfma_f32_16x16x32_bf16 v[12:15], v[216:219], v[88:91], v[172:175]
	v_mfma_f32_16x16x32_bf16 v[4:7], v[4:7], v[112:115], v[16:19]
	v_mfma_f32_16x16x32_bf16 v[24:27], v[220:223], v[108:111], v[12:15]
	v_mfma_f32_16x16x32_bf16 v[12:15], v[8:11], v[240:243], v[4:7]
	v_mfma_f32_16x16x32_bf16 v[4:7], v[216:219], v[112:115], v[20:23]
	v_mfma_f32_16x16x32_bf16 v[8:11], v[220:223], v[240:243], v[4:7]
	v_mfma_f32_16x16x32_bf16 v[4:7], v[224:227], v[32:35], v[176:179]
	v_mfma_f32_16x16x32_bf16 v[52:55], v[228:231], v[36:39], v[4:7]
	v_mfma_f32_16x16x32_bf16 v[4:7], v[232:235], v[32:35], v[180:183]
	v_mfma_f32_16x16x32_bf16 v[48:51], v[236:239], v[36:39], v[4:7]
	v_mfma_f32_16x16x32_bf16 v[4:7], v[224:227], v[60:63], v[186:189]
	v_mfma_f32_16x16x32_bf16 v[36:39], v[228:231], v[84:87], v[4:7]
	v_mfma_f32_16x16x32_bf16 v[4:7], v[232:235], v[60:63], v[190:193]
	v_mfma_f32_16x16x32_bf16 v[32:35], v[236:239], v[84:87], v[4:7]
	v_mfma_f32_16x16x32_bf16 v[4:7], v[224:227], v[88:91], v[194:197]
	v_mfma_f32_16x16x32_bf16 v[20:23], v[228:231], v[108:111], v[4:7]
	v_mfma_f32_16x16x32_bf16 v[4:7], v[232:235], v[88:91], v[198:201]
	v_mfma_f32_16x16x32_bf16 v[0:3], v[224:227], v[112:115], v[0:3]
	v_mfma_f32_16x16x32_bf16 v[16:19], v[236:239], v[108:111], v[4:7]
	v_mfma_f32_16x16x32_bf16 v[4:7], v[228:231], v[240:243], v[0:3]
	v_mfma_f32_16x16x32_bf16 v[0:3], v[232:235], v[112:115], v[212:215]
	v_mfma_f32_16x16x32_bf16 v[0:3], v[236:239], v[240:243], v[0:3]
	s_barrier
	s_add_u32 s73, s48, 0x200
	s_addc_u32 s74, s49, 0
	s_add_u32 s75, s4, 0x200
	s_addc_u32 s76, s5, 0
	s_add_u32 s4, s48, 0x160180
	s_addc_u32 s5, s49, 0
	s_mov_b32 s77, 0
.LBB0_2987:
	s_cmpk_eq_i32 s77, 0x54
	s_cselect_b32 s52, s44, s73
	s_cselect_b32 s53, s45, s74
	s_cselect_b32 s50, s46, s75
	s_cselect_b32 s51, s47, s76
	s_add_u32 s48, s52, 0x80
	s_addc_u32 s49, s53, 0
	s_add_i32 s78, 0, 0x10000
	s_add_i32 s80, 0, 0x14000
	v_add_u32_e32 v108, s78, v206
	v_add_u32_e32 v138, s80, v206
	ds_read_b128 v[60:63], v108
	ds_read_b128 v[84:87], v108 offset:1024
	ds_read_b128 v[88:91], v108 offset:2048
	ds_read_b128 v[108:111], v108 offset:3072
	ds_read_b128 v[112:115], v138
	ds_read_b128 v[134:137], v138 offset:1024
	ds_read_b128 v[156:159], v138 offset:2048
	ds_read_b128 v[160:163], v138 offset:3072
	s_mov_b32 m0, s0
	ds_read_b128 v[164:167], v209
	ds_read_b128 v[168:171], v209 offset:1024
	ds_read_b128 v[172:175], v209 offset:2048
	ds_read_b128 v[176:179], v209 offset:3072
	ds_read_b128 v[180:183], v209 offset:4096
	ds_read_b128 v[186:189], v209 offset:5120
	ds_read_b128 v[190:193], v209 offset:6144
	ds_read_b128 v[194:197], v209 offset:7168
	global_load_lds_dwordx4 v202, s[4:5]
	s_mov_b32 m0, s1
	s_nop 0
	global_load_lds_dwordx4 v204, s[4:5]
	s_waitcnt vmcnt(8)
	s_waitcnt lgkmcnt(0)
	s_barrier
	v_mfma_f32_16x16x32_bf16 v[152:155], v[60:63], v[164:167], v[152:155]
	v_mfma_f32_16x16x32_bf16 v[148:151], v[88:91], v[164:167], v[148:151]
	v_mfma_f32_16x16x32_bf16 v[128:131], v[60:63], v[172:175], v[128:131]
	v_mfma_f32_16x16x32_bf16 v[124:127], v[88:91], v[172:175], v[124:127]
	v_mfma_f32_16x16x32_bf16 v[104:107], v[60:63], v[180:183], v[104:107]
	v_mfma_f32_16x16x32_bf16 v[100:103], v[88:91], v[180:183], v[100:103]
	v_mfma_f32_16x16x32_bf16 v[80:83], v[60:63], v[190:193], v[80:83]
	v_mfma_f32_16x16x32_bf16 v[76:79], v[88:91], v[190:193], v[76:79]
	v_mfma_f32_16x16x32_bf16 v[152:155], v[84:87], v[168:171], v[152:155]
	v_mfma_f32_16x16x32_bf16 v[148:151], v[108:111], v[168:171], v[148:151]
	v_mfma_f32_16x16x32_bf16 v[128:131], v[84:87], v[176:179], v[128:131]
	v_mfma_f32_16x16x32_bf16 v[124:127], v[108:111], v[176:179], v[124:127]
	v_mfma_f32_16x16x32_bf16 v[104:107], v[84:87], v[186:189], v[104:107]
	v_mfma_f32_16x16x32_bf16 v[100:103], v[108:111], v[186:189], v[100:103]
	v_mfma_f32_16x16x32_bf16 v[80:83], v[84:87], v[194:197], v[80:83]
	v_mfma_f32_16x16x32_bf16 v[76:79], v[108:111], v[194:197], v[76:79]
	v_mfma_f32_16x16x32_bf16 v[144:147], v[112:115], v[164:167], v[144:147]
	v_mfma_f32_16x16x32_bf16 v[138:141], v[156:159], v[164:167], v[140:143]
	v_mfma_f32_16x16x32_bf16 v[120:123], v[112:115], v[172:175], v[120:123]
	v_mfma_f32_16x16x32_bf16 v[116:119], v[156:159], v[172:175], v[116:119]
	v_mfma_f32_16x16x32_bf16 v[96:99], v[112:115], v[180:183], v[96:99]
	v_mfma_f32_16x16x32_bf16 v[92:95], v[156:159], v[180:183], v[92:95]
	v_mfma_f32_16x16x32_bf16 v[72:75], v[112:115], v[190:193], v[72:75]
	v_mfma_f32_16x16x32_bf16 v[68:71], v[156:159], v[190:193], v[68:71]
	v_mfma_f32_16x16x32_bf16 v[144:147], v[134:137], v[168:171], v[144:147]
	v_mfma_f32_16x16x32_bf16 v[138:141], v[160:163], v[168:171], v[138:141]
	v_mfma_f32_16x16x32_bf16 v[120:123], v[134:137], v[176:179], v[120:123]
	v_mfma_f32_16x16x32_bf16 v[116:119], v[160:163], v[176:179], v[116:119]
	v_mfma_f32_16x16x32_bf16 v[96:99], v[134:137], v[186:189], v[96:99]
	v_mfma_f32_16x16x32_bf16 v[92:95], v[160:163], v[186:189], v[92:95]
	v_mfma_f32_16x16x32_bf16 v[72:75], v[134:137], v[194:197], v[72:75]
	v_mfma_f32_16x16x32_bf16 v[68:71], v[160:163], v[194:197], v[68:71]
	s_barrier
	s_add_i32 s78, s78, s25
	s_mov_b32 m0, s78
	ds_read_b128 v[164:167], v209 offset:16384
	ds_read_b128 v[168:171], v209 offset:17408
	ds_read_b128 v[172:175], v209 offset:18432
	ds_read_b128 v[176:179], v209 offset:19456
	ds_read_b128 v[180:183], v209 offset:20480
	ds_read_b128 v[186:189], v209 offset:21504
	ds_read_b128 v[190:193], v209 offset:22528
	ds_read_b128 v[194:197], v209 offset:23552
	global_load_lds_dwordx4 v203, s[50:51]
	s_add_i32 m0, s78, 0x2000
	s_add_u32 s78, s50, 0x160000
	s_addc_u32 s79, s51, 0
	s_add_i32 s80, s80, s25
	s_nop 0
	global_load_lds_dwordx4 v205, s[50:51]
	s_mov_b32 m0, s80
	s_nop 0
	global_load_lds_dwordx4 v203, s[78:79]
	s_add_i32 m0, s80, 0x2000
	s_nop 0
	global_load_lds_dwordx4 v205, s[78:79]
	s_mov_b32 m0, s26
	s_nop 0
	global_load_lds_dwordx4 v202, s[52:53]
	s_mov_b32 m0, s57
	s_nop 0
	global_load_lds_dwordx4 v204, s[52:53]
	s_waitcnt vmcnt(8)
	s_waitcnt lgkmcnt(0)
	s_barrier
	v_mfma_f32_16x16x32_bf16 v[64:67], v[60:63], v[164:167], v[64:67]
	v_mfma_f32_16x16x32_bf16 v[56:59], v[88:91], v[164:167], v[56:59]
	v_mfma_f32_16x16x32_bf16 v[44:47], v[60:63], v[172:175], v[44:47]
	v_mfma_f32_16x16x32_bf16 v[40:43], v[88:91], v[172:175], v[40:43]
	v_mfma_f32_16x16x32_bf16 v[28:31], v[60:63], v[180:183], v[28:31]
	v_mfma_f32_16x16x32_bf16 v[24:27], v[88:91], v[180:183], v[24:27]
	v_mfma_f32_16x16x32_bf16 v[12:15], v[60:63], v[190:193], v[12:15]
	v_mfma_f32_16x16x32_bf16 v[8:11], v[88:91], v[190:193], v[8:11]
	v_mfma_f32_16x16x32_bf16 v[64:67], v[84:87], v[168:171], v[64:67]
	v_mfma_f32_16x16x32_bf16 v[56:59], v[108:111], v[168:171], v[56:59]
	v_mfma_f32_16x16x32_bf16 v[44:47], v[84:87], v[176:179], v[44:47]
	v_mfma_f32_16x16x32_bf16 v[40:43], v[108:111], v[176:179], v[40:43]
	v_mfma_f32_16x16x32_bf16 v[28:31], v[84:87], v[186:189], v[28:31]
	v_mfma_f32_16x16x32_bf16 v[24:27], v[108:111], v[186:189], v[24:27]
	v_mfma_f32_16x16x32_bf16 v[12:15], v[84:87], v[194:197], v[12:15]
	v_mfma_f32_16x16x32_bf16 v[8:11], v[108:111], v[194:197], v[8:11]
	v_mfma_f32_16x16x32_bf16 v[52:55], v[112:115], v[164:167], v[52:55]
	v_mfma_f32_16x16x32_bf16 v[48:51], v[156:159], v[164:167], v[48:51]
	v_mfma_f32_16x16x32_bf16 v[36:39], v[112:115], v[172:175], v[36:39]
	v_mfma_f32_16x16x32_bf16 v[32:35], v[156:159], v[172:175], v[32:35]
	v_mfma_f32_16x16x32_bf16 v[20:23], v[112:115], v[180:183], v[20:23]
	v_mfma_f32_16x16x32_bf16 v[16:19], v[156:159], v[180:183], v[16:19]
	v_mfma_f32_16x16x32_bf16 v[4:7], v[112:115], v[190:193], v[4:7]
	v_mfma_f32_16x16x32_bf16 v[0:3], v[156:159], v[190:193], v[0:3]
	v_mfma_f32_16x16x32_bf16 v[52:55], v[134:137], v[168:171], v[52:55]
	v_mfma_f32_16x16x32_bf16 v[48:51], v[160:163], v[168:171], v[48:51]
	v_mfma_f32_16x16x32_bf16 v[36:39], v[134:137], v[176:179], v[36:39]
	v_mfma_f32_16x16x32_bf16 v[32:35], v[160:163], v[176:179], v[32:35]
	v_mfma_f32_16x16x32_bf16 v[20:23], v[134:137], v[186:189], v[20:23]
	v_mfma_f32_16x16x32_bf16 v[16:19], v[160:163], v[186:189], v[16:19]
	v_mfma_f32_16x16x32_bf16 v[4:7], v[134:137], v[194:197], v[4:7]
	v_mfma_f32_16x16x32_bf16 v[0:3], v[160:163], v[194:197], v[0:3]
	s_barrier
	ds_read_b128 v[60:63], v132
	ds_read_b128 v[84:87], v132 offset:1024
	ds_read_b128 v[88:91], v132 offset:2048
	ds_read_b128 v[108:111], v132 offset:3072
	ds_read_b128 v[112:115], v133
	ds_read_b128 v[134:137], v133 offset:1024
	ds_read_b128 v[156:159], v133 offset:2048
	ds_read_b128 v[160:163], v133 offset:3072
	s_add_u32 s52, s52, 0x160000
	s_addc_u32 s53, s53, 0
	s_mov_b32 m0, s58
	ds_read_b128 v[164:167], v209 offset:32768
	ds_read_b128 v[168:171], v209 offset:33792
	ds_read_b128 v[172:175], v209 offset:34816
	ds_read_b128 v[176:179], v209 offset:35840
	ds_read_b128 v[180:183], v209 offset:36864
	ds_read_b128 v[186:189], v209 offset:37888
	ds_read_b128 v[190:193], v209 offset:38912
	ds_read_b128 v[194:197], v209 offset:39936
	global_load_lds_dwordx4 v202, s[52:53]
	s_mov_b32 m0, s59
	s_nop 0
	global_load_lds_dwordx4 v204, s[52:53]
	s_waitcnt vmcnt(8)
	s_waitcnt lgkmcnt(0)
	s_barrier
	v_mfma_f32_16x16x32_bf16 v[152:155], v[60:63], v[164:167], v[152:155]
	v_mfma_f32_16x16x32_bf16 v[148:151], v[88:91], v[164:167], v[148:151]
	v_mfma_f32_16x16x32_bf16 v[128:131], v[60:63], v[172:175], v[128:131]
	v_mfma_f32_16x16x32_bf16 v[124:127], v[88:91], v[172:175], v[124:127]
	v_mfma_f32_16x16x32_bf16 v[104:107], v[60:63], v[180:183], v[104:107]
	v_mfma_f32_16x16x32_bf16 v[100:103], v[88:91], v[180:183], v[100:103]
	v_mfma_f32_16x16x32_bf16 v[80:83], v[60:63], v[190:193], v[80:83]
	v_mfma_f32_16x16x32_bf16 v[76:79], v[88:91], v[190:193], v[76:79]
	v_mfma_f32_16x16x32_bf16 v[152:155], v[84:87], v[168:171], v[152:155]
	v_mfma_f32_16x16x32_bf16 v[148:151], v[108:111], v[168:171], v[148:151]
	v_mfma_f32_16x16x32_bf16 v[128:131], v[84:87], v[176:179], v[128:131]
	v_mfma_f32_16x16x32_bf16 v[124:127], v[108:111], v[176:179], v[124:127]
	v_mfma_f32_16x16x32_bf16 v[104:107], v[84:87], v[186:189], v[104:107]
	v_mfma_f32_16x16x32_bf16 v[100:103], v[108:111], v[186:189], v[100:103]
	v_mfma_f32_16x16x32_bf16 v[80:83], v[84:87], v[194:197], v[80:83]
	v_mfma_f32_16x16x32_bf16 v[76:79], v[108:111], v[194:197], v[76:79]
	v_mfma_f32_16x16x32_bf16 v[142:145], v[112:115], v[164:167], v[144:147]
	v_mfma_f32_16x16x32_bf16 v[138:141], v[156:159], v[164:167], v[138:141]
	v_mfma_f32_16x16x32_bf16 v[120:123], v[112:115], v[172:175], v[120:123]
	v_mfma_f32_16x16x32_bf16 v[116:119], v[156:159], v[172:175], v[116:119]
	v_mfma_f32_16x16x32_bf16 v[96:99], v[112:115], v[180:183], v[96:99]
	v_mfma_f32_16x16x32_bf16 v[92:95], v[156:159], v[180:183], v[92:95]
	v_mfma_f32_16x16x32_bf16 v[72:75], v[112:115], v[190:193], v[72:75]
	v_mfma_f32_16x16x32_bf16 v[68:71], v[156:159], v[190:193], v[68:71]
	v_mfma_f32_16x16x32_bf16 v[144:147], v[134:137], v[168:171], v[142:145]
	v_mfma_f32_16x16x32_bf16 v[140:143], v[160:163], v[168:171], v[138:141]
	v_mfma_f32_16x16x32_bf16 v[120:123], v[134:137], v[176:179], v[120:123]
	v_mfma_f32_16x16x32_bf16 v[116:119], v[160:163], v[176:179], v[116:119]
	v_mfma_f32_16x16x32_bf16 v[96:99], v[134:137], v[186:189], v[96:99]
	v_mfma_f32_16x16x32_bf16 v[92:95], v[160:163], v[186:189], v[92:95]
	v_mfma_f32_16x16x32_bf16 v[72:75], v[134:137], v[194:197], v[72:75]
	v_mfma_f32_16x16x32_bf16 v[68:71], v[160:163], v[194:197], v[68:71]
	s_barrier
	s_add_u32 s52, s50, 0x80
	s_mov_b32 m0, s12
	s_addc_u32 s53, s51, 0
	ds_read_b128 v[164:167], v209 offset:49152
	ds_read_b128 v[168:171], v209 offset:50176
	ds_read_b128 v[172:175], v209 offset:51200
	ds_read_b128 v[176:179], v209 offset:52224
	ds_read_b128 v[180:183], v209 offset:53248
	ds_read_b128 v[186:189], v209 offset:54272
	ds_read_b128 v[190:193], v209 offset:55296
	ds_read_b128 v[194:197], v209 offset:56320
	s_add_u32 s50, s50, 0x160080
	global_load_lds_dwordx4 v203, s[52:53]
	s_mov_b32 m0, s20
	s_addc_u32 s51, s51, 0
	global_load_lds_dwordx4 v205, s[52:53]
	s_mov_b32 m0, s21
	s_nop 0
	global_load_lds_dwordx4 v203, s[50:51]
	s_mov_b32 m0, s72
	s_nop 0
	global_load_lds_dwordx4 v205, s[50:51]
	s_mov_b32 m0, s60
	s_nop 0
	global_load_lds_dwordx4 v202, s[48:49]
	s_mov_b32 m0, s61
	s_nop 0
	global_load_lds_dwordx4 v204, s[48:49]
	s_waitcnt vmcnt(8)
	s_waitcnt lgkmcnt(0)
	s_barrier
	v_mfma_f32_16x16x32_bf16 v[64:67], v[60:63], v[164:167], v[64:67]
	v_mfma_f32_16x16x32_bf16 v[56:59], v[88:91], v[164:167], v[56:59]
	v_mfma_f32_16x16x32_bf16 v[44:47], v[60:63], v[172:175], v[44:47]
	v_mfma_f32_16x16x32_bf16 v[40:43], v[88:91], v[172:175], v[40:43]
	v_mfma_f32_16x16x32_bf16 v[28:31], v[60:63], v[180:183], v[28:31]
	v_mfma_f32_16x16x32_bf16 v[24:27], v[88:91], v[180:183], v[24:27]
	v_mfma_f32_16x16x32_bf16 v[12:15], v[60:63], v[190:193], v[12:15]
	v_mfma_f32_16x16x32_bf16 v[8:11], v[88:91], v[190:193], v[8:11]
	v_mfma_f32_16x16x32_bf16 v[64:67], v[84:87], v[168:171], v[64:67]
	v_mfma_f32_16x16x32_bf16 v[56:59], v[108:111], v[168:171], v[56:59]
	v_mfma_f32_16x16x32_bf16 v[44:47], v[84:87], v[176:179], v[44:47]
	v_mfma_f32_16x16x32_bf16 v[40:43], v[108:111], v[176:179], v[40:43]
	v_mfma_f32_16x16x32_bf16 v[28:31], v[84:87], v[186:189], v[28:31]
	v_mfma_f32_16x16x32_bf16 v[24:27], v[108:111], v[186:189], v[24:27]
	v_mfma_f32_16x16x32_bf16 v[12:15], v[84:87], v[194:197], v[12:15]
	v_mfma_f32_16x16x32_bf16 v[8:11], v[108:111], v[194:197], v[8:11]
	v_mfma_f32_16x16x32_bf16 v[52:55], v[112:115], v[164:167], v[52:55]
	v_mfma_f32_16x16x32_bf16 v[48:51], v[156:159], v[164:167], v[48:51]
	v_mfma_f32_16x16x32_bf16 v[36:39], v[112:115], v[172:175], v[36:39]
	v_mfma_f32_16x16x32_bf16 v[32:35], v[156:159], v[172:175], v[32:35]
	v_mfma_f32_16x16x32_bf16 v[20:23], v[112:115], v[180:183], v[20:23]
	v_mfma_f32_16x16x32_bf16 v[16:19], v[156:159], v[180:183], v[16:19]
	v_mfma_f32_16x16x32_bf16 v[4:7], v[112:115], v[190:193], v[4:7]
	v_mfma_f32_16x16x32_bf16 v[0:3], v[156:159], v[190:193], v[0:3]
	v_mfma_f32_16x16x32_bf16 v[52:55], v[134:137], v[168:171], v[52:55]
	v_mfma_f32_16x16x32_bf16 v[48:51], v[160:163], v[168:171], v[48:51]
	v_mfma_f32_16x16x32_bf16 v[36:39], v[134:137], v[176:179], v[36:39]
	v_mfma_f32_16x16x32_bf16 v[32:35], v[160:163], v[176:179], v[32:35]
	v_mfma_f32_16x16x32_bf16 v[20:23], v[134:137], v[186:189], v[20:23]
	v_mfma_f32_16x16x32_bf16 v[16:19], v[160:163], v[186:189], v[16:19]
	v_mfma_f32_16x16x32_bf16 v[4:7], v[134:137], v[194:197], v[4:7]
	v_mfma_f32_16x16x32_bf16 v[0:3], v[160:163], v[194:197], v[0:3]
	s_barrier
	s_add_i32 s77, s77, 2
	s_add_u32 s73, s73, 0x100
	s_addc_u32 s74, s74, 0
	s_add_u32 s75, s75, 0x100
	s_addc_u32 s76, s76, 0
	s_add_u32 s4, s4, 0x100
	s_addc_u32 s5, s5, 0
	s_cmpk_gt_u32 s77, 0x55
	s_cbranch_scc0 .LBB0_2987
	s_and_b64 vcc, exec, s[34:35]
	s_cbranch_vccz .LBB0_2990
	s_barrier
